# all flat_ loads/stores/atomics issued as global_ ops (they only address global memory; LDS goes through ds_)
# speedup vs baseline: 1.0014x; 1.0014x over previous
.LBB0_5:
	v_ashrrev_i32_e32 v6, 3, v4
	v_ashrrev_i32_e32 v7, 31, v6
	s_waitcnt lgkmcnt(0)
	v_lshl_add_u64 v[8:9], v[6:7], 2, s[38:39]
	global_load_dword v8, v[8:9], off
	v_add_u32_e32 v4, s9, v4
	v_cmp_lt_i32_e32 vcc, s10, v4
	v_lshlrev_b64 v[6:7], 6, v[6:7]
	s_or_b64 s[4:5], vcc, s[4:5]
	v_lshl_add_u64 v[6:7], v[2:3], 0, v[6:7]
	s_waitcnt vmcnt(0)
	v_cvt_f32_i32_e32 v8, v8
	v_mul_f32_e32 v8, v5, v8
	v_cvt_f64_f32_e32 v[8:9], v8
	v_mul_f64 v[10:11], v[8:9], s[6:7]
	v_floor_f64_e32 v[10:11], v[10:11]
	v_fma_f64 v[8:9], v[8:9], s[6:7], -v[10:11]
	v_cvt_f32_f64_e32 v8, v[8:9]
	v_cos_f32_e32 v9, v8
	v_sin_f32_e32 v8, v8
	global_store_dword v[6:7], v9, off
	global_store_dword v[6:7], v8, off offset:32
	s_andn2_b64 exec, exec, s[4:5]
	s_cbranch_execnz .LBB0_5

.LBB0_7:
	s_or_b64 exec, exec, s[8:9]
	v_mov_b32_e32 v0, s15
	v_add_co_u32_e32 v0, vcc, 0x3000, v0
	v_mov_b32_e32 v1, s14
	s_nop 0
	v_addc_co_u32_e32 v1, vcc, 0, v1, vcc
	v_mov_b32_e32 v2, 1
	global_atomic_add v[0:1], v2, off

.LBB0_13:
	s_cmpk_gt_i32 s23, 0xaff
	s_mov_b64 s[14:15], -1
	s_cbranch_scc0 .LBB0_15
	s_and_b32 s14, s21, 0x7fffffc0
	s_addk_i32 s14, 0xea00
	s_and_b32 s24, s16, 0x3e0
	v_add_u32_e32 v32, s14, v7
	v_add_u32_e32 v34, s14, v8
	v_add_u32_e32 v40, s14, v9
	v_add_u32_e32 v42, s14, v10
	v_add_u32_e32 v48, s14, v11
	v_add_u32_e32 v50, s14, v12
	s_lshl_b32 s92, s24, 2
	v_ashrrev_i32_e32 v33, 31, v32
	v_ashrrev_i32_e32 v35, 31, v34
	v_ashrrev_i32_e32 v41, 31, v40
	v_ashrrev_i32_e32 v43, 31, v42
	v_ashrrev_i32_e32 v49, 31, v48
	v_ashrrev_i32_e32 v51, 31, v50
	v_lshl_add_u64 v[60:61], v[0:1], 0, s[92:93]
	v_lshlrev_b64 v[32:33], 12, v[32:33]
	v_lshlrev_b64 v[34:35], 12, v[34:35]
	v_lshlrev_b64 v[40:41], 12, v[40:41]
	v_lshlrev_b64 v[42:43], 12, v[42:43]
	v_lshlrev_b64 v[48:49], 12, v[48:49]
	v_lshlrev_b64 v[50:51], 12, v[50:51]
	v_lshl_add_u64 v[32:33], v[60:61], 0, v[32:33]
	v_lshl_add_u64 v[36:37], v[60:61], 0, v[34:35]
	v_lshl_add_u64 v[40:41], v[60:61], 0, v[40:41]
	v_lshl_add_u64 v[44:45], v[60:61], 0, v[42:43]
	v_lshl_add_u64 v[48:49], v[60:61], 0, v[48:49]
	v_lshl_add_u64 v[52:53], v[60:61], 0, v[50:51]
	global_load_dwordx4 v[32:35], v[32:33], off
	s_nop 0
	global_load_dwordx4 v[36:39], v[36:37], off
	s_nop 0
	global_load_dwordx4 v[40:43], v[40:41], off
	s_nop 0
	global_load_dwordx4 v[44:47], v[44:45], off
	s_nop 0
	global_load_dwordx4 v[48:51], v[48:49], off
	s_nop 0
	global_load_dwordx4 v[52:55], v[52:53], off
	v_add_u32_e32 v56, s14, v13
	v_ashrrev_i32_e32 v57, 31, v56
	v_lshlrev_b64 v[56:57], 12, v[56:57]
	v_add_u32_e32 v62, s14, v14
	v_lshl_add_u64 v[56:57], v[60:61], 0, v[56:57]
	v_ashrrev_i32_e32 v63, 31, v62
	global_load_dwordx4 v[56:59], v[56:57], off
	v_lshlrev_b64 v[62:63], 12, v[62:63]
	v_lshl_add_u64 v[60:61], v[60:61], 0, v[62:63]
	global_load_dwordx4 v[60:63], v[60:61], off
	s_mov_b32 s15, s93
	v_add_u32_e32 v31, s24, v7
	v_lshl_add_u64 v[64:65], s[14:15], 1, v[2:3]
	v_add_u32_e32 v66, s24, v8
	s_waitcnt vmcnt(0)
	ds_write2_b32 v16, v32, v33 offset1:1
	ds_write2_b32 v16, v34, v35 offset0:2 offset1:3
	ds_write2_b32 v17, v36, v37 offset1:1
	ds_write2_b32 v18, v38, v39 offset1:1
	ds_write2_b32 v19, v40, v41 offset1:1
	ds_write2_b32 v20, v42, v43 offset1:1
	ds_write2_b32 v21, v44, v45 offset1:1
	ds_write2_b32 v22, v46, v47 offset1:1
	ds_write2_b32 v23, v48, v49 offset1:1
	ds_write2_b32 v24, v50, v51 offset1:1
	ds_write2_b32 v25, v52, v53 offset1:1
	ds_write2_b32 v26, v54, v55 offset1:1
	ds_write2_b32 v27, v56, v57 offset1:1
	ds_write2_b32 v28, v58, v59 offset1:1
	ds_write2_b32 v29, v60, v61 offset1:1
	ds_write2_b32 v30, v62, v63 offset1:1
	s_waitcnt lgkmcnt(0)
	ds_read_b32 v32, v15
	ds_read_b32 v33, v15 offset:132
	ds_read_b32 v34, v15 offset:264
	ds_read_b32 v35, v15 offset:396
	ds_read_b32 v38, v15 offset:528
	ds_read_b32 v39, v15 offset:660
	ds_read_b32 v40, v15 offset:792
	ds_read_b32 v41, v15 offset:924
	v_mad_i64_i32 v[36:37], s[14:15], v31, s63, v[64:65]
	s_waitcnt lgkmcnt(0)
	v_cvt_pk_bf16_f32 v32, v32, v33
	s_waitcnt lgkmcnt(4)
	v_cvt_pk_bf16_f32 v33, v34, v35
	s_waitcnt lgkmcnt(2)
	v_cvt_pk_bf16_f32 v34, v38, v39
	s_waitcnt lgkmcnt(0)
	v_cvt_pk_bf16_f32 v35, v40, v41
	global_store_dwordx4 v[36:37], v[32:35], off
	ds_read_b32 v31, v15 offset:32
	ds_read_b32 v32, v15 offset:164
	ds_read_b32 v33, v15 offset:296
	ds_read_b32 v34, v15 offset:428
	ds_read_b32 v35, v15 offset:560
	ds_read_b32 v38, v15 offset:692
	ds_read_b32 v39, v15 offset:824
	ds_read_b32 v40, v15 offset:956
	v_mad_i64_i32 v[36:37], s[14:15], v66, s63, v[64:65]
	s_waitcnt lgkmcnt(0)
	v_cvt_pk_bf16_f32 v32, v31, v32
	v_cvt_pk_bf16_f32 v33, v33, v34
	v_cvt_pk_bf16_f32 v34, v35, v38
	v_cvt_pk_bf16_f32 v35, v39, v40
	global_store_dwordx4 v[36:37], v[32:35], off
	ds_read_b32 v31, v15 offset:64
	ds_read_b32 v32, v15 offset:196
	ds_read_b32 v33, v15 offset:328
	ds_read_b32 v34, v15 offset:460
	ds_read_b32 v35, v15 offset:592
	ds_read_b32 v36, v15 offset:724
	ds_read_b32 v37, v15 offset:856
	ds_read_b32 v38, v15 offset:988
	s_waitcnt lgkmcnt(0)
	v_cvt_pk_bf16_f32 v32, v31, v32
	v_add_u32_e32 v31, s24, v9
	v_cvt_pk_bf16_f32 v33, v33, v34
	v_cvt_pk_bf16_f32 v34, v35, v36
	v_cvt_pk_bf16_f32 v35, v37, v38
	v_mad_i64_i32 v[36:37], s[14:15], v31, s63, v[64:65]
	global_store_dwordx4 v[36:37], v[32:35], off
	ds_read_b32 v31, v15 offset:96
	ds_read_b32 v32, v15 offset:228
	ds_read_b32 v33, v15 offset:360
	ds_read_b32 v34, v15 offset:492
	ds_read_b32 v35, v15 offset:624
	ds_read_b32 v36, v15 offset:756
	ds_read_b32 v37, v15 offset:888
	ds_read_b32 v38, v15 offset:1020
	s_waitcnt lgkmcnt(0)
	v_cvt_pk_bf16_f32 v32, v31, v32
	v_add_u32_e32 v31, s24, v10
	v_cvt_pk_bf16_f32 v33, v33, v34
	v_cvt_pk_bf16_f32 v34, v35, v36
	v_cvt_pk_bf16_f32 v35, v37, v38
	v_mad_i64_i32 v[36:37], s[14:15], v31, s63, v[64:65]
	global_store_dwordx4 v[36:37], v[32:35], off
	s_waitcnt lgkmcnt(0)
	s_mov_b64 s[14:15], 0
.LBB0_15:
	s_andn2_b64 vcc, exec, s[14:15]
	s_cbranch_vccnz .LBB0_12
	s_mul_hi_i32 s14, s23, 0x2e8ba2e9
	s_lshr_b32 s15, s14, 31
	s_ashr_i32 s14, s14, 5
	s_add_i32 s26, s14, s15
	s_mul_i32 s14, s26, 0xffffea00
	s_add_i32 s27, s16, s14
	s_mul_i32 s14, s26, 0xfffff500
	s_add_i32 s14, s18, s14
	s_and_b32 s14, s14, 0xffffff80
	s_and_b32 s15, s27, 0x60
	s_or_b32 s14, s14, s15
	v_readlane_b32 s52, v254, 10
	s_bitcmp0_b32 s23, 2
	v_readlane_b32 s58, v254, 16
	v_readlane_b32 s60, v254, 18
	v_readlane_b32 s59, v254, 17
	v_readlane_b32 s61, v254, 19
	s_cselect_b32 s24, s58, s60
	s_cselect_b32 s15, s59, s61
	s_add_u32 s24, s24, s12
	s_addc_u32 s25, s15, s13
	s_ashr_i32 s15, s14, 31
	s_lshl_b64 s[14:15], s[14:15], 2
	s_add_u32 s24, s24, s14
	s_addc_u32 s25, s25, s15
	s_lshl_b32 s14, s26, 6
	v_lshl_add_u64 v[60:61], s[24:25], 0, v[136:137]
	v_add_u32_e32 v31, s14, v7
	s_movk_i32 s6, 0x2c00
	v_mad_i64_i32 v[32:33], s[24:25], v31, s6, v[60:61]
	v_add_u32_e32 v31, s14, v8
	v_mad_i64_i32 v[36:37], s[24:25], v31, s6, v[60:61]
	v_add_u32_e32 v31, s14, v9
	v_mad_i64_i32 v[40:41], s[24:25], v31, s6, v[60:61]
	v_add_u32_e32 v31, s14, v10
	v_mad_i64_i32 v[44:45], s[24:25], v31, s6, v[60:61]
	v_add_u32_e32 v31, s14, v11
	v_mad_i64_i32 v[48:49], s[24:25], v31, s6, v[60:61]
	v_add_u32_e32 v31, s14, v12
	v_mad_i64_i32 v[52:53], s[24:25], v31, s6, v[60:61]
	global_load_dwordx4 v[32:35], v[32:33], off
	s_nop 0
	global_load_dwordx4 v[36:39], v[36:37], off
	s_nop 0
	global_load_dwordx4 v[40:43], v[40:41], off
	s_nop 0
	global_load_dwordx4 v[44:47], v[44:45], off
	s_nop 0
	global_load_dwordx4 v[48:51], v[48:49], off
	s_nop 0
	global_load_dwordx4 v[52:55], v[52:53], off
	v_add_u32_e32 v31, s14, v13
	v_mad_i64_i32 v[56:57], s[24:25], v31, s6, v[60:61]
	global_load_dwordx4 v[56:59], v[56:57], off
	v_add_u32_e32 v31, s14, v14
	v_mad_i64_i32 v[60:61], s[24:25], v31, s6, v[60:61]
	global_load_dwordx4 v[60:63], v[60:61], off
	v_add_u32_e32 v64, s27, v7
	v_ashrrev_i32_e32 v65, 31, v64
	s_ashr_i32 s15, s14, 31
	v_lshlrev_b64 v[68:69], 11, v[64:65]
	v_lshl_add_u64 v[70:71], s[14:15], 1, v[4:5]
	v_add_u32_e32 v66, 8, v64
	v_ashrrev_i32_e32 v67, 31, v66
	v_lshlrev_b64 v[66:67], 11, v[66:67]
	v_readlane_b32 s62, v254, 20
	v_readlane_b32 s63, v254, 21
	s_movk_i32 s63, 0x1600
	v_readlane_b32 s62, v254, 9
	v_readlane_b32 s53, v254, 11
	v_readlane_b32 s54, v254, 12
	v_readlane_b32 s55, v254, 13
	v_readlane_b32 s56, v254, 14
	v_readlane_b32 s57, v254, 15
	v_readlane_b32 s64, v254, 22
	v_readlane_b32 s65, v254, 23
	v_readlane_b32 s66, v254, 24
	v_readlane_b32 s67, v254, 25
	s_waitcnt vmcnt(0)
	ds_write2_b32 v16, v32, v33 offset1:1
	ds_write2_b32 v16, v34, v35 offset0:2 offset1:3
	ds_write2_b32 v17, v36, v37 offset1:1
	ds_write2_b32 v18, v38, v39 offset1:1
	ds_write2_b32 v19, v40, v41 offset1:1
	ds_write2_b32 v20, v42, v43 offset1:1
	ds_write2_b32 v21, v44, v45 offset1:1
	ds_write2_b32 v22, v46, v47 offset1:1
	ds_write2_b32 v23, v48, v49 offset1:1
	ds_write2_b32 v24, v50, v51 offset1:1
	ds_write2_b32 v25, v52, v53 offset1:1
	ds_write2_b32 v26, v54, v55 offset1:1
	ds_write2_b32 v27, v56, v57 offset1:1
	ds_write2_b32 v28, v58, v59 offset1:1
	ds_write2_b32 v29, v60, v61 offset1:1
	ds_write2_b32 v30, v62, v63 offset1:1
	s_waitcnt lgkmcnt(0)
	ds_read_b32 v31, v15
	ds_read_b32 v32, v15 offset:132
	ds_read_b32 v33, v15 offset:264
	ds_read_b32 v34, v15 offset:396
	ds_read_b32 v35, v15 offset:528
	ds_read_b32 v38, v15 offset:660
	ds_read_b32 v39, v15 offset:792
	ds_read_b32 v40, v15 offset:924
	v_lshl_add_u64 v[36:37], v[70:71], 0, v[68:69]
	s_waitcnt lgkmcnt(0)
	v_cvt_pk_bf16_f32 v32, v31, v32
	v_cvt_pk_bf16_f32 v33, v33, v34
	v_cvt_pk_bf16_f32 v34, v35, v38
	v_cvt_pk_bf16_f32 v35, v39, v40
	global_store_dwordx4 v[36:37], v[32:35], off
	ds_read_b32 v31, v15 offset:32
	ds_read_b32 v32, v15 offset:164
	ds_read_b32 v33, v15 offset:296
	ds_read_b32 v34, v15 offset:428
	ds_read_b32 v35, v15 offset:560
	ds_read_b32 v38, v15 offset:692
	ds_read_b32 v39, v15 offset:824
	ds_read_b32 v40, v15 offset:956
	v_lshl_add_u64 v[36:37], v[70:71], 0, v[66:67]
	s_waitcnt lgkmcnt(0)
	v_cvt_pk_bf16_f32 v32, v31, v32
	v_cvt_pk_bf16_f32 v33, v33, v34
	v_cvt_pk_bf16_f32 v34, v35, v38
	v_cvt_pk_bf16_f32 v35, v39, v40
	global_store_dwordx4 v[36:37], v[32:35], off
	ds_read_b32 v31, v15 offset:64
	ds_read_b32 v32, v15 offset:196
	ds_read_b32 v33, v15 offset:328
	ds_read_b32 v34, v15 offset:460
	ds_read_b32 v35, v15 offset:592
	ds_read_b32 v36, v15 offset:724
	ds_read_b32 v37, v15 offset:856
	ds_read_b32 v38, v15 offset:988
	s_waitcnt lgkmcnt(0)
	v_cvt_pk_bf16_f32 v33, v33, v34
	v_cvt_pk_bf16_f32 v32, v31, v32
	v_cvt_pk_bf16_f32 v34, v35, v36
	v_add_u32_e32 v36, 16, v64
	v_cvt_pk_bf16_f32 v35, v37, v38
	v_ashrrev_i32_e32 v37, 31, v36
	v_lshlrev_b64 v[36:37], 11, v[36:37]
	v_lshl_add_u64 v[36:37], v[70:71], 0, v[36:37]
	global_store_dwordx4 v[36:37], v[32:35], off
	ds_read_b32 v31, v15 offset:96
	ds_read_b32 v32, v15 offset:228
	ds_read_b32 v33, v15 offset:360
	ds_read_b32 v34, v15 offset:492
	ds_read_b32 v35, v15 offset:624
	ds_read_b32 v36, v15 offset:756
	ds_read_b32 v37, v15 offset:888
	ds_read_b32 v38, v15 offset:1020
	s_waitcnt lgkmcnt(0)
	v_cvt_pk_bf16_f32 v33, v33, v34
	v_cvt_pk_bf16_f32 v32, v31, v32
	v_cvt_pk_bf16_f32 v34, v35, v36
	v_add_u32_e32 v36, 24, v64
	v_cvt_pk_bf16_f32 v35, v37, v38
	v_ashrrev_i32_e32 v37, 31, v36
	v_lshlrev_b64 v[36:37], 11, v[36:37]
	v_lshl_add_u64 v[36:37], v[70:71], 0, v[36:37]
	global_store_dwordx4 v[36:37], v[32:35], off
	s_waitcnt lgkmcnt(0)
	s_branch .LBB0_12

.LBB0_20:
	s_ashr_i32 s3, s2, 31
	s_lshl_b64 s[8:9], s[2:3], 12
	v_lshl_add_u64 v[16:17], v[80:81], 0, s[8:9]
	s_add_i32 s8, s2, s7
	s_cmp_lt_i32 s8, 0x8000
	global_load_dwordx4 v[72:75], v[16:17], off
	global_load_dwordx4 v[68:71], v[16:17], off offset:1024
	global_load_dwordx4 v[64:67], v[16:17], off offset:3072
	global_load_dwordx4 v[76:79], v[16:17], off offset:2048
	s_cselect_b32 s10, s8, s2
	s_ashr_i32 s11, s10, 31
	s_lshl_b64 s[10:11], s[10:11], 12
	s_add_i32 s14, s21, s2
	s_cmp_lt_i32 s14, 0x8000
	v_lshl_add_u64 v[16:17], v[80:81], 0, s[10:11]
	s_cselect_b64 s[16:17], -1, 0
	global_load_dwordx4 v[60:63], v[16:17], off
	global_load_dwordx4 v[56:59], v[16:17], off offset:1024
	global_load_dwordx4 v[52:55], v[16:17], off offset:2048
	global_load_dwordx4 v[48:51], v[16:17], off offset:3072
	s_and_b64 s[10:11], s[16:17], exec
	s_cselect_b32 s10, s14, s2
	s_ashr_i32 s11, s10, 31
	s_lshl_b64 s[10:11], s[10:11], 12
	v_lshl_add_u64 v[16:17], v[80:81], 0, s[10:11]
	global_load_dwordx4 v[44:47], v[16:17], off
	global_load_dwordx4 v[40:43], v[16:17], off offset:1024
	global_load_dwordx4 v[36:39], v[16:17], off offset:2048
	s_add_i32 s10, s22, s2
	s_cmp_lt_i32 s10, 0x8000
	s_cselect_b64 s[12:13], -1, 0
	s_and_b64 s[18:19], s[12:13], exec
	s_cselect_b32 s18, s10, s2
	global_load_dwordx4 v[32:35], v[16:17], off offset:3072
	s_ashr_i32 s19, s18, 31
	s_lshl_b64 s[18:19], s[18:19], 12
	v_lshl_add_u64 v[16:17], v[80:81], 0, s[18:19]
	global_load_dwordx4 v[28:31], v[16:17], off
	global_load_dwordx4 v[24:27], v[16:17], off offset:1024
	global_load_dwordx4 v[20:23], v[16:17], off offset:2048
	s_nop 0
	global_load_dwordx4 v[16:19], v[16:17], off offset:3072
	s_lshl_b64 s[18:19], s[2:3], 11
	s_cmpk_gt_i32 s8, 0x7fff
	s_waitcnt vmcnt(0) lgkmcnt(0)
	v_pk_mul_f32 v[90:91], v[74:75], v[74:75]
	v_pk_mul_f32 v[92:93], v[72:73], v[72:73]
	v_pk_mul_f32 v[94:95], v[70:71], v[70:71]
	v_pk_mul_f32 v[96:97], v[68:69], v[68:69]
	v_mul_f32_e32 v101, v64, v64
	v_mul_f32_e32 v98, v77, v77
	v_mul_f32_e32 v100, v79, v79
	v_pk_mov_b32 v[102:103], v[92:93], v[90:91] op_sel:[1,0]
	v_mov_b32_e32 v93, v91
	v_pk_mov_b32 v[90:91], v[96:97], v[94:95] op_sel:[1,0]
	v_mov_b32_e32 v97, v95
	v_mul_f32_e32 v105, v66, v66
	v_mul_f32_e32 v106, v67, v67
	v_pk_fma_f32 v[94:95], v[76:77], v[76:77], v[98:99] op_sel_hi:[1,1,0]
	v_pk_fma_f32 v[98:99], v[78:79], v[78:79], v[100:101] op_sel_hi:[1,1,0]
	v_pk_add_f32 v[92:93], v[102:103], v[92:93]
	v_pk_add_f32 v[90:91], v[90:91], v[96:97]
	v_mul_f32_e32 v104, v65, v65
	v_mov_b32_e32 v95, v105
	v_mov_b32_e32 v99, v106
	v_pk_add_f32 v[92:93], v[92:93], v[92:93] op_sel:[0,1] op_sel_hi:[1,0]
	v_pk_add_f32 v[90:91], v[90:91], v[90:91] op_sel:[0,1] op_sel_hi:[1,0]
	v_pk_add_f32 v[94:95], v[94:95], v[98:99]
	v_mov_b32_e32 v93, v101
	v_mov_b32_e32 v91, v104
	v_mul_f32_e32 v96, v61, v61
	v_mul_f32_e32 v97, v63, v63
	v_mul_f32_e32 v98, v57, v57
	v_mul_f32_e32 v99, v59, v59
	v_mul_f32_e32 v100, v53, v53
	v_mul_f32_e32 v101, v55, v55
	v_pk_add_f32 v[90:91], v[92:93], v[90:91]
	v_fmac_f32_e32 v96, v60, v60
	v_fmac_f32_e32 v97, v62, v62
	v_fmac_f32_e32 v98, v56, v56
	v_fmac_f32_e32 v99, v58, v58
	v_mul_f32_e32 v102, v49, v49
	v_mul_f32_e32 v103, v51, v51
	v_fmac_f32_e32 v100, v52, v52
	v_fmac_f32_e32 v101, v54, v54
	v_pk_add_f32 v[90:91], v[90:91], v[94:95]
	v_add_f32_e32 v92, v96, v97
	v_add_f32_e32 v93, v98, v99
	v_fmac_f32_e32 v102, v48, v48
	v_fmac_f32_e32 v103, v50, v50
	v_add_f32_e32 v94, v100, v101
	v_add_f32_e32 v90, v90, v91
	v_add_f32_e32 v91, v92, v93
	v_add_f32_e32 v91, v91, v94
	v_add_f32_e32 v92, v102, v103
	v_add_f32_e32 v91, v91, v92
	v_mul_f32_e32 v92, v45, v45
	v_mul_f32_e32 v93, v47, v47
	v_fmac_f32_e32 v92, v44, v44
	v_fmac_f32_e32 v93, v46, v46
	v_add_f32_e32 v92, v92, v93
	v_mul_f32_e32 v93, v41, v41
	v_mul_f32_e32 v94, v43, v43
	v_fmac_f32_e32 v93, v40, v40
	v_fmac_f32_e32 v94, v42, v42
	v_add_f32_e32 v93, v93, v94
	v_add_f32_e32 v92, v92, v93
	v_mul_f32_e32 v93, v37, v37
	v_mul_f32_e32 v94, v39, v39
	v_fmac_f32_e32 v93, v36, v36
	v_fmac_f32_e32 v94, v38, v38
	v_add_f32_e32 v93, v93, v94
	v_add_f32_e32 v92, v92, v93
	v_mul_f32_e32 v93, v33, v33
	v_mul_f32_e32 v94, v35, v35
	v_fmac_f32_e32 v93, v32, v32
	v_fmac_f32_e32 v94, v34, v34
	v_add_f32_e32 v93, v93, v94
	v_add_f32_e32 v92, v92, v93
	v_mul_f32_e32 v93, v29, v29
	v_mul_f32_e32 v94, v31, v31
	v_fmac_f32_e32 v93, v28, v28
	v_fmac_f32_e32 v94, v30, v30
	v_add_f32_e32 v93, v93, v94
	v_mul_f32_e32 v94, v25, v25
	v_mul_f32_e32 v95, v27, v27
	v_fmac_f32_e32 v94, v24, v24
	v_fmac_f32_e32 v95, v26, v26
	v_add_f32_e32 v94, v94, v95
	v_add_f32_e32 v93, v93, v94
	v_mul_f32_e32 v94, v21, v21
	v_mul_f32_e32 v95, v23, v23
	ds_bpermute_b32 v96, v84, v90
	v_fmac_f32_e32 v94, v20, v20
	v_fmac_f32_e32 v95, v22, v22
	v_add_f32_e32 v94, v94, v95
	v_add_f32_e32 v93, v93, v94
	v_mul_f32_e32 v94, v17, v17
	v_mul_f32_e32 v95, v19, v19
	v_fmac_f32_e32 v94, v16, v16
	v_fmac_f32_e32 v95, v18, v18
	v_add_f32_e32 v94, v94, v95
	s_waitcnt lgkmcnt(0)
	v_add_f32_e32 v90, v90, v96
	v_add_f32_e32 v93, v93, v94
	ds_bpermute_b32 v96, v85, v90
	ds_bpermute_b32 v97, v84, v91
	ds_bpermute_b32 v94, v84, v92
	ds_bpermute_b32 v95, v84, v93
	s_waitcnt lgkmcnt(3)
	v_add_f32_e32 v90, v90, v96
	s_waitcnt lgkmcnt(2)
	v_add_f32_e32 v91, v91, v97
	s_waitcnt lgkmcnt(1)
	v_add_f32_e32 v92, v92, v94
	s_waitcnt lgkmcnt(0)
	v_add_f32_e32 v93, v93, v95
	ds_bpermute_b32 v95, v86, v90
	ds_bpermute_b32 v97, v85, v91
	ds_bpermute_b32 v94, v85, v92
	s_waitcnt lgkmcnt(2)
	v_add_f32_e32 v90, v90, v95
	s_waitcnt lgkmcnt(1)
	v_add_f32_e32 v91, v91, v97
	s_waitcnt lgkmcnt(0)
	v_add_f32_e32 v92, v92, v94
	ds_bpermute_b32 v95, v87, v90
	ds_bpermute_b32 v96, v86, v91
	ds_bpermute_b32 v97, v86, v92
	ds_bpermute_b32 v94, v85, v93
	s_waitcnt lgkmcnt(3)
	v_add_f32_e32 v90, v90, v95
	s_waitcnt lgkmcnt(2)
	v_add_f32_e32 v91, v91, v96
	s_waitcnt lgkmcnt(1)
	v_add_f32_e32 v92, v92, v97
	ds_bpermute_b32 v97, v88, v90
	ds_bpermute_b32 v95, v87, v91
	s_waitcnt lgkmcnt(2)
	v_add_f32_e32 v93, v93, v94
	ds_bpermute_b32 v94, v86, v93
	ds_bpermute_b32 v96, v87, v92
	s_waitcnt lgkmcnt(3)
	v_add_f32_e32 v90, v90, v97
	s_waitcnt lgkmcnt(2)
	v_add_f32_e32 v91, v91, v95
	ds_bpermute_b32 v95, v89, v90
	s_waitcnt lgkmcnt(2)
	v_add_f32_e32 v93, v93, v94
	ds_bpermute_b32 v94, v87, v93
	s_waitcnt lgkmcnt(2)
	v_add_f32_e32 v92, v92, v96
	ds_bpermute_b32 v96, v88, v92
	s_waitcnt lgkmcnt(2)
	v_add_f32_e32 v90, v90, v95
	v_mov_b32_e32 v95, 0x358637bd
	v_fmamk_f32 v90, v90, 0x3a800000, v95
	v_mul_f32_e32 v95, 0x4f800000, v90
	v_cmp_gt_f32_e32 vcc, s6, v90
	s_waitcnt lgkmcnt(1)
	v_add_f32_e32 v93, v93, v94
	ds_bpermute_b32 v94, v88, v91
	v_cndmask_b32_e32 v95, v90, v95, vcc
	ds_bpermute_b32 v97, v88, v93
	v_sqrt_f32_e32 v98, v95
	s_waitcnt lgkmcnt(2)
	v_add_f32_e32 v92, v92, v96
	s_waitcnt lgkmcnt(1)
	v_add_f32_e32 v94, v91, v94
	v_add_u32_e32 v91, -1, v98
	s_waitcnt lgkmcnt(0)
	v_add_f32_e32 v90, v93, v97
	v_fma_f32 v93, -v91, v98, v95
	v_cmp_ge_f32_e64 s[2:3], 0, v93
	v_add_u32_e32 v93, 1, v98
	v_fma_f32 v96, -v93, v98, v95
	v_cndmask_b32_e64 v91, v98, v91, s[2:3]
	v_cmp_lt_f32_e64 s[2:3], 0, v96
	s_nop 1
	v_cndmask_b32_e64 v91, v91, v93, s[2:3]
	v_mul_f32_e32 v93, 0x37800000, v91
	v_cndmask_b32_e32 v91, v91, v93, vcc
	v_mov_b32_e32 v93, 0x260
	v_cmp_class_f32_e32 vcc, v95, v93
	ds_bpermute_b32 v93, v89, v92
	s_nop 0
	v_cndmask_b32_e32 v96, v91, v95, vcc
	v_div_scale_f32 v97, s[2:3], v96, v96, 1.0
	v_rcp_f32_e32 v98, v97
	ds_bpermute_b32 v95, v89, v94
	ds_bpermute_b32 v91, v89, v90
	v_fma_f32 v99, -v97, v98, 1.0
	v_fmac_f32_e32 v98, v99, v98
	v_div_scale_f32 v99, vcc, 1.0, v96, 1.0
	v_mul_f32_e32 v100, v99, v98
	v_fma_f32 v101, -v97, v100, v99
	v_fmac_f32_e32 v100, v101, v98
	v_fma_f32 v97, -v97, v100, v99
	v_div_fmas_f32 v97, v97, v98, v100
	v_div_fixup_f32 v96, v97, v96, 1.0
	v_pk_mul_f32 v[68:69], v[68:69], v[96:97] op_sel_hi:[1,0]
	v_pk_mul_f32 v[70:71], v[70:71], v[96:97] op_sel_hi:[1,0]
	v_pk_mul_f32 v[68:69], v[4:5], v[68:69]
	v_pk_mul_f32 v[70:71], v[6:7], v[70:71]
	v_lshl_add_u64 v[98:99], v[82:83], 0, s[18:19]
	v_cvt_pk_bf16_f32 v68, v68, v69
	v_cvt_pk_bf16_f32 v69, v70, v71
	v_pk_mul_f32 v[72:73], v[72:73], v[96:97] op_sel_hi:[1,0]
	v_pk_mul_f32 v[74:75], v[74:75], v[96:97] op_sel_hi:[1,0]
	global_store_dwordx2 v[98:99], v[68:69], off offset:512
	v_pk_mul_f32 v[68:69], v[76:77], v[96:97] op_sel_hi:[1,0]
	v_pk_mul_f32 v[70:71], v[78:79], v[96:97] op_sel_hi:[1,0]
	v_pk_mul_f32 v[64:65], v[64:65], v[96:97] op_sel_hi:[1,0]
	v_pk_mul_f32 v[66:67], v[66:67], v[96:97] op_sel_hi:[1,0]
	v_pk_mul_f32 v[74:75], v[2:3], v[74:75]
	v_pk_mul_f32 v[72:73], v[0:1], v[72:73]
	v_pk_mul_f32 v[70:71], v[10:11], v[70:71]
	v_pk_mul_f32 v[68:69], v[8:9], v[68:69]
	v_pk_mul_f32 v[66:67], v[14:15], v[66:67]
	v_pk_mul_f32 v[64:65], v[12:13], v[64:65]
	v_cvt_pk_bf16_f32 v72, v72, v73
	v_cvt_pk_bf16_f32 v73, v74, v75
	v_cvt_pk_bf16_f32 v68, v68, v69
	v_cvt_pk_bf16_f32 v69, v70, v71
	v_cvt_pk_bf16_f32 v64, v64, v65
	v_cvt_pk_bf16_f32 v65, v66, v67
	global_store_dwordx2 v[98:99], v[72:73], off
	global_store_dwordx2 v[98:99], v[68:69], off offset:1024
	global_store_dwordx2 v[98:99], v[64:65], off offset:1536
	s_cbranch_scc0 .LBB0_23
	s_andn2_b64 vcc, exec, s[16:17]
	s_cbranch_vccz .LBB0_24

.LBB0_23:
	s_waitcnt lgkmcnt(0)
	v_add_f32_e32 v64, v94, v95
	v_mov_b32_e32 v65, 0x358637bd
	v_fmamk_f32 v64, v64, 0x3a800000, v65
	v_mul_f32_e32 v65, 0x4f800000, v64
	v_cmp_gt_f32_e32 vcc, s6, v64
	s_ashr_i32 s9, s8, 31
	s_nop 0
	v_cndmask_b32_e32 v64, v64, v65, vcc
	v_sqrt_f32_e32 v65, v64
	s_nop 0
	v_add_u32_e32 v66, -1, v65
	v_fma_f32 v68, -v66, v65, v64
	v_add_u32_e32 v67, 1, v65
	v_cmp_ge_f32_e64 s[2:3], 0, v68
	s_nop 1
	v_cndmask_b32_e64 v66, v65, v66, s[2:3]
	v_fma_f32 v65, -v67, v65, v64
	v_cmp_lt_f32_e64 s[2:3], 0, v65
	s_nop 1
	v_cndmask_b32_e64 v65, v66, v67, s[2:3]
	v_mul_f32_e32 v66, 0x37800000, v65
	v_cndmask_b32_e32 v65, v65, v66, vcc
	v_mov_b32_e32 v66, 0x260
	v_cmp_class_f32_e32 vcc, v64, v66
	s_nop 1
	v_cndmask_b32_e32 v64, v65, v64, vcc
	v_div_scale_f32 v65, s[2:3], v64, v64, 1.0
	v_rcp_f32_e32 v66, v65
	s_lshl_b64 s[2:3], s[8:9], 11
	v_fma_f32 v67, -v65, v66, 1.0
	v_fmac_f32_e32 v66, v67, v66
	v_div_scale_f32 v67, vcc, 1.0, v64, 1.0
	v_mul_f32_e32 v68, v67, v66
	v_fma_f32 v69, -v65, v68, v67
	v_fmac_f32_e32 v68, v69, v66
	v_fma_f32 v65, -v65, v68, v67
	v_div_fmas_f32 v65, v65, v66, v68
	v_div_fixup_f32 v64, v65, v64, 1.0
	v_pk_mul_f32 v[60:61], v[60:61], v[64:65] op_sel_hi:[1,0]
	v_pk_mul_f32 v[62:63], v[62:63], v[64:65] op_sel_hi:[1,0]
	v_pk_mul_f32 v[56:57], v[56:57], v[64:65] op_sel_hi:[1,0]
	v_pk_mul_f32 v[58:59], v[58:59], v[64:65] op_sel_hi:[1,0]
	v_pk_mul_f32 v[52:53], v[52:53], v[64:65] op_sel_hi:[1,0]
	v_pk_mul_f32 v[54:55], v[54:55], v[64:65] op_sel_hi:[1,0]
	v_pk_mul_f32 v[48:49], v[48:49], v[64:65] op_sel_hi:[1,0]
	v_pk_mul_f32 v[50:51], v[50:51], v[64:65] op_sel_hi:[1,0]
	v_pk_mul_f32 v[62:63], v[2:3], v[62:63]
	v_pk_mul_f32 v[60:61], v[0:1], v[60:61]
	v_pk_mul_f32 v[58:59], v[6:7], v[58:59]
	v_pk_mul_f32 v[56:57], v[4:5], v[56:57]
	v_pk_mul_f32 v[54:55], v[10:11], v[54:55]
	v_pk_mul_f32 v[52:53], v[8:9], v[52:53]
	v_pk_mul_f32 v[50:51], v[14:15], v[50:51]
	v_pk_mul_f32 v[48:49], v[12:13], v[48:49]
	v_lshl_add_u64 v[66:67], v[82:83], 0, s[2:3]
	v_cvt_pk_bf16_f32 v60, v60, v61
	v_cvt_pk_bf16_f32 v61, v62, v63
	v_cvt_pk_bf16_f32 v56, v56, v57
	v_cvt_pk_bf16_f32 v57, v58, v59
	v_cvt_pk_bf16_f32 v52, v52, v53
	v_cvt_pk_bf16_f32 v53, v54, v55
	v_cvt_pk_bf16_f32 v48, v48, v49
	v_cvt_pk_bf16_f32 v49, v50, v51
	global_store_dwordx2 v[66:67], v[60:61], off
	global_store_dwordx2 v[66:67], v[56:57], off offset:512
	global_store_dwordx2 v[66:67], v[52:53], off offset:1024
	global_store_dwordx2 v[66:67], v[48:49], off offset:1536
	s_andn2_b64 vcc, exec, s[16:17]
	s_cbranch_vccnz .LBB0_22
.LBB0_24:
	s_waitcnt lgkmcnt(0)
	v_add_f32_e32 v48, v92, v93
	v_mov_b32_e32 v49, 0x358637bd
	v_fmamk_f32 v48, v48, 0x3a800000, v49
	v_mul_f32_e32 v49, 0x4f800000, v48
	v_cmp_gt_f32_e32 vcc, s6, v48
	s_ashr_i32 s15, s14, 31
	s_nop 0
	v_cndmask_b32_e32 v48, v48, v49, vcc
	v_sqrt_f32_e32 v49, v48
	s_nop 0
	v_add_u32_e32 v50, -1, v49
	v_fma_f32 v52, -v50, v49, v48
	v_add_u32_e32 v51, 1, v49
	v_cmp_ge_f32_e64 s[2:3], 0, v52
	s_nop 1
	v_cndmask_b32_e64 v50, v49, v50, s[2:3]
	v_fma_f32 v49, -v51, v49, v48
	v_cmp_lt_f32_e64 s[2:3], 0, v49
	s_nop 1
	v_cndmask_b32_e64 v49, v50, v51, s[2:3]
	v_mul_f32_e32 v50, 0x37800000, v49
	v_cndmask_b32_e32 v49, v49, v50, vcc
	v_mov_b32_e32 v50, 0x260
	v_cmp_class_f32_e32 vcc, v48, v50
	s_nop 1
	v_cndmask_b32_e32 v48, v49, v48, vcc
	v_div_scale_f32 v49, s[2:3], v48, v48, 1.0
	v_rcp_f32_e32 v50, v49
	s_lshl_b64 s[2:3], s[14:15], 11
	v_fma_f32 v51, -v49, v50, 1.0
	v_fmac_f32_e32 v50, v51, v50
	v_div_scale_f32 v51, vcc, 1.0, v48, 1.0
	v_mul_f32_e32 v52, v51, v50
	v_fma_f32 v53, -v49, v52, v51
	v_fmac_f32_e32 v52, v53, v50
	v_fma_f32 v49, -v49, v52, v51
	v_div_fmas_f32 v49, v49, v50, v52
	v_div_fixup_f32 v48, v49, v48, 1.0
	v_pk_mul_f32 v[44:45], v[44:45], v[48:49] op_sel_hi:[1,0]
	v_pk_mul_f32 v[46:47], v[46:47], v[48:49] op_sel_hi:[1,0]
	v_pk_mul_f32 v[40:41], v[40:41], v[48:49] op_sel_hi:[1,0]
	v_pk_mul_f32 v[42:43], v[42:43], v[48:49] op_sel_hi:[1,0]
	v_pk_mul_f32 v[36:37], v[36:37], v[48:49] op_sel_hi:[1,0]
	v_pk_mul_f32 v[38:39], v[38:39], v[48:49] op_sel_hi:[1,0]
	v_pk_mul_f32 v[32:33], v[32:33], v[48:49] op_sel_hi:[1,0]
	v_pk_mul_f32 v[34:35], v[34:35], v[48:49] op_sel_hi:[1,0]
	v_pk_mul_f32 v[46:47], v[2:3], v[46:47]
	v_pk_mul_f32 v[44:45], v[0:1], v[44:45]
	v_pk_mul_f32 v[42:43], v[6:7], v[42:43]
	v_pk_mul_f32 v[40:41], v[4:5], v[40:41]
	v_pk_mul_f32 v[38:39], v[10:11], v[38:39]
	v_pk_mul_f32 v[36:37], v[8:9], v[36:37]
	v_pk_mul_f32 v[34:35], v[14:15], v[34:35]
	v_pk_mul_f32 v[32:33], v[12:13], v[32:33]
	v_lshl_add_u64 v[50:51], v[82:83], 0, s[2:3]
	v_cvt_pk_bf16_f32 v44, v44, v45
	v_cvt_pk_bf16_f32 v45, v46, v47
	v_cvt_pk_bf16_f32 v40, v40, v41
	v_cvt_pk_bf16_f32 v41, v42, v43
	v_cvt_pk_bf16_f32 v36, v36, v37
	v_cvt_pk_bf16_f32 v37, v38, v39
	v_cvt_pk_bf16_f32 v32, v32, v33
	v_cvt_pk_bf16_f32 v33, v34, v35
	global_store_dwordx2 v[50:51], v[44:45], off
	global_store_dwordx2 v[50:51], v[40:41], off offset:512
	global_store_dwordx2 v[50:51], v[36:37], off offset:1024
	global_store_dwordx2 v[50:51], v[32:33], off offset:1536
	s_andn2_b64 vcc, exec, s[12:13]
	s_cbranch_vccnz .LBB0_19
.LBB0_25:
	s_waitcnt lgkmcnt(0)
	v_add_f32_e32 v32, v90, v91
	v_mov_b32_e32 v33, 0x358637bd
	v_fmamk_f32 v32, v32, 0x3a800000, v33
	v_mul_f32_e32 v33, 0x4f800000, v32
	v_cmp_gt_f32_e32 vcc, s6, v32
	s_ashr_i32 s11, s10, 31
	s_nop 0
	v_cndmask_b32_e32 v32, v32, v33, vcc
	v_sqrt_f32_e32 v33, v32
	s_nop 0
	v_add_u32_e32 v34, -1, v33
	v_fma_f32 v36, -v34, v33, v32
	v_add_u32_e32 v35, 1, v33
	v_cmp_ge_f32_e64 s[2:3], 0, v36
	s_nop 1
	v_cndmask_b32_e64 v34, v33, v34, s[2:3]
	v_fma_f32 v33, -v35, v33, v32
	v_cmp_lt_f32_e64 s[2:3], 0, v33
	s_nop 1
	v_cndmask_b32_e64 v33, v34, v35, s[2:3]
	v_mul_f32_e32 v34, 0x37800000, v33
	v_cndmask_b32_e32 v33, v33, v34, vcc
	v_mov_b32_e32 v34, 0x260
	v_cmp_class_f32_e32 vcc, v32, v34
	s_nop 1
	v_cndmask_b32_e32 v32, v33, v32, vcc
	v_div_scale_f32 v33, s[2:3], v32, v32, 1.0
	v_rcp_f32_e32 v34, v33
	s_lshl_b64 s[2:3], s[10:11], 11
	v_fma_f32 v35, -v33, v34, 1.0
	v_fmac_f32_e32 v34, v35, v34
	v_div_scale_f32 v35, vcc, 1.0, v32, 1.0
	v_mul_f32_e32 v36, v35, v34
	v_fma_f32 v37, -v33, v36, v35
	v_fmac_f32_e32 v36, v37, v34
	v_fma_f32 v33, -v33, v36, v35
	v_div_fmas_f32 v33, v33, v34, v36
	v_div_fixup_f32 v32, v33, v32, 1.0
	v_pk_mul_f32 v[28:29], v[28:29], v[32:33] op_sel_hi:[1,0]
	v_pk_mul_f32 v[30:31], v[30:31], v[32:33] op_sel_hi:[1,0]
	v_pk_mul_f32 v[24:25], v[24:25], v[32:33] op_sel_hi:[1,0]
	v_pk_mul_f32 v[26:27], v[26:27], v[32:33] op_sel_hi:[1,0]
	v_pk_mul_f32 v[20:21], v[20:21], v[32:33] op_sel_hi:[1,0]
	v_pk_mul_f32 v[22:23], v[22:23], v[32:33] op_sel_hi:[1,0]
	v_pk_mul_f32 v[16:17], v[16:17], v[32:33] op_sel_hi:[1,0]
	v_pk_mul_f32 v[18:19], v[18:19], v[32:33] op_sel_hi:[1,0]
	v_pk_mul_f32 v[30:31], v[2:3], v[30:31]
	v_pk_mul_f32 v[28:29], v[0:1], v[28:29]
	v_pk_mul_f32 v[26:27], v[6:7], v[26:27]
	v_pk_mul_f32 v[24:25], v[4:5], v[24:25]
	v_pk_mul_f32 v[22:23], v[10:11], v[22:23]
	v_pk_mul_f32 v[20:21], v[8:9], v[20:21]
	v_pk_mul_f32 v[18:19], v[14:15], v[18:19]
	v_pk_mul_f32 v[16:17], v[12:13], v[16:17]
	v_lshl_add_u64 v[34:35], v[82:83], 0, s[2:3]
	v_cvt_pk_bf16_f32 v28, v28, v29
	v_cvt_pk_bf16_f32 v29, v30, v31
	v_cvt_pk_bf16_f32 v24, v24, v25
	v_cvt_pk_bf16_f32 v25, v26, v27
	v_cvt_pk_bf16_f32 v20, v20, v21
	v_cvt_pk_bf16_f32 v21, v22, v23
	v_cvt_pk_bf16_f32 v16, v16, v17
	v_cvt_pk_bf16_f32 v17, v18, v19
	global_store_dwordx2 v[34:35], v[28:29], off
	global_store_dwordx2 v[34:35], v[24:25], off offset:512
	global_store_dwordx2 v[34:35], v[20:21], off offset:1024
	global_store_dwordx2 v[34:35], v[16:17], off offset:1536
	s_branch .LBB0_19
.LBB0_26:
	s_xor_b64 s[6:7], s[4:5], -1
	v_writelane_b32 v254, s6, 62
	s_mov_b64 s[2:3], -1
	s_and_b64 vcc, exec, s[6:7]
	v_writelane_b32 v254, s7, 63
	s_cbranch_vccz .LBB0_44
	v_readlane_b32 s8, v254, 26
	v_readlane_b32 s9, v254, 27
	v_readlane_b32 s22, v254, 40
	v_readlane_b32 s23, v254, 41
	s_mov_b64 s[8:9], s[22:23]
	v_mbcnt_lo_u32_b32 v0, -1, 0
	v_mbcnt_hi_u32_b32 v0, -1, v0
	v_readlane_b32 s2, v254, 4
	s_waitcnt vmcnt(0) lgkmcnt(0)
	v_readlane_b32 s10, v254, 28
	v_readlane_b32 s11, v254, 29
	v_cmp_eq_u32_e32 vcc, 0, v0
	v_readlane_b32 s3, v254, 5
	s_add_i32 s6, s34, 1
	s_and_b64 s[10:11], s[2:3], vcc
	v_readlane_b32 s12, v254, 30
	v_readlane_b32 s13, v254, 31
	v_readlane_b32 s14, v254, 32
	v_readlane_b32 s15, v254, 33
	v_readlane_b32 s16, v254, 34
	v_readlane_b32 s17, v254, 35
	v_readlane_b32 s18, v254, 36
	v_readlane_b32 s19, v254, 37
	v_readlane_b32 s20, v254, 38
	v_readlane_b32 s21, v254, 39
	s_waitcnt lgkmcnt(0)
	s_barrier
	s_and_saveexec_b64 s[2:3], s[10:11]
	s_cbranch_execz .LBB0_43
	s_getreg_b32 s7, hwreg(HW_REG_XCC_ID, 0, 4)
	s_lshl_b32 s7, s7, 8
	s_and_b32 s7, s7, 0x700
	s_add_u32 s18, s8, s7
	s_addc_u32 s7, s9, 0
	v_mov_b32_e32 v0, s18
	v_add_co_u32_e32 v8, vcc, 0x2000, v0
	v_mov_b32_e32 v0, s7
	s_nop 0
	v_addc_co_u32_e32 v9, vcc, 0, v0, vcc
	v_mov_b32_e32 v0, s8
	v_add_co_u32_e32 v10, vcc, 0x2000, v0
	v_mov_b32_e32 v0, s9
	s_nop 0
	v_addc_co_u32_e32 v11, vcc, 0, v0, vcc
	global_load_dword v12, v[8:9], off sc1
	global_load_dword v4, v[10:11], off sc1
	global_load_dword v0, v[10:11], off offset:256 sc1
	global_load_dword v5, v[10:11], off offset:512 sc1
	global_load_dword v1, v[10:11], off offset:768 sc1
	global_load_dword v6, v[10:11], off offset:1024 sc1
	global_load_dword v2, v[10:11], off offset:1280 sc1
	global_load_dword v7, v[10:11], off offset:1536 sc1
	global_load_dword v3, v[10:11], off offset:1792 sc1
	v_mov_b32_e32 v10, 1
	global_atomic_add v8, v[8:9], v10, off offset:2048 sc0
	s_waitcnt vmcnt(0) lgkmcnt(0)
	v_mul_lo_u32 v9, v12, s6
	v_add_u32_e32 v8, 1, v8
	v_cmp_ne_u32_e32 vcc, v8, v9
	s_and_saveexec_b64 s[10:11], vcc
	s_xor_b64 s[10:11], exec, s[10:11]
	s_cbranch_execz .LBB0_33
	v_mov_b32_e32 v0, s18
	v_add_co_u32_e32 v0, vcc, 0x3000, v0
	v_mov_b32_e32 v1, s7
	s_nop 0
	v_addc_co_u32_e32 v1, vcc, 0, v1, vcc
	global_load_dword v0, v[0:1], off sc1
	s_add_u32 s12, s18, 0x3000
	s_addc_u32 s13, s7, 0
	s_waitcnt vmcnt(0) lgkmcnt(0)
	v_cmp_gt_u32_e32 vcc, s6, v0
	s_and_saveexec_b64 s[14:15], vcc
	s_cbranch_execz .LBB0_32
	s_mov_b64 s[16:17], 0
.LBB0_31:
	v_mov_b64_e32 v[0:1], s[12:13]
	s_sleep 2
	global_load_dword v0, v[0:1], off sc1
	s_waitcnt vmcnt(0) lgkmcnt(0)
	v_readfirstlane_b32 s19, v0
	s_cmp_ge_u32 s19, s6
	s_cselect_b64 s[22:23], -1, 0
	s_and_b64 s[22:23], exec, s[22:23]
	s_or_b64 s[16:17], s[22:23], s[16:17]
	s_andn2_b64 exec, exec, s[16:17]
	s_cbranch_execnz .LBB0_31

.LBB0_33:
	s_andn2_saveexec_b64 s[10:11], s[10:11]
	s_cbranch_execz .LBB0_42
	v_mov_b32_e32 v8, s8
	s_movk_i32 s12, 0x3000
	v_add_co_u32_e32 v8, vcc, s12, v8
	v_mov_b32_e32 v9, s9
	buffer_wbl2 sc1
	s_waitcnt vmcnt(0)
	v_addc_co_u32_e32 v9, vcc, 0, v9, vcc
	v_mov_b32_e32 v10, 1
	global_atomic_add v8, v[8:9], v10, off offset:2048 sc0
	v_cmp_ne_u32_e32 vcc, 0, v4
	s_add_u32 s8, s8, 0x3900
	s_addc_u32 s9, s9, 0
	v_cndmask_b32_e64 v4, 0, 1, vcc
	v_cmp_ne_u32_e32 vcc, 0, v5
	s_nop 1
	v_cndmask_b32_e64 v5, 0, 1, vcc
	v_cmp_ne_u32_e32 vcc, 0, v6
	s_nop 1
	v_cndmask_b32_e64 v6, 0, 1, vcc
	v_cmp_ne_u32_e32 vcc, 0, v7
	s_nop 1
	v_cndmask_b32_e64 v7, 0, 1, vcc
	v_cmp_ne_u32_e32 vcc, 0, v0
	s_nop 1
	v_addc_co_u32_e32 v0, vcc, 0, v4, vcc
	v_cmp_ne_u32_e32 vcc, 0, v1
	s_waitcnt vmcnt(0) lgkmcnt(0)
	v_add_u32_e32 v1, 1, v8
	v_addc_co_u32_e32 v0, vcc, v0, v5, vcc
	v_cmp_ne_u32_e32 vcc, 0, v2
	s_nop 1
	v_addc_co_u32_e32 v0, vcc, v0, v6, vcc
	v_cmp_ne_u32_e32 vcc, 0, v3
	s_nop 1
	v_addc_co_u32_e32 v0, vcc, v0, v7, vcc
	v_mul_lo_u32 v0, v0, s6
	v_cmp_ne_u32_e32 vcc, v1, v0
	s_and_saveexec_b64 s[12:13], vcc
	s_xor_b64 s[12:13], exec, s[12:13]
	s_cbranch_execz .LBB0_39
	v_mov_b64_e32 v[0:1], s[8:9]
	global_load_dword v0, v[0:1], off sc1
	s_waitcnt vmcnt(0) lgkmcnt(0)
	v_cmp_gt_u32_e32 vcc, s6, v0
	s_and_saveexec_b64 s[14:15], vcc
	s_cbranch_execz .LBB0_38
	s_mov_b64 s[16:17], 0
.LBB0_37:
	v_mov_b64_e32 v[0:1], s[8:9]
	s_sleep 2
	global_load_dword v0, v[0:1], off sc1
	s_waitcnt vmcnt(0) lgkmcnt(0)
	v_readfirstlane_b32 s19, v0
	s_cmp_ge_u32 s19, s6
	s_cselect_b64 s[22:23], -1, 0
	s_and_b64 s[22:23], exec, s[22:23]
	s_or_b64 s[16:17], s[22:23], s[16:17]
	s_andn2_b64 exec, exec, s[16:17]
	s_cbranch_execnz .LBB0_37

.LBB0_39:
	s_andn2_saveexec_b64 s[12:13], s[12:13]
	s_cbranch_execz .LBB0_41
	v_mov_b64_e32 v[0:1], s[8:9]
	v_mov_b32_e32 v2, 1
	global_atomic_add v[0:1], v2, off
.LBB0_41:
	s_or_b64 exec, exec, s[12:13]
	v_mov_b32_e32 v0, s18
	v_add_co_u32_e32 v0, vcc, 0x3000, v0
	v_mov_b32_e32 v1, s7
	s_nop 0
	v_addc_co_u32_e32 v1, vcc, 0, v1, vcc
	v_mov_b32_e32 v2, 1
	global_atomic_add v[0:1], v2, off

.LBB0_68:
	s_lshl_b32 s19, s26, 8
	v_mbcnt_lo_u32_b32 v142, -1, 0
	v_mbcnt_hi_u32_b32 v142, -1, v142
	s_add_i32 s19, s19, s43
	v_and_or_b32 v143, v142, 15, s19
	s_lshl_b32 s19, s27, 7
	v_ashrrev_i32_e32 v142, 1, v142
	s_or_b32 s19, s19, s44
	v_and_b32_e32 v142, -8, v142
	v_add_u32_e32 v142, s19, v142
	v_mov_b64_e32 v[144:145], s[14:15]
	v_mad_i64_i32 v[144:145], s[26:27], v143, s63, v[144:145]
	v_ashrrev_i32_e32 v143, 31, v142
	v_lshl_add_u64 v[142:143], v[142:143], 1, v[144:145]
	v_mul_f32_e32 v144, 0xbfb8aa3b, v124
	v_mul_f32_e32 v145, 0xbfb8aa3b, v125
	v_exp_f32_e32 v144, v144
	v_exp_f32_e32 v145, v145
	s_mov_b64 s[6:7], 0x16000
	s_mov_b64 s[26:27], 0x58000
	v_add_f32_e32 v144, 1.0, v144
	v_add_f32_e32 v145, 1.0, v145
	v_rcp_f32_e32 v144, v144
	v_rcp_f32_e32 v145, v145
	s_andn2_b64 vcc, exec, s[2:3]
	s_movk_i32 s72, 0x1800
	v_pk_mul_f32 v[124:125], v[124:125], v[144:145]
	s_nop 0
	v_pk_mul_f32 v[120:121], v[124:125], v[120:121]
	v_mul_f32_e32 v124, 0xbfb8aa3b, v126
	v_mul_f32_e32 v125, 0xbfb8aa3b, v127
	v_exp_f32_e32 v124, v124
	v_exp_f32_e32 v125, v125
	v_add_f32_e32 v124, 1.0, v124
	v_add_f32_e32 v125, 1.0, v125
	v_rcp_f32_e32 v124, v124
	v_rcp_f32_e32 v125, v125
	s_nop 0
	v_pk_mul_f32 v[124:125], v[126:127], v[124:125]
	s_nop 0
	v_pk_mul_f32 v[122:123], v[124:125], v[122:123]
	v_mul_f32_e32 v124, 0xbfb8aa3b, v116
	v_mul_f32_e32 v125, 0xbfb8aa3b, v117
	v_exp_f32_e32 v124, v124
	v_exp_f32_e32 v125, v125
	v_add_f32_e32 v124, 1.0, v124
	v_add_f32_e32 v125, 1.0, v125
	v_rcp_f32_e32 v124, v124
	v_rcp_f32_e32 v125, v125
	s_nop 0
	v_pk_mul_f32 v[116:117], v[116:117], v[124:125]
	s_nop 0
	v_pk_mul_f32 v[116:117], v[116:117], v[112:113]
	v_mul_f32_e32 v112, 0xbfb8aa3b, v118
	v_mul_f32_e32 v113, 0xbfb8aa3b, v119
	v_exp_f32_e32 v112, v112
	v_exp_f32_e32 v113, v113
	v_add_f32_e32 v112, 1.0, v112
	v_add_f32_e32 v113, 1.0, v113
	v_rcp_f32_e32 v112, v112
	v_rcp_f32_e32 v113, v113
	s_nop 0
	v_pk_mul_f32 v[112:113], v[118:119], v[112:113]
	s_nop 0
	v_pk_mul_f32 v[118:119], v[112:113], v[114:115]
	v_cvt_pk_bf16_f32 v112, v120, v121
	v_cvt_pk_bf16_f32 v113, v122, v123
	v_cvt_pk_bf16_f32 v114, v116, v117
	v_cvt_pk_bf16_f32 v115, v118, v119
	global_store_dwordx4 v[142:143], v[112:115], off nt
	s_nop 1
	v_mul_f32_e32 v114, 0xbfb8aa3b, v108
	v_mul_f32_e32 v115, 0xbfb8aa3b, v109
	v_exp_f32_e32 v114, v114
	v_exp_f32_e32 v115, v115
	v_lshl_add_u64 v[112:113], v[142:143], 0, s[6:7]
	v_add_f32_e32 v114, 1.0, v114
	v_add_f32_e32 v115, 1.0, v115
	v_rcp_f32_e32 v114, v114
	v_rcp_f32_e32 v115, v115
	s_nop 0
	v_pk_mul_f32 v[108:109], v[108:109], v[114:115]
	s_nop 0
	v_pk_mul_f32 v[104:105], v[108:109], v[104:105]
	v_mul_f32_e32 v108, 0xbfb8aa3b, v110
	v_mul_f32_e32 v109, 0xbfb8aa3b, v111
	v_exp_f32_e32 v108, v108
	v_exp_f32_e32 v109, v109
	v_add_f32_e32 v108, 1.0, v108
	v_add_f32_e32 v109, 1.0, v109
	v_rcp_f32_e32 v108, v108
	v_rcp_f32_e32 v109, v109
	s_nop 0
	v_pk_mul_f32 v[108:109], v[110:111], v[108:109]
	s_nop 0
	v_pk_mul_f32 v[106:107], v[108:109], v[106:107]
	v_mul_f32_e32 v108, 0xbfb8aa3b, v100
	v_mul_f32_e32 v109, 0xbfb8aa3b, v101
	v_exp_f32_e32 v108, v108
	v_exp_f32_e32 v109, v109
	v_add_f32_e32 v108, 1.0, v108
	v_add_f32_e32 v109, 1.0, v109
	v_rcp_f32_e32 v108, v108
	v_rcp_f32_e32 v109, v109
	s_nop 0
	v_pk_mul_f32 v[100:101], v[100:101], v[108:109]
	s_nop 0
	v_pk_mul_f32 v[100:101], v[100:101], v[96:97]
	v_mul_f32_e32 v96, 0xbfb8aa3b, v102
	v_mul_f32_e32 v97, 0xbfb8aa3b, v103
	v_exp_f32_e32 v96, v96
	v_exp_f32_e32 v97, v97
	v_add_f32_e32 v96, 1.0, v96
	v_add_f32_e32 v97, 1.0, v97
	v_rcp_f32_e32 v96, v96
	v_rcp_f32_e32 v97, v97
	s_nop 0
	v_pk_mul_f32 v[96:97], v[102:103], v[96:97]
	s_nop 0
	v_pk_mul_f32 v[102:103], v[96:97], v[98:99]
	v_cvt_pk_bf16_f32 v96, v104, v105
	v_cvt_pk_bf16_f32 v97, v106, v107
	v_cvt_pk_bf16_f32 v98, v100, v101
	v_cvt_pk_bf16_f32 v99, v102, v103
	global_store_dwordx4 v[112:113], v[96:99], off nt
	s_nop 1
	v_mul_f32_e32 v98, 0xbfb8aa3b, v92
	v_mul_f32_e32 v99, 0xbfb8aa3b, v93
	v_exp_f32_e32 v98, v98
	v_exp_f32_e32 v99, v99
	v_lshl_add_u64 v[96:97], v[112:113], 0, s[6:7]
	v_add_f32_e32 v98, 1.0, v98
	v_add_f32_e32 v99, 1.0, v99
	v_rcp_f32_e32 v98, v98
	v_rcp_f32_e32 v99, v99
	s_nop 0
	v_pk_mul_f32 v[92:93], v[92:93], v[98:99]
	s_nop 0
	v_pk_mul_f32 v[88:89], v[92:93], v[88:89]
	v_mul_f32_e32 v92, 0xbfb8aa3b, v94
	v_mul_f32_e32 v93, 0xbfb8aa3b, v95
	v_exp_f32_e32 v92, v92
	v_exp_f32_e32 v93, v93
	v_add_f32_e32 v92, 1.0, v92
	v_add_f32_e32 v93, 1.0, v93
	v_rcp_f32_e32 v92, v92
	v_rcp_f32_e32 v93, v93
	s_nop 0
	v_pk_mul_f32 v[92:93], v[94:95], v[92:93]
	s_nop 0
	v_pk_mul_f32 v[90:91], v[92:93], v[90:91]
	v_mul_f32_e32 v92, 0xbfb8aa3b, v84
	v_mul_f32_e32 v93, 0xbfb8aa3b, v85
	v_exp_f32_e32 v92, v92
	v_exp_f32_e32 v93, v93
	v_add_f32_e32 v92, 1.0, v92
	v_add_f32_e32 v93, 1.0, v93
	v_rcp_f32_e32 v92, v92
	v_rcp_f32_e32 v93, v93
	s_nop 0
	v_pk_mul_f32 v[84:85], v[84:85], v[92:93]
	s_nop 0
	v_pk_mul_f32 v[84:85], v[84:85], v[80:81]
	v_mul_f32_e32 v80, 0xbfb8aa3b, v86
	v_mul_f32_e32 v81, 0xbfb8aa3b, v87
	v_exp_f32_e32 v80, v80
	v_exp_f32_e32 v81, v81
	v_add_f32_e32 v80, 1.0, v80
	v_add_f32_e32 v81, 1.0, v81
	v_rcp_f32_e32 v80, v80
	v_rcp_f32_e32 v81, v81
	s_nop 0
	v_pk_mul_f32 v[80:81], v[86:87], v[80:81]
	s_nop 0
	v_pk_mul_f32 v[86:87], v[80:81], v[82:83]
	v_cvt_pk_bf16_f32 v80, v88, v89
	v_cvt_pk_bf16_f32 v81, v90, v91
	v_cvt_pk_bf16_f32 v82, v84, v85
	v_cvt_pk_bf16_f32 v83, v86, v87
	global_store_dwordx4 v[96:97], v[80:83], off nt
	s_nop 1
	v_mul_f32_e32 v82, 0xbfb8aa3b, v76
	v_mul_f32_e32 v83, 0xbfb8aa3b, v77
	v_exp_f32_e32 v82, v82
	v_exp_f32_e32 v83, v83
	v_lshl_add_u64 v[80:81], v[96:97], 0, s[6:7]
	v_add_f32_e32 v82, 1.0, v82
	v_add_f32_e32 v83, 1.0, v83
	v_rcp_f32_e32 v82, v82
	v_rcp_f32_e32 v83, v83
	s_nop 0
	v_pk_mul_f32 v[76:77], v[76:77], v[82:83]
	s_nop 0
	v_pk_mul_f32 v[72:73], v[76:77], v[72:73]
	v_mul_f32_e32 v76, 0xbfb8aa3b, v78
	v_mul_f32_e32 v77, 0xbfb8aa3b, v79
	v_exp_f32_e32 v76, v76
	v_exp_f32_e32 v77, v77
	v_add_f32_e32 v76, 1.0, v76
	v_add_f32_e32 v77, 1.0, v77
	v_rcp_f32_e32 v76, v76
	v_rcp_f32_e32 v77, v77
	s_nop 0
	v_pk_mul_f32 v[76:77], v[78:79], v[76:77]
	s_nop 0
	v_pk_mul_f32 v[74:75], v[76:77], v[74:75]
	v_mul_f32_e32 v76, 0xbfb8aa3b, v68
	v_mul_f32_e32 v77, 0xbfb8aa3b, v69
	v_exp_f32_e32 v76, v76
	v_exp_f32_e32 v77, v77
	v_add_f32_e32 v76, 1.0, v76
	v_add_f32_e32 v77, 1.0, v77
	v_rcp_f32_e32 v76, v76
	v_rcp_f32_e32 v77, v77
	s_nop 0
	v_pk_mul_f32 v[68:69], v[68:69], v[76:77]
	s_nop 0
	v_pk_mul_f32 v[68:69], v[68:69], v[64:65]
	v_mul_f32_e32 v64, 0xbfb8aa3b, v70
	v_mul_f32_e32 v65, 0xbfb8aa3b, v71
	v_exp_f32_e32 v64, v64
	v_exp_f32_e32 v65, v65
	v_add_f32_e32 v64, 1.0, v64
	v_add_f32_e32 v65, 1.0, v65
	v_rcp_f32_e32 v64, v64
	v_rcp_f32_e32 v65, v65
	s_nop 0
	v_pk_mul_f32 v[64:65], v[70:71], v[64:65]
	s_nop 0
	v_pk_mul_f32 v[70:71], v[64:65], v[66:67]
	v_cvt_pk_bf16_f32 v64, v72, v73
	v_cvt_pk_bf16_f32 v65, v74, v75
	v_cvt_pk_bf16_f32 v66, v68, v69
	v_cvt_pk_bf16_f32 v67, v70, v71
	global_store_dwordx4 v[80:81], v[64:67], off nt
	s_nop 1
	v_mul_f32_e32 v66, 0xbfb8aa3b, v60
	v_mul_f32_e32 v67, 0xbfb8aa3b, v61
	v_exp_f32_e32 v66, v66
	v_exp_f32_e32 v67, v67
	v_lshl_add_u64 v[64:65], v[80:81], 0, s[6:7]
	v_add_f32_e32 v66, 1.0, v66
	v_add_f32_e32 v67, 1.0, v67
	v_rcp_f32_e32 v66, v66
	v_rcp_f32_e32 v67, v67
	v_lshl_add_u64 v[64:65], v[64:65], 0, s[26:27]
	v_pk_mul_f32 v[60:61], v[60:61], v[66:67]
	s_nop 0
	v_pk_mul_f32 v[56:57], v[60:61], v[56:57]
	v_mul_f32_e32 v60, 0xbfb8aa3b, v62
	v_mul_f32_e32 v61, 0xbfb8aa3b, v63
	v_exp_f32_e32 v60, v60
	v_exp_f32_e32 v61, v61
	v_add_f32_e32 v60, 1.0, v60
	v_add_f32_e32 v61, 1.0, v61
	v_rcp_f32_e32 v60, v60
	v_rcp_f32_e32 v61, v61
	s_nop 0
	v_pk_mul_f32 v[60:61], v[62:63], v[60:61]
	s_nop 0
	v_pk_mul_f32 v[58:59], v[60:61], v[58:59]
	v_mul_f32_e32 v60, 0xbfb8aa3b, v52
	v_mul_f32_e32 v61, 0xbfb8aa3b, v53
	v_exp_f32_e32 v60, v60
	v_exp_f32_e32 v61, v61
	v_add_f32_e32 v60, 1.0, v60
	v_add_f32_e32 v61, 1.0, v61
	v_rcp_f32_e32 v60, v60
	v_rcp_f32_e32 v61, v61
	s_nop 0
	v_pk_mul_f32 v[52:53], v[52:53], v[60:61]
	s_nop 0
	v_pk_mul_f32 v[52:53], v[52:53], v[48:49]
	v_mul_f32_e32 v48, 0xbfb8aa3b, v54
	v_mul_f32_e32 v49, 0xbfb8aa3b, v55
	v_exp_f32_e32 v48, v48
	v_exp_f32_e32 v49, v49
	v_add_f32_e32 v48, 1.0, v48
	v_add_f32_e32 v49, 1.0, v49
	v_rcp_f32_e32 v48, v48
	v_rcp_f32_e32 v49, v49
	s_nop 0
	v_pk_mul_f32 v[48:49], v[54:55], v[48:49]
	s_nop 0
	v_pk_mul_f32 v[54:55], v[48:49], v[50:51]
	v_cvt_pk_bf16_f32 v48, v56, v57
	v_cvt_pk_bf16_f32 v49, v58, v59
	v_cvt_pk_bf16_f32 v50, v52, v53
	v_cvt_pk_bf16_f32 v51, v54, v55
	global_store_dwordx4 v[64:65], v[48:51], off nt
	s_nop 1
	v_mul_f32_e32 v50, 0xbfb8aa3b, v44
	v_mul_f32_e32 v51, 0xbfb8aa3b, v45
	v_exp_f32_e32 v50, v50
	v_exp_f32_e32 v51, v51
	v_lshl_add_u64 v[48:49], v[64:65], 0, s[6:7]
	v_add_f32_e32 v50, 1.0, v50
	v_add_f32_e32 v51, 1.0, v51
	v_rcp_f32_e32 v50, v50
	v_rcp_f32_e32 v51, v51
	s_nop 0
	v_pk_mul_f32 v[44:45], v[44:45], v[50:51]
	s_nop 0
	v_pk_mul_f32 v[40:41], v[44:45], v[40:41]
	v_mul_f32_e32 v44, 0xbfb8aa3b, v46
	v_mul_f32_e32 v45, 0xbfb8aa3b, v47
	v_exp_f32_e32 v44, v44
	v_exp_f32_e32 v45, v45
	v_add_f32_e32 v44, 1.0, v44
	v_add_f32_e32 v45, 1.0, v45
	v_rcp_f32_e32 v44, v44
	v_rcp_f32_e32 v45, v45
	s_nop 0
	v_pk_mul_f32 v[44:45], v[46:47], v[44:45]
	s_nop 0
	v_pk_mul_f32 v[42:43], v[44:45], v[42:43]
	v_mul_f32_e32 v44, 0xbfb8aa3b, v36
	v_mul_f32_e32 v45, 0xbfb8aa3b, v37
	v_exp_f32_e32 v44, v44
	v_exp_f32_e32 v45, v45
	v_add_f32_e32 v44, 1.0, v44
	v_add_f32_e32 v45, 1.0, v45
	v_rcp_f32_e32 v44, v44
	v_rcp_f32_e32 v45, v45
	s_nop 0
	v_pk_mul_f32 v[36:37], v[36:37], v[44:45]
	s_nop 0
	v_pk_mul_f32 v[36:37], v[36:37], v[32:33]
	v_mul_f32_e32 v32, 0xbfb8aa3b, v38
	v_mul_f32_e32 v33, 0xbfb8aa3b, v39
	v_exp_f32_e32 v32, v32
	v_exp_f32_e32 v33, v33
	v_add_f32_e32 v32, 1.0, v32
	v_add_f32_e32 v33, 1.0, v33
	v_rcp_f32_e32 v32, v32
	v_rcp_f32_e32 v33, v33
	s_nop 0
	v_pk_mul_f32 v[32:33], v[38:39], v[32:33]
	s_nop 0
	v_pk_mul_f32 v[38:39], v[32:33], v[34:35]
	v_cvt_pk_bf16_f32 v32, v40, v41
	v_cvt_pk_bf16_f32 v33, v42, v43
	v_cvt_pk_bf16_f32 v34, v36, v37
	v_cvt_pk_bf16_f32 v35, v38, v39
	global_store_dwordx4 v[48:49], v[32:35], off nt
	s_nop 1
	v_mul_f32_e32 v34, 0xbfb8aa3b, v28
	v_mul_f32_e32 v35, 0xbfb8aa3b, v29
	v_exp_f32_e32 v34, v34
	v_exp_f32_e32 v35, v35
	v_lshl_add_u64 v[32:33], v[48:49], 0, s[6:7]
	v_add_f32_e32 v34, 1.0, v34
	v_add_f32_e32 v35, 1.0, v35
	v_rcp_f32_e32 v34, v34
	v_rcp_f32_e32 v35, v35
	s_nop 0
	v_pk_mul_f32 v[28:29], v[28:29], v[34:35]
	s_nop 0
	v_pk_mul_f32 v[24:25], v[28:29], v[24:25]
	v_mul_f32_e32 v28, 0xbfb8aa3b, v30
	v_mul_f32_e32 v29, 0xbfb8aa3b, v31
	v_exp_f32_e32 v28, v28
	v_exp_f32_e32 v29, v29
	v_add_f32_e32 v28, 1.0, v28
	v_add_f32_e32 v29, 1.0, v29
	v_rcp_f32_e32 v28, v28
	v_rcp_f32_e32 v29, v29
	s_nop 0
	v_pk_mul_f32 v[28:29], v[30:31], v[28:29]
	s_nop 0
	v_pk_mul_f32 v[26:27], v[28:29], v[26:27]
	v_mul_f32_e32 v28, 0xbfb8aa3b, v20
	v_mul_f32_e32 v29, 0xbfb8aa3b, v21
	v_exp_f32_e32 v28, v28
	v_exp_f32_e32 v29, v29
	v_add_f32_e32 v28, 1.0, v28
	v_add_f32_e32 v29, 1.0, v29
	v_rcp_f32_e32 v28, v28
	v_rcp_f32_e32 v29, v29
	s_nop 0
	v_pk_mul_f32 v[20:21], v[20:21], v[28:29]
	s_nop 0
	v_pk_mul_f32 v[20:21], v[20:21], v[16:17]
	v_mul_f32_e32 v16, 0xbfb8aa3b, v22
	v_mul_f32_e32 v17, 0xbfb8aa3b, v23
	v_exp_f32_e32 v16, v16
	v_exp_f32_e32 v17, v17
	v_add_f32_e32 v16, 1.0, v16
	v_add_f32_e32 v17, 1.0, v17
	v_rcp_f32_e32 v16, v16
	v_rcp_f32_e32 v17, v17
	s_nop 0
	v_pk_mul_f32 v[16:17], v[22:23], v[16:17]
	s_nop 0
	v_pk_mul_f32 v[22:23], v[16:17], v[18:19]
	v_cvt_pk_bf16_f32 v16, v24, v25
	v_cvt_pk_bf16_f32 v17, v26, v27
	v_cvt_pk_bf16_f32 v18, v20, v21
	v_cvt_pk_bf16_f32 v19, v22, v23
	global_store_dwordx4 v[32:33], v[16:19], off nt
	s_nop 1
	v_mul_f32_e32 v18, 0xbfb8aa3b, v12
	v_mul_f32_e32 v19, 0xbfb8aa3b, v13
	v_exp_f32_e32 v18, v18
	v_exp_f32_e32 v19, v19
	v_lshl_add_u64 v[16:17], v[32:33], 0, s[6:7]
	v_add_f32_e32 v18, 1.0, v18
	v_add_f32_e32 v19, 1.0, v19
	v_rcp_f32_e32 v18, v18
	v_rcp_f32_e32 v19, v19
	s_nop 0
	v_pk_mul_f32 v[12:13], v[12:13], v[18:19]
	s_nop 0
	v_pk_mul_f32 v[8:9], v[12:13], v[8:9]
	v_mul_f32_e32 v12, 0xbfb8aa3b, v14
	v_mul_f32_e32 v13, 0xbfb8aa3b, v15
	v_exp_f32_e32 v12, v12
	v_exp_f32_e32 v13, v13
	v_add_f32_e32 v12, 1.0, v12
	v_add_f32_e32 v13, 1.0, v13
	v_rcp_f32_e32 v12, v12
	v_rcp_f32_e32 v13, v13
	s_nop 0
	v_pk_mul_f32 v[12:13], v[14:15], v[12:13]
	s_nop 0
	v_pk_mul_f32 v[10:11], v[12:13], v[10:11]
	v_mul_f32_e32 v12, 0xbfb8aa3b, v4
	v_mul_f32_e32 v13, 0xbfb8aa3b, v5
	v_exp_f32_e32 v12, v12
	v_exp_f32_e32 v13, v13
	v_add_f32_e32 v12, 1.0, v12
	v_add_f32_e32 v13, 1.0, v13
	v_rcp_f32_e32 v12, v12
	v_rcp_f32_e32 v13, v13
	s_nop 0
	v_pk_mul_f32 v[4:5], v[4:5], v[12:13]
	s_nop 0
	v_pk_mul_f32 v[4:5], v[4:5], v[0:1]
	v_mul_f32_e32 v0, 0xbfb8aa3b, v6
	v_mul_f32_e32 v1, 0xbfb8aa3b, v7
	v_exp_f32_e32 v0, v0
	v_exp_f32_e32 v1, v1
	v_add_f32_e32 v0, 1.0, v0
	v_add_f32_e32 v1, 1.0, v1
	v_rcp_f32_e32 v0, v0
	v_rcp_f32_e32 v1, v1
	s_nop 0
	v_pk_mul_f32 v[0:1], v[6:7], v[0:1]
	s_nop 0
	v_pk_mul_f32 v[6:7], v[0:1], v[2:3]
	v_cvt_pk_bf16_f32 v0, v8, v9
	v_cvt_pk_bf16_f32 v1, v10, v11
	v_cvt_pk_bf16_f32 v2, v4, v5
	v_cvt_pk_bf16_f32 v3, v6, v7
	global_store_dwordx4 v[16:17], v[0:3], off nt
	s_nop 1
	v_lshl_add_u64 v[0:1], v[16:17], 0, s[6:7]
	s_nop 0
	v_lshl_add_u64 v[0:1], v[0:1], 0, s[26:27]
	s_mov_b64 s[26:27], -1
	s_cbranch_vccnz .LBB0_61
	s_andn2_b64 vcc, exec, s[12:13]
	s_cbranch_vccnz .LBB0_60
	s_barrier
	s_branch .LBB0_60

.LBB0_72:
	v_readlane_b32 s8, v254, 26
	v_readlane_b32 s9, v254, 27
	v_readlane_b32 s22, v254, 40
	v_readlane_b32 s23, v254, 41
	s_mov_b64 s[8:9], s[22:23]
	v_mbcnt_lo_u32_b32 v0, -1, 0
	v_mbcnt_hi_u32_b32 v0, -1, v0
	v_readlane_b32 s2, v254, 4
	s_waitcnt vmcnt(0) lgkmcnt(0)
	v_cmp_eq_u32_e32 vcc, 0, v0
	v_readlane_b32 s3, v254, 5
	s_and_b64 s[2:3], s[2:3], vcc
	v_readlane_b32 s10, v254, 28
	v_readlane_b32 s11, v254, 29
	v_readlane_b32 s12, v254, 30
	v_readlane_b32 s13, v254, 31
	v_readlane_b32 s14, v254, 32
	v_readlane_b32 s15, v254, 33
	v_readlane_b32 s16, v254, 34
	v_readlane_b32 s17, v254, 35
	v_readlane_b32 s18, v254, 36
	v_readlane_b32 s19, v254, 37
	v_readlane_b32 s20, v254, 38
	v_readlane_b32 s21, v254, 39
	s_waitcnt vmcnt(0) lgkmcnt(0)
	s_barrier
	s_and_saveexec_b64 s[10:11], s[2:3]
	s_xor_b64 s[2:3], exec, s[10:11]
	s_cbranch_execz .LBB0_88
	s_getreg_b32 s10, hwreg(HW_REG_XCC_ID, 0, 4)
	v_readlane_b32 s6, v255, 0
	s_lshl_b32 s10, s10, 8
	s_add_i32 s20, s6, 1
	s_and_b32 s10, s10, 0x700
	s_add_u32 s19, s8, s10
	s_addc_u32 s18, s9, 0
	v_mov_b32_e32 v0, s19
	v_add_co_u32_e32 v8, vcc, 0x2000, v0
	v_mov_b32_e32 v0, s18
	s_nop 0
	v_addc_co_u32_e32 v9, vcc, 0, v0, vcc
	v_mov_b32_e32 v0, s8
	v_add_co_u32_e32 v10, vcc, 0x2000, v0
	v_mov_b32_e32 v0, s9
	s_nop 0
	v_addc_co_u32_e32 v11, vcc, 0, v0, vcc
	global_load_dword v12, v[8:9], off sc1
	global_load_dword v4, v[10:11], off sc1
	global_load_dword v0, v[10:11], off offset:256 sc1
	global_load_dword v5, v[10:11], off offset:512 sc1
	global_load_dword v1, v[10:11], off offset:768 sc1
	global_load_dword v6, v[10:11], off offset:1024 sc1
	global_load_dword v2, v[10:11], off offset:1280 sc1
	global_load_dword v7, v[10:11], off offset:1536 sc1
	global_load_dword v3, v[10:11], off offset:1792 sc1
	v_mov_b32_e32 v10, 1
	global_atomic_add v8, v[8:9], v10, off offset:2048 sc0
	s_waitcnt vmcnt(0) lgkmcnt(0)
	v_mul_lo_u32 v9, v12, s20
	v_add_u32_e32 v8, 1, v8
	v_cmp_ne_u32_e32 vcc, v8, v9
	s_and_saveexec_b64 s[10:11], vcc
	s_xor_b64 s[10:11], exec, s[10:11]
	s_cbranch_execz .LBB0_78
	v_mov_b32_e32 v0, s19
	v_add_co_u32_e32 v0, vcc, 0x3000, v0
	v_mov_b32_e32 v1, s18
	s_nop 0
	v_addc_co_u32_e32 v1, vcc, 0, v1, vcc
	global_load_dword v0, v[0:1], off sc1
	s_add_u32 s12, s19, 0x3000
	s_addc_u32 s13, s18, 0
	s_waitcnt vmcnt(0) lgkmcnt(0)
	v_cmp_gt_u32_e32 vcc, s20, v0
	s_and_saveexec_b64 s[14:15], vcc
	s_cbranch_execz .LBB0_77
	s_mov_b64 s[16:17], 0
.LBB0_76:
	v_mov_b64_e32 v[0:1], s[12:13]
	s_sleep 2
	global_load_dword v0, v[0:1], off sc1
	s_waitcnt vmcnt(0) lgkmcnt(0)
	v_readfirstlane_b32 s21, v0
	s_cmp_ge_u32 s21, s20
	s_cselect_b64 s[22:23], -1, 0
	s_and_b64 s[22:23], exec, s[22:23]
	s_or_b64 s[16:17], s[22:23], s[16:17]
	s_andn2_b64 exec, exec, s[16:17]
	s_cbranch_execnz .LBB0_76

.LBB0_78:
	s_andn2_saveexec_b64 s[10:11], s[10:11]
	s_cbranch_execz .LBB0_87
	v_mov_b32_e32 v8, s8
	s_movk_i32 s6, 0x3000
	v_add_co_u32_e32 v8, vcc, s6, v8
	v_mov_b32_e32 v9, s9
	buffer_wbl2 sc1
	s_waitcnt vmcnt(0)
	v_addc_co_u32_e32 v9, vcc, 0, v9, vcc
	v_mov_b32_e32 v10, 1
	global_atomic_add v8, v[8:9], v10, off offset:2048 sc0
	v_cmp_ne_u32_e32 vcc, 0, v4
	s_add_u32 s8, s8, 0x3900
	s_addc_u32 s9, s9, 0
	v_cndmask_b32_e64 v4, 0, 1, vcc
	v_cmp_ne_u32_e32 vcc, 0, v5
	s_nop 1
	v_cndmask_b32_e64 v5, 0, 1, vcc
	v_cmp_ne_u32_e32 vcc, 0, v6
	s_nop 1
	v_cndmask_b32_e64 v6, 0, 1, vcc
	v_cmp_ne_u32_e32 vcc, 0, v7
	s_nop 1
	v_cndmask_b32_e64 v7, 0, 1, vcc
	v_cmp_ne_u32_e32 vcc, 0, v0
	s_nop 1
	v_addc_co_u32_e32 v0, vcc, 0, v4, vcc
	v_cmp_ne_u32_e32 vcc, 0, v1
	s_waitcnt vmcnt(0) lgkmcnt(0)
	v_add_u32_e32 v1, 1, v8
	v_addc_co_u32_e32 v0, vcc, v0, v5, vcc
	v_cmp_ne_u32_e32 vcc, 0, v2
	s_nop 1
	v_addc_co_u32_e32 v0, vcc, v0, v6, vcc
	v_cmp_ne_u32_e32 vcc, 0, v3
	s_nop 1
	v_addc_co_u32_e32 v0, vcc, v0, v7, vcc
	v_mul_lo_u32 v0, v0, s20
	v_cmp_ne_u32_e32 vcc, v1, v0
	s_and_saveexec_b64 s[12:13], vcc
	s_xor_b64 s[12:13], exec, s[12:13]
	s_cbranch_execz .LBB0_84
	v_mov_b64_e32 v[0:1], s[8:9]
	global_load_dword v0, v[0:1], off sc1
	s_waitcnt vmcnt(0) lgkmcnt(0)
	v_cmp_gt_u32_e32 vcc, s20, v0
	s_and_saveexec_b64 s[14:15], vcc
	s_cbranch_execz .LBB0_83
	s_mov_b64 s[16:17], 0
.LBB0_82:
	v_mov_b64_e32 v[0:1], s[8:9]
	s_sleep 2
	global_load_dword v0, v[0:1], off sc1
	s_waitcnt vmcnt(0) lgkmcnt(0)
	v_readfirstlane_b32 s21, v0
	s_cmp_ge_u32 s21, s20
	s_cselect_b64 s[22:23], -1, 0
	s_and_b64 s[22:23], exec, s[22:23]
	s_or_b64 s[16:17], s[22:23], s[16:17]
	s_andn2_b64 exec, exec, s[16:17]
	s_cbranch_execnz .LBB0_82

.LBB0_86:
	s_or_b64 exec, exec, s[12:13]
	v_mov_b32_e32 v0, s19
	v_add_co_u32_e32 v0, vcc, 0x3000, v0
	v_mov_b32_e32 v1, s18
	s_nop 0
	v_addc_co_u32_e32 v1, vcc, 0, v1, vcc
	v_mov_b32_e32 v2, 1
	global_atomic_add v[0:1], v2, off

.LBB0_112:
	s_lshl_b32 s22, s52, 8
	v_mbcnt_lo_u32_b32 v129, -1, 0
	v_mbcnt_hi_u32_b32 v129, -1, v129
	s_add_i32 s22, s22, s39
	v_and_or_b32 v128, v129, 15, s22
	s_lshl_b32 s22, s53, 8
	v_ashrrev_i32_e32 v129, 1, v129
	v_and_b32_e32 v129, -8, v129
	s_or_b32 s22, s22, s40
	v_add_u32_e32 v130, s22, v129
	v_ashrrev_i32_e32 v129, 31, v128
	v_lshlrev_b64 v[128:129], 12, v[128:129]
	v_ashrrev_i32_e32 v131, 31, v130
	v_lshl_add_u64 v[132:133], s[6:7], 0, v[128:129]
	v_lshlrev_b64 v[130:131], 2, v[130:131]
	v_lshl_add_u64 v[168:169], v[132:133], 0, v[130:131]
	v_lshl_add_u64 v[128:129], s[60:61], 0, v[128:129]
	v_lshl_add_u64 v[170:171], v[128:129], 0, v[130:131]
	v_add_co_u32_e32 v128, vcc, s94, v168
	global_load_dwordx4 v[174:177], v[168:169], off
	global_load_dwordx4 v[178:181], v[168:169], off offset:16
	global_load_dwordx4 v[182:185], v[168:169], off offset:512
	global_load_dwordx4 v[186:189], v[168:169], off offset:528
	v_addc_co_u32_e32 v129, vcc, 0, v169, vcc
	global_load_dwordx4 v[190:193], v[128:129], off
	global_load_dwordx4 v[194:197], v[128:129], off offset:16
	global_load_dwordx4 v[198:201], v[128:129], off offset:512
	global_load_dwordx4 v[216:219], v[128:129], off offset:528
	v_add_co_u32_e32 v128, vcc, s0, v168
	s_mov_b64 s[8:9], 0x80000
	s_nop 0
	v_addc_co_u32_e32 v129, vcc, 0, v169, vcc
	global_load_dwordx4 v[220:223], v[128:129], off
	global_load_dwordx4 v[154:157], v[128:129], off offset:16
	global_load_dwordx4 v[150:153], v[128:129], off offset:512
	global_load_dwordx4 v[146:149], v[128:129], off offset:528
	v_add_co_u32_e32 v128, vcc, s1, v168
	s_mov_b64 s[22:23], -1
	s_nop 0
	v_addc_co_u32_e32 v129, vcc, 0, v169, vcc
	global_load_dwordx4 v[142:145], v[128:129], off
	global_load_dwordx4 v[138:141], v[128:129], off offset:16
	global_load_dwordx4 v[132:135], v[128:129], off offset:512
	s_nop 0
	global_load_dwordx4 v[128:131], v[128:129], off offset:528
	s_waitcnt vmcnt(0) lgkmcnt(0)
	v_pk_fma_f32 v[126:127], v[126:127], 0.5, v[176:177] op_sel_hi:[1,0,1]
	v_pk_fma_f32 v[124:125], v[124:125], 0.5, v[174:175] op_sel_hi:[1,0,1]
	v_pk_fma_f32 v[114:115], v[114:115], 0.5, v[184:185] op_sel_hi:[1,0,1]
	v_pk_fma_f32 v[112:113], v[112:113], 0.5, v[182:183] op_sel_hi:[1,0,1]
	global_store_dwordx4 v[170:171], v[112:115], off offset:512
	v_pk_fma_f32 v[98:99], v[98:99], 0.5, v[200:201] op_sel_hi:[1,0,1]
	v_pk_fma_f32 v[96:97], v[96:97], 0.5, v[198:199] op_sel_hi:[1,0,1]
	v_add_co_u32_e32 v112, vcc, s94, v170
	v_pk_fma_f32 v[94:95], v[94:95], 0.5, v[218:219] op_sel_hi:[1,0,1]
	s_nop 0
	v_addc_co_u32_e32 v113, vcc, 0, v171, vcc
	global_store_dwordx4 v[112:113], v[96:99], off offset:512
	v_pk_fma_f32 v[92:93], v[92:93], 0.5, v[216:217] op_sel_hi:[1,0,1]
	v_pk_fma_f32 v[82:83], v[82:83], 0.5, v[148:149] op_sel_hi:[1,0,1]
	v_add_co_u32_e32 v96, vcc, s0, v170
	v_pk_fma_f32 v[80:81], v[80:81], 0.5, v[146:147] op_sel_hi:[1,0,1]
	s_nop 0
	v_addc_co_u32_e32 v97, vcc, 0, v171, vcc
	v_pk_fma_f32 v[110:111], v[110:111], 0.5, v[188:189] op_sel_hi:[1,0,1]
	v_pk_fma_f32 v[108:109], v[108:109], 0.5, v[186:187] op_sel_hi:[1,0,1]
	global_store_dwordx4 v[112:113], v[92:95], off offset:528
	global_store_dwordx4 v[96:97], v[80:83], off offset:528
	v_pk_fma_f32 v[122:123], v[122:123], 0.5, v[180:181] op_sel_hi:[1,0,1]
	v_pk_fma_f32 v[94:95], v[102:103], 0.5, v[222:223] op_sel_hi:[1,0,1]
	v_pk_fma_f32 v[92:93], v[100:101], 0.5, v[220:221] op_sel_hi:[1,0,1]
	v_add_co_u32_e32 v80, vcc, s1, v170
	v_pk_fma_f32 v[120:121], v[120:121], 0.5, v[178:179] op_sel_hi:[1,0,1]
	global_store_dwordx4 v[170:171], v[108:111], off offset:528
	v_pk_fma_f32 v[106:107], v[106:107], 0.5, v[196:197] op_sel_hi:[1,0,1]
	v_pk_fma_f32 v[104:105], v[104:105], 0.5, v[194:195] op_sel_hi:[1,0,1]
	v_pk_fma_f32 v[110:111], v[118:119], 0.5, v[192:193] op_sel_hi:[1,0,1]
	v_pk_fma_f32 v[108:109], v[116:117], 0.5, v[190:191] op_sel_hi:[1,0,1]
	global_store_dwordx4 v[96:97], v[92:95], off
	v_pk_fma_f32 v[90:91], v[90:91], 0.5, v[156:157] op_sel_hi:[1,0,1]
	v_pk_fma_f32 v[88:89], v[88:89], 0.5, v[154:155] op_sel_hi:[1,0,1]
	v_pk_fma_f32 v[86:87], v[86:87], 0.5, v[152:153] op_sel_hi:[1,0,1]
	v_pk_fma_f32 v[84:85], v[84:85], 0.5, v[150:151] op_sel_hi:[1,0,1]
	v_pk_fma_f32 v[78:79], v[78:79], 0.5, v[144:145] op_sel_hi:[1,0,1]
	v_pk_fma_f32 v[76:77], v[76:77], 0.5, v[142:143] op_sel_hi:[1,0,1]
	v_addc_co_u32_e32 v81, vcc, 0, v171, vcc
	v_pk_fma_f32 v[74:75], v[74:75], 0.5, v[140:141] op_sel_hi:[1,0,1]
	v_pk_fma_f32 v[72:73], v[72:73], 0.5, v[138:139] op_sel_hi:[1,0,1]
	v_pk_fma_f32 v[70:71], v[70:71], 0.5, v[134:135] op_sel_hi:[1,0,1]
	v_pk_fma_f32 v[68:69], v[68:69], 0.5, v[132:133] op_sel_hi:[1,0,1]
	v_pk_fma_f32 v[66:67], v[66:67], 0.5, v[130:131] op_sel_hi:[1,0,1]
	v_pk_fma_f32 v[64:65], v[64:65], 0.5, v[128:129] op_sel_hi:[1,0,1]
	v_lshl_add_u64 v[94:95], v[168:169], 0, s[8:9]
	v_lshl_add_u64 v[92:93], v[170:171], 0, s[8:9]
	global_store_dwordx4 v[170:171], v[124:127], off
	global_store_dwordx4 v[170:171], v[120:123], off offset:16
	global_store_dwordx4 v[112:113], v[108:111], off
	global_store_dwordx4 v[112:113], v[104:107], off offset:16
	global_store_dwordx4 v[96:97], v[88:91], off offset:16
	global_store_dwordx4 v[96:97], v[84:87], off offset:512
	global_store_dwordx4 v[80:81], v[76:79], off
	global_store_dwordx4 v[80:81], v[72:75], off offset:16
	global_store_dwordx4 v[80:81], v[68:71], off offset:512
	global_store_dwordx4 v[80:81], v[64:67], off offset:528
	global_load_dwordx4 v[96:99], v[94:95], off
	global_load_dwordx4 v[100:103], v[94:95], off offset:16
	global_load_dwordx4 v[104:107], v[94:95], off offset:512
	global_load_dwordx4 v[108:111], v[94:95], off offset:528
	v_add_co_u32_e32 v64, vcc, s94, v94
	s_waitcnt vmcnt(0) lgkmcnt(0)
	v_pk_fma_f32 v[62:63], v[62:63], 0.5, v[98:99] op_sel_hi:[1,0,1]
	v_addc_co_u32_e32 v65, vcc, 0, v95, vcc
	global_load_dwordx4 v[112:115], v[64:65], off
	global_load_dwordx4 v[116:119], v[64:65], off offset:16
	global_load_dwordx4 v[120:123], v[64:65], off offset:512
	global_load_dwordx4 v[124:127], v[64:65], off offset:528
	v_add_co_u32_e32 v64, vcc, s0, v94
	v_pk_fma_f32 v[50:51], v[50:51], 0.5, v[106:107] op_sel_hi:[1,0,1]
	s_nop 0
	v_addc_co_u32_e32 v65, vcc, 0, v95, vcc
	global_load_dwordx4 v[128:131], v[64:65], off
	global_load_dwordx4 v[88:91], v[64:65], off offset:16
	global_load_dwordx4 v[84:87], v[64:65], off offset:512
	global_load_dwordx4 v[80:83], v[64:65], off offset:528
	v_add_co_u32_e32 v64, vcc, s1, v94
	v_pk_fma_f32 v[48:49], v[48:49], 0.5, v[104:105] op_sel_hi:[1,0,1]
	s_nop 0
	v_addc_co_u32_e32 v65, vcc, 0, v95, vcc
	global_load_dwordx4 v[76:79], v[64:65], off
	global_load_dwordx4 v[72:75], v[64:65], off offset:16
	global_load_dwordx4 v[68:71], v[64:65], off offset:512
	s_nop 0
	global_load_dwordx4 v[64:67], v[64:65], off offset:528
	v_pk_fma_f32 v[46:47], v[46:47], 0.5, v[110:111] op_sel_hi:[1,0,1]
	global_store_dwordx4 v[92:93], v[48:51], off offset:512
	v_pk_fma_f32 v[44:45], v[44:45], 0.5, v[108:109] op_sel_hi:[1,0,1]
	v_pk_fma_f32 v[60:61], v[60:61], 0.5, v[96:97] op_sel_hi:[1,0,1]
	v_add_co_u32_e32 v48, vcc, s94, v92
	v_pk_fma_f32 v[58:59], v[58:59], 0.5, v[102:103] op_sel_hi:[1,0,1]
	s_nop 0
	v_addc_co_u32_e32 v49, vcc, 0, v93, vcc
	v_pk_fma_f32 v[56:57], v[56:57], 0.5, v[100:101] op_sel_hi:[1,0,1]
	global_store_dwordx4 v[92:93], v[44:47], off offset:528
	global_store_dwordx4 v[92:93], v[60:63], off
	global_store_dwordx4 v[92:93], v[56:59], off offset:16
	s_waitcnt vmcnt(0) lgkmcnt(0)
	v_pk_fma_f32 v[46:47], v[54:55], 0.5, v[114:115] op_sel_hi:[1,0,1]
	v_pk_fma_f32 v[44:45], v[52:53], 0.5, v[112:113] op_sel_hi:[1,0,1]
	v_pk_fma_f32 v[34:35], v[34:35], 0.5, v[122:123] op_sel_hi:[1,0,1]
	v_pk_fma_f32 v[32:33], v[32:33], 0.5, v[120:121] op_sel_hi:[1,0,1]
	global_store_dwordx4 v[48:49], v[32:35], off offset:512
	v_pk_fma_f32 v[30:31], v[30:31], 0.5, v[126:127] op_sel_hi:[1,0,1]
	v_pk_fma_f32 v[28:29], v[28:29], 0.5, v[124:125] op_sel_hi:[1,0,1]
	v_add_co_u32_e32 v32, vcc, s0, v92
	v_pk_fma_f32 v[18:19], v[18:19], 0.5, v[86:87] op_sel_hi:[1,0,1]
	s_nop 0
	v_addc_co_u32_e32 v33, vcc, 0, v93, vcc
	v_pk_fma_f32 v[16:17], v[16:17], 0.5, v[84:85] op_sel_hi:[1,0,1]
	global_store_dwordx4 v[32:33], v[16:19], off offset:512
	v_pk_fma_f32 v[14:15], v[14:15], 0.5, v[82:83] op_sel_hi:[1,0,1]
	v_pk_fma_f32 v[12:13], v[12:13], 0.5, v[80:81] op_sel_hi:[1,0,1]
	v_add_co_u32_e32 v16, vcc, s1, v92
	v_pk_fma_f32 v[2:3], v[2:3], 0.5, v[66:67] op_sel_hi:[1,0,1]
	s_nop 0
	v_addc_co_u32_e32 v17, vcc, 0, v93, vcc
	v_pk_fma_f32 v[0:1], v[0:1], 0.5, v[64:65] op_sel_hi:[1,0,1]
	v_pk_fma_f32 v[42:43], v[42:43], 0.5, v[118:119] op_sel_hi:[1,0,1]
	v_pk_fma_f32 v[40:41], v[40:41], 0.5, v[116:117] op_sel_hi:[1,0,1]
	global_store_dwordx4 v[48:49], v[28:31], off offset:528
	v_pk_fma_f32 v[26:27], v[26:27], 0.5, v[90:91] op_sel_hi:[1,0,1]
	v_pk_fma_f32 v[24:25], v[24:25], 0.5, v[88:89] op_sel_hi:[1,0,1]
	v_pk_fma_f32 v[30:31], v[38:39], 0.5, v[130:131] op_sel_hi:[1,0,1]
	v_pk_fma_f32 v[28:29], v[36:37], 0.5, v[128:129] op_sel_hi:[1,0,1]
	global_store_dwordx4 v[32:33], v[12:15], off offset:528
	v_pk_fma_f32 v[10:11], v[10:11], 0.5, v[74:75] op_sel_hi:[1,0,1]
	v_pk_fma_f32 v[8:9], v[8:9], 0.5, v[72:73] op_sel_hi:[1,0,1]
	v_pk_fma_f32 v[14:15], v[22:23], 0.5, v[78:79] op_sel_hi:[1,0,1]
	v_pk_fma_f32 v[12:13], v[20:21], 0.5, v[76:77] op_sel_hi:[1,0,1]
	v_pk_fma_f32 v[6:7], v[6:7], 0.5, v[70:71] op_sel_hi:[1,0,1]
	v_pk_fma_f32 v[4:5], v[4:5], 0.5, v[68:69] op_sel_hi:[1,0,1]
	global_store_dwordx4 v[16:17], v[0:3], off offset:528
	s_and_b64 vcc, exec, s[2:3]
	global_store_dwordx4 v[48:49], v[44:47], off
	v_lshl_add_u64 v[0:1], v[94:95], 0, s[8:9]
	v_lshl_add_u64 v[2:3], v[92:93], 0, s[8:9]
	global_store_dwordx4 v[48:49], v[40:43], off offset:16
	global_store_dwordx4 v[32:33], v[28:31], off
	global_store_dwordx4 v[32:33], v[24:27], off offset:16
	global_store_dwordx4 v[16:17], v[12:15], off
	global_store_dwordx4 v[16:17], v[8:11], off offset:16
	global_store_dwordx4 v[16:17], v[4:7], off offset:512
	s_cbranch_vccnz .LBB0_97
	s_andn2_b64 vcc, exec, s[66:67]
	s_cbranch_vccnz .LBB0_96
	s_barrier
	s_branch .LBB0_96

.LBB0_116:
	v_readlane_b32 s8, v254, 26
	v_readlane_b32 s22, v254, 40
	v_readlane_b32 s23, v254, 41
	s_mov_b64 s[4:5], s[22:23]
	v_mbcnt_lo_u32_b32 v0, -1, 0
	v_mbcnt_hi_u32_b32 v0, -1, v0
	v_readlane_b32 s2, v254, 4
	s_waitcnt vmcnt(0) lgkmcnt(0)
	v_readlane_b32 s9, v254, 27
	v_cmp_eq_u32_e32 vcc, 0, v0
	v_readlane_b32 s3, v254, 5
	s_and_b64 s[8:9], s[2:3], vcc
	v_readlane_b32 s10, v254, 28
	v_readlane_b32 s11, v254, 29
	v_readlane_b32 s12, v254, 30
	v_readlane_b32 s13, v254, 31
	v_readlane_b32 s14, v254, 32
	v_readlane_b32 s15, v254, 33
	v_readlane_b32 s16, v254, 34
	v_readlane_b32 s17, v254, 35
	v_readlane_b32 s18, v254, 36
	v_readlane_b32 s19, v254, 37
	v_readlane_b32 s20, v254, 38
	v_readlane_b32 s21, v254, 39
	s_waitcnt lgkmcnt(0)
	s_barrier
	s_and_saveexec_b64 s[2:3], s[8:9]
	v_readlane_b32 s62, v254, 9
	s_cbranch_execz .LBB0_132
	s_getreg_b32 s8, hwreg(HW_REG_XCC_ID, 0, 4)
	v_readlane_b32 s6, v255, 0
	s_lshl_b32 s8, s8, 8
	s_add_i32 s18, s6, 2
	s_and_b32 s8, s8, 0x700
	s_add_u32 s17, s4, s8
	s_addc_u32 s16, s5, 0
	v_mov_b32_e32 v0, s17
	v_add_co_u32_e32 v8, vcc, 0x2000, v0
	v_mov_b32_e32 v0, s16
	s_nop 0
	v_addc_co_u32_e32 v9, vcc, 0, v0, vcc
	v_mov_b32_e32 v0, s4
	v_add_co_u32_e32 v10, vcc, 0x2000, v0
	v_mov_b32_e32 v0, s5
	s_nop 0
	v_addc_co_u32_e32 v11, vcc, 0, v0, vcc
	global_load_dword v12, v[8:9], off sc1
	global_load_dword v0, v[10:11], off sc1
	global_load_dword v1, v[10:11], off offset:256 sc1
	global_load_dword v2, v[10:11], off offset:512 sc1
	global_load_dword v3, v[10:11], off offset:768 sc1
	global_load_dword v4, v[10:11], off offset:1024 sc1
	global_load_dword v5, v[10:11], off offset:1280 sc1
	global_load_dword v6, v[10:11], off offset:1536 sc1
	global_load_dword v7, v[10:11], off offset:1792 sc1
	v_mov_b32_e32 v10, 1
	global_atomic_add v8, v[8:9], v10, off offset:2048 sc0
	s_waitcnt vmcnt(0) lgkmcnt(0)
	v_mul_lo_u32 v9, v12, s18
	v_add_u32_e32 v8, 1, v8
	v_cmp_ne_u32_e32 vcc, v8, v9
	s_and_saveexec_b64 s[8:9], vcc
	s_xor_b64 s[8:9], exec, s[8:9]
	s_cbranch_execz .LBB0_122
	v_mov_b32_e32 v0, s17
	v_add_co_u32_e32 v0, vcc, 0x3000, v0
	v_mov_b32_e32 v1, s16
	s_nop 0
	v_addc_co_u32_e32 v1, vcc, 0, v1, vcc
	global_load_dword v0, v[0:1], off sc1
	s_add_u32 s10, s17, 0x3000
	s_addc_u32 s11, s16, 0
	s_waitcnt vmcnt(0) lgkmcnt(0)
	v_cmp_gt_u32_e32 vcc, s18, v0
	s_and_saveexec_b64 s[12:13], vcc
	s_cbranch_execz .LBB0_121
	s_mov_b64 s[14:15], 0
.LBB0_120:
	v_mov_b64_e32 v[0:1], s[10:11]
	s_sleep 2
	global_load_dword v0, v[0:1], off sc1
	s_waitcnt vmcnt(0) lgkmcnt(0)
	v_readfirstlane_b32 s19, v0
	s_cmp_ge_u32 s19, s18
	s_cselect_b64 s[20:21], -1, 0
	s_and_b64 s[20:21], exec, s[20:21]
	s_or_b64 s[14:15], s[20:21], s[14:15]
	s_andn2_b64 exec, exec, s[14:15]
	s_cbranch_execnz .LBB0_120

.LBB0_122:
	s_andn2_saveexec_b64 s[8:9], s[8:9]
	s_cbranch_execz .LBB0_131
	v_cmp_ne_u32_e32 vcc, 0, v0
	s_movk_i32 s6, 0x3000
	buffer_wbl2 sc1
	v_cndmask_b32_e64 v0, 0, 1, vcc
	v_cmp_ne_u32_e32 vcc, 0, v1
	s_waitcnt vmcnt(0)
	s_nop 1
	v_addc_co_u32_e32 v0, vcc, 0, v0, vcc
	v_cmp_ne_u32_e32 vcc, 0, v2
	s_nop 1
	v_cndmask_b32_e64 v1, 0, 1, vcc
	v_cmp_ne_u32_e32 vcc, 0, v3
	v_mov_b32_e32 v3, 1
	s_nop 0
	v_addc_co_u32_e32 v0, vcc, v0, v1, vcc
	v_cmp_ne_u32_e32 vcc, 0, v4
	s_nop 1
	v_cndmask_b32_e64 v1, 0, 1, vcc
	v_cmp_ne_u32_e32 vcc, 0, v5
	s_nop 1
	v_addc_co_u32_e32 v0, vcc, v0, v1, vcc
	v_cmp_ne_u32_e32 vcc, 0, v6
	s_nop 1
	v_cndmask_b32_e64 v1, 0, 1, vcc
	v_cmp_ne_u32_e32 vcc, 0, v7
	s_nop 1
	v_addc_co_u32_e32 v2, vcc, v0, v1, vcc
	v_mov_b32_e32 v0, s4
	v_add_co_u32_e32 v0, vcc, s6, v0
	v_mov_b32_e32 v1, s5
	s_nop 0
	v_addc_co_u32_e32 v1, vcc, 0, v1, vcc
	global_atomic_add v0, v[0:1], v3, off offset:2048 sc0
	v_mul_lo_u32 v1, v2, s18
	s_add_u32 s4, s4, 0x3900
	s_addc_u32 s5, s5, 0
	s_waitcnt vmcnt(0) lgkmcnt(0)
	v_add_u32_e32 v0, 1, v0
	v_cmp_ne_u32_e32 vcc, v0, v1
	s_and_saveexec_b64 s[10:11], vcc
	s_xor_b64 s[10:11], exec, s[10:11]
	s_cbranch_execz .LBB0_128
	v_mov_b64_e32 v[0:1], s[4:5]
	global_load_dword v0, v[0:1], off sc1
	s_waitcnt vmcnt(0) lgkmcnt(0)
	v_cmp_gt_u32_e32 vcc, s18, v0
	s_and_saveexec_b64 s[12:13], vcc
	s_cbranch_execz .LBB0_127
	s_mov_b64 s[14:15], 0
.LBB0_126:
	v_mov_b64_e32 v[0:1], s[4:5]
	s_sleep 2
	global_load_dword v0, v[0:1], off sc1
	s_waitcnt vmcnt(0) lgkmcnt(0)
	v_readfirstlane_b32 s19, v0
	s_cmp_ge_u32 s19, s18
	s_cselect_b64 s[20:21], -1, 0
	s_and_b64 s[20:21], exec, s[20:21]
	s_or_b64 s[14:15], s[20:21], s[14:15]
	s_andn2_b64 exec, exec, s[14:15]
	s_cbranch_execnz .LBB0_126

.LBB0_128:
	s_andn2_saveexec_b64 s[10:11], s[10:11]
	s_cbranch_execz .LBB0_130
	v_mov_b64_e32 v[0:1], s[4:5]
	v_mov_b32_e32 v2, 1
	global_atomic_add v[0:1], v2, off
.LBB0_130:
	s_or_b64 exec, exec, s[10:11]
	v_mov_b32_e32 v0, s17
	v_add_co_u32_e32 v0, vcc, 0x3000, v0
	v_mov_b32_e32 v1, s16
	s_nop 0
	v_addc_co_u32_e32 v1, vcc, 0, v1, vcc
	v_mov_b32_e32 v2, 1
	global_atomic_add v[0:1], v2, off

.LBB0_136:
	s_or_b64 exec, exec, s[24:25]
	v_add_u32_e32 v34, 0x18c0, v49
	s_waitcnt vmcnt(1)
	ds_write2_b32 v34, v0, v1 offset1:1
	v_add_u32_e32 v0, 0x18c8, v49
	ds_write2_b32 v0, v2, v3 offset1:1
	v_add_u32_e32 v0, 0x1ce0, v49
	s_waitcnt vmcnt(0)
	ds_write2_b32 v0, v4, v5 offset1:1
	v_add_u32_e32 v0, 0x1ce8, v49
	ds_write2_b32 v0, v6, v7 offset1:1
	s_waitcnt lgkmcnt(0)
	ds_read_b32 v0, v47
	ds_read_b32 v1, v47 offset:132
	s_ashr_i32 s21, s20, 31
	v_lshl_add_u64 v[4:5], s[20:21], 1, v[28:29]
	s_waitcnt lgkmcnt(0)
	v_cvt_pk_bf16_f32 v0, v0, v1
	ds_read_b32 v1, v47 offset:264
	ds_read_b32 v2, v47 offset:396
	s_waitcnt lgkmcnt(0)
	v_cvt_pk_bf16_f32 v1, v1, v2
	ds_read_b32 v2, v47 offset:528
	ds_read_b32 v3, v47 offset:660
	s_waitcnt lgkmcnt(0)
	v_cvt_pk_bf16_f32 v2, v2, v3
	ds_read_b32 v3, v47 offset:792
	ds_read_b32 v6, v47 offset:924
	s_waitcnt lgkmcnt(0)
	v_cvt_pk_bf16_f32 v3, v3, v6
	v_add_u32_e32 v6, s18, v37
	v_ashrrev_i32_e32 v7, 31, v6
	v_lshlrev_b64 v[6:7], 11, v[6:7]
	v_lshl_add_u64 v[6:7], v[4:5], 0, v[6:7]
	global_store_dwordx4 v[6:7], v[0:3], off
	ds_read_b32 v0, v47 offset:32
	ds_read_b32 v1, v47 offset:164
	s_waitcnt lgkmcnt(0)
	v_cvt_pk_bf16_f32 v0, v0, v1
	ds_read_b32 v1, v47 offset:296
	ds_read_b32 v2, v47 offset:428
	s_waitcnt lgkmcnt(0)
	v_cvt_pk_bf16_f32 v1, v1, v2
	ds_read_b32 v2, v47 offset:560
	ds_read_b32 v3, v47 offset:692
	s_waitcnt lgkmcnt(0)
	v_cvt_pk_bf16_f32 v2, v2, v3
	ds_read_b32 v3, v47 offset:824
	ds_read_b32 v6, v47 offset:956
	s_waitcnt lgkmcnt(0)
	v_cvt_pk_bf16_f32 v3, v3, v6
	v_add_u32_e32 v6, s18, v40
	v_ashrrev_i32_e32 v7, 31, v6
	v_lshlrev_b64 v[6:7], 11, v[6:7]
	v_lshl_add_u64 v[6:7], v[4:5], 0, v[6:7]
	global_store_dwordx4 v[6:7], v[0:3], off
	ds_read_b32 v0, v47 offset:64
	ds_read_b32 v1, v47 offset:196
	s_waitcnt lgkmcnt(0)
	v_cvt_pk_bf16_f32 v0, v0, v1
	ds_read_b32 v1, v47 offset:328
	ds_read_b32 v2, v47 offset:460
	s_waitcnt lgkmcnt(0)
	v_cvt_pk_bf16_f32 v1, v1, v2
	ds_read_b32 v2, v47 offset:592
	ds_read_b32 v3, v47 offset:724
	s_waitcnt lgkmcnt(0)
	v_cvt_pk_bf16_f32 v2, v2, v3
	ds_read_b32 v3, v47 offset:856
	ds_read_b32 v6, v47 offset:988
	s_waitcnt lgkmcnt(0)
	v_cvt_pk_bf16_f32 v3, v3, v6
	v_add_u32_e32 v6, s18, v41
	v_ashrrev_i32_e32 v7, 31, v6
	v_lshlrev_b64 v[6:7], 11, v[6:7]
	v_lshl_add_u64 v[6:7], v[4:5], 0, v[6:7]
	global_store_dwordx4 v[6:7], v[0:3], off
	ds_read_b32 v0, v47 offset:96
	ds_read_b32 v1, v47 offset:228
	s_waitcnt lgkmcnt(0)
	v_cvt_pk_bf16_f32 v0, v0, v1
	ds_read_b32 v1, v47 offset:360
	ds_read_b32 v2, v47 offset:492
	s_waitcnt lgkmcnt(0)
	v_cvt_pk_bf16_f32 v1, v1, v2
	ds_read_b32 v2, v47 offset:624
	ds_read_b32 v3, v47 offset:756
	s_waitcnt lgkmcnt(0)
	v_cvt_pk_bf16_f32 v2, v2, v3
	ds_read_b32 v3, v47 offset:888
	ds_read_b32 v6, v47 offset:1020
	s_waitcnt lgkmcnt(0)
	v_cvt_pk_bf16_f32 v3, v3, v6
	v_add_u32_e32 v6, s18, v42
	v_ashrrev_i32_e32 v7, 31, v6
	v_lshlrev_b64 v[6:7], 11, v[6:7]
	v_lshl_add_u64 v[4:5], v[4:5], 0, v[6:7]
	global_store_dwordx4 v[4:5], v[0:3], off
	s_waitcnt lgkmcnt(0)

.LBB0_153:
	s_and_b64 vcc, exec, s[18:19]
	s_cbranch_vccz .LBB0_155
	s_add_i32 s18, s44, 0xffffe880
	s_lshr_b32 s92, s18, 2
	v_readlane_b32 s52, v254, 42
	s_cmp_lt_u32 s18, 4
	v_readlane_b32 s56, v254, 46
	v_readlane_b32 s62, v254, 52
	v_readlane_b32 s57, v254, 47
	v_readlane_b32 s63, v254, 53
	s_cselect_b32 s19, s56, s62
	s_cselect_b32 s18, s57, s63
	s_add_u32 s19, s19, s16
	s_addc_u32 s20, s18, s17
	s_lshl_b32 s21, s44, 5
	s_and_b32 s18, s21, 32
	s_lshl_b32 s22, s18, 2
	s_add_u32 s22, s19, s22
	s_addc_u32 s23, s20, 0
	s_and_b32 s19, s21, 64
	s_waitcnt lgkmcnt(0)
	v_add_u32_e32 v0, s19, v37
	v_lshlrev_b32_e32 v136, 2, v8
	v_ashrrev_i32_e32 v1, 31, v0
	v_lshl_add_u64 v[4:5], s[22:23], 0, v[136:137]
	v_lshlrev_b64 v[0:1], 8, v[0:1]
	v_lshl_add_u64 v[0:1], v[4:5], 0, v[0:1]
	global_load_dwordx4 v[0:3], v[0:1], off
	v_add_u32_e32 v6, v38, v39
	v_add_u32_e32 v7, 0x420, v6
	s_lshl_b64 s[20:21], s[92:93], 14
	s_add_u32 s20, s39, s20
	s_addc_u32 s21, s40, s21
	v_lshlrev_b32_e32 v136, 1, v10
	s_movk_i32 s6, 0x300
	v_readlane_b32 s53, v254, 43
	v_readlane_b32 s54, v254, 44
	v_readlane_b32 s55, v254, 45
	v_readlane_b32 s58, v254, 48
	v_readlane_b32 s59, v254, 49
	v_readlane_b32 s60, v254, 50
	v_readlane_b32 s61, v254, 51
	v_readlane_b32 s64, v254, 54
	v_readlane_b32 s65, v254, 55
	v_readlane_b32 s66, v254, 56
	v_readlane_b32 s67, v254, 57
	s_waitcnt vmcnt(0)
	ds_write2_b32 v6, v0, v1 offset1:1
	ds_write2_b32 v6, v2, v3 offset0:2 offset1:3
	v_add_u32_e32 v0, s19, v40
	v_ashrrev_i32_e32 v1, 31, v0
	v_lshlrev_b64 v[0:1], 8, v[0:1]
	v_lshl_add_u64 v[0:1], v[4:5], 0, v[0:1]
	global_load_dwordx4 v[0:3], v[0:1], off
	s_waitcnt vmcnt(0)
	ds_write2_b32 v7, v0, v1 offset1:1
	v_add_u32_e32 v0, 0x428, v6
	ds_write2_b32 v0, v2, v3 offset1:1
	v_add_u32_e32 v0, s19, v41
	v_ashrrev_i32_e32 v1, 31, v0
	v_lshlrev_b64 v[0:1], 8, v[0:1]
	v_lshl_add_u64 v[0:1], v[4:5], 0, v[0:1]
	global_load_dwordx4 v[0:3], v[0:1], off
	v_add_u32_e32 v7, 0x840, v6
	s_waitcnt vmcnt(0)
	ds_write2_b32 v7, v0, v1 offset1:1
	v_add_u32_e32 v0, 0x848, v6
	ds_write2_b32 v0, v2, v3 offset1:1
	v_add_u32_e32 v0, s19, v42
	v_ashrrev_i32_e32 v1, 31, v0
	v_lshlrev_b64 v[0:1], 8, v[0:1]
	v_lshl_add_u64 v[0:1], v[4:5], 0, v[0:1]
	global_load_dwordx4 v[0:3], v[0:1], off
	v_add_u32_e32 v7, 0xc60, v6
	s_waitcnt vmcnt(0)
	ds_write2_b32 v7, v0, v1 offset1:1
	v_add_u32_e32 v0, 0xc68, v6
	ds_write2_b32 v0, v2, v3 offset1:1
	v_add_u32_e32 v0, s19, v43
	v_ashrrev_i32_e32 v1, 31, v0
	v_lshlrev_b64 v[0:1], 8, v[0:1]
	v_lshl_add_u64 v[0:1], v[4:5], 0, v[0:1]
	global_load_dwordx4 v[0:3], v[0:1], off
	v_add_u32_e32 v7, 0x1080, v6
	s_waitcnt vmcnt(0)
	ds_write2_b32 v7, v0, v1 offset1:1
	v_add_u32_e32 v0, 0x1088, v6
	ds_write2_b32 v0, v2, v3 offset1:1
	v_add_u32_e32 v0, s19, v44
	v_ashrrev_i32_e32 v1, 31, v0
	v_lshlrev_b64 v[0:1], 8, v[0:1]
	v_lshl_add_u64 v[0:1], v[4:5], 0, v[0:1]
	global_load_dwordx4 v[0:3], v[0:1], off
	v_add_u32_e32 v7, 0x14a0, v6
	s_waitcnt vmcnt(0)
	ds_write2_b32 v7, v0, v1 offset1:1
	v_add_u32_e32 v0, 0x14a8, v6
	ds_write2_b32 v0, v2, v3 offset1:1
	v_add_u32_e32 v0, s19, v45
	v_ashrrev_i32_e32 v1, 31, v0
	v_lshlrev_b64 v[0:1], 8, v[0:1]
	v_lshl_add_u64 v[0:1], v[4:5], 0, v[0:1]
	global_load_dwordx4 v[0:3], v[0:1], off
	v_add_u32_e32 v7, 0x18c0, v6
	s_waitcnt vmcnt(0)
	ds_write2_b32 v7, v0, v1 offset1:1
	v_add_u32_e32 v0, 0x18c8, v6
	ds_write2_b32 v0, v2, v3 offset1:1
	v_add_u32_e32 v0, s19, v46
	v_ashrrev_i32_e32 v1, 31, v0
	v_lshlrev_b64 v[0:1], 8, v[0:1]
	v_lshl_add_u64 v[0:1], v[4:5], 0, v[0:1]
	global_load_dwordx4 v[0:3], v[0:1], off
	v_add_u32_e32 v4, 0x1ce0, v6
	s_lshl_b32 s19, s19, 1
	s_add_u32 s20, s20, s19
	s_addc_u32 s21, s21, 0
	s_waitcnt vmcnt(0)
	ds_write2_b32 v4, v0, v1 offset1:1
	v_add_u32_e32 v0, 0x1ce8, v6
	ds_write2_b32 v0, v2, v3 offset1:1
	s_waitcnt lgkmcnt(0)
	ds_read_b32 v2, v47
	ds_read_b32 v3, v47 offset:132
	v_lshl_add_u64 v[0:1], s[20:21], 0, v[136:137]
	s_waitcnt lgkmcnt(0)
	v_cvt_pk_bf16_f32 v2, v2, v3
	ds_read_b32 v3, v47 offset:264
	ds_read_b32 v4, v47 offset:396
	s_waitcnt lgkmcnt(0)
	v_cvt_pk_bf16_f32 v3, v3, v4
	ds_read_b32 v4, v47 offset:528
	ds_read_b32 v5, v47 offset:660
	s_waitcnt lgkmcnt(0)
	v_cvt_pk_bf16_f32 v4, v4, v5
	ds_read_b32 v5, v47 offset:792
	ds_read_b32 v6, v47 offset:924
	s_waitcnt lgkmcnt(0)
	v_cvt_pk_bf16_f32 v5, v5, v6
	v_add_u32_e32 v6, s18, v37
	v_ashrrev_i32_e32 v7, 31, v6
	v_lshlrev_b64 v[6:7], 8, v[6:7]
	v_lshl_add_u64 v[6:7], v[0:1], 0, v[6:7]
	global_store_dwordx4 v[6:7], v[2:5], off
	ds_read_b32 v2, v47 offset:32
	ds_read_b32 v3, v47 offset:164
	s_waitcnt lgkmcnt(0)
	v_cvt_pk_bf16_f32 v2, v2, v3
	ds_read_b32 v3, v47 offset:296
	ds_read_b32 v4, v47 offset:428
	s_waitcnt lgkmcnt(0)
	v_cvt_pk_bf16_f32 v3, v3, v4
	ds_read_b32 v4, v47 offset:560
	ds_read_b32 v5, v47 offset:692
	s_waitcnt lgkmcnt(0)
	v_cvt_pk_bf16_f32 v4, v4, v5
	ds_read_b32 v5, v47 offset:824
	ds_read_b32 v6, v47 offset:956
	s_waitcnt lgkmcnt(0)
	v_cvt_pk_bf16_f32 v5, v5, v6
	v_add_u32_e32 v6, s18, v40
	v_ashrrev_i32_e32 v7, 31, v6
	v_lshlrev_b64 v[6:7], 8, v[6:7]
	v_lshl_add_u64 v[6:7], v[0:1], 0, v[6:7]
	global_store_dwordx4 v[6:7], v[2:5], off
	ds_read_b32 v2, v47 offset:64
	ds_read_b32 v3, v47 offset:196
	s_waitcnt lgkmcnt(0)
	v_cvt_pk_bf16_f32 v2, v2, v3
	ds_read_b32 v3, v47 offset:328
	ds_read_b32 v4, v47 offset:460
	s_waitcnt lgkmcnt(0)
	v_cvt_pk_bf16_f32 v3, v3, v4
	ds_read_b32 v4, v47 offset:592
	ds_read_b32 v5, v47 offset:724
	s_waitcnt lgkmcnt(0)
	v_cvt_pk_bf16_f32 v4, v4, v5
	ds_read_b32 v5, v47 offset:856
	ds_read_b32 v6, v47 offset:988
	s_waitcnt lgkmcnt(0)
	v_cvt_pk_bf16_f32 v5, v5, v6
	v_add_u32_e32 v6, s18, v41
	v_ashrrev_i32_e32 v7, 31, v6
	v_lshlrev_b64 v[6:7], 8, v[6:7]
	v_lshl_add_u64 v[6:7], v[0:1], 0, v[6:7]
	global_store_dwordx4 v[6:7], v[2:5], off
	ds_read_b32 v2, v47 offset:96
	ds_read_b32 v3, v47 offset:228
	s_waitcnt lgkmcnt(0)
	v_cvt_pk_bf16_f32 v2, v2, v3
	ds_read_b32 v3, v47 offset:360
	ds_read_b32 v4, v47 offset:492
	s_waitcnt lgkmcnt(0)
	v_cvt_pk_bf16_f32 v3, v3, v4
	ds_read_b32 v4, v47 offset:624
	ds_read_b32 v5, v47 offset:756
	s_waitcnt lgkmcnt(0)
	v_cvt_pk_bf16_f32 v4, v4, v5
	ds_read_b32 v5, v47 offset:888
	ds_read_b32 v6, v47 offset:1020
	s_waitcnt lgkmcnt(0)
	v_cvt_pk_bf16_f32 v5, v5, v6
	v_add_u32_e32 v6, s18, v42
	v_ashrrev_i32_e32 v7, 31, v6
	v_lshlrev_b64 v[6:7], 8, v[6:7]
	v_lshl_add_u64 v[0:1], v[0:1], 0, v[6:7]
	global_store_dwordx4 v[0:1], v[2:5], off
	s_waitcnt lgkmcnt(0)

.LBB0_156:
	s_andn2_b64 vcc, exec, s[18:19]
	s_cbranch_vccnz .LBB0_158
	s_add_i32 s18, s44, 0xffffe980
	s_and_b32 s92, s18, 0xffffff80
	s_cmpk_lt_u32 s18, 0x80
	s_cselect_b32 s19, s36, s38
	s_cselect_b32 s20, s35, s37
	s_lshl_b32 s18, s44, 5
	s_and_b32 s18, s18, 0x60
	s_lshl_b32 s21, s18, 2
	s_add_u32 s22, s20, s21
	s_addc_u32 s23, s19, 0
	s_lshl_b32 s19, s44, 4
	s_and_b32 s19, s19, 0x7c0
	s_waitcnt lgkmcnt(0)
	v_add_u32_e32 v0, s19, v37
	v_lshlrev_b32_e32 v136, 2, v8
	v_ashrrev_i32_e32 v1, 31, v0
	v_lshl_add_u64 v[4:5], s[22:23], 0, v[136:137]
	v_lshlrev_b64 v[0:1], 9, v[0:1]
	v_lshl_add_u64 v[0:1], v[4:5], 0, v[0:1]
	global_load_dwordx4 v[0:3], v[0:1], off
	v_add_u32_e32 v6, v38, v39
	v_add_u32_e32 v7, 0x420, v6
	s_lshl_b64 s[20:21], s[92:93], 12
	s_add_u32 s20, s41, s20
	s_addc_u32 s21, s42, s21
	v_lshlrev_b32_e32 v136, 1, v10
	s_waitcnt vmcnt(0)
	ds_write2_b32 v6, v0, v1 offset1:1
	ds_write2_b32 v6, v2, v3 offset0:2 offset1:3
	v_add_u32_e32 v0, s19, v40
	v_ashrrev_i32_e32 v1, 31, v0
	v_lshlrev_b64 v[0:1], 9, v[0:1]
	v_lshl_add_u64 v[0:1], v[4:5], 0, v[0:1]
	global_load_dwordx4 v[0:3], v[0:1], off
	s_waitcnt vmcnt(0)
	ds_write2_b32 v7, v0, v1 offset1:1
	v_add_u32_e32 v0, 0x428, v6
	ds_write2_b32 v0, v2, v3 offset1:1
	v_add_u32_e32 v0, s19, v41
	v_ashrrev_i32_e32 v1, 31, v0
	v_lshlrev_b64 v[0:1], 9, v[0:1]
	v_lshl_add_u64 v[0:1], v[4:5], 0, v[0:1]
	global_load_dwordx4 v[0:3], v[0:1], off
	v_add_u32_e32 v7, 0x840, v6
	s_waitcnt vmcnt(0)
	ds_write2_b32 v7, v0, v1 offset1:1
	v_add_u32_e32 v0, 0x848, v6
	ds_write2_b32 v0, v2, v3 offset1:1
	v_add_u32_e32 v0, s19, v42
	v_ashrrev_i32_e32 v1, 31, v0
	v_lshlrev_b64 v[0:1], 9, v[0:1]
	v_lshl_add_u64 v[0:1], v[4:5], 0, v[0:1]
	global_load_dwordx4 v[0:3], v[0:1], off
	v_add_u32_e32 v7, 0xc60, v6
	s_waitcnt vmcnt(0)
	ds_write2_b32 v7, v0, v1 offset1:1
	v_add_u32_e32 v0, 0xc68, v6
	ds_write2_b32 v0, v2, v3 offset1:1
	v_add_u32_e32 v0, s19, v43
	v_ashrrev_i32_e32 v1, 31, v0
	v_lshlrev_b64 v[0:1], 9, v[0:1]
	v_lshl_add_u64 v[0:1], v[4:5], 0, v[0:1]
	global_load_dwordx4 v[0:3], v[0:1], off
	v_add_u32_e32 v7, 0x1080, v6
	s_waitcnt vmcnt(0)
	ds_write2_b32 v7, v0, v1 offset1:1
	v_add_u32_e32 v0, 0x1088, v6
	ds_write2_b32 v0, v2, v3 offset1:1
	v_add_u32_e32 v0, s19, v44
	v_ashrrev_i32_e32 v1, 31, v0
	v_lshlrev_b64 v[0:1], 9, v[0:1]
	v_lshl_add_u64 v[0:1], v[4:5], 0, v[0:1]
	global_load_dwordx4 v[0:3], v[0:1], off
	v_add_u32_e32 v7, 0x14a0, v6
	s_waitcnt vmcnt(0)
	ds_write2_b32 v7, v0, v1 offset1:1
	v_add_u32_e32 v0, 0x14a8, v6
	ds_write2_b32 v0, v2, v3 offset1:1
	v_add_u32_e32 v0, s19, v45
	v_ashrrev_i32_e32 v1, 31, v0
	v_lshlrev_b64 v[0:1], 9, v[0:1]
	v_lshl_add_u64 v[0:1], v[4:5], 0, v[0:1]
	global_load_dwordx4 v[0:3], v[0:1], off
	v_add_u32_e32 v7, 0x18c0, v6
	s_waitcnt vmcnt(0)
	ds_write2_b32 v7, v0, v1 offset1:1
	v_add_u32_e32 v0, 0x18c8, v6
	ds_write2_b32 v0, v2, v3 offset1:1
	v_add_u32_e32 v0, s19, v46
	v_ashrrev_i32_e32 v1, 31, v0
	v_lshlrev_b64 v[0:1], 9, v[0:1]
	v_lshl_add_u64 v[0:1], v[4:5], 0, v[0:1]
	global_load_dwordx4 v[0:3], v[0:1], off
	v_add_u32_e32 v4, 0x1ce0, v6
	s_lshl_b32 s19, s19, 1
	s_add_u32 s20, s20, s19
	s_addc_u32 s21, s21, 0
	s_waitcnt vmcnt(0)
	ds_write2_b32 v4, v0, v1 offset1:1
	v_add_u32_e32 v0, 0x1ce8, v6
	ds_write2_b32 v0, v2, v3 offset1:1
	s_waitcnt lgkmcnt(0)
	ds_read_b32 v2, v47
	ds_read_b32 v3, v47 offset:132
	v_lshl_add_u64 v[0:1], s[20:21], 0, v[136:137]
	s_waitcnt lgkmcnt(0)
	v_cvt_pk_bf16_f32 v2, v2, v3
	ds_read_b32 v3, v47 offset:264
	ds_read_b32 v4, v47 offset:396
	s_waitcnt lgkmcnt(0)
	v_cvt_pk_bf16_f32 v3, v3, v4
	ds_read_b32 v4, v47 offset:528
	ds_read_b32 v5, v47 offset:660
	s_waitcnt lgkmcnt(0)
	v_cvt_pk_bf16_f32 v4, v4, v5
	ds_read_b32 v5, v47 offset:792
	ds_read_b32 v6, v47 offset:924
	s_waitcnt lgkmcnt(0)
	v_cvt_pk_bf16_f32 v5, v5, v6
	v_add_u32_e32 v6, s18, v37
	v_ashrrev_i32_e32 v7, 31, v6
	v_lshlrev_b64 v[6:7], 12, v[6:7]
	v_lshl_add_u64 v[6:7], v[0:1], 0, v[6:7]
	global_store_dwordx4 v[6:7], v[2:5], off
	ds_read_b32 v2, v47 offset:32
	ds_read_b32 v3, v47 offset:164
	s_waitcnt lgkmcnt(0)
	v_cvt_pk_bf16_f32 v2, v2, v3
	ds_read_b32 v3, v47 offset:296
	ds_read_b32 v4, v47 offset:428
	s_waitcnt lgkmcnt(0)
	v_cvt_pk_bf16_f32 v3, v3, v4
	ds_read_b32 v4, v47 offset:560
	ds_read_b32 v5, v47 offset:692
	s_waitcnt lgkmcnt(0)
	v_cvt_pk_bf16_f32 v4, v4, v5
	ds_read_b32 v5, v47 offset:824
	ds_read_b32 v6, v47 offset:956
	s_waitcnt lgkmcnt(0)
	v_cvt_pk_bf16_f32 v5, v5, v6
	v_add_u32_e32 v6, s18, v40
	v_ashrrev_i32_e32 v7, 31, v6
	v_lshlrev_b64 v[6:7], 12, v[6:7]
	v_lshl_add_u64 v[6:7], v[0:1], 0, v[6:7]
	global_store_dwordx4 v[6:7], v[2:5], off
	ds_read_b32 v2, v47 offset:64
	ds_read_b32 v3, v47 offset:196
	s_waitcnt lgkmcnt(0)
	v_cvt_pk_bf16_f32 v2, v2, v3
	ds_read_b32 v3, v47 offset:328
	ds_read_b32 v4, v47 offset:460
	s_waitcnt lgkmcnt(0)
	v_cvt_pk_bf16_f32 v3, v3, v4
	ds_read_b32 v4, v47 offset:592
	ds_read_b32 v5, v47 offset:724
	s_waitcnt lgkmcnt(0)
	v_cvt_pk_bf16_f32 v4, v4, v5
	ds_read_b32 v5, v47 offset:856
	ds_read_b32 v6, v47 offset:988
	s_waitcnt lgkmcnt(0)
	v_cvt_pk_bf16_f32 v5, v5, v6
	v_add_u32_e32 v6, s18, v41
	v_ashrrev_i32_e32 v7, 31, v6
	v_lshlrev_b64 v[6:7], 12, v[6:7]
	v_lshl_add_u64 v[6:7], v[0:1], 0, v[6:7]
	global_store_dwordx4 v[6:7], v[2:5], off
	ds_read_b32 v2, v47 offset:96
	ds_read_b32 v3, v47 offset:228
	s_waitcnt lgkmcnt(0)
	v_cvt_pk_bf16_f32 v2, v2, v3
	ds_read_b32 v3, v47 offset:360
	ds_read_b32 v4, v47 offset:492
	s_waitcnt lgkmcnt(0)
	v_cvt_pk_bf16_f32 v3, v3, v4
	ds_read_b32 v4, v47 offset:624
	ds_read_b32 v5, v47 offset:756
	s_waitcnt lgkmcnt(0)
	v_cvt_pk_bf16_f32 v4, v4, v5
	ds_read_b32 v5, v47 offset:888
	ds_read_b32 v6, v47 offset:1020
	s_waitcnt lgkmcnt(0)
	v_cvt_pk_bf16_f32 v5, v5, v6
	v_add_u32_e32 v6, s18, v42
	v_ashrrev_i32_e32 v7, 31, v6
	v_lshlrev_b64 v[6:7], 12, v[6:7]
	v_lshl_add_u64 v[0:1], v[0:1], 0, v[6:7]
	global_store_dwordx4 v[0:1], v[2:5], off
	s_waitcnt lgkmcnt(0)

.LBB0_159:
	s_andn2_b64 vcc, exec, s[18:19]
	s_cbranch_vccnz .LBB0_161
	s_lshl_b32 s18, s44, 5
	s_and_b32 s20, s18, 0x3e0
	s_lshl_b32 s18, s44, 1
	s_and_b32 s18, s18, 0x3fc0
	s_addk_i32 s18, 0xd700
	s_waitcnt lgkmcnt(0)
	v_add_u32_e32 v0, s18, v37
	s_lshl_b32 s92, s20, 2
	v_ashrrev_i32_e32 v1, 31, v0
	v_lshl_add_u64 v[4:5], v[12:13], 0, s[92:93]
	v_lshlrev_b64 v[0:1], 12, v[0:1]
	v_lshl_add_u64 v[0:1], v[4:5], 0, v[0:1]
	global_load_dwordx4 v[0:3], v[0:1], off
	v_add_u32_e32 v6, v38, v39
	v_add_u32_e32 v7, 0x420, v6
	s_mov_b32 s19, s93
	s_waitcnt vmcnt(0)
	ds_write2_b32 v6, v0, v1 offset1:1
	ds_write2_b32 v6, v2, v3 offset0:2 offset1:3
	v_add_u32_e32 v0, s18, v40
	v_ashrrev_i32_e32 v1, 31, v0
	v_lshlrev_b64 v[0:1], 12, v[0:1]
	v_lshl_add_u64 v[0:1], v[4:5], 0, v[0:1]
	global_load_dwordx4 v[0:3], v[0:1], off
	s_waitcnt vmcnt(0)
	ds_write2_b32 v7, v0, v1 offset1:1
	v_add_u32_e32 v0, 0x428, v6
	ds_write2_b32 v0, v2, v3 offset1:1
	v_add_u32_e32 v0, s18, v41
	v_ashrrev_i32_e32 v1, 31, v0
	v_lshlrev_b64 v[0:1], 12, v[0:1]
	v_lshl_add_u64 v[0:1], v[4:5], 0, v[0:1]
	global_load_dwordx4 v[0:3], v[0:1], off
	v_add_u32_e32 v7, 0x840, v6
	s_waitcnt vmcnt(0)
	ds_write2_b32 v7, v0, v1 offset1:1
	v_add_u32_e32 v0, 0x848, v6
	ds_write2_b32 v0, v2, v3 offset1:1
	v_add_u32_e32 v0, s18, v42
	v_ashrrev_i32_e32 v1, 31, v0
	v_lshlrev_b64 v[0:1], 12, v[0:1]
	v_lshl_add_u64 v[0:1], v[4:5], 0, v[0:1]
	global_load_dwordx4 v[0:3], v[0:1], off
	v_add_u32_e32 v7, 0xc60, v6
	s_waitcnt vmcnt(0)
	ds_write2_b32 v7, v0, v1 offset1:1
	v_add_u32_e32 v0, 0xc68, v6
	ds_write2_b32 v0, v2, v3 offset1:1
	v_add_u32_e32 v0, s18, v43
	v_ashrrev_i32_e32 v1, 31, v0
	v_lshlrev_b64 v[0:1], 12, v[0:1]
	v_lshl_add_u64 v[0:1], v[4:5], 0, v[0:1]
	global_load_dwordx4 v[0:3], v[0:1], off
	v_add_u32_e32 v7, 0x1080, v6
	s_waitcnt vmcnt(0)
	ds_write2_b32 v7, v0, v1 offset1:1
	v_add_u32_e32 v0, 0x1088, v6
	ds_write2_b32 v0, v2, v3 offset1:1
	v_add_u32_e32 v0, s18, v44
	v_ashrrev_i32_e32 v1, 31, v0
	v_lshlrev_b64 v[0:1], 12, v[0:1]
	v_lshl_add_u64 v[0:1], v[4:5], 0, v[0:1]
	global_load_dwordx4 v[0:3], v[0:1], off
	v_add_u32_e32 v7, 0x14a0, v6
	s_waitcnt vmcnt(0)
	ds_write2_b32 v7, v0, v1 offset1:1
	v_add_u32_e32 v0, 0x14a8, v6
	ds_write2_b32 v0, v2, v3 offset1:1
	v_add_u32_e32 v0, s18, v45
	v_ashrrev_i32_e32 v1, 31, v0
	v_lshlrev_b64 v[0:1], 12, v[0:1]
	v_lshl_add_u64 v[0:1], v[4:5], 0, v[0:1]
	global_load_dwordx4 v[0:3], v[0:1], off
	v_add_u32_e32 v7, 0x18c0, v6
	s_waitcnt vmcnt(0)
	ds_write2_b32 v7, v0, v1 offset1:1
	v_add_u32_e32 v0, 0x18c8, v6
	ds_write2_b32 v0, v2, v3 offset1:1
	v_add_u32_e32 v0, s18, v46
	v_ashrrev_i32_e32 v1, 31, v0
	v_lshlrev_b64 v[0:1], 12, v[0:1]
	v_lshl_add_u64 v[0:1], v[4:5], 0, v[0:1]
	global_load_dwordx4 v[0:3], v[0:1], off
	v_add_u32_e32 v4, 0x1ce0, v6
	s_waitcnt vmcnt(0)
	ds_write2_b32 v4, v0, v1 offset1:1
	v_add_u32_e32 v0, 0x1ce8, v6
	ds_write2_b32 v0, v2, v3 offset1:1
	s_waitcnt lgkmcnt(0)
	ds_read_b32 v2, v47
	ds_read_b32 v3, v47 offset:132
	v_lshl_add_u64 v[0:1], s[18:19], 1, v[14:15]
	s_waitcnt lgkmcnt(0)
	v_cvt_pk_bf16_f32 v2, v2, v3
	ds_read_b32 v3, v47 offset:264
	ds_read_b32 v4, v47 offset:396
	s_waitcnt lgkmcnt(0)
	v_cvt_pk_bf16_f32 v3, v3, v4
	ds_read_b32 v4, v47 offset:528
	ds_read_b32 v5, v47 offset:660
	s_waitcnt lgkmcnt(0)
	v_cvt_pk_bf16_f32 v4, v4, v5
	ds_read_b32 v5, v47 offset:792
	ds_read_b32 v6, v47 offset:924
	s_waitcnt lgkmcnt(0)
	v_cvt_pk_bf16_f32 v5, v5, v6
	v_add_u32_e32 v6, s20, v37
	v_ashrrev_i32_e32 v7, 31, v6
	v_lshlrev_b64 v[6:7], 11, v[6:7]
	v_lshl_add_u64 v[6:7], v[0:1], 0, v[6:7]
	global_store_dwordx4 v[6:7], v[2:5], off
	ds_read_b32 v2, v47 offset:32
	ds_read_b32 v3, v47 offset:164
	s_waitcnt lgkmcnt(0)
	v_cvt_pk_bf16_f32 v2, v2, v3
	ds_read_b32 v3, v47 offset:296
	ds_read_b32 v4, v47 offset:428
	s_waitcnt lgkmcnt(0)
	v_cvt_pk_bf16_f32 v3, v3, v4
	ds_read_b32 v4, v47 offset:560
	ds_read_b32 v5, v47 offset:692
	s_waitcnt lgkmcnt(0)
	v_cvt_pk_bf16_f32 v4, v4, v5
	ds_read_b32 v5, v47 offset:824
	ds_read_b32 v6, v47 offset:956
	s_waitcnt lgkmcnt(0)
	v_cvt_pk_bf16_f32 v5, v5, v6
	v_add_u32_e32 v6, s20, v40
	v_ashrrev_i32_e32 v7, 31, v6
	v_lshlrev_b64 v[6:7], 11, v[6:7]
	v_lshl_add_u64 v[6:7], v[0:1], 0, v[6:7]
	global_store_dwordx4 v[6:7], v[2:5], off
	ds_read_b32 v2, v47 offset:64
	ds_read_b32 v3, v47 offset:196
	s_waitcnt lgkmcnt(0)
	v_cvt_pk_bf16_f32 v2, v2, v3
	ds_read_b32 v3, v47 offset:328
	ds_read_b32 v4, v47 offset:460
	s_waitcnt lgkmcnt(0)
	v_cvt_pk_bf16_f32 v3, v3, v4
	ds_read_b32 v4, v47 offset:592
	ds_read_b32 v5, v47 offset:724
	s_waitcnt lgkmcnt(0)
	v_cvt_pk_bf16_f32 v4, v4, v5
	ds_read_b32 v5, v47 offset:856
	ds_read_b32 v6, v47 offset:988
	s_waitcnt lgkmcnt(0)
	v_cvt_pk_bf16_f32 v5, v5, v6
	v_add_u32_e32 v6, s20, v41
	v_ashrrev_i32_e32 v7, 31, v6
	v_lshlrev_b64 v[6:7], 11, v[6:7]
	v_lshl_add_u64 v[6:7], v[0:1], 0, v[6:7]
	global_store_dwordx4 v[6:7], v[2:5], off
	ds_read_b32 v2, v47 offset:96
	ds_read_b32 v3, v47 offset:228
	s_waitcnt lgkmcnt(0)
	v_cvt_pk_bf16_f32 v2, v2, v3
	ds_read_b32 v3, v47 offset:360
	ds_read_b32 v4, v47 offset:492
	s_waitcnt lgkmcnt(0)
	v_cvt_pk_bf16_f32 v3, v3, v4
	ds_read_b32 v4, v47 offset:624
	ds_read_b32 v5, v47 offset:756
	s_waitcnt lgkmcnt(0)
	v_cvt_pk_bf16_f32 v4, v4, v5
	ds_read_b32 v5, v47 offset:888
	ds_read_b32 v6, v47 offset:1020
	s_waitcnt lgkmcnt(0)
	v_cvt_pk_bf16_f32 v5, v5, v6
	v_add_u32_e32 v6, s20, v42
	v_ashrrev_i32_e32 v7, 31, v6
	v_lshlrev_b64 v[6:7], 11, v[6:7]
	v_lshl_add_u64 v[0:1], v[0:1], 0, v[6:7]
	global_store_dwordx4 v[0:1], v[2:5], off
	s_waitcnt lgkmcnt(0)

.LBB0_162:
	s_andn2_b64 vcc, exec, s[18:19]
	s_cbranch_vccnz .LBB0_164
	s_lshl_b32 s18, s44, 5
	s_and_b32 s20, s18, 0x3e0
	s_lshl_b32 s18, s44, 1
	s_and_b32 s18, s18, 0x3fc0
	s_addk_i32 s18, 0xd880
	s_waitcnt lgkmcnt(0)
	v_add_u32_e32 v0, s18, v37
	s_lshl_b32 s92, s20, 2
	v_ashrrev_i32_e32 v1, 31, v0
	v_lshl_add_u64 v[4:5], v[18:19], 0, s[92:93]
	v_lshlrev_b64 v[0:1], 12, v[0:1]
	v_lshl_add_u64 v[0:1], v[4:5], 0, v[0:1]
	global_load_dwordx4 v[0:3], v[0:1], off
	v_add_u32_e32 v6, v38, v39
	v_add_u32_e32 v7, 0x420, v6
	s_mov_b32 s19, s93
	s_waitcnt vmcnt(0)
	ds_write2_b32 v6, v0, v1 offset1:1
	ds_write2_b32 v6, v2, v3 offset0:2 offset1:3
	v_add_u32_e32 v0, s18, v40
	v_ashrrev_i32_e32 v1, 31, v0
	v_lshlrev_b64 v[0:1], 12, v[0:1]
	v_lshl_add_u64 v[0:1], v[4:5], 0, v[0:1]
	global_load_dwordx4 v[0:3], v[0:1], off
	s_waitcnt vmcnt(0)
	ds_write2_b32 v7, v0, v1 offset1:1
	v_add_u32_e32 v0, 0x428, v6
	ds_write2_b32 v0, v2, v3 offset1:1
	v_add_u32_e32 v0, s18, v41
	v_ashrrev_i32_e32 v1, 31, v0
	v_lshlrev_b64 v[0:1], 12, v[0:1]
	v_lshl_add_u64 v[0:1], v[4:5], 0, v[0:1]
	global_load_dwordx4 v[0:3], v[0:1], off
	v_add_u32_e32 v7, 0x840, v6
	s_waitcnt vmcnt(0)
	ds_write2_b32 v7, v0, v1 offset1:1
	v_add_u32_e32 v0, 0x848, v6
	ds_write2_b32 v0, v2, v3 offset1:1
	v_add_u32_e32 v0, s18, v42
	v_ashrrev_i32_e32 v1, 31, v0
	v_lshlrev_b64 v[0:1], 12, v[0:1]
	v_lshl_add_u64 v[0:1], v[4:5], 0, v[0:1]
	global_load_dwordx4 v[0:3], v[0:1], off
	v_add_u32_e32 v7, 0xc60, v6
	s_waitcnt vmcnt(0)
	ds_write2_b32 v7, v0, v1 offset1:1
	v_add_u32_e32 v0, 0xc68, v6
	ds_write2_b32 v0, v2, v3 offset1:1
	v_add_u32_e32 v0, s18, v43
	v_ashrrev_i32_e32 v1, 31, v0
	v_lshlrev_b64 v[0:1], 12, v[0:1]
	v_lshl_add_u64 v[0:1], v[4:5], 0, v[0:1]
	global_load_dwordx4 v[0:3], v[0:1], off
	v_add_u32_e32 v7, 0x1080, v6
	s_waitcnt vmcnt(0)
	ds_write2_b32 v7, v0, v1 offset1:1
	v_add_u32_e32 v0, 0x1088, v6
	ds_write2_b32 v0, v2, v3 offset1:1
	v_add_u32_e32 v0, s18, v44
	v_ashrrev_i32_e32 v1, 31, v0
	v_lshlrev_b64 v[0:1], 12, v[0:1]
	v_lshl_add_u64 v[0:1], v[4:5], 0, v[0:1]
	global_load_dwordx4 v[0:3], v[0:1], off
	v_add_u32_e32 v7, 0x14a0, v6
	s_waitcnt vmcnt(0)
	ds_write2_b32 v7, v0, v1 offset1:1
	v_add_u32_e32 v0, 0x14a8, v6
	ds_write2_b32 v0, v2, v3 offset1:1
	v_add_u32_e32 v0, s18, v45
	v_ashrrev_i32_e32 v1, 31, v0
	v_lshlrev_b64 v[0:1], 12, v[0:1]
	v_lshl_add_u64 v[0:1], v[4:5], 0, v[0:1]
	global_load_dwordx4 v[0:3], v[0:1], off
	v_add_u32_e32 v7, 0x18c0, v6
	s_waitcnt vmcnt(0)
	ds_write2_b32 v7, v0, v1 offset1:1
	v_add_u32_e32 v0, 0x18c8, v6
	ds_write2_b32 v0, v2, v3 offset1:1
	v_add_u32_e32 v0, s18, v46
	v_ashrrev_i32_e32 v1, 31, v0
	v_lshlrev_b64 v[0:1], 12, v[0:1]
	v_lshl_add_u64 v[0:1], v[4:5], 0, v[0:1]
	global_load_dwordx4 v[0:3], v[0:1], off
	v_add_u32_e32 v4, 0x1ce0, v6
	s_waitcnt vmcnt(0)
	ds_write2_b32 v4, v0, v1 offset1:1
	v_add_u32_e32 v0, 0x1ce8, v6
	ds_write2_b32 v0, v2, v3 offset1:1
	s_waitcnt lgkmcnt(0)
	ds_read_b32 v2, v47
	ds_read_b32 v3, v47 offset:132
	v_lshl_add_u64 v[0:1], s[18:19], 1, v[20:21]
	s_waitcnt lgkmcnt(0)
	v_cvt_pk_bf16_f32 v2, v2, v3
	ds_read_b32 v3, v47 offset:264
	ds_read_b32 v4, v47 offset:396
	s_waitcnt lgkmcnt(0)
	v_cvt_pk_bf16_f32 v3, v3, v4
	ds_read_b32 v4, v47 offset:528
	ds_read_b32 v5, v47 offset:660
	s_waitcnt lgkmcnt(0)
	v_cvt_pk_bf16_f32 v4, v4, v5
	ds_read_b32 v5, v47 offset:792
	ds_read_b32 v6, v47 offset:924
	s_waitcnt lgkmcnt(0)
	v_cvt_pk_bf16_f32 v5, v5, v6
	v_add_u32_e32 v6, s20, v37
	v_mad_i64_i32 v[6:7], s[18:19], v6, s6, v[0:1]
	global_store_dwordx4 v[6:7], v[2:5], off
	ds_read_b32 v2, v47 offset:32
	ds_read_b32 v3, v47 offset:164
	s_waitcnt lgkmcnt(0)
	v_cvt_pk_bf16_f32 v2, v2, v3
	ds_read_b32 v3, v47 offset:296
	ds_read_b32 v4, v47 offset:428
	s_waitcnt lgkmcnt(0)
	v_cvt_pk_bf16_f32 v3, v3, v4
	ds_read_b32 v4, v47 offset:560
	ds_read_b32 v5, v47 offset:692
	s_waitcnt lgkmcnt(0)
	v_cvt_pk_bf16_f32 v4, v4, v5
	ds_read_b32 v5, v47 offset:824
	ds_read_b32 v6, v47 offset:956
	s_waitcnt lgkmcnt(0)
	v_cvt_pk_bf16_f32 v5, v5, v6
	v_add_u32_e32 v6, s20, v40
	v_mad_i64_i32 v[6:7], s[18:19], v6, s6, v[0:1]
	global_store_dwordx4 v[6:7], v[2:5], off
	ds_read_b32 v2, v47 offset:64
	ds_read_b32 v3, v47 offset:196
	s_waitcnt lgkmcnt(0)
	v_cvt_pk_bf16_f32 v2, v2, v3
	ds_read_b32 v3, v47 offset:328
	ds_read_b32 v4, v47 offset:460
	s_waitcnt lgkmcnt(0)
	v_cvt_pk_bf16_f32 v3, v3, v4
	ds_read_b32 v4, v47 offset:592
	ds_read_b32 v5, v47 offset:724
	s_waitcnt lgkmcnt(0)
	v_cvt_pk_bf16_f32 v4, v4, v5
	ds_read_b32 v5, v47 offset:856
	ds_read_b32 v6, v47 offset:988
	s_waitcnt lgkmcnt(0)
	v_cvt_pk_bf16_f32 v5, v5, v6
	v_add_u32_e32 v6, s20, v41
	v_mad_i64_i32 v[6:7], s[18:19], v6, s6, v[0:1]
	global_store_dwordx4 v[6:7], v[2:5], off
	ds_read_b32 v2, v47 offset:96
	ds_read_b32 v3, v47 offset:228
	s_waitcnt lgkmcnt(0)
	v_cvt_pk_bf16_f32 v2, v2, v3
	ds_read_b32 v3, v47 offset:360
	ds_read_b32 v4, v47 offset:492
	s_waitcnt lgkmcnt(0)
	v_cvt_pk_bf16_f32 v3, v3, v4
	ds_read_b32 v4, v47 offset:624
	ds_read_b32 v5, v47 offset:756
	s_waitcnt lgkmcnt(0)
	v_cvt_pk_bf16_f32 v4, v4, v5
	ds_read_b32 v5, v47 offset:888
	ds_read_b32 v6, v47 offset:1020
	s_waitcnt lgkmcnt(0)
	v_cvt_pk_bf16_f32 v5, v5, v6
	v_add_u32_e32 v6, s20, v42
	v_mad_i64_i32 v[0:1], s[18:19], v6, s6, v[0:1]
	global_store_dwordx4 v[0:1], v[2:5], off
	s_waitcnt lgkmcnt(0)

.LBB0_165:
	s_andn2_b64 vcc, exec, s[18:19]
	s_cbranch_vccnz .LBB0_167
	s_lshl_b32 s18, s44, 5
	s_and_b32 s20, s18, 0x3e0
	s_lshl_b32 s18, s44, 1
	s_and_b32 s18, s18, 0x3fc0
	s_addk_i32 s18, 0xda80
	s_waitcnt lgkmcnt(0)
	v_add_u32_e32 v0, s18, v37
	s_lshl_b32 s92, s20, 2
	v_ashrrev_i32_e32 v1, 31, v0
	v_lshl_add_u64 v[4:5], v[22:23], 0, s[92:93]
	v_lshlrev_b64 v[0:1], 12, v[0:1]
	v_lshl_add_u64 v[0:1], v[4:5], 0, v[0:1]
	global_load_dwordx4 v[0:3], v[0:1], off
	v_add_u32_e32 v6, v38, v39
	v_add_u32_e32 v7, 0x420, v6
	s_mov_b32 s19, s93
	s_waitcnt vmcnt(0)
	ds_write2_b32 v6, v0, v1 offset1:1
	ds_write2_b32 v6, v2, v3 offset0:2 offset1:3
	v_add_u32_e32 v0, s18, v40
	v_ashrrev_i32_e32 v1, 31, v0
	v_lshlrev_b64 v[0:1], 12, v[0:1]
	v_lshl_add_u64 v[0:1], v[4:5], 0, v[0:1]
	global_load_dwordx4 v[0:3], v[0:1], off
	s_waitcnt vmcnt(0)
	ds_write2_b32 v7, v0, v1 offset1:1
	v_add_u32_e32 v0, 0x428, v6
	ds_write2_b32 v0, v2, v3 offset1:1
	v_add_u32_e32 v0, s18, v41
	v_ashrrev_i32_e32 v1, 31, v0
	v_lshlrev_b64 v[0:1], 12, v[0:1]
	v_lshl_add_u64 v[0:1], v[4:5], 0, v[0:1]
	global_load_dwordx4 v[0:3], v[0:1], off
	v_add_u32_e32 v7, 0x840, v6
	s_waitcnt vmcnt(0)
	ds_write2_b32 v7, v0, v1 offset1:1
	v_add_u32_e32 v0, 0x848, v6
	ds_write2_b32 v0, v2, v3 offset1:1
	v_add_u32_e32 v0, s18, v42
	v_ashrrev_i32_e32 v1, 31, v0
	v_lshlrev_b64 v[0:1], 12, v[0:1]
	v_lshl_add_u64 v[0:1], v[4:5], 0, v[0:1]
	global_load_dwordx4 v[0:3], v[0:1], off
	v_add_u32_e32 v7, 0xc60, v6
	s_waitcnt vmcnt(0)
	ds_write2_b32 v7, v0, v1 offset1:1
	v_add_u32_e32 v0, 0xc68, v6
	ds_write2_b32 v0, v2, v3 offset1:1
	v_add_u32_e32 v0, s18, v43
	v_ashrrev_i32_e32 v1, 31, v0
	v_lshlrev_b64 v[0:1], 12, v[0:1]
	v_lshl_add_u64 v[0:1], v[4:5], 0, v[0:1]
	global_load_dwordx4 v[0:3], v[0:1], off
	v_add_u32_e32 v7, 0x1080, v6
	s_waitcnt vmcnt(0)
	ds_write2_b32 v7, v0, v1 offset1:1
	v_add_u32_e32 v0, 0x1088, v6
	ds_write2_b32 v0, v2, v3 offset1:1
	v_add_u32_e32 v0, s18, v44
	v_ashrrev_i32_e32 v1, 31, v0
	v_lshlrev_b64 v[0:1], 12, v[0:1]
	v_lshl_add_u64 v[0:1], v[4:5], 0, v[0:1]
	global_load_dwordx4 v[0:3], v[0:1], off
	v_add_u32_e32 v7, 0x14a0, v6
	s_waitcnt vmcnt(0)
	ds_write2_b32 v7, v0, v1 offset1:1
	v_add_u32_e32 v0, 0x14a8, v6
	ds_write2_b32 v0, v2, v3 offset1:1
	v_add_u32_e32 v0, s18, v45
	v_ashrrev_i32_e32 v1, 31, v0
	v_lshlrev_b64 v[0:1], 12, v[0:1]
	v_lshl_add_u64 v[0:1], v[4:5], 0, v[0:1]
	global_load_dwordx4 v[0:3], v[0:1], off
	v_add_u32_e32 v7, 0x18c0, v6
	s_waitcnt vmcnt(0)
	ds_write2_b32 v7, v0, v1 offset1:1
	v_add_u32_e32 v0, 0x18c8, v6
	ds_write2_b32 v0, v2, v3 offset1:1
	v_add_u32_e32 v0, s18, v46
	v_ashrrev_i32_e32 v1, 31, v0
	v_lshlrev_b64 v[0:1], 12, v[0:1]
	v_lshl_add_u64 v[0:1], v[4:5], 0, v[0:1]
	global_load_dwordx4 v[0:3], v[0:1], off
	v_add_u32_e32 v4, 0x1ce0, v6
	s_waitcnt vmcnt(0)
	ds_write2_b32 v4, v0, v1 offset1:1
	v_add_u32_e32 v0, 0x1ce8, v6
	ds_write2_b32 v0, v2, v3 offset1:1
	s_waitcnt lgkmcnt(0)
	ds_read_b32 v2, v47
	ds_read_b32 v3, v47 offset:132
	v_lshl_add_u64 v[0:1], s[18:19], 1, v[24:25]
	s_waitcnt lgkmcnt(0)
	v_cvt_pk_bf16_f32 v2, v2, v3
	ds_read_b32 v3, v47 offset:264
	ds_read_b32 v4, v47 offset:396
	s_waitcnt lgkmcnt(0)
	v_cvt_pk_bf16_f32 v3, v3, v4
	ds_read_b32 v4, v47 offset:528
	ds_read_b32 v5, v47 offset:660
	s_waitcnt lgkmcnt(0)
	v_cvt_pk_bf16_f32 v4, v4, v5
	ds_read_b32 v5, v47 offset:792
	ds_read_b32 v6, v47 offset:924
	s_waitcnt lgkmcnt(0)
	v_cvt_pk_bf16_f32 v5, v5, v6
	v_add_u32_e32 v6, s20, v37
	v_ashrrev_i32_e32 v7, 31, v6
	v_lshlrev_b64 v[6:7], 10, v[6:7]
	v_lshl_add_u64 v[6:7], v[0:1], 0, v[6:7]
	global_store_dwordx4 v[6:7], v[2:5], off
	ds_read_b32 v2, v47 offset:32
	ds_read_b32 v3, v47 offset:164
	s_waitcnt lgkmcnt(0)
	v_cvt_pk_bf16_f32 v2, v2, v3
	ds_read_b32 v3, v47 offset:296
	ds_read_b32 v4, v47 offset:428
	s_waitcnt lgkmcnt(0)
	v_cvt_pk_bf16_f32 v3, v3, v4
	ds_read_b32 v4, v47 offset:560
	ds_read_b32 v5, v47 offset:692
	s_waitcnt lgkmcnt(0)
	v_cvt_pk_bf16_f32 v4, v4, v5
	ds_read_b32 v5, v47 offset:824
	ds_read_b32 v6, v47 offset:956
	s_waitcnt lgkmcnt(0)
	v_cvt_pk_bf16_f32 v5, v5, v6
	v_add_u32_e32 v6, s20, v40
	v_ashrrev_i32_e32 v7, 31, v6
	v_lshlrev_b64 v[6:7], 10, v[6:7]
	v_lshl_add_u64 v[6:7], v[0:1], 0, v[6:7]
	global_store_dwordx4 v[6:7], v[2:5], off
	ds_read_b32 v2, v47 offset:64
	ds_read_b32 v3, v47 offset:196
	s_waitcnt lgkmcnt(0)
	v_cvt_pk_bf16_f32 v2, v2, v3
	ds_read_b32 v3, v47 offset:328
	ds_read_b32 v4, v47 offset:460
	s_waitcnt lgkmcnt(0)
	v_cvt_pk_bf16_f32 v3, v3, v4
	ds_read_b32 v4, v47 offset:592
	ds_read_b32 v5, v47 offset:724
	s_waitcnt lgkmcnt(0)
	v_cvt_pk_bf16_f32 v4, v4, v5
	ds_read_b32 v5, v47 offset:856
	ds_read_b32 v6, v47 offset:988
	s_waitcnt lgkmcnt(0)
	v_cvt_pk_bf16_f32 v5, v5, v6
	v_add_u32_e32 v6, s20, v41
	v_ashrrev_i32_e32 v7, 31, v6
	v_lshlrev_b64 v[6:7], 10, v[6:7]
	v_lshl_add_u64 v[6:7], v[0:1], 0, v[6:7]
	global_store_dwordx4 v[6:7], v[2:5], off
	ds_read_b32 v2, v47 offset:96
	ds_read_b32 v3, v47 offset:228
	s_waitcnt lgkmcnt(0)
	v_cvt_pk_bf16_f32 v2, v2, v3
	ds_read_b32 v3, v47 offset:360
	ds_read_b32 v4, v47 offset:492
	s_waitcnt lgkmcnt(0)
	v_cvt_pk_bf16_f32 v3, v3, v4
	ds_read_b32 v4, v47 offset:624
	ds_read_b32 v5, v47 offset:756
	s_waitcnt lgkmcnt(0)
	v_cvt_pk_bf16_f32 v4, v4, v5
	ds_read_b32 v5, v47 offset:888
	ds_read_b32 v6, v47 offset:1020
	s_waitcnt lgkmcnt(0)
	v_cvt_pk_bf16_f32 v5, v5, v6
	v_add_u32_e32 v6, s20, v42
	v_ashrrev_i32_e32 v7, 31, v6
	v_lshlrev_b64 v[6:7], 10, v[6:7]
	v_lshl_add_u64 v[0:1], v[0:1], 0, v[6:7]
	global_store_dwordx4 v[0:1], v[2:5], off
	s_waitcnt lgkmcnt(0)

.LBB0_168:
	s_andn2_b64 vcc, exec, s[18:19]
	s_cbranch_vccnz .LBB0_170
	s_lshl_b32 s18, s44, 5
	s_and_b32 s20, s18, 0x3e0
	s_lshl_b32 s18, s44, 1
	s_and_b32 s18, s18, 0x3fc0
	s_addk_i32 s18, 0xdc00
	s_waitcnt lgkmcnt(0)
	v_add_u32_e32 v0, s18, v37
	s_lshl_b32 s92, s20, 2
	v_ashrrev_i32_e32 v1, 31, v0
	v_lshl_add_u64 v[4:5], v[16:17], 0, s[92:93]
	v_lshlrev_b64 v[0:1], 12, v[0:1]
	v_lshl_add_u64 v[0:1], v[4:5], 0, v[0:1]
	global_load_dwordx4 v[0:3], v[0:1], off
	v_add_u32_e32 v6, v38, v39
	v_add_u32_e32 v7, 0x420, v6
	s_mov_b32 s19, s93
	s_waitcnt vmcnt(0)
	ds_write2_b32 v6, v0, v1 offset1:1
	ds_write2_b32 v6, v2, v3 offset0:2 offset1:3
	v_add_u32_e32 v0, s18, v40
	v_ashrrev_i32_e32 v1, 31, v0
	v_lshlrev_b64 v[0:1], 12, v[0:1]
	v_lshl_add_u64 v[0:1], v[4:5], 0, v[0:1]
	global_load_dwordx4 v[0:3], v[0:1], off
	s_waitcnt vmcnt(0)
	ds_write2_b32 v7, v0, v1 offset1:1
	v_add_u32_e32 v0, 0x428, v6
	ds_write2_b32 v0, v2, v3 offset1:1
	v_add_u32_e32 v0, s18, v41
	v_ashrrev_i32_e32 v1, 31, v0
	v_lshlrev_b64 v[0:1], 12, v[0:1]
	v_lshl_add_u64 v[0:1], v[4:5], 0, v[0:1]
	global_load_dwordx4 v[0:3], v[0:1], off
	v_add_u32_e32 v7, 0x840, v6
	s_waitcnt vmcnt(0)
	ds_write2_b32 v7, v0, v1 offset1:1
	v_add_u32_e32 v0, 0x848, v6
	ds_write2_b32 v0, v2, v3 offset1:1
	v_add_u32_e32 v0, s18, v42
	v_ashrrev_i32_e32 v1, 31, v0
	v_lshlrev_b64 v[0:1], 12, v[0:1]
	v_lshl_add_u64 v[0:1], v[4:5], 0, v[0:1]
	global_load_dwordx4 v[0:3], v[0:1], off
	v_add_u32_e32 v7, 0xc60, v6
	s_waitcnt vmcnt(0)
	ds_write2_b32 v7, v0, v1 offset1:1
	v_add_u32_e32 v0, 0xc68, v6
	ds_write2_b32 v0, v2, v3 offset1:1
	v_add_u32_e32 v0, s18, v43
	v_ashrrev_i32_e32 v1, 31, v0
	v_lshlrev_b64 v[0:1], 12, v[0:1]
	v_lshl_add_u64 v[0:1], v[4:5], 0, v[0:1]
	global_load_dwordx4 v[0:3], v[0:1], off
	v_add_u32_e32 v7, 0x1080, v6
	s_waitcnt vmcnt(0)
	ds_write2_b32 v7, v0, v1 offset1:1
	v_add_u32_e32 v0, 0x1088, v6
	ds_write2_b32 v0, v2, v3 offset1:1
	v_add_u32_e32 v0, s18, v44
	v_ashrrev_i32_e32 v1, 31, v0
	v_lshlrev_b64 v[0:1], 12, v[0:1]
	v_lshl_add_u64 v[0:1], v[4:5], 0, v[0:1]
	global_load_dwordx4 v[0:3], v[0:1], off
	v_add_u32_e32 v7, 0x14a0, v6
	s_waitcnt vmcnt(0)
	ds_write2_b32 v7, v0, v1 offset1:1
	v_add_u32_e32 v0, 0x14a8, v6
	ds_write2_b32 v0, v2, v3 offset1:1
	v_add_u32_e32 v0, s18, v45
	v_ashrrev_i32_e32 v1, 31, v0
	v_lshlrev_b64 v[0:1], 12, v[0:1]
	v_lshl_add_u64 v[0:1], v[4:5], 0, v[0:1]
	global_load_dwordx4 v[0:3], v[0:1], off
	v_add_u32_e32 v7, 0x18c0, v6
	s_waitcnt vmcnt(0)
	ds_write2_b32 v7, v0, v1 offset1:1
	v_add_u32_e32 v0, 0x18c8, v6
	ds_write2_b32 v0, v2, v3 offset1:1
	v_add_u32_e32 v0, s18, v46
	v_ashrrev_i32_e32 v1, 31, v0
	v_lshlrev_b64 v[0:1], 12, v[0:1]
	v_lshl_add_u64 v[0:1], v[4:5], 0, v[0:1]
	global_load_dwordx4 v[0:3], v[0:1], off
	v_add_u32_e32 v4, 0x1ce0, v6
	s_waitcnt vmcnt(0)
	ds_write2_b32 v4, v0, v1 offset1:1
	v_add_u32_e32 v0, 0x1ce8, v6
	ds_write2_b32 v0, v2, v3 offset1:1
	s_waitcnt lgkmcnt(0)
	ds_read_b32 v2, v47
	ds_read_b32 v3, v47 offset:132
	v_lshl_add_u64 v[0:1], s[18:19], 1, v[26:27]
	s_waitcnt lgkmcnt(0)
	v_cvt_pk_bf16_f32 v2, v2, v3
	ds_read_b32 v3, v47 offset:264
	ds_read_b32 v4, v47 offset:396
	s_waitcnt lgkmcnt(0)
	v_cvt_pk_bf16_f32 v3, v3, v4
	ds_read_b32 v4, v47 offset:528
	ds_read_b32 v5, v47 offset:660
	s_waitcnt lgkmcnt(0)
	v_cvt_pk_bf16_f32 v4, v4, v5
	ds_read_b32 v5, v47 offset:792
	ds_read_b32 v6, v47 offset:924
	s_waitcnt lgkmcnt(0)
	v_cvt_pk_bf16_f32 v5, v5, v6
	v_add_u32_e32 v6, s20, v37
	v_mad_i64_i32 v[6:7], s[18:19], v6, s6, v[0:1]
	global_store_dwordx4 v[6:7], v[2:5], off
	ds_read_b32 v2, v47 offset:32
	ds_read_b32 v3, v47 offset:164
	s_waitcnt lgkmcnt(0)
	v_cvt_pk_bf16_f32 v2, v2, v3
	ds_read_b32 v3, v47 offset:296
	ds_read_b32 v4, v47 offset:428
	s_waitcnt lgkmcnt(0)
	v_cvt_pk_bf16_f32 v3, v3, v4
	ds_read_b32 v4, v47 offset:560
	ds_read_b32 v5, v47 offset:692
	s_waitcnt lgkmcnt(0)
	v_cvt_pk_bf16_f32 v4, v4, v5
	ds_read_b32 v5, v47 offset:824
	ds_read_b32 v6, v47 offset:956
	s_waitcnt lgkmcnt(0)
	v_cvt_pk_bf16_f32 v5, v5, v6
	v_add_u32_e32 v6, s20, v40
	v_mad_i64_i32 v[6:7], s[18:19], v6, s6, v[0:1]
	global_store_dwordx4 v[6:7], v[2:5], off
	ds_read_b32 v2, v47 offset:64
	ds_read_b32 v3, v47 offset:196
	s_waitcnt lgkmcnt(0)
	v_cvt_pk_bf16_f32 v2, v2, v3
	ds_read_b32 v3, v47 offset:328
	ds_read_b32 v4, v47 offset:460
	s_waitcnt lgkmcnt(0)
	v_cvt_pk_bf16_f32 v3, v3, v4
	ds_read_b32 v4, v47 offset:592
	ds_read_b32 v5, v47 offset:724
	s_waitcnt lgkmcnt(0)
	v_cvt_pk_bf16_f32 v4, v4, v5
	ds_read_b32 v5, v47 offset:856
	ds_read_b32 v6, v47 offset:988
	s_waitcnt lgkmcnt(0)
	v_cvt_pk_bf16_f32 v5, v5, v6
	v_add_u32_e32 v6, s20, v41
	v_mad_i64_i32 v[6:7], s[18:19], v6, s6, v[0:1]
	global_store_dwordx4 v[6:7], v[2:5], off
	ds_read_b32 v2, v47 offset:96
	ds_read_b32 v3, v47 offset:228
	s_waitcnt lgkmcnt(0)
	v_cvt_pk_bf16_f32 v2, v2, v3
	ds_read_b32 v3, v47 offset:360
	ds_read_b32 v4, v47 offset:492
	s_waitcnt lgkmcnt(0)
	v_cvt_pk_bf16_f32 v3, v3, v4
	ds_read_b32 v4, v47 offset:624
	ds_read_b32 v5, v47 offset:756
	s_waitcnt lgkmcnt(0)
	v_cvt_pk_bf16_f32 v4, v4, v5
	ds_read_b32 v5, v47 offset:888
	ds_read_b32 v6, v47 offset:1020
	s_waitcnt lgkmcnt(0)
	v_cvt_pk_bf16_f32 v5, v5, v6
	v_add_u32_e32 v6, s20, v42
	v_mad_i64_i32 v[0:1], s[18:19], v6, s6, v[0:1]
	global_store_dwordx4 v[0:1], v[2:5], off
	s_waitcnt lgkmcnt(0)

.LBB0_200:
	s_ashr_i32 s9, s8, 31
	s_lshl_b64 s[2:3], s[8:9], 12
	s_add_i32 s4, s8, s28
	v_lshl_add_u64 v[16:17], v[80:81], 0, s[2:3]
	s_cmp_lt_i32 s4, 0x8000
	global_load_dwordx4 v[72:75], v[16:17], off
	global_load_dwordx4 v[68:71], v[16:17], off offset:1024
	global_load_dwordx4 v[64:67], v[16:17], off offset:3072
	global_load_dwordx4 v[76:79], v[16:17], off offset:2048
	s_cselect_b32 s2, s4, s8
	s_ashr_i32 s3, s2, 31
	s_lshl_b64 s[2:3], s[2:3], 12
	s_add_i32 s14, s7, s8
	s_cmp_lt_i32 s14, 0x8000
	v_lshl_add_u64 v[16:17], v[80:81], 0, s[2:3]
	s_cselect_b64 s[16:17], -1, 0
	global_load_dwordx4 v[60:63], v[16:17], off
	global_load_dwordx4 v[56:59], v[16:17], off offset:1024
	global_load_dwordx4 v[52:55], v[16:17], off offset:2048
	global_load_dwordx4 v[48:51], v[16:17], off offset:3072
	s_and_b64 s[2:3], s[16:17], exec
	s_cselect_b32 s2, s14, s8
	s_ashr_i32 s3, s2, 31
	s_lshl_b64 s[2:3], s[2:3], 12
	v_lshl_add_u64 v[16:17], v[80:81], 0, s[2:3]
	global_load_dwordx4 v[44:47], v[16:17], off
	global_load_dwordx4 v[40:43], v[16:17], off offset:1024
	global_load_dwordx4 v[36:39], v[16:17], off offset:2048
	s_add_i32 s10, s18, s8
	s_cmp_lt_i32 s10, 0x8000
	s_cselect_b64 s[12:13], -1, 0
	s_and_b64 s[2:3], s[12:13], exec
	s_cselect_b32 s2, s10, s8
	global_load_dwordx4 v[32:35], v[16:17], off offset:3072
	s_ashr_i32 s3, s2, 31
	s_lshl_b64 s[2:3], s[2:3], 12
	v_lshl_add_u64 v[16:17], v[80:81], 0, s[2:3]
	global_load_dwordx4 v[28:31], v[16:17], off
	global_load_dwordx4 v[24:27], v[16:17], off offset:1024
	global_load_dwordx4 v[20:23], v[16:17], off offset:2048
	s_nop 0
	global_load_dwordx4 v[16:19], v[16:17], off offset:3072
	s_lshl_b64 s[8:9], s[8:9], 11
	s_cmpk_gt_i32 s4, 0x7fff
	s_waitcnt vmcnt(0) lgkmcnt(0)
	v_pk_mul_f32 v[90:91], v[74:75], v[74:75]
	v_pk_mul_f32 v[92:93], v[72:73], v[72:73]
	v_pk_mul_f32 v[94:95], v[70:71], v[70:71]
	v_pk_mul_f32 v[96:97], v[68:69], v[68:69]
	v_mul_f32_e32 v101, v64, v64
	v_mul_f32_e32 v98, v77, v77
	v_mul_f32_e32 v100, v79, v79
	v_pk_mov_b32 v[102:103], v[92:93], v[90:91] op_sel:[1,0]
	v_mov_b32_e32 v93, v91
	v_pk_mov_b32 v[90:91], v[96:97], v[94:95] op_sel:[1,0]
	v_mov_b32_e32 v97, v95
	v_mul_f32_e32 v105, v66, v66
	v_mul_f32_e32 v106, v67, v67
	v_pk_fma_f32 v[94:95], v[76:77], v[76:77], v[98:99] op_sel_hi:[1,1,0]
	v_pk_fma_f32 v[98:99], v[78:79], v[78:79], v[100:101] op_sel_hi:[1,1,0]
	v_pk_add_f32 v[92:93], v[102:103], v[92:93]
	v_pk_add_f32 v[90:91], v[90:91], v[96:97]
	v_mul_f32_e32 v104, v65, v65
	v_mov_b32_e32 v95, v105
	v_mov_b32_e32 v99, v106
	v_pk_add_f32 v[92:93], v[92:93], v[92:93] op_sel:[0,1] op_sel_hi:[1,0]
	v_pk_add_f32 v[90:91], v[90:91], v[90:91] op_sel:[0,1] op_sel_hi:[1,0]
	v_pk_add_f32 v[94:95], v[94:95], v[98:99]
	v_mov_b32_e32 v93, v101
	v_mov_b32_e32 v91, v104
	v_mul_f32_e32 v96, v61, v61
	v_mul_f32_e32 v97, v63, v63
	v_mul_f32_e32 v98, v57, v57
	v_mul_f32_e32 v99, v59, v59
	v_mul_f32_e32 v100, v53, v53
	v_mul_f32_e32 v101, v55, v55
	v_pk_add_f32 v[90:91], v[92:93], v[90:91]
	v_fmac_f32_e32 v96, v60, v60
	v_fmac_f32_e32 v97, v62, v62
	v_fmac_f32_e32 v98, v56, v56
	v_fmac_f32_e32 v99, v58, v58
	v_mul_f32_e32 v102, v49, v49
	v_mul_f32_e32 v103, v51, v51
	v_fmac_f32_e32 v100, v52, v52
	v_fmac_f32_e32 v101, v54, v54
	v_pk_add_f32 v[90:91], v[90:91], v[94:95]
	v_add_f32_e32 v92, v96, v97
	v_add_f32_e32 v93, v98, v99
	v_fmac_f32_e32 v102, v48, v48
	v_fmac_f32_e32 v103, v50, v50
	v_add_f32_e32 v94, v100, v101
	v_add_f32_e32 v90, v90, v91
	v_add_f32_e32 v91, v92, v93
	v_add_f32_e32 v91, v91, v94
	v_add_f32_e32 v92, v102, v103
	v_add_f32_e32 v91, v91, v92
	v_mul_f32_e32 v92, v45, v45
	v_mul_f32_e32 v93, v47, v47
	v_fmac_f32_e32 v92, v44, v44
	v_fmac_f32_e32 v93, v46, v46
	v_add_f32_e32 v92, v92, v93
	v_mul_f32_e32 v93, v41, v41
	v_mul_f32_e32 v94, v43, v43
	v_fmac_f32_e32 v93, v40, v40
	v_fmac_f32_e32 v94, v42, v42
	v_add_f32_e32 v93, v93, v94
	v_add_f32_e32 v92, v92, v93
	v_mul_f32_e32 v93, v37, v37
	v_mul_f32_e32 v94, v39, v39
	v_fmac_f32_e32 v93, v36, v36
	v_fmac_f32_e32 v94, v38, v38
	v_add_f32_e32 v93, v93, v94
	v_add_f32_e32 v92, v92, v93
	v_mul_f32_e32 v93, v33, v33
	v_mul_f32_e32 v94, v35, v35
	v_fmac_f32_e32 v93, v32, v32
	v_fmac_f32_e32 v94, v34, v34
	v_add_f32_e32 v93, v93, v94
	v_add_f32_e32 v92, v92, v93
	v_mul_f32_e32 v93, v29, v29
	v_mul_f32_e32 v94, v31, v31
	v_fmac_f32_e32 v93, v28, v28
	v_fmac_f32_e32 v94, v30, v30
	v_add_f32_e32 v93, v93, v94
	v_mul_f32_e32 v94, v25, v25
	v_mul_f32_e32 v95, v27, v27
	v_fmac_f32_e32 v94, v24, v24
	v_fmac_f32_e32 v95, v26, v26
	v_add_f32_e32 v94, v94, v95
	v_add_f32_e32 v93, v93, v94
	v_mul_f32_e32 v94, v21, v21
	v_mul_f32_e32 v95, v23, v23
	ds_bpermute_b32 v96, v84, v90
	v_fmac_f32_e32 v94, v20, v20
	v_fmac_f32_e32 v95, v22, v22
	v_add_f32_e32 v94, v94, v95
	v_add_f32_e32 v93, v93, v94
	v_mul_f32_e32 v94, v17, v17
	v_mul_f32_e32 v95, v19, v19
	v_fmac_f32_e32 v94, v16, v16
	v_fmac_f32_e32 v95, v18, v18
	v_add_f32_e32 v94, v94, v95
	s_waitcnt lgkmcnt(0)
	v_add_f32_e32 v90, v90, v96
	v_add_f32_e32 v93, v93, v94
	ds_bpermute_b32 v96, v85, v90
	ds_bpermute_b32 v97, v84, v91
	ds_bpermute_b32 v94, v84, v92
	ds_bpermute_b32 v95, v84, v93
	s_waitcnt lgkmcnt(3)
	v_add_f32_e32 v90, v90, v96
	s_waitcnt lgkmcnt(2)
	v_add_f32_e32 v91, v91, v97
	s_waitcnt lgkmcnt(1)
	v_add_f32_e32 v92, v92, v94
	s_waitcnt lgkmcnt(0)
	v_add_f32_e32 v93, v93, v95
	ds_bpermute_b32 v95, v86, v90
	ds_bpermute_b32 v97, v85, v91
	ds_bpermute_b32 v94, v85, v92
	s_waitcnt lgkmcnt(2)
	v_add_f32_e32 v90, v90, v95
	s_waitcnt lgkmcnt(1)
	v_add_f32_e32 v91, v91, v97
	s_waitcnt lgkmcnt(0)
	v_add_f32_e32 v92, v92, v94
	ds_bpermute_b32 v95, v87, v90
	ds_bpermute_b32 v96, v86, v91
	ds_bpermute_b32 v97, v86, v92
	ds_bpermute_b32 v94, v85, v93
	s_waitcnt lgkmcnt(3)
	v_add_f32_e32 v90, v90, v95
	s_waitcnt lgkmcnt(2)
	v_add_f32_e32 v91, v91, v96
	s_waitcnt lgkmcnt(1)
	v_add_f32_e32 v92, v92, v97
	ds_bpermute_b32 v97, v88, v90
	ds_bpermute_b32 v95, v87, v91
	s_waitcnt lgkmcnt(2)
	v_add_f32_e32 v93, v93, v94
	ds_bpermute_b32 v94, v86, v93
	ds_bpermute_b32 v96, v87, v92
	s_waitcnt lgkmcnt(3)
	v_add_f32_e32 v90, v90, v97
	s_waitcnt lgkmcnt(2)
	v_add_f32_e32 v91, v91, v95
	ds_bpermute_b32 v95, v89, v90
	s_waitcnt lgkmcnt(2)
	v_add_f32_e32 v93, v93, v94
	ds_bpermute_b32 v94, v87, v93
	s_waitcnt lgkmcnt(2)
	v_add_f32_e32 v92, v92, v96
	ds_bpermute_b32 v96, v88, v92
	s_waitcnt lgkmcnt(2)
	v_add_f32_e32 v90, v90, v95
	v_mov_b32_e32 v95, 0x358637bd
	v_fmamk_f32 v90, v90, 0x3a800000, v95
	v_mul_f32_e32 v95, 0x4f800000, v90
	v_cmp_gt_f32_e32 vcc, s6, v90
	s_waitcnt lgkmcnt(1)
	v_add_f32_e32 v93, v93, v94
	ds_bpermute_b32 v94, v88, v91
	v_cndmask_b32_e32 v95, v90, v95, vcc
	ds_bpermute_b32 v97, v88, v93
	v_sqrt_f32_e32 v98, v95
	s_waitcnt lgkmcnt(2)
	v_add_f32_e32 v92, v92, v96
	s_waitcnt lgkmcnt(1)
	v_add_f32_e32 v94, v91, v94
	v_add_u32_e32 v91, -1, v98
	s_waitcnt lgkmcnt(0)
	v_add_f32_e32 v90, v93, v97
	v_fma_f32 v93, -v91, v98, v95
	v_cmp_ge_f32_e64 s[2:3], 0, v93
	v_add_u32_e32 v93, 1, v98
	v_fma_f32 v96, -v93, v98, v95
	v_cndmask_b32_e64 v91, v98, v91, s[2:3]
	v_cmp_lt_f32_e64 s[2:3], 0, v96
	s_nop 1
	v_cndmask_b32_e64 v91, v91, v93, s[2:3]
	v_mul_f32_e32 v93, 0x37800000, v91
	v_cndmask_b32_e32 v91, v91, v93, vcc
	v_mov_b32_e32 v93, 0x260
	v_cmp_class_f32_e32 vcc, v95, v93
	ds_bpermute_b32 v93, v89, v92
	s_nop 0
	v_cndmask_b32_e32 v96, v91, v95, vcc
	v_div_scale_f32 v97, s[2:3], v96, v96, 1.0
	v_rcp_f32_e32 v98, v97
	ds_bpermute_b32 v95, v89, v94
	ds_bpermute_b32 v91, v89, v90
	v_fma_f32 v99, -v97, v98, 1.0
	v_fmac_f32_e32 v98, v99, v98
	v_div_scale_f32 v99, vcc, 1.0, v96, 1.0
	v_mul_f32_e32 v100, v99, v98
	v_fma_f32 v101, -v97, v100, v99
	v_fmac_f32_e32 v100, v101, v98
	v_fma_f32 v97, -v97, v100, v99
	v_div_fmas_f32 v97, v97, v98, v100
	v_div_fixup_f32 v96, v97, v96, 1.0
	v_pk_mul_f32 v[68:69], v[68:69], v[96:97] op_sel_hi:[1,0]
	v_pk_mul_f32 v[70:71], v[70:71], v[96:97] op_sel_hi:[1,0]
	v_pk_mul_f32 v[68:69], v[4:5], v[68:69]
	v_pk_mul_f32 v[70:71], v[6:7], v[70:71]
	v_lshl_add_u64 v[98:99], v[82:83], 0, s[8:9]
	v_cvt_pk_bf16_f32 v68, v68, v69
	v_cvt_pk_bf16_f32 v69, v70, v71
	v_pk_mul_f32 v[72:73], v[72:73], v[96:97] op_sel_hi:[1,0]
	v_pk_mul_f32 v[74:75], v[74:75], v[96:97] op_sel_hi:[1,0]
	global_store_dwordx2 v[98:99], v[68:69], off offset:512
	v_pk_mul_f32 v[68:69], v[76:77], v[96:97] op_sel_hi:[1,0]
	v_pk_mul_f32 v[70:71], v[78:79], v[96:97] op_sel_hi:[1,0]
	v_pk_mul_f32 v[64:65], v[64:65], v[96:97] op_sel_hi:[1,0]
	v_pk_mul_f32 v[66:67], v[66:67], v[96:97] op_sel_hi:[1,0]
	v_pk_mul_f32 v[74:75], v[2:3], v[74:75]
	v_pk_mul_f32 v[72:73], v[0:1], v[72:73]
	v_pk_mul_f32 v[70:71], v[10:11], v[70:71]
	v_pk_mul_f32 v[68:69], v[8:9], v[68:69]
	v_pk_mul_f32 v[66:67], v[14:15], v[66:67]
	v_pk_mul_f32 v[64:65], v[12:13], v[64:65]
	v_cvt_pk_bf16_f32 v72, v72, v73
	v_cvt_pk_bf16_f32 v73, v74, v75
	v_cvt_pk_bf16_f32 v68, v68, v69
	v_cvt_pk_bf16_f32 v69, v70, v71
	v_cvt_pk_bf16_f32 v64, v64, v65
	v_cvt_pk_bf16_f32 v65, v66, v67
	global_store_dwordx2 v[98:99], v[72:73], off
	global_store_dwordx2 v[98:99], v[68:69], off offset:1024
	global_store_dwordx2 v[98:99], v[64:65], off offset:1536
	s_cbranch_scc0 .LBB0_203
	s_andn2_b64 vcc, exec, s[16:17]
	s_cbranch_vccz .LBB0_204

.LBB0_203:
	s_waitcnt lgkmcnt(0)
	v_add_f32_e32 v64, v94, v95
	v_mov_b32_e32 v65, 0x358637bd
	v_fmamk_f32 v64, v64, 0x3a800000, v65
	v_mul_f32_e32 v65, 0x4f800000, v64
	v_cmp_gt_f32_e32 vcc, s6, v64
	s_ashr_i32 s5, s4, 31
	s_nop 0
	v_cndmask_b32_e32 v64, v64, v65, vcc
	v_sqrt_f32_e32 v65, v64
	s_nop 0
	v_add_u32_e32 v66, -1, v65
	v_fma_f32 v68, -v66, v65, v64
	v_add_u32_e32 v67, 1, v65
	v_cmp_ge_f32_e64 s[2:3], 0, v68
	s_nop 1
	v_cndmask_b32_e64 v66, v65, v66, s[2:3]
	v_fma_f32 v65, -v67, v65, v64
	v_cmp_lt_f32_e64 s[2:3], 0, v65
	s_nop 1
	v_cndmask_b32_e64 v65, v66, v67, s[2:3]
	v_mul_f32_e32 v66, 0x37800000, v65
	v_cndmask_b32_e32 v65, v65, v66, vcc
	v_mov_b32_e32 v66, 0x260
	v_cmp_class_f32_e32 vcc, v64, v66
	s_nop 1
	v_cndmask_b32_e32 v64, v65, v64, vcc
	v_div_scale_f32 v65, s[2:3], v64, v64, 1.0
	v_rcp_f32_e32 v66, v65
	s_lshl_b64 s[2:3], s[4:5], 11
	v_fma_f32 v67, -v65, v66, 1.0
	v_fmac_f32_e32 v66, v67, v66
	v_div_scale_f32 v67, vcc, 1.0, v64, 1.0
	v_mul_f32_e32 v68, v67, v66
	v_fma_f32 v69, -v65, v68, v67
	v_fmac_f32_e32 v68, v69, v66
	v_fma_f32 v65, -v65, v68, v67
	v_div_fmas_f32 v65, v65, v66, v68
	v_div_fixup_f32 v64, v65, v64, 1.0
	v_pk_mul_f32 v[60:61], v[60:61], v[64:65] op_sel_hi:[1,0]
	v_pk_mul_f32 v[62:63], v[62:63], v[64:65] op_sel_hi:[1,0]
	v_pk_mul_f32 v[56:57], v[56:57], v[64:65] op_sel_hi:[1,0]
	v_pk_mul_f32 v[58:59], v[58:59], v[64:65] op_sel_hi:[1,0]
	v_pk_mul_f32 v[52:53], v[52:53], v[64:65] op_sel_hi:[1,0]
	v_pk_mul_f32 v[54:55], v[54:55], v[64:65] op_sel_hi:[1,0]
	v_pk_mul_f32 v[48:49], v[48:49], v[64:65] op_sel_hi:[1,0]
	v_pk_mul_f32 v[50:51], v[50:51], v[64:65] op_sel_hi:[1,0]
	v_pk_mul_f32 v[62:63], v[2:3], v[62:63]
	v_pk_mul_f32 v[60:61], v[0:1], v[60:61]
	v_pk_mul_f32 v[58:59], v[6:7], v[58:59]
	v_pk_mul_f32 v[56:57], v[4:5], v[56:57]
	v_pk_mul_f32 v[54:55], v[10:11], v[54:55]
	v_pk_mul_f32 v[52:53], v[8:9], v[52:53]
	v_pk_mul_f32 v[50:51], v[14:15], v[50:51]
	v_pk_mul_f32 v[48:49], v[12:13], v[48:49]
	v_lshl_add_u64 v[66:67], v[82:83], 0, s[2:3]
	v_cvt_pk_bf16_f32 v60, v60, v61
	v_cvt_pk_bf16_f32 v61, v62, v63
	v_cvt_pk_bf16_f32 v56, v56, v57
	v_cvt_pk_bf16_f32 v57, v58, v59
	v_cvt_pk_bf16_f32 v52, v52, v53
	v_cvt_pk_bf16_f32 v53, v54, v55
	v_cvt_pk_bf16_f32 v48, v48, v49
	v_cvt_pk_bf16_f32 v49, v50, v51
	global_store_dwordx2 v[66:67], v[60:61], off
	global_store_dwordx2 v[66:67], v[56:57], off offset:512
	global_store_dwordx2 v[66:67], v[52:53], off offset:1024
	global_store_dwordx2 v[66:67], v[48:49], off offset:1536
	s_andn2_b64 vcc, exec, s[16:17]
	s_cbranch_vccnz .LBB0_202

.LBB0_207:
	v_readlane_b32 s8, v254, 26
	v_readlane_b32 s22, v254, 40
	v_readlane_b32 s23, v254, 41
	s_add_i32 s2, s2, 3
	s_mov_b64 s[4:5], s[22:23]
	v_writelane_b32 v255, s2, 1
	s_waitcnt lgkmcnt(0)
	v_mbcnt_lo_u32_b32 v0, -1, 0
	v_mbcnt_hi_u32_b32 v0, -1, v0
	v_readlane_b32 s2, v254, 4
	s_waitcnt vmcnt(0) lgkmcnt(0)
	v_readlane_b32 s9, v254, 27
	v_cmp_eq_u32_e32 vcc, 0, v0
	v_readlane_b32 s3, v254, 5
	s_and_b64 s[8:9], s[2:3], vcc
	v_readlane_b32 s10, v254, 28
	v_readlane_b32 s11, v254, 29
	v_readlane_b32 s12, v254, 30
	v_readlane_b32 s13, v254, 31
	v_readlane_b32 s14, v254, 32
	v_readlane_b32 s15, v254, 33
	v_readlane_b32 s16, v254, 34
	v_readlane_b32 s17, v254, 35
	v_readlane_b32 s18, v254, 36
	v_readlane_b32 s19, v254, 37
	v_readlane_b32 s20, v254, 38
	v_readlane_b32 s21, v254, 39
	s_barrier
	s_and_saveexec_b64 s[2:3], s[8:9]
	s_cbranch_execz .LBB0_223
	s_getreg_b32 s7, hwreg(HW_REG_XCC_ID, 0, 4)
	s_lshl_b32 s7, s7, 8
	s_and_b32 s7, s7, 0x700
	s_add_u32 s16, s4, s7
	s_addc_u32 s7, s5, 0
	v_mov_b32_e32 v0, s16
	v_add_co_u32_e32 v8, vcc, 0x2000, v0
	v_mov_b32_e32 v0, s7
	s_nop 0
	v_addc_co_u32_e32 v9, vcc, 0, v0, vcc
	v_mov_b32_e32 v0, s4
	v_add_co_u32_e32 v10, vcc, 0x2000, v0
	v_mov_b32_e32 v0, s5
	s_nop 0
	v_addc_co_u32_e32 v11, vcc, 0, v0, vcc
	global_load_dword v12, v[8:9], off sc1
	global_load_dword v0, v[10:11], off sc1
	global_load_dword v1, v[10:11], off offset:256 sc1
	global_load_dword v2, v[10:11], off offset:512 sc1
	global_load_dword v3, v[10:11], off offset:768 sc1
	global_load_dword v4, v[10:11], off offset:1024 sc1
	global_load_dword v5, v[10:11], off offset:1280 sc1
	global_load_dword v6, v[10:11], off offset:1536 sc1
	global_load_dword v7, v[10:11], off offset:1792 sc1
	v_mov_b32_e32 v10, 1
	global_atomic_add v8, v[8:9], v10, off offset:2048 sc0
	v_readlane_b32 s6, v255, 1
	s_waitcnt vmcnt(0) lgkmcnt(0)
	v_add_u32_e32 v8, 1, v8
	v_mul_lo_u32 v9, v12, s6
	v_cmp_ne_u32_e32 vcc, v8, v9
	s_and_saveexec_b64 s[8:9], vcc
	s_xor_b64 s[8:9], exec, s[8:9]
	s_cbranch_execz .LBB0_213
	v_mov_b32_e32 v0, s16
	v_add_co_u32_e32 v0, vcc, 0x3000, v0
	v_mov_b32_e32 v1, s7
	s_nop 0
	v_addc_co_u32_e32 v1, vcc, 0, v1, vcc
	global_load_dword v0, v[0:1], off sc1
	s_add_u32 s10, s16, 0x3000
	s_addc_u32 s11, s7, 0
	s_waitcnt vmcnt(0) lgkmcnt(0)
	v_cmp_gt_u32_e32 vcc, s6, v0
	s_and_saveexec_b64 s[12:13], vcc
	s_cbranch_execz .LBB0_212
	s_mov_b64 s[14:15], 0
.LBB0_211:
	v_mov_b64_e32 v[0:1], s[10:11]
	s_sleep 2
	global_load_dword v0, v[0:1], off sc1
	s_waitcnt vmcnt(0) lgkmcnt(0)
	v_readfirstlane_b32 s17, v0
	s_cmp_ge_u32 s17, s6
	s_cselect_b64 s[18:19], -1, 0
	s_and_b64 s[18:19], exec, s[18:19]
	s_or_b64 s[14:15], s[18:19], s[14:15]
	v_readlane_b32 s6, v255, 1
	s_andn2_b64 exec, exec, s[14:15]
	s_cbranch_execnz .LBB0_211

.LBB0_213:
	s_andn2_saveexec_b64 s[8:9], s[8:9]
	s_cbranch_execz .LBB0_222
	v_cmp_ne_u32_e32 vcc, 0, v0
	s_movk_i32 s10, 0x3000
	buffer_wbl2 sc1
	v_cndmask_b32_e64 v0, 0, 1, vcc
	v_cmp_ne_u32_e32 vcc, 0, v1
	s_waitcnt vmcnt(0)
	s_nop 1
	v_addc_co_u32_e32 v0, vcc, 0, v0, vcc
	v_cmp_ne_u32_e32 vcc, 0, v2
	s_nop 1
	v_cndmask_b32_e64 v1, 0, 1, vcc
	v_cmp_ne_u32_e32 vcc, 0, v3
	v_mov_b32_e32 v3, 1
	s_nop 0
	v_addc_co_u32_e32 v0, vcc, v0, v1, vcc
	v_cmp_ne_u32_e32 vcc, 0, v4
	s_nop 1
	v_cndmask_b32_e64 v1, 0, 1, vcc
	v_cmp_ne_u32_e32 vcc, 0, v5
	s_nop 1
	v_addc_co_u32_e32 v0, vcc, v0, v1, vcc
	v_cmp_ne_u32_e32 vcc, 0, v6
	s_nop 1
	v_cndmask_b32_e64 v1, 0, 1, vcc
	v_cmp_ne_u32_e32 vcc, 0, v7
	s_nop 1
	v_addc_co_u32_e32 v2, vcc, v0, v1, vcc
	v_mov_b32_e32 v0, s4
	v_add_co_u32_e32 v0, vcc, s10, v0
	v_mov_b32_e32 v1, s5
	s_nop 0
	v_addc_co_u32_e32 v1, vcc, 0, v1, vcc
	global_atomic_add v0, v[0:1], v3, off offset:2048 sc0
	v_mul_lo_u32 v1, v2, s6
	s_add_u32 s4, s4, 0x3900
	s_addc_u32 s5, s5, 0
	s_waitcnt vmcnt(0) lgkmcnt(0)
	v_add_u32_e32 v0, 1, v0
	v_cmp_ne_u32_e32 vcc, v0, v1
	s_and_saveexec_b64 s[10:11], vcc
	s_xor_b64 s[10:11], exec, s[10:11]
	s_cbranch_execz .LBB0_219
	v_mov_b64_e32 v[0:1], s[4:5]
	global_load_dword v0, v[0:1], off sc1
	s_waitcnt vmcnt(0) lgkmcnt(0)
	v_cmp_gt_u32_e32 vcc, s6, v0
	s_and_saveexec_b64 s[12:13], vcc
	s_cbranch_execz .LBB0_218
	s_mov_b64 s[14:15], 0
.LBB0_217:
	v_mov_b64_e32 v[0:1], s[4:5]
	s_sleep 2
	global_load_dword v0, v[0:1], off sc1
	s_waitcnt vmcnt(0) lgkmcnt(0)
	v_readfirstlane_b32 s17, v0
	s_cmp_ge_u32 s17, s6
	s_cselect_b64 s[18:19], -1, 0
	s_and_b64 s[18:19], exec, s[18:19]
	s_or_b64 s[14:15], s[18:19], s[14:15]
	v_readlane_b32 s6, v255, 1
	s_andn2_b64 exec, exec, s[14:15]
	s_cbranch_execnz .LBB0_217

.LBB0_221:
	s_or_b64 exec, exec, s[10:11]
	v_mov_b32_e32 v0, s16
	v_add_co_u32_e32 v0, vcc, 0x3000, v0
	v_mov_b32_e32 v1, s7
	s_nop 0
	v_addc_co_u32_e32 v1, vcc, 0, v1, vcc
	v_mov_b32_e32 v2, 1
	global_atomic_add v[0:1], v2, off

.LBB0_255:
	s_and_b64 s[42:43], s[26:27], s[8:9]
	v_cndmask_b32_e64 v128, 0, 1, s[42:43]
	v_cmp_ne_u32_e64 s[8:9], 1, v128
	s_andn2_b64 vcc, exec, s[42:43]
	s_cbranch_vccnz .LBB0_257
	v_ashrrev_i32_e32 v229, 31, v228
	v_lshlrev_b64 v[128:129], 6, v[228:229]
	v_lshl_add_u64 v[128:129], s[20:21], 0, v[128:129]
	global_load_dwordx4 v[194:197], v[128:129], off
	global_load_dwordx4 v[186:189], v[128:129], off offset:16
	global_load_dwordx4 v[198:201], v[128:129], off offset:32
	global_load_dwordx4 v[190:193], v[128:129], off offset:48
	v_or_b32_e32 v128, 16, v228
	v_ashrrev_i32_e32 v129, 31, v128
	v_lshlrev_b64 v[128:129], 6, v[128:129]
	v_lshl_add_u64 v[128:129], s[20:21], 0, v[128:129]
	global_load_dwordx4 v[178:181], v[128:129], off
	global_load_dwordx4 v[170:173], v[128:129], off offset:16
	global_load_dwordx4 v[182:185], v[128:129], off offset:32
	global_load_dwordx4 v[174:177], v[128:129], off offset:48
	v_or_b32_e32 v128, 32, v228
	v_ashrrev_i32_e32 v129, 31, v128
	v_lshlrev_b64 v[128:129], 6, v[128:129]
	v_lshl_add_u64 v[128:129], s[20:21], 0, v[128:129]
	global_load_dwordx4 v[166:169], v[128:129], off
	global_load_dwordx4 v[154:157], v[128:129], off offset:16
	global_load_dwordx4 v[162:165], v[128:129], off offset:32
	global_load_dwordx4 v[158:161], v[128:129], off offset:48
	v_or_b32_e32 v128, 48, v228
	v_ashrrev_i32_e32 v129, 31, v128
	v_lshlrev_b64 v[128:129], 6, v[128:129]
	v_lshl_add_u64 v[128:129], s[20:21], 0, v[128:129]
	global_load_dwordx4 v[146:149], v[128:129], off
	global_load_dwordx4 v[138:141], v[128:129], off offset:16
	global_load_dwordx4 v[150:153], v[128:129], off offset:32
	global_load_dwordx4 v[142:145], v[128:129], off offset:48

.LBB0_265:
	v_cvt_pk_bf16_f32 v128, v128, v129
	v_cvt_pk_bf16_f32 v129, v130, v131
	v_cvt_pk_bf16_f32 v130, v132, v133
	v_add_co_u32_e32 v132, vcc, 0x1000, v236
	v_cvt_pk_bf16_f32 v131, v134, v135
	s_nop 0
	v_addc_co_u32_e32 v133, vcc, 0, v237, vcc
	s_and_b64 vcc, exec, s[8:9]
	v_add_u32_e32 v236, 0x80, v228
	global_store_dwordx4 v[132:133], v[128:131], off offset:2048 nt
	s_cbranch_vccnz .LBB0_267
	v_ashrrev_i32_e32 v237, 31, v236
	v_lshlrev_b64 v[128:129], 6, v[236:237]
	v_lshl_add_u64 v[128:129], s[20:21], 0, v[128:129]
	v_ashrrev_i32_e32 v229, 31, v228
	s_waitcnt lgkmcnt(0)
	global_load_dwordx4 v[194:197], v[128:129], off
	global_load_dwordx4 v[186:189], v[128:129], off offset:16
	global_load_dwordx4 v[198:201], v[128:129], off offset:32
	global_load_dwordx4 v[190:193], v[128:129], off offset:48
	v_lshlrev_b64 v[128:129], 6, v[228:229]
	v_lshl_add_u64 v[128:129], s[20:21], 0, v[128:129]
	s_mov_b64 s[38:39], 0x2400
	v_lshl_add_u64 v[130:131], v[128:129], 0, s[38:39]
	v_add_co_u32_e32 v132, vcc, 0x2000, v128
	s_mov_b64 s[38:39], 0x2800
	s_nop 0
	v_addc_co_u32_e32 v133, vcc, 0, v129, vcc
	global_load_dwordx4 v[170:173], v[130:131], off offset:16
	global_load_dwordx4 v[182:185], v[130:131], off offset:32
	global_load_dwordx4 v[178:181], v[132:133], off offset:1024
	global_load_dwordx4 v[174:177], v[130:131], off offset:48
	v_lshl_add_u64 v[130:131], v[128:129], 0, s[38:39]
	s_mov_b64 s[38:39], 0x2c00
	global_load_dwordx4 v[154:157], v[130:131], off offset:16
	global_load_dwordx4 v[162:165], v[130:131], off offset:32
	v_lshl_add_u64 v[128:129], v[128:129], 0, s[38:39]
	global_load_dwordx4 v[166:169], v[132:133], off offset:2048
	global_load_dwordx4 v[146:149], v[132:133], off offset:3072
	global_load_dwordx4 v[158:161], v[130:131], off offset:48
	global_load_dwordx4 v[138:141], v[128:129], off offset:16
	global_load_dwordx4 v[150:153], v[128:129], off offset:32
	global_load_dwordx4 v[142:145], v[128:129], off offset:48

.LBB0_292:
	s_and_b64 s[42:43], s[26:27], s[8:9]
	v_cndmask_b32_e64 v64, 0, 1, s[42:43]
	v_cmp_ne_u32_e64 s[8:9], 1, v64
	s_andn2_b64 vcc, exec, s[42:43]
	v_ashrrev_i32_e32 v229, 31, v228
	s_cbranch_vccnz .LBB0_294
	v_lshlrev_b64 v[64:65], 6, v[228:229]
	v_lshl_add_u64 v[64:65], s[20:21], 0, v[64:65]
	s_waitcnt lgkmcnt(0)
	global_load_dwordx4 v[194:197], v[64:65], off
	global_load_dwordx4 v[186:189], v[64:65], off offset:16
	global_load_dwordx4 v[198:201], v[64:65], off offset:32
	global_load_dwordx4 v[190:193], v[64:65], off offset:48
	v_or_b32_e32 v64, 16, v228
	v_ashrrev_i32_e32 v65, 31, v64
	v_lshlrev_b64 v[64:65], 6, v[64:65]
	v_lshl_add_u64 v[64:65], s[20:21], 0, v[64:65]
	global_load_dwordx4 v[178:181], v[64:65], off
	global_load_dwordx4 v[170:173], v[64:65], off offset:16
	global_load_dwordx4 v[182:185], v[64:65], off offset:32
	global_load_dwordx4 v[174:177], v[64:65], off offset:48
	v_or_b32_e32 v64, 32, v228
	v_ashrrev_i32_e32 v65, 31, v64
	v_lshlrev_b64 v[64:65], 6, v[64:65]
	v_lshl_add_u64 v[64:65], s[20:21], 0, v[64:65]
	global_load_dwordx4 v[166:169], v[64:65], off
	global_load_dwordx4 v[154:157], v[64:65], off offset:16
	global_load_dwordx4 v[162:165], v[64:65], off offset:32
	global_load_dwordx4 v[158:161], v[64:65], off offset:48
	v_or_b32_e32 v64, 48, v228
	v_ashrrev_i32_e32 v65, 31, v64
	v_lshlrev_b64 v[64:65], 6, v[64:65]
	v_lshl_add_u64 v[64:65], s[20:21], 0, v[64:65]
	global_load_dwordx4 v[146:149], v[64:65], off
	global_load_dwordx4 v[138:141], v[64:65], off offset:16
	global_load_dwordx4 v[150:153], v[64:65], off offset:32
	global_load_dwordx4 v[142:145], v[64:65], off offset:48

.LBB0_302:
	v_cvt_pk_bf16_f32 v64, v64, v65
	v_cvt_pk_bf16_f32 v65, v66, v67
	v_cvt_pk_bf16_f32 v66, v68, v69
	v_add_co_u32_e32 v68, vcc, 0x1000, v74
	v_cvt_pk_bf16_f32 v67, v70, v71
	s_nop 0
	v_addc_co_u32_e32 v69, vcc, 0, v75, vcc
	s_and_b64 vcc, exec, s[8:9]
	v_add_u32_e32 v74, 0x80, v228
	global_store_dwordx4 v[68:69], v[64:67], off offset:2048 nt
	s_cbranch_vccnz .LBB0_304
	v_ashrrev_i32_e32 v75, 31, v74
	v_lshlrev_b64 v[64:65], 6, v[74:75]
	v_lshl_add_u64 v[64:65], s[20:21], 0, v[64:65]
	s_waitcnt lgkmcnt(0)
	global_load_dwordx4 v[194:197], v[64:65], off
	global_load_dwordx4 v[186:189], v[64:65], off offset:16
	global_load_dwordx4 v[198:201], v[64:65], off offset:32
	global_load_dwordx4 v[190:193], v[64:65], off offset:48
	v_lshlrev_b64 v[64:65], 6, v[228:229]
	v_lshl_add_u64 v[64:65], s[20:21], 0, v[64:65]
	s_mov_b64 s[40:41], 0x2400
	v_lshl_add_u64 v[66:67], v[64:65], 0, s[40:41]
	v_add_co_u32_e32 v68, vcc, 0x2000, v64
	s_mov_b64 s[40:41], 0x2800
	s_nop 0
	v_addc_co_u32_e32 v69, vcc, 0, v65, vcc
	global_load_dwordx4 v[170:173], v[66:67], off offset:16
	global_load_dwordx4 v[182:185], v[66:67], off offset:32
	global_load_dwordx4 v[178:181], v[68:69], off offset:1024
	global_load_dwordx4 v[174:177], v[66:67], off offset:48
	v_lshl_add_u64 v[66:67], v[64:65], 0, s[40:41]
	s_mov_b64 s[40:41], 0x2c00
	global_load_dwordx4 v[154:157], v[66:67], off offset:16
	global_load_dwordx4 v[162:165], v[66:67], off offset:32
	v_lshl_add_u64 v[64:65], v[64:65], 0, s[40:41]
	global_load_dwordx4 v[166:169], v[68:69], off offset:2048
	global_load_dwordx4 v[146:149], v[68:69], off offset:3072
	global_load_dwordx4 v[158:161], v[66:67], off offset:48
	global_load_dwordx4 v[138:141], v[64:65], off offset:16
	global_load_dwordx4 v[150:153], v[64:65], off offset:32
	global_load_dwordx4 v[142:145], v[64:65], off offset:48

.LBB0_313:
	s_and_b64 vcc, exec, s[8:9]
	s_cbranch_vccz .LBB0_317
	v_cmp_gt_i32_e32 vcc, 24, v232
	s_and_saveexec_b64 s[4:5], vcc
	s_cbranch_execz .LBB0_316
	v_mul_f32_e32 v66, 0xbfb8aa3b, v56
	v_mul_f32_e32 v67, 0xbfb8aa3b, v57
	v_mul_f32_e32 v68, 0xbfb8aa3b, v58
	v_mul_f32_e32 v69, 0xbfb8aa3b, v59
	v_exp_f32_e32 v66, v66
	v_exp_f32_e32 v67, v67
	v_exp_f32_e32 v68, v68
	v_exp_f32_e32 v69, v69
	v_add_f32_e32 v66, 1.0, v66
	v_add_f32_e32 v67, 1.0, v67
	v_add_f32_e32 v68, 1.0, v68
	v_add_f32_e32 v69, 1.0, v69
	v_rcp_f32_e32 v66, v66
	v_rcp_f32_e32 v67, v67
	v_rcp_f32_e32 v68, v68
	v_rcp_f32_e32 v69, v69
	v_lshl_add_u64 v[64:65], v[232:233], 2, s[22:23]
	s_movk_i32 s8, 0x60
	v_mad_i64_i32 v[70:71], s[6:7], v228, s8, v[64:65]
	global_store_dwordx4 v[70:71], v[66:69], off
	s_nop 1
	v_mul_f32_e32 v66, 0xbfb8aa3b, v60
	v_mul_f32_e32 v67, 0xbfb8aa3b, v61
	v_mul_f32_e32 v68, 0xbfb8aa3b, v62
	v_mul_f32_e32 v69, 0xbfb8aa3b, v63
	v_exp_f32_e32 v66, v66
	v_exp_f32_e32 v67, v67
	v_exp_f32_e32 v68, v68
	v_exp_f32_e32 v69, v69
	v_add_f32_e32 v66, 1.0, v66
	v_add_f32_e32 v67, 1.0, v67
	v_add_f32_e32 v68, 1.0, v68
	v_add_f32_e32 v69, 1.0, v69
	v_rcp_f32_e32 v66, v66
	v_rcp_f32_e32 v67, v67
	v_rcp_f32_e32 v68, v68
	v_rcp_f32_e32 v69, v69
	global_store_dwordx4 v[70:71], v[66:69], off offset:16
	s_nop 1
	v_or_b32_e32 v66, 16, v228
	v_mad_i64_i32 v[70:71], s[6:7], v66, s8, v[64:65]
	v_mul_f32_e32 v66, 0xbfb8aa3b, v48
	v_mul_f32_e32 v67, 0xbfb8aa3b, v49
	v_mul_f32_e32 v68, 0xbfb8aa3b, v50
	v_mul_f32_e32 v69, 0xbfb8aa3b, v51
	v_exp_f32_e32 v66, v66
	v_exp_f32_e32 v67, v67
	v_exp_f32_e32 v68, v68
	v_exp_f32_e32 v69, v69
	v_add_f32_e32 v66, 1.0, v66
	v_add_f32_e32 v67, 1.0, v67
	v_add_f32_e32 v68, 1.0, v68
	v_add_f32_e32 v69, 1.0, v69
	v_rcp_f32_e32 v66, v66
	v_rcp_f32_e32 v67, v67
	v_rcp_f32_e32 v68, v68
	v_rcp_f32_e32 v69, v69
	global_store_dwordx4 v[70:71], v[66:69], off
	s_nop 1
	v_mul_f32_e32 v66, 0xbfb8aa3b, v52
	v_mul_f32_e32 v67, 0xbfb8aa3b, v53
	v_mul_f32_e32 v68, 0xbfb8aa3b, v54
	v_mul_f32_e32 v69, 0xbfb8aa3b, v55
	v_exp_f32_e32 v66, v66
	v_exp_f32_e32 v67, v67
	v_exp_f32_e32 v68, v68
	v_exp_f32_e32 v69, v69
	v_add_f32_e32 v66, 1.0, v66
	v_add_f32_e32 v67, 1.0, v67
	v_add_f32_e32 v68, 1.0, v68
	v_add_f32_e32 v69, 1.0, v69
	v_rcp_f32_e32 v66, v66
	v_rcp_f32_e32 v67, v67
	v_rcp_f32_e32 v68, v68
	v_rcp_f32_e32 v69, v69
	global_store_dwordx4 v[70:71], v[66:69], off offset:16
	s_nop 1
	v_or_b32_e32 v66, 32, v228
	v_mad_i64_i32 v[70:71], s[6:7], v66, s8, v[64:65]
	v_mul_f32_e32 v66, 0xbfb8aa3b, v40
	v_mul_f32_e32 v67, 0xbfb8aa3b, v41
	v_mul_f32_e32 v68, 0xbfb8aa3b, v42
	v_mul_f32_e32 v69, 0xbfb8aa3b, v43
	v_exp_f32_e32 v66, v66
	v_exp_f32_e32 v67, v67
	v_exp_f32_e32 v68, v68
	v_exp_f32_e32 v69, v69
	v_add_f32_e32 v66, 1.0, v66
	v_add_f32_e32 v67, 1.0, v67
	v_add_f32_e32 v68, 1.0, v68
	v_add_f32_e32 v69, 1.0, v69
	v_rcp_f32_e32 v66, v66
	v_rcp_f32_e32 v67, v67
	v_rcp_f32_e32 v68, v68
	v_rcp_f32_e32 v69, v69
	global_store_dwordx4 v[70:71], v[66:69], off
	s_nop 1
	v_mul_f32_e32 v66, 0xbfb8aa3b, v44
	v_mul_f32_e32 v67, 0xbfb8aa3b, v45
	v_mul_f32_e32 v68, 0xbfb8aa3b, v46
	v_mul_f32_e32 v69, 0xbfb8aa3b, v47
	v_exp_f32_e32 v66, v66
	v_exp_f32_e32 v67, v67
	v_exp_f32_e32 v68, v68
	v_exp_f32_e32 v69, v69
	v_add_f32_e32 v66, 1.0, v66
	v_add_f32_e32 v67, 1.0, v67
	v_add_f32_e32 v68, 1.0, v68
	v_add_f32_e32 v69, 1.0, v69
	v_rcp_f32_e32 v66, v66
	v_rcp_f32_e32 v67, v67
	v_rcp_f32_e32 v68, v68
	v_rcp_f32_e32 v69, v69
	global_store_dwordx4 v[70:71], v[66:69], off offset:16
	s_nop 1
	v_or_b32_e32 v66, 48, v228
	v_mad_i64_i32 v[70:71], s[6:7], v66, s8, v[64:65]
	v_mul_f32_e32 v66, 0xbfb8aa3b, v32
	v_mul_f32_e32 v67, 0xbfb8aa3b, v33
	v_mul_f32_e32 v68, 0xbfb8aa3b, v34
	v_mul_f32_e32 v69, 0xbfb8aa3b, v35
	v_exp_f32_e32 v66, v66
	v_exp_f32_e32 v67, v67
	v_exp_f32_e32 v68, v68
	v_exp_f32_e32 v69, v69
	v_add_f32_e32 v66, 1.0, v66
	v_add_f32_e32 v67, 1.0, v67
	v_add_f32_e32 v68, 1.0, v68
	v_add_f32_e32 v69, 1.0, v69
	v_rcp_f32_e32 v66, v66
	v_rcp_f32_e32 v67, v67
	v_rcp_f32_e32 v68, v68
	v_rcp_f32_e32 v69, v69
	global_store_dwordx4 v[70:71], v[66:69], off
	s_nop 1
	v_mul_f32_e32 v66, 0xbfb8aa3b, v36
	v_mul_f32_e32 v67, 0xbfb8aa3b, v37
	v_mul_f32_e32 v68, 0xbfb8aa3b, v38
	v_mul_f32_e32 v69, 0xbfb8aa3b, v39
	v_exp_f32_e32 v66, v66
	v_exp_f32_e32 v67, v67
	v_exp_f32_e32 v68, v68
	v_exp_f32_e32 v69, v69
	v_add_f32_e32 v66, 1.0, v66
	v_add_f32_e32 v67, 1.0, v67
	v_add_f32_e32 v68, 1.0, v68
	v_add_f32_e32 v69, 1.0, v69
	v_rcp_f32_e32 v66, v66
	v_rcp_f32_e32 v67, v67
	v_rcp_f32_e32 v68, v68
	v_rcp_f32_e32 v69, v69
	global_store_dwordx4 v[70:71], v[66:69], off offset:16
	s_nop 1
	v_add_u32_e32 v66, 0x80, v228
	v_mad_i64_i32 v[70:71], s[6:7], v66, s8, v[64:65]
	v_mul_f32_e32 v66, 0xbfb8aa3b, v24
	v_mul_f32_e32 v67, 0xbfb8aa3b, v25
	v_mul_f32_e32 v68, 0xbfb8aa3b, v26
	v_mul_f32_e32 v69, 0xbfb8aa3b, v27
	v_exp_f32_e32 v66, v66
	v_exp_f32_e32 v67, v67
	v_exp_f32_e32 v68, v68
	v_exp_f32_e32 v69, v69
	v_add_f32_e32 v66, 1.0, v66
	v_add_f32_e32 v67, 1.0, v67
	v_add_f32_e32 v68, 1.0, v68
	v_add_f32_e32 v69, 1.0, v69
	v_rcp_f32_e32 v66, v66
	v_rcp_f32_e32 v67, v67
	v_rcp_f32_e32 v68, v68
	v_rcp_f32_e32 v69, v69
	global_store_dwordx4 v[70:71], v[66:69], off
	s_nop 1
	v_mul_f32_e32 v66, 0xbfb8aa3b, v28
	v_mul_f32_e32 v67, 0xbfb8aa3b, v29
	v_mul_f32_e32 v68, 0xbfb8aa3b, v30
	v_mul_f32_e32 v69, 0xbfb8aa3b, v31
	v_exp_f32_e32 v66, v66
	v_exp_f32_e32 v67, v67
	v_exp_f32_e32 v68, v68
	v_exp_f32_e32 v69, v69
	v_add_f32_e32 v66, 1.0, v66
	v_add_f32_e32 v67, 1.0, v67
	v_add_f32_e32 v68, 1.0, v68
	v_add_f32_e32 v69, 1.0, v69
	v_rcp_f32_e32 v66, v66
	v_rcp_f32_e32 v67, v67
	v_rcp_f32_e32 v68, v68
	v_rcp_f32_e32 v69, v69
	global_store_dwordx4 v[70:71], v[66:69], off offset:16
	s_nop 1
	v_add_u32_e32 v66, 0x90, v228
	v_mad_i64_i32 v[70:71], s[6:7], v66, s8, v[64:65]
	v_mul_f32_e32 v66, 0xbfb8aa3b, v16
	v_mul_f32_e32 v67, 0xbfb8aa3b, v17
	v_mul_f32_e32 v68, 0xbfb8aa3b, v18
	v_mul_f32_e32 v69, 0xbfb8aa3b, v19
	v_exp_f32_e32 v66, v66
	v_exp_f32_e32 v67, v67
	v_exp_f32_e32 v68, v68
	v_exp_f32_e32 v69, v69
	v_add_f32_e32 v66, 1.0, v66
	v_add_f32_e32 v67, 1.0, v67
	v_add_f32_e32 v68, 1.0, v68
	v_add_f32_e32 v69, 1.0, v69
	v_rcp_f32_e32 v66, v66
	v_rcp_f32_e32 v67, v67
	v_rcp_f32_e32 v68, v68
	v_rcp_f32_e32 v69, v69
	global_store_dwordx4 v[70:71], v[66:69], off
	s_nop 1
	v_mul_f32_e32 v66, 0xbfb8aa3b, v20
	v_mul_f32_e32 v67, 0xbfb8aa3b, v21
	v_mul_f32_e32 v68, 0xbfb8aa3b, v22
	v_mul_f32_e32 v69, 0xbfb8aa3b, v23
	v_exp_f32_e32 v66, v66
	v_exp_f32_e32 v67, v67
	v_exp_f32_e32 v68, v68
	v_exp_f32_e32 v69, v69
	v_add_f32_e32 v66, 1.0, v66
	v_add_f32_e32 v67, 1.0, v67
	v_add_f32_e32 v68, 1.0, v68
	v_add_f32_e32 v69, 1.0, v69
	v_rcp_f32_e32 v66, v66
	v_rcp_f32_e32 v67, v67
	v_rcp_f32_e32 v68, v68
	v_rcp_f32_e32 v69, v69
	global_store_dwordx4 v[70:71], v[66:69], off offset:16
	s_nop 1
	v_add_u32_e32 v66, 0xa0, v228
	v_mad_i64_i32 v[70:71], s[6:7], v66, s8, v[64:65]
	v_mul_f32_e32 v66, 0xbfb8aa3b, v8
	v_mul_f32_e32 v67, 0xbfb8aa3b, v9
	v_mul_f32_e32 v68, 0xbfb8aa3b, v10
	v_mul_f32_e32 v69, 0xbfb8aa3b, v11
	v_exp_f32_e32 v66, v66
	v_exp_f32_e32 v67, v67
	v_exp_f32_e32 v68, v68
	v_exp_f32_e32 v69, v69
	v_add_f32_e32 v66, 1.0, v66
	v_add_f32_e32 v67, 1.0, v67
	v_add_f32_e32 v68, 1.0, v68
	v_add_f32_e32 v69, 1.0, v69
	v_rcp_f32_e32 v66, v66
	v_rcp_f32_e32 v67, v67
	v_rcp_f32_e32 v68, v68
	v_rcp_f32_e32 v69, v69
	global_store_dwordx4 v[70:71], v[66:69], off
	s_nop 1
	v_mul_f32_e32 v66, 0xbfb8aa3b, v12
	v_mul_f32_e32 v67, 0xbfb8aa3b, v13
	v_mul_f32_e32 v68, 0xbfb8aa3b, v14
	v_mul_f32_e32 v69, 0xbfb8aa3b, v15
	v_exp_f32_e32 v66, v66
	v_exp_f32_e32 v67, v67
	v_exp_f32_e32 v68, v68
	v_exp_f32_e32 v69, v69
	v_add_f32_e32 v66, 1.0, v66
	v_add_f32_e32 v67, 1.0, v67
	v_add_f32_e32 v68, 1.0, v68
	v_add_f32_e32 v69, 1.0, v69
	v_rcp_f32_e32 v66, v66
	v_rcp_f32_e32 v67, v67
	v_rcp_f32_e32 v68, v68
	v_rcp_f32_e32 v69, v69
	global_store_dwordx4 v[70:71], v[66:69], off offset:16
	s_nop 1
	v_add_u32_e32 v66, 0xb0, v228
	v_mad_i64_i32 v[68:69], s[6:7], v66, s8, v[64:65]
	v_mul_f32_e32 v64, 0xbfb8aa3b, v0
	v_mul_f32_e32 v65, 0xbfb8aa3b, v1
	v_mul_f32_e32 v66, 0xbfb8aa3b, v2
	v_mul_f32_e32 v67, 0xbfb8aa3b, v3
	v_exp_f32_e32 v64, v64
	v_exp_f32_e32 v65, v65
	v_exp_f32_e32 v66, v66
	v_exp_f32_e32 v67, v67
	v_add_f32_e32 v64, 1.0, v64
	v_add_f32_e32 v65, 1.0, v65
	v_add_f32_e32 v66, 1.0, v66
	v_add_f32_e32 v67, 1.0, v67
	v_rcp_f32_e32 v64, v64
	v_rcp_f32_e32 v65, v65
	v_rcp_f32_e32 v66, v66
	v_rcp_f32_e32 v67, v67
	global_store_dwordx4 v[68:69], v[64:67], off
	s_nop 1
	v_mul_f32_e32 v64, 0xbfb8aa3b, v4
	v_mul_f32_e32 v65, 0xbfb8aa3b, v5
	v_mul_f32_e32 v66, 0xbfb8aa3b, v6
	v_mul_f32_e32 v67, 0xbfb8aa3b, v7
	v_exp_f32_e32 v64, v64
	v_exp_f32_e32 v65, v65
	v_exp_f32_e32 v66, v66
	v_exp_f32_e32 v67, v67
	v_add_f32_e32 v64, 1.0, v64
	v_add_f32_e32 v65, 1.0, v65
	v_add_f32_e32 v66, 1.0, v66
	v_add_f32_e32 v67, 1.0, v67
	v_rcp_f32_e32 v64, v64
	v_rcp_f32_e32 v65, v65
	v_rcp_f32_e32 v66, v66
	v_rcp_f32_e32 v67, v67
	global_store_dwordx4 v[68:69], v[64:67], off offset:16

.LBB0_324:
	v_readlane_b32 s12, v254, 26
	v_readlane_b32 s26, v254, 40
	v_readlane_b32 s27, v254, 41
	s_mov_b64 s[4:5], s[26:27]
	v_mbcnt_lo_u32_b32 v0, -1, 0
	v_mbcnt_hi_u32_b32 v0, -1, v0
	v_readlane_b32 s2, v254, 4
	s_waitcnt vmcnt(0) lgkmcnt(0)
	v_cmp_eq_u32_e32 vcc, 0, v0
	v_readlane_b32 s3, v254, 5
	s_and_b64 s[2:3], s[2:3], vcc
	v_readlane_b32 s13, v254, 27
	v_readlane_b32 s14, v254, 28
	v_readlane_b32 s15, v254, 29
	v_readlane_b32 s16, v254, 30
	v_readlane_b32 s17, v254, 31
	v_readlane_b32 s18, v254, 32
	v_readlane_b32 s19, v254, 33
	v_readlane_b32 s20, v254, 34
	v_readlane_b32 s21, v254, 35
	v_readlane_b32 s22, v254, 36
	v_readlane_b32 s23, v254, 37
	v_readlane_b32 s24, v254, 38
	v_readlane_b32 s25, v254, 39
	s_waitcnt vmcnt(0) lgkmcnt(0)
	s_barrier
	s_and_saveexec_b64 s[6:7], s[2:3]
	s_xor_b64 s[2:3], exec, s[6:7]
	s_cbranch_execz .LBB0_340
	v_readlane_b32 s6, v255, 1
	s_add_i32 s18, s6, 1
	s_getreg_b32 s6, hwreg(HW_REG_XCC_ID, 0, 4)
	s_lshl_b32 s6, s6, 8
	s_and_b32 s6, s6, 0x700
	s_add_u32 s17, s4, s6
	s_addc_u32 s16, s5, 0
	v_mov_b32_e32 v0, s17
	v_add_co_u32_e32 v8, vcc, 0x2000, v0
	v_mov_b32_e32 v0, s16
	s_nop 0
	v_addc_co_u32_e32 v9, vcc, 0, v0, vcc
	v_mov_b32_e32 v0, s4
	v_add_co_u32_e32 v10, vcc, 0x2000, v0
	v_mov_b32_e32 v0, s5
	s_nop 0
	v_addc_co_u32_e32 v11, vcc, 0, v0, vcc
	global_load_dword v12, v[8:9], off sc1
	global_load_dword v0, v[10:11], off sc1
	global_load_dword v1, v[10:11], off offset:256 sc1
	global_load_dword v2, v[10:11], off offset:512 sc1
	global_load_dword v3, v[10:11], off offset:768 sc1
	global_load_dword v4, v[10:11], off offset:1024 sc1
	global_load_dword v5, v[10:11], off offset:1280 sc1
	global_load_dword v6, v[10:11], off offset:1536 sc1
	global_load_dword v7, v[10:11], off offset:1792 sc1
	v_mov_b32_e32 v10, 1
	global_atomic_add v8, v[8:9], v10, off offset:2048 sc0
	s_waitcnt vmcnt(0) lgkmcnt(0)
	v_mul_lo_u32 v9, v12, s18
	v_add_u32_e32 v8, 1, v8
	v_cmp_ne_u32_e32 vcc, v8, v9
	s_and_saveexec_b64 s[6:7], vcc
	s_xor_b64 s[6:7], exec, s[6:7]
	s_cbranch_execz .LBB0_330
	v_mov_b32_e32 v0, s17
	v_add_co_u32_e32 v0, vcc, 0x3000, v0
	v_mov_b32_e32 v1, s16
	s_nop 0
	v_addc_co_u32_e32 v1, vcc, 0, v1, vcc
	global_load_dword v0, v[0:1], off sc1
	s_add_u32 s8, s17, 0x3000
	s_addc_u32 s9, s16, 0
	s_waitcnt vmcnt(0) lgkmcnt(0)
	v_cmp_gt_u32_e32 vcc, s18, v0
	s_and_saveexec_b64 s[12:13], vcc
	s_cbranch_execz .LBB0_329
	s_mov_b64 s[14:15], 0
.LBB0_328:
	v_mov_b64_e32 v[0:1], s[8:9]
	s_sleep 2
	global_load_dword v0, v[0:1], off sc1
	s_waitcnt vmcnt(0) lgkmcnt(0)
	v_readfirstlane_b32 s19, v0
	s_cmp_ge_u32 s19, s18
	s_cselect_b64 s[20:21], -1, 0
	s_and_b64 s[20:21], exec, s[20:21]
	s_or_b64 s[14:15], s[20:21], s[14:15]
	s_andn2_b64 exec, exec, s[14:15]
	s_cbranch_execnz .LBB0_328

.LBB0_330:
	s_andn2_saveexec_b64 s[6:7], s[6:7]
	s_cbranch_execz .LBB0_339
	v_cmp_ne_u32_e32 vcc, 0, v0
	s_movk_i32 s8, 0x3000
	buffer_wbl2 sc1
	v_cndmask_b32_e64 v0, 0, 1, vcc
	v_cmp_ne_u32_e32 vcc, 0, v1
	s_waitcnt vmcnt(0)
	s_nop 1
	v_addc_co_u32_e32 v0, vcc, 0, v0, vcc
	v_cmp_ne_u32_e32 vcc, 0, v2
	s_nop 1
	v_cndmask_b32_e64 v1, 0, 1, vcc
	v_cmp_ne_u32_e32 vcc, 0, v3
	v_mov_b32_e32 v3, 1
	s_nop 0
	v_addc_co_u32_e32 v0, vcc, v0, v1, vcc
	v_cmp_ne_u32_e32 vcc, 0, v4
	s_nop 1
	v_cndmask_b32_e64 v1, 0, 1, vcc
	v_cmp_ne_u32_e32 vcc, 0, v5
	s_nop 1
	v_addc_co_u32_e32 v0, vcc, v0, v1, vcc
	v_cmp_ne_u32_e32 vcc, 0, v6
	s_nop 1
	v_cndmask_b32_e64 v1, 0, 1, vcc
	v_cmp_ne_u32_e32 vcc, 0, v7
	s_nop 1
	v_addc_co_u32_e32 v2, vcc, v0, v1, vcc
	v_mov_b32_e32 v0, s4
	v_add_co_u32_e32 v0, vcc, s8, v0
	v_mov_b32_e32 v1, s5
	s_nop 0
	v_addc_co_u32_e32 v1, vcc, 0, v1, vcc
	global_atomic_add v0, v[0:1], v3, off offset:2048 sc0
	v_mul_lo_u32 v1, v2, s18
	s_add_u32 s4, s4, 0x3900
	s_addc_u32 s5, s5, 0
	s_waitcnt vmcnt(0) lgkmcnt(0)
	v_add_u32_e32 v0, 1, v0
	v_cmp_ne_u32_e32 vcc, v0, v1
	s_and_saveexec_b64 s[8:9], vcc
	s_xor_b64 s[8:9], exec, s[8:9]
	s_cbranch_execz .LBB0_336
	v_mov_b64_e32 v[0:1], s[4:5]
	global_load_dword v0, v[0:1], off sc1
	s_waitcnt vmcnt(0) lgkmcnt(0)
	v_cmp_gt_u32_e32 vcc, s18, v0
	s_and_saveexec_b64 s[12:13], vcc
	s_cbranch_execz .LBB0_335
	s_mov_b64 s[14:15], 0

.LBB0_336:
	s_andn2_saveexec_b64 s[8:9], s[8:9]
	s_cbranch_execz .LBB0_338
	v_mov_b64_e32 v[0:1], s[4:5]
	v_mov_b32_e32 v2, 1
	global_atomic_add v[0:1], v2, off
.LBB0_338:
	s_or_b64 exec, exec, s[8:9]
	v_mov_b32_e32 v0, s17
	v_add_co_u32_e32 v0, vcc, 0x3000, v0
	v_mov_b32_e32 v1, s16
	s_nop 0
	v_addc_co_u32_e32 v1, vcc, 0, v1, vcc
	v_mov_b32_e32 v2, 1
	global_atomic_add v[0:1], v2, off

.LBB0_342:
	s_ashr_i32 s17, s16, 31
	s_lshl_b64 s[16:17], s[16:17], 19
	s_add_u32 s18, s18, s16
	s_addc_u32 s19, s19, s17
	s_add_u32 s16, s20, s16
	s_addc_u32 s17, s21, s17
	s_lshr_b32 s20, 0x1000, s22
	s_and_b32 s21, s35, 0xfc0
	s_add_i32 s20, s20, -1
	s_and_b32 s20, s20, s21
	s_sub_i32 s23, 12, s22
	v_add_u32_e32 v29, s20, v0
	s_lshr_b32 s23, s21, s23
	v_lshl_add_u64 v[18:19], s[18:19], 0, v[136:137]
	v_lshlrev_b32_e32 v30, s22, v29
	v_add_u32_e32 v30, s23, v30
	v_ashrrev_i32_e32 v31, 31, v30
	v_lshlrev_b64 v[30:31], 7, v[30:31]
	v_lshl_add_u64 v[30:31], v[18:19], 0, v[30:31]
	global_load_dwordx4 v[64:67], v[30:31], off
	v_add_lshl_u32 v30, v29, 8, s22
	v_add_u32_e32 v30, s23, v30
	v_ashrrev_i32_e32 v31, 31, v30
	v_lshlrev_b64 v[30:31], 7, v[30:31]
	v_lshl_add_u64 v[30:31], v[18:19], 0, v[30:31]
	global_load_dwordx4 v[68:71], v[30:31], off
	v_add_lshl_u32 v30, v29, 16, s22
	v_add_u32_e32 v30, s23, v30
	v_ashrrev_i32_e32 v31, 31, v30
	v_lshlrev_b64 v[30:31], 7, v[30:31]
	v_lshl_add_u64 v[30:31], v[18:19], 0, v[30:31]
	global_load_dwordx4 v[72:75], v[30:31], off
	v_add_lshl_u32 v30, v29, 24, s22
	v_add_u32_e32 v30, s23, v30
	v_ashrrev_i32_e32 v31, 31, v30
	v_lshlrev_b64 v[30:31], 7, v[30:31]
	v_lshl_add_u64 v[30:31], v[18:19], 0, v[30:31]
	global_load_dwordx4 v[76:79], v[30:31], off
	v_add_lshl_u32 v30, v29, 32, s22
	v_add_u32_e32 v30, s23, v30
	v_ashrrev_i32_e32 v31, 31, v30
	v_lshlrev_b64 v[30:31], 7, v[30:31]
	v_lshl_add_u64 v[30:31], v[18:19], 0, v[30:31]
	global_load_dwordx4 v[80:83], v[30:31], off
	v_add_lshl_u32 v30, v29, 40, s22
	v_add_u32_e32 v30, s23, v30
	v_ashrrev_i32_e32 v31, 31, v30
	v_lshlrev_b64 v[30:31], 7, v[30:31]
	v_lshl_add_u64 v[30:31], v[18:19], 0, v[30:31]
	global_load_dwordx4 v[84:87], v[30:31], off
	v_add_lshl_u32 v30, v29, 48, s22
	v_add_u32_e32 v30, s23, v30
	v_ashrrev_i32_e32 v31, 31, v30
	v_lshlrev_b64 v[30:31], 7, v[30:31]
	v_lshl_add_u64 v[30:31], v[18:19], 0, v[30:31]
	global_load_dwordx4 v[88:91], v[30:31], off
	v_add_lshl_u32 v30, v29, 56, s22
	v_add_u32_e32 v30, s23, v30
	v_ashrrev_i32_e32 v31, 31, v30
	v_lshlrev_b64 v[30:31], 7, v[30:31]
	v_lshl_add_u64 v[30:31], v[18:19], 0, v[30:31]
	global_load_dwordx4 v[92:95], v[30:31], off
	s_lshl_b32 s18, s21, 1
	s_add_u32 s16, s16, s18
	s_addc_u32 s17, s17, 0
	s_add_i32 s27, s27, s28
	s_add_i32 s35, s35, s36
	s_cmpk_gt_i32 s27, 0x1bff
	v_lshl_add_u64 v[18:19], s[16:17], 0, v[136:137]
	s_waitcnt vmcnt(0) lgkmcnt(0)
	ds_write_b128 v28, v[64:67]
	ds_write_b128 v28, v[68:71] offset:1152
	ds_write_b128 v28, v[72:75] offset:2304
	ds_write_b128 v28, v[76:79] offset:3456
	ds_write_b128 v28, v[80:83] offset:4608
	ds_write_b128 v28, v[84:87] offset:5760
	ds_write_b128 v28, v[88:91] offset:6912
	ds_write_b128 v28, v[92:95] offset:8064
	s_waitcnt vmcnt(0) lgkmcnt(0)
	ds_read_u16 v29, v21
	ds_read_u16 v30, v21 offset:144
	ds_read_u16 v31, v21 offset:288
	ds_read_u16 v34, v21 offset:432
	ds_read_u16 v32, v21 offset:2304
	ds_read_u16 v35, v21 offset:2448
	ds_read_u16 v33, v21 offset:2592
	ds_read_u16 v36, v21 offset:2736
	s_waitcnt lgkmcnt(4)
	v_perm_b32 v31, v34, v31, s85
	v_perm_b32 v30, v30, v29, s85
	s_waitcnt lgkmcnt(2)
	v_perm_b32 v32, v35, v32, s85
	v_lshl_add_u64 v[34:35], v[18:19], 0, v[2:3]
	s_waitcnt lgkmcnt(0)
	v_perm_b32 v33, v36, v33, s85
	global_store_dwordx4 v[34:35], v[30:33], off
	ds_read_u16 v29, v1
	ds_read_u16 v30, v1 offset:144
	ds_read_u16 v31, v1 offset:288
	ds_read_u16 v34, v1 offset:432
	ds_read_u16 v32, v1 offset:2304
	ds_read_u16 v35, v1 offset:2448
	ds_read_u16 v33, v1 offset:2592
	ds_read_u16 v36, v1 offset:2736
	s_waitcnt lgkmcnt(0)
	v_perm_b32 v31, v34, v31, s85
	v_perm_b32 v30, v30, v29, s85
	v_perm_b32 v32, v35, v32, s85
	v_lshl_add_u64 v[34:35], v[18:19], 0, v[4:5]
	v_perm_b32 v33, v36, v33, s85
	global_store_dwordx4 v[34:35], v[30:33], off
	ds_read_u16 v29, v22
	ds_read_u16 v30, v22 offset:144
	ds_read_u16 v31, v22 offset:288
	ds_read_u16 v34, v22 offset:432
	ds_read_u16 v32, v22 offset:2304
	ds_read_u16 v35, v22 offset:2448
	ds_read_u16 v33, v22 offset:2592
	ds_read_u16 v36, v22 offset:2736
	s_waitcnt lgkmcnt(0)
	v_perm_b32 v31, v34, v31, s85
	v_perm_b32 v30, v30, v29, s85
	v_perm_b32 v32, v35, v32, s85
	v_lshl_add_u64 v[34:35], v[18:19], 0, v[6:7]
	v_perm_b32 v33, v36, v33, s85
	global_store_dwordx4 v[34:35], v[30:33], off
	ds_read_u16 v29, v23
	ds_read_u16 v30, v23 offset:144
	ds_read_u16 v31, v23 offset:288
	ds_read_u16 v34, v23 offset:432
	ds_read_u16 v32, v23 offset:2304
	ds_read_u16 v35, v23 offset:2448
	ds_read_u16 v33, v23 offset:2592
	ds_read_u16 v36, v23 offset:2736
	s_waitcnt lgkmcnt(0)
	v_perm_b32 v31, v34, v31, s85
	v_perm_b32 v30, v30, v29, s85
	v_perm_b32 v32, v35, v32, s85
	v_lshl_add_u64 v[34:35], v[18:19], 0, v[8:9]
	v_perm_b32 v33, v36, v33, s85
	global_store_dwordx4 v[34:35], v[30:33], off
	ds_read_u16 v29, v24
	ds_read_u16 v30, v24 offset:144
	ds_read_u16 v31, v24 offset:288
	ds_read_u16 v34, v24 offset:432
	ds_read_u16 v32, v24 offset:2304
	ds_read_u16 v35, v24 offset:2448
	ds_read_u16 v33, v24 offset:2592
	ds_read_u16 v36, v24 offset:2736
	s_waitcnt lgkmcnt(0)
	v_perm_b32 v31, v34, v31, s85
	v_perm_b32 v30, v30, v29, s85
	v_perm_b32 v32, v35, v32, s85
	v_lshl_add_u64 v[34:35], v[18:19], 0, v[10:11]
	v_perm_b32 v33, v36, v33, s85
	global_store_dwordx4 v[34:35], v[30:33], off
	ds_read_u16 v29, v25
	ds_read_u16 v30, v25 offset:144
	ds_read_u16 v31, v25 offset:288
	ds_read_u16 v34, v25 offset:432
	ds_read_u16 v32, v25 offset:2304
	ds_read_u16 v35, v25 offset:2448
	ds_read_u16 v33, v25 offset:2592
	ds_read_u16 v36, v25 offset:2736
	s_waitcnt lgkmcnt(0)
	v_perm_b32 v31, v34, v31, s85
	v_perm_b32 v30, v30, v29, s85
	v_perm_b32 v32, v35, v32, s85
	v_lshl_add_u64 v[34:35], v[18:19], 0, v[12:13]
	v_perm_b32 v33, v36, v33, s85
	global_store_dwordx4 v[34:35], v[30:33], off
	ds_read_u16 v29, v26
	ds_read_u16 v30, v26 offset:144
	ds_read_u16 v31, v26 offset:288
	ds_read_u16 v34, v26 offset:432
	ds_read_u16 v32, v26 offset:2304
	ds_read_u16 v35, v26 offset:2448
	ds_read_u16 v33, v26 offset:2592
	ds_read_u16 v36, v26 offset:2736
	s_waitcnt lgkmcnt(0)
	v_perm_b32 v31, v34, v31, s85
	v_perm_b32 v30, v30, v29, s85
	v_perm_b32 v32, v35, v32, s85
	v_lshl_add_u64 v[34:35], v[18:19], 0, v[14:15]
	v_perm_b32 v33, v36, v33, s85
	global_store_dwordx4 v[34:35], v[30:33], off
	ds_read_u16 v29, v27
	ds_read_u16 v30, v27 offset:144
	ds_read_u16 v31, v27 offset:288
	ds_read_u16 v34, v27 offset:432
	ds_read_u16 v32, v27 offset:2304
	ds_read_u16 v35, v27 offset:2448
	ds_read_u16 v33, v27 offset:2592
	ds_read_u16 v36, v27 offset:2736
	s_waitcnt lgkmcnt(0)
	v_perm_b32 v31, v34, v31, s85
	v_perm_b32 v30, v30, v29, s85
	v_perm_b32 v32, v35, v32, s85
	v_lshl_add_u64 v[18:19], v[18:19], 0, v[16:17]
	v_perm_b32 v33, v36, v33, s85
	global_store_dwordx4 v[18:19], v[30:33], off
	s_waitcnt lgkmcnt(0)
	s_cbranch_scc1 .LBB0_355

.LBB0_359:
	v_add_u32_e32 v26, -7, v33
	v_min_u32_e32 v26, 0xfff, v26
	v_lshlrev_b32_e32 v136, 7, v26
	v_lshl_add_u64 v[26:27], v[24:25], 0, s[8:9]
	v_add_co_u32_e32 v26, vcc, 0x2c00000, v26
	v_lshl_add_u64 v[42:43], v[22:23], 0, v[136:137]
	s_nop 0
	v_addc_co_u32_e32 v27, vcc, 0, v27, vcc
	global_load_dwordx4 v[34:37], v[26:27], off
	global_load_dwordx4 v[38:41], v[42:43], off
	s_add_u32 s8, s8, 0x400
	s_addc_u32 s9, s9, 0
	s_cmpk_eq_i32 s8, 0x1000
	s_waitcnt vmcnt(0) lgkmcnt(0)
	v_mfma_f32_16x16x32_bf16 v[0:3], v[34:37], v[38:41], v[0:3]
	global_load_dwordx4 v[34:37], v[26:27], off offset:64
	global_load_dwordx4 v[38:41], v[42:43], off offset:64
	s_waitcnt vmcnt(0) lgkmcnt(0)
	v_mfma_f32_16x16x32_bf16 v[0:3], v[34:37], v[38:41], v[0:3]
	v_add_u32_e32 v34, -6, v33
	v_min_u32_e32 v34, 0xfff, v34
	v_lshlrev_b32_e32 v136, 7, v34
	v_lshl_add_u64 v[42:43], v[22:23], 0, v[136:137]
	global_load_dwordx4 v[34:37], v[26:27], off offset:128
	global_load_dwordx4 v[38:41], v[42:43], off
	s_waitcnt vmcnt(0) lgkmcnt(0)
	v_mfma_f32_16x16x32_bf16 v[0:3], v[34:37], v[38:41], v[0:3]
	global_load_dwordx4 v[34:37], v[26:27], off offset:192
	global_load_dwordx4 v[38:41], v[42:43], off offset:64
	s_waitcnt vmcnt(0) lgkmcnt(0)
	v_mfma_f32_16x16x32_bf16 v[0:3], v[34:37], v[38:41], v[0:3]
	v_add_u32_e32 v34, -5, v33
	v_min_u32_e32 v34, 0xfff, v34
	v_lshlrev_b32_e32 v136, 7, v34
	v_lshl_add_u64 v[42:43], v[22:23], 0, v[136:137]
	global_load_dwordx4 v[34:37], v[26:27], off offset:256
	global_load_dwordx4 v[38:41], v[42:43], off
	s_waitcnt vmcnt(0) lgkmcnt(0)
	v_mfma_f32_16x16x32_bf16 v[0:3], v[34:37], v[38:41], v[0:3]
	global_load_dwordx4 v[34:37], v[26:27], off offset:320
	global_load_dwordx4 v[38:41], v[42:43], off offset:64
	s_waitcnt vmcnt(0) lgkmcnt(0)
	v_mfma_f32_16x16x32_bf16 v[0:3], v[34:37], v[38:41], v[0:3]
	v_add_u32_e32 v34, -4, v33
	v_min_u32_e32 v34, 0xfff, v34
	v_lshlrev_b32_e32 v136, 7, v34
	v_lshl_add_u64 v[42:43], v[22:23], 0, v[136:137]
	global_load_dwordx4 v[34:37], v[26:27], off offset:384
	global_load_dwordx4 v[38:41], v[42:43], off
	s_waitcnt vmcnt(0) lgkmcnt(0)
	v_mfma_f32_16x16x32_bf16 v[0:3], v[34:37], v[38:41], v[0:3]
	global_load_dwordx4 v[34:37], v[26:27], off offset:448
	global_load_dwordx4 v[38:41], v[42:43], off offset:64
	s_waitcnt vmcnt(0) lgkmcnt(0)
	v_mfma_f32_16x16x32_bf16 v[0:3], v[34:37], v[38:41], v[0:3]
	v_add_u32_e32 v34, -3, v33
	v_min_u32_e32 v34, 0xfff, v34
	v_lshlrev_b32_e32 v136, 7, v34
	v_lshl_add_u64 v[42:43], v[22:23], 0, v[136:137]
	global_load_dwordx4 v[34:37], v[26:27], off offset:512
	global_load_dwordx4 v[38:41], v[42:43], off
	s_waitcnt vmcnt(0) lgkmcnt(0)
	v_mfma_f32_16x16x32_bf16 v[0:3], v[34:37], v[38:41], v[0:3]
	global_load_dwordx4 v[34:37], v[26:27], off offset:576
	global_load_dwordx4 v[38:41], v[42:43], off offset:64
	s_waitcnt vmcnt(0) lgkmcnt(0)
	v_mfma_f32_16x16x32_bf16 v[0:3], v[34:37], v[38:41], v[0:3]
	v_add_u32_e32 v34, -2, v33
	v_min_u32_e32 v34, 0xfff, v34
	v_lshlrev_b32_e32 v136, 7, v34
	v_lshl_add_u64 v[42:43], v[22:23], 0, v[136:137]
	global_load_dwordx4 v[34:37], v[26:27], off offset:640
	global_load_dwordx4 v[38:41], v[42:43], off
	s_waitcnt vmcnt(0) lgkmcnt(0)
	v_mfma_f32_16x16x32_bf16 v[0:3], v[34:37], v[38:41], v[0:3]
	global_load_dwordx4 v[34:37], v[26:27], off offset:704
	global_load_dwordx4 v[38:41], v[42:43], off offset:64
	s_waitcnt vmcnt(0) lgkmcnt(0)
	v_mfma_f32_16x16x32_bf16 v[0:3], v[34:37], v[38:41], v[0:3]
	v_add_u32_e32 v34, -1, v33
	v_min_u32_e32 v34, 0xfff, v34
	v_lshlrev_b32_e32 v136, 7, v34
	v_lshl_add_u64 v[42:43], v[22:23], 0, v[136:137]
	global_load_dwordx4 v[34:37], v[26:27], off offset:768
	global_load_dwordx4 v[38:41], v[42:43], off
	s_waitcnt vmcnt(0) lgkmcnt(0)
	v_mfma_f32_16x16x32_bf16 v[0:3], v[34:37], v[38:41], v[0:3]
	global_load_dwordx4 v[34:37], v[26:27], off offset:832
	global_load_dwordx4 v[38:41], v[42:43], off offset:64
	s_waitcnt vmcnt(0) lgkmcnt(0)
	v_mfma_f32_16x16x32_bf16 v[34:37], v[34:37], v[38:41], v[0:3]
	s_nop 3
	v_min_u32_e32 v0, 0xfff, v33
	v_lshlrev_b32_e32 v136, 7, v0
	v_lshl_add_u64 v[0:1], v[22:23], 0, v[136:137]
	global_load_dwordx4 v[38:41], v[26:27], off offset:896
	global_load_dwordx4 v[42:45], v[0:1], off
	v_add_u32_e32 v33, 8, v33
	s_waitcnt vmcnt(0) lgkmcnt(0)
	v_mfma_f32_16x16x32_bf16 v[34:37], v[38:41], v[42:45], v[34:37]
	global_load_dwordx4 v[38:41], v[26:27], off offset:960
	s_nop 0
	global_load_dwordx4 v[0:3], v[0:1], off offset:64
	s_waitcnt vmcnt(0) lgkmcnt(0)
	v_mfma_f32_16x16x32_bf16 v[0:3], v[38:41], v[0:3], v[34:37]
	s_cbranch_scc0 .LBB0_359
	s_and_b32 s8, s16, 0xffffff80
	s_ashr_i32 s9, s8, 31
	v_lshl_add_u64 v[22:23], s[8:9], 2, v[18:19]
	global_load_dwordx4 v[22:25], v[22:23], off
	s_and_b64 vcc, exec, s[6:7]
	s_waitcnt vmcnt(0) lgkmcnt(0)
	s_nop 0
	v_pk_add_f32 v[0:1], v[0:1], v[22:23]
	v_pk_add_f32 v[2:3], v[2:3], v[24:25]
	v_mul_f32_e32 v22, 0x3d372713, v0
	v_mul_f32_e32 v23, 0x3d372713, v1
	v_mul_f32_e32 v24, 0x3d372713, v2
	v_mul_f32_e32 v25, 0x3d372713, v3
	v_mul_f32_e32 v22, v0, v22
	v_mul_f32_e32 v23, v1, v23
	v_mul_f32_e32 v24, v2, v24
	v_mul_f32_e32 v25, v3, v25
	v_fma_f32 v22, v0, v22, v0
	v_fma_f32 v23, v1, v23, v1
	v_fma_f32 v24, v2, v24, v2
	v_fma_f32 v25, v3, v25, v3
	v_mul_f32_e32 v22, 0x3f4c422a, v22
	v_mul_f32_e32 v23, 0x3f4c422a, v23
	v_mul_f32_e32 v24, 0x3f4c422a, v24
	v_mul_f32_e32 v25, 0x3f4c422a, v25
	v_add_f32_e32 v22, v22, v22
	v_add_f32_e32 v23, v23, v23
	v_add_f32_e32 v24, v24, v24
	v_add_f32_e32 v25, v25, v25
	v_mul_f32_e32 v22, 0x3fb8aa3b, v22
	v_mul_f32_e32 v23, 0x3fb8aa3b, v23
	v_mul_f32_e32 v24, 0x3fb8aa3b, v24
	v_mul_f32_e32 v25, 0x3fb8aa3b, v25
	v_exp_f32_e32 v22, v22
	v_exp_f32_e32 v23, v23
	v_exp_f32_e32 v24, v24
	v_exp_f32_e32 v25, v25
	v_add_f32_e32 v22, 1.0, v22
	v_add_f32_e32 v23, 1.0, v23
	v_add_f32_e32 v24, 1.0, v24
	v_add_f32_e32 v25, 1.0, v25
	v_rcp_f32_e32 v22, v22
	v_rcp_f32_e32 v23, v23
	v_rcp_f32_e32 v24, v24
	v_rcp_f32_e32 v25, v25
	v_pk_mul_f32 v[0:1], v[0:1], 0.5 op_sel_hi:[1,0]
	v_pk_fma_f32 v[22:23], v[22:23], 2.0, 1.0 op_sel_hi:[1,0,0] neg_lo:[1,0,0] neg_hi:[1,0,0]
	v_pk_mul_f32 v[2:3], v[2:3], 0.5 op_sel_hi:[1,0]
	v_pk_fma_f32 v[24:25], v[24:25], 2.0, 1.0 op_sel_hi:[1,0,0] neg_lo:[1,0,0] neg_hi:[1,0,0]
	v_pk_add_f32 v[22:23], v[22:23], 1.0 op_sel_hi:[1,0]
	v_pk_add_f32 v[24:25], v[24:25], 1.0 op_sel_hi:[1,0]
	v_pk_mul_f32 v[0:1], v[0:1], v[22:23]
	v_pk_mul_f32 v[2:3], v[2:3], v[24:25]
	v_cvt_pk_bf16_f32 v0, v0, v1
	v_cvt_pk_bf16_f32 v1, v2, v3
	ds_write_b64 v30, v[0:1]
	s_waitcnt lgkmcnt(0)
	s_barrier
	s_cbranch_vccz .LBB0_357
	s_lshl_b64 s[2:3], s[2:3], 14
	v_lshl_add_u64 v[26:27], v[8:9], 0, s[2:3]
	global_load_dwordx2 v[0:1], v[26:27], off
	global_load_dwordx2 v[2:3], v[26:27], off offset:32
	global_load_dwordx2 v[22:23], v[26:27], off offset:64
	global_load_dwordx2 v[24:25], v[26:27], off offset:96
	global_load_dwordx2 v[34:35], v[26:27], off offset:128
	global_load_dwordx2 v[36:37], v[26:27], off offset:160
	global_load_dwordx2 v[38:39], v[26:27], off offset:192
	global_load_dwordx2 v[40:41], v[26:27], off offset:224
	ds_read2_b64 v[42:45], v29 offset1:4
	s_and_b32 s9, s16, 15
	s_lshl_b32 s8, s17, 15
	s_mov_b64 s[2:3], -1
	s_cmpk_gt_u32 s16, 0x7f
	s_waitcnt vmcnt(0) lgkmcnt(0)
	v_mfma_f32_16x16x32_bf16 v[0:3], v[0:3], v[42:45], 0
	ds_read2_b64 v[42:45], v29 offset0:8 offset1:12
	s_waitcnt lgkmcnt(0)
	v_mfma_f32_16x16x32_bf16 v[0:3], v[22:25], v[42:45], v[0:3]
	ds_read2_b64 v[22:25], v29 offset0:16 offset1:20
	ds_read2_b64 v[42:45], v29 offset0:24 offset1:28
	s_waitcnt lgkmcnt(1)
	v_mfma_f32_16x16x32_bf16 v[0:3], v[34:37], v[22:25], v[0:3]
	s_waitcnt lgkmcnt(0)
	v_mfma_f32_16x16x32_bf16 v[22:25], v[38:41], v[42:45], v[0:3]
	s_nop 5
	v_lshl_or_b32 v2, s9, 4, v28
	s_nop 0
	v_cvt_pk_bf16_f32 v0, v22, v23
	v_cvt_pk_bf16_f32 v1, v24, v25
	s_cbranch_scc0 .LBB0_363
	s_add_u32 s2, s12, s8
	s_addc_u32 s3, s13, 0
	s_lshl_b32 s9, s9, 2
	s_and_b32 s9, s9, 4
	v_and_b32_e32 v3, 0xe3, v2
	v_or3_b32 v3, s9, v31, v3
	v_lshlrev_b32_e32 v136, 1, v3
	v_lshl_add_u64 v[22:23], s[2:3], 0, v[136:137]
	v_lshl_add_u64 v[24:25], v[22:23], 0, v[10:11]
	global_store_short v[24:25], v0, off
	v_lshl_add_u64 v[24:25], v[22:23], 0, v[12:13]
	global_store_short_d16_hi v[24:25], v0, off
	v_lshl_add_u64 v[24:25], v[22:23], 0, v[14:15]
	v_lshl_add_u64 v[22:23], v[22:23], 0, v[16:17]
	global_store_short v[24:25], v1, off
	global_store_short_d16_hi v[22:23], v1, off
	s_mov_b64 s[2:3], 0
.LBB0_363:
	s_andn2_b64 vcc, exec, s[2:3]
	s_cbranch_vccnz .LBB0_357
	s_add_u32 s2, s14, s8
	s_addc_u32 s3, s15, 0
	v_lshlrev_b32_e32 v136, 7, v2
	v_lshl_add_u64 v[2:3], s[2:3], 0, v[136:137]
	v_lshl_add_u64 v[2:3], s[4:5], 1, v[2:3]
	v_lshl_add_u64 v[2:3], v[6:7], 1, v[2:3]
	global_store_dwordx2 v[2:3], v[0:1], off
	s_branch .LBB0_357
.LBB0_365:
	v_readlane_b32 s4, v254, 26
	v_readlane_b32 s5, v254, 27
	v_readlane_b32 s18, v254, 40
	v_readlane_b32 s19, v254, 41
	s_mov_b64 s[4:5], s[18:19]
	v_mbcnt_lo_u32_b32 v0, -1, 0
	v_mbcnt_hi_u32_b32 v0, -1, v0
	v_readlane_b32 s2, v254, 4
	s_waitcnt vmcnt(0) lgkmcnt(0)
	v_readlane_b32 s6, v254, 28
	v_readlane_b32 s7, v254, 29
	v_cmp_eq_u32_e32 vcc, 0, v0
	v_readlane_b32 s3, v254, 5
	s_and_b64 s[6:7], s[2:3], vcc
	v_readlane_b32 s8, v254, 30
	v_readlane_b32 s9, v254, 31
	v_readlane_b32 s10, v254, 32
	v_readlane_b32 s11, v254, 33
	v_readlane_b32 s12, v254, 34
	v_readlane_b32 s13, v254, 35
	v_readlane_b32 s14, v254, 36
	v_readlane_b32 s15, v254, 37
	v_readlane_b32 s16, v254, 38
	v_readlane_b32 s17, v254, 39
	s_waitcnt lgkmcnt(0)
	s_barrier
	s_and_saveexec_b64 s[2:3], s[6:7]
	s_cbranch_execz .LBB0_381
	v_readlane_b32 s6, v255, 1
	s_add_i32 s16, s6, 2
	s_getreg_b32 s6, hwreg(HW_REG_XCC_ID, 0, 4)
	s_lshl_b32 s6, s6, 8
	s_and_b32 s6, s6, 0x700
	s_add_u32 s15, s4, s6
	s_addc_u32 s14, s5, 0
	v_mov_b32_e32 v0, s15
	v_add_co_u32_e32 v8, vcc, 0x2000, v0
	v_mov_b32_e32 v0, s14
	s_nop 0
	v_addc_co_u32_e32 v9, vcc, 0, v0, vcc
	v_mov_b32_e32 v0, s4
	v_add_co_u32_e32 v10, vcc, 0x2000, v0
	v_mov_b32_e32 v0, s5
	s_nop 0
	v_addc_co_u32_e32 v11, vcc, 0, v0, vcc
	global_load_dword v12, v[8:9], off sc1
	global_load_dword v0, v[10:11], off sc1
	global_load_dword v1, v[10:11], off offset:256 sc1
	global_load_dword v2, v[10:11], off offset:512 sc1
	global_load_dword v3, v[10:11], off offset:768 sc1
	global_load_dword v4, v[10:11], off offset:1024 sc1
	global_load_dword v5, v[10:11], off offset:1280 sc1
	global_load_dword v6, v[10:11], off offset:1536 sc1
	global_load_dword v7, v[10:11], off offset:1792 sc1
	v_mov_b32_e32 v10, 1
	global_atomic_add v8, v[8:9], v10, off offset:2048 sc0
	s_waitcnt vmcnt(0) lgkmcnt(0)
	v_mul_lo_u32 v9, v12, s16
	v_add_u32_e32 v8, 1, v8
	v_cmp_ne_u32_e32 vcc, v8, v9
	s_and_saveexec_b64 s[6:7], vcc
	s_xor_b64 s[6:7], exec, s[6:7]
	s_cbranch_execz .LBB0_371
	v_mov_b32_e32 v0, s15
	v_add_co_u32_e32 v0, vcc, 0x3000, v0
	v_mov_b32_e32 v1, s14
	s_nop 0
	v_addc_co_u32_e32 v1, vcc, 0, v1, vcc
	global_load_dword v0, v[0:1], off sc1
	s_add_u32 s8, s15, 0x3000
	s_addc_u32 s9, s14, 0
	s_waitcnt vmcnt(0) lgkmcnt(0)
	v_cmp_gt_u32_e32 vcc, s16, v0
	s_and_saveexec_b64 s[10:11], vcc
	s_cbranch_execz .LBB0_370
	s_mov_b64 s[12:13], 0
.LBB0_369:
	v_mov_b64_e32 v[0:1], s[8:9]
	s_sleep 2
	global_load_dword v0, v[0:1], off sc1
	s_waitcnt vmcnt(0) lgkmcnt(0)
	v_readfirstlane_b32 s17, v0
	s_cmp_ge_u32 s17, s16
	s_cselect_b64 s[18:19], -1, 0
	s_and_b64 s[18:19], exec, s[18:19]
	s_or_b64 s[12:13], s[18:19], s[12:13]
	s_andn2_b64 exec, exec, s[12:13]
	s_cbranch_execnz .LBB0_369

.LBB0_371:
	s_andn2_saveexec_b64 s[6:7], s[6:7]
	s_cbranch_execz .LBB0_380
	v_cmp_ne_u32_e32 vcc, 0, v0
	s_movk_i32 s8, 0x3000
	buffer_wbl2 sc1
	v_cndmask_b32_e64 v0, 0, 1, vcc
	v_cmp_ne_u32_e32 vcc, 0, v1
	s_waitcnt vmcnt(0)
	s_nop 1
	v_addc_co_u32_e32 v0, vcc, 0, v0, vcc
	v_cmp_ne_u32_e32 vcc, 0, v2
	s_nop 1
	v_cndmask_b32_e64 v1, 0, 1, vcc
	v_cmp_ne_u32_e32 vcc, 0, v3
	v_mov_b32_e32 v3, 1
	s_nop 0
	v_addc_co_u32_e32 v0, vcc, v0, v1, vcc
	v_cmp_ne_u32_e32 vcc, 0, v4
	s_nop 1
	v_cndmask_b32_e64 v1, 0, 1, vcc
	v_cmp_ne_u32_e32 vcc, 0, v5
	s_nop 1
	v_addc_co_u32_e32 v0, vcc, v0, v1, vcc
	v_cmp_ne_u32_e32 vcc, 0, v6
	s_nop 1
	v_cndmask_b32_e64 v1, 0, 1, vcc
	v_cmp_ne_u32_e32 vcc, 0, v7
	s_nop 1
	v_addc_co_u32_e32 v2, vcc, v0, v1, vcc
	v_mov_b32_e32 v0, s4
	v_add_co_u32_e32 v0, vcc, s8, v0
	v_mov_b32_e32 v1, s5
	s_nop 0
	v_addc_co_u32_e32 v1, vcc, 0, v1, vcc
	global_atomic_add v0, v[0:1], v3, off offset:2048 sc0
	v_mul_lo_u32 v1, v2, s16
	s_add_u32 s4, s4, 0x3900
	s_addc_u32 s5, s5, 0
	s_waitcnt vmcnt(0) lgkmcnt(0)
	v_add_u32_e32 v0, 1, v0
	v_cmp_ne_u32_e32 vcc, v0, v1
	s_and_saveexec_b64 s[8:9], vcc
	s_xor_b64 s[8:9], exec, s[8:9]
	s_cbranch_execz .LBB0_377
	v_mov_b64_e32 v[0:1], s[4:5]
	global_load_dword v0, v[0:1], off sc1
	s_waitcnt vmcnt(0) lgkmcnt(0)
	v_cmp_gt_u32_e32 vcc, s16, v0
	s_and_saveexec_b64 s[10:11], vcc
	s_cbranch_execz .LBB0_376
	s_mov_b64 s[12:13], 0
.LBB0_375:
	v_mov_b64_e32 v[0:1], s[4:5]
	s_sleep 2
	global_load_dword v0, v[0:1], off sc1
	s_waitcnt vmcnt(0) lgkmcnt(0)
	v_readfirstlane_b32 s17, v0
	s_cmp_ge_u32 s17, s16
	s_cselect_b64 s[18:19], -1, 0
	s_and_b64 s[18:19], exec, s[18:19]
	s_or_b64 s[12:13], s[18:19], s[12:13]
	s_andn2_b64 exec, exec, s[12:13]
	s_cbranch_execnz .LBB0_375

.LBB0_381:
	s_or_b64 exec, exec, s[2:3]
	s_mov_b32 s2, s33
	v_readlane_b32 s8, v254, 26
	s_barrier
	v_readlane_b32 s20, v254, 38
	v_readlane_b32 s21, v254, 39
	v_readlane_b32 s22, v254, 40
	v_readlane_b32 s23, v254, 41
	v_readlane_b32 s73, v254, 3
	v_readlane_b32 s7, v254, 0
	s_mov_b64 s[2:3], s[20:21]
	s_mov_b64 s[74:75], s[22:23]
	v_mbcnt_lo_u32_b32 v200, -1, 0
	v_mbcnt_hi_u32_b32 v200, -1, v200
	s_lshl_b32 s2, s37, 3
	v_readlane_b32 s3, v255, 2
	s_and_b32 s6, s7, 7
	s_or_b32 s2, s2, s3
	s_or_b32 s2, s6, s2
	s_lshl_b32 s92, s2, 6
	s_lshl_b32 s4, s73, 6
	s_lshl_b64 s[2:3], s[92:93], 2
	s_add_u32 s2, s74, s2
	s_addc_u32 s3, s75, s3
	v_writelane_b32 v255, s2, 5
	v_sub_u32_e32 v0, 0, v200
	v_mov_b32_e32 v201, 0
	v_writelane_b32 v255, s3, 6
	s_mov_b32 s63, s4
	v_cmp_eq_u32_e64 s[2:3], s4, v0
	v_readlane_b32 s9, v254, 27
	v_readlane_b32 s10, v254, 28
	v_readlane_b32 s11, v254, 29
	v_readlane_b32 s12, v254, 30
	v_readlane_b32 s13, v254, 31
	v_readlane_b32 s14, v254, 32
	v_readlane_b32 s15, v254, 33
	v_readlane_b32 s16, v254, 34
	v_readlane_b32 s17, v254, 35
	v_readlane_b32 s18, v254, 36
	v_readlane_b32 s19, v254, 37
	s_and_saveexec_b64 s[4:5], s[2:3]
	s_cbranch_execz .LBB0_383
	v_readlane_b32 s8, v255, 5
	v_readlane_b32 s9, v255, 6
	v_mov_b32_e32 v2, 1
	s_nop 0
	v_mov_b64_e32 v[0:1], s[8:9]
	global_atomic_add v201, v[0:1], v2, off sc0

.LBB0_386:
	v_lshlrev_b32_e32 v136, 7, v117
	v_lshl_add_u64 v[16:17], v[16:17], 0, v[136:137]
	v_ashrrev_i32_e32 v117, 31, v116
	v_lshl_add_u64 v[16:17], v[116:117], 1, v[16:17]
	v_cvt_pk_bf16_f32 v0, v0, v1
	v_cvt_pk_bf16_f32 v1, v2, v3
	global_store_dwordx2 v[16:17], v[0:1], off
	v_cvt_pk_bf16_f32 v0, v4, v5
	v_cvt_pk_bf16_f32 v1, v6, v7
	global_store_dwordx2 v[16:17], v[0:1], off offset:32
	v_cvt_pk_bf16_f32 v0, v8, v9
	v_cvt_pk_bf16_f32 v1, v10, v11
	global_store_dwordx2 v[16:17], v[0:1], off offset:64
	v_cvt_pk_bf16_f32 v0, v12, v13
	v_cvt_pk_bf16_f32 v1, v14, v15
	global_store_dwordx2 v[16:17], v[0:1], off offset:96

.LBB0_390:
	s_or_b64 exec, exec, s[4:5]
	s_add_i32 s4, 0, 0x20000
	v_mov_b32_e32 v0, s4
	s_waitcnt lgkmcnt(0)
	s_barrier
	ds_read_b32 v0, v0
	s_movk_i32 s4, 0x13f
	s_waitcnt lgkmcnt(0)
	v_cmp_lt_i32_e64 s[4:5], s4, v0
	v_readfirstlane_b32 s69, v0
	s_and_b64 vcc, exec, s[4:5]
	s_cbranch_vccnz .LBB0_387
	s_and_saveexec_b64 s[6:7], s[2:3]
	s_cbranch_execz .LBB0_393
	v_readlane_b32 s8, v255, 5
	v_readlane_b32 s9, v255, 6
	v_mov_b32_e32 v2, 1
	s_nop 0
	v_mov_b64_e32 v[0:1], s[8:9]
	s_waitcnt vmcnt(0)
	global_atomic_add v201, v[0:1], v2, off sc0
.LBB0_393:
	s_or_b64 exec, exec, s[6:7]
	v_mov_b32_e32 v115, v200
	s_cmpk_gt_i32 s69, 0x7f
	s_mov_b64 s[6:7], -1
	s_cbranch_scc0 .LBB0_413
	s_cmpk_gt_u32 s69, 0xdf
	s_cbranch_scc0 .LBB0_403
	s_add_i32 s6, s69, 0xffffff20
	s_lshr_b32 s18, s6, 5
	v_readlane_b32 s6, v255, 7
	s_add_i32 s18, s18, s6
	s_not_b32 s6, s69
	s_lshl_b32 s6, s6, 7
	s_and_b32 s6, s6, 0xf80
	v_readlane_b32 s7, v255, 8
	v_and_b32_e32 v5, 15, v115
	s_add_i32 s10, s6, s7
	v_ashrrev_i32_e32 v4, 4, v115
	v_or_b32_e32 v72, s10, v5
	s_lshl_b32 s8, s18, 19
	v_readlane_b32 s6, v255, 9
	s_add_u32 s6, s6, s8
	v_readlane_b32 s7, v255, 10
	v_ashrrev_i32_e32 v73, 31, v72
	v_lshlrev_b32_e32 v74, 3, v4
	s_addc_u32 s7, s7, 0
	v_lshlrev_b64 v[0:1], 7, v[72:73]
	v_ashrrev_i32_e32 v75, 31, v74
	v_lshl_add_u64 v[0:1], s[6:7], 0, v[0:1]
	v_lshlrev_b64 v[2:3], 1, v[74:75]
	v_lshl_add_u64 v[0:1], v[0:1], 0, v[2:3]
	global_load_dwordx4 v[16:19], v[0:1], off
	global_load_dwordx4 v[20:23], v[0:1], off offset:64
	v_readlane_b32 s6, v255, 11
	s_add_u32 s6, s6, s8
	v_readlane_b32 s7, v255, 12
	s_addc_u32 s7, s7, 0
	v_readlane_b32 s9, v255, 13
	s_add_u32 s8, s9, s8
	v_readlane_b32 s9, v255, 14
	v_lshlrev_b32_e32 v136, 7, v5
	s_addc_u32 s9, s9, 0
	v_lshl_add_u64 v[76:77], s[6:7], 0, v[136:137]
	v_lshlrev_b32_e32 v136, 13, v5
	v_lshl_add_u64 v[0:1], s[8:9], 0, v[136:137]
	v_lshl_add_u64 v[78:79], v[0:1], 0, v[2:3]
	v_lshlrev_b32_e32 v0, 2, v115
	v_xor_b32_e32 v88, 64, v0
	v_xor_b32_e32 v89, 0x80, v0
	v_xor_b32_e32 v90, 0xc0, v0
	v_xor_b32_e32 v0, 1, v4
	v_cmp_gt_i32_e64 s[6:7], v0, v4
	v_xor_b32_e32 v0, 2, v4
	v_cmp_gt_i32_e64 s[8:9], v0, v4
	v_xor_b32_e32 v0, 3, v4
	v_mov_b32_e32 v136, v137
	s_ashr_i32 s12, s10, 6
	s_and_b32 s19, s10, 0xffffffc0
	v_lshlrev_b32_e32 v116, 2, v4
	v_cmp_gt_i32_e64 s[10:11], v0, v4
	v_lshl_add_u64 v[80:81], v[76:77], 0, v[2:3]
	v_mov_b32_e32 v138, v137
	v_mov_b32_e32 v139, v137
	v_mov_b64_e32 v[0:1], v[136:137]
	v_mov_b64_e32 v[4:5], v[136:137]
	v_mov_b64_e32 v[8:9], v[136:137]
	v_mov_b64_e32 v[12:13], v[136:137]
	s_add_i32 s20, s12, -2
	v_mov_b32_e32 v83, 0
	s_mov_b32 s14, s19
	v_mov_b64_e32 v[2:3], v[138:139]
	v_mov_b64_e32 v[6:7], v[138:139]
	v_mov_b64_e32 v[10:11], v[138:139]
	v_mov_b64_e32 v[14:15], v[138:139]
	s_mov_b32 s21, s12
	s_or_b32 s13, s12, 1
	s_mov_b32 s14, 0
	s_mov_b32 s15, 0
	s_mov_b32 s21, 0
	v_readlane_b32 s20, v255, 8
	v_lshrrev_b32_e32 v129, 3, v115
	s_lshr_b32 s20, s20, 1
	v_add_u32_e32 v129, s20, v129
	v_and_b32_e32 v134, 7, v115
	v_mul_u32_u24_e32 v128, 0xa0, v129
	v_lshl_add_u32 v128, v134, 4, v128
	v_and_b32_e32 v135, 15, v115
	v_mul_u32_u24_e32 v127, 0xa0, v135
	v_lshrrev_b32_e32 v135, 4, v115
	v_lshl_add_u32 v127, v135, 4, v127
	s_lshl_b32 s20, s20, 1
	v_mov_b32_e32 v156, s20
	v_lshrrev_b32_e32 v156, 2, v156
	s_lshl_b32 s20, s18, 19
	v_readlane_b32 s16, v255, 11
	v_readlane_b32 s17, v255, 12
	s_lshl_b32 s92, s13, 6
	s_add_u32 s16, s16, s20
	s_addc_u32 s17, s17, 0
	v_add_u32_e32 v135, s92, v129
	v_lshlrev_b32_e32 v135, 7, v135
	v_lshl_add_u32 v142, v134, 4, v135
	v_mov_b32_e32 v143, 0
	v_lshl_add_u64 v[130:131], s[16:17], 0, v[142:143]
	v_readlane_b32 s16, v255, 13
	v_readlane_b32 s17, v255, 14
	s_add_u32 s16, s16, s20
	s_addc_u32 s17, s17, 0
	v_lshlrev_b32_e32 v135, 13, v129
	v_lshl_add_u32 v135, v134, 4, v135
	s_lshl_b32 s92, s92, 1
	v_add_u32_e32 v142, s92, v135
	v_lshl_add_u64 v[132:133], s[16:17], 0, v[142:143]
	global_load_dwordx4 v[140:143], v[130:131], off
	global_load_dwordx4 v[144:147], v[132:133], off
	s_waitcnt vmcnt(0)
	ds_write_b128 v128, v[140:143] offset:16384
	ds_write_b128 v128, v[144:147] offset:26624
	s_waitcnt lgkmcnt(0)
	s_barrier

.LBB0_403:
	s_and_b64 vcc, exec, s[6:7]
	s_cbranch_vccz .LBB0_412
	s_add_i32 s6, s69, 0xffffff80
	s_lshl_b32 s72, s69, 3
	s_lshr_b32 s6, s6, 5
	v_readlane_b32 s7, v255, 7
	s_bfe_u32 s10, s69, 0x40001
	s_and_b32 s8, s72, 8
	s_add_i32 s40, s6, s7
	s_add_i32 s44, s8, s73
	s_lshl_b32 s9, s10, 8
	s_add_i32 s45, s9, s44
	s_lshl_b32 s11, s40, 19
	v_and_b32_e32 v111, 15, v115
	s_add_u32 s6, s60, s11
	v_lshlrev_b32_e32 v113, 4, v111
	s_addc_u32 s7, s61, 0
	v_readlane_b32 s12, v255, 15
	v_add_u32_e32 v88, s45, v113
	s_add_u32 s38, s12, s11
	v_readlane_b32 s12, v255, 16
	s_addc_u32 s39, s12, 0
	v_readlane_b32 s12, v255, 17
	v_ashrrev_i32_e32 v89, 31, v88
	s_add_u32 s52, s12, s11
	v_readlane_b32 s11, v255, 18
	v_lshlrev_b64 v[0:1], 7, v[88:89]
	s_addc_u32 s53, s11, 0
	v_lshl_add_u64 v[32:33], s[6:7], 0, v[0:1]
	v_lshlrev_b32_e32 v0, 2, v115
	s_lshl_b32 s6, s10, 2
	v_xor_b32_e32 v109, 64, v0
	v_xor_b32_e32 v108, 0x80, v0
	v_add_u32_e32 v0, s63, v115
	s_add_i32 s7, s6, -2
	v_ashrrev_i32_e32 v112, 4, v115
	s_cmp_lg_u32 s10, 0
	v_ashrrev_i32_e32 v2, 3, v0
	v_lshlrev_b32_e32 v0, 3, v115
	v_lshlrev_b32_e32 v90, 3, v112
	s_cselect_b32 s92, s7, 0
	s_or_b32 s84, s6, 3
	v_and_b32_e32 v4, 56, v0
	s_movk_i32 s6, 0x50
	v_ashrrev_i32_e32 v91, 31, v90
	v_mad_u64_u32 v[34:35], s[6:7], v2, s6, v[4:5]
	v_lshl_add_u64 v[0:1], v[90:91], 1, v[32:33]
	s_lshl_b32 s6, s92, 6
	v_ashrrev_i32_e32 v3, 31, v2
	global_load_dwordx4 v[16:19], v[0:1], off
	global_load_dwordx4 v[20:23], v[0:1], off offset:64
	v_lshlrev_b64 v[0:1], 13, v[2:3]
	v_add_u32_e32 v2, s6, v2
	v_ashrrev_i32_e32 v3, 31, v2
	v_lshlrev_b64 v[2:3], 7, v[2:3]
	s_ashr_i32 s7, s6, 31
	v_lshl_add_u64 v[6:7], s[38:39], 0, v[2:3]
	v_lshlrev_b32_e32 v136, 1, v4
	v_lshl_add_u64 v[8:9], s[52:53], 0, v[0:1]
	v_lshl_add_u64 v[4:5], v[6:7], 0, v[136:137]
	v_lshl_add_u64 v[8:9], s[6:7], 1, v[8:9]
	global_load_dwordx4 v[4:7], v[4:5], off
	v_lshl_add_u64 v[8:9], v[8:9], 0, v[136:137]
	global_load_dwordx4 v[8:11], v[8:9], off
	s_cmp_gt_i32 s92, s84
	v_lshl_add_u32 v12, v34, 1, 0
	s_mov_b32 s78, 0
	v_lshlrev_b32_e32 v110, 2, v112
	s_waitcnt vmcnt(0) lgkmcnt(0)
	ds_write_b128 v12, v[4:7] offset:16384
	ds_write_b128 v12, v[8:11] offset:26624
	s_waitcnt lgkmcnt(0)
	s_barrier
	s_cbranch_scc1 .LBB0_616
	s_mov_b32 s41, s93
	s_lshl_b64 s[10:11], s[40:41], 19
	v_lshl_add_u64 v[2:3], s[10:11], 0, v[2:3]
	v_lshl_add_u64 v[0:1], s[10:11], 0, v[0:1]
	s_lshl_b64 s[10:11], s[6:7], 1
	v_readlane_b32 s7, v255, 41
	s_add_u32 s10, s7, s10
	v_readlane_b32 s7, v255, 42
	v_and_b32_e32 v4, 7, v115
	s_addc_u32 s11, s7, s11
	v_readlane_b32 s7, v255, 43
	v_lshlrev_b32_e32 v136, 4, v4
	s_add_i32 s7, s7, s9
	v_lshl_add_u64 v[0:1], v[0:1], 0, v[136:137]
	s_add_i32 s8, s8, s7
	v_readlane_b32 s12, v255, 39
	v_lshl_add_u64 v[38:39], s[10:11], 0, v[0:1]
	v_add_u32_e32 v0, s8, v113
	v_lshlrev_b32_e32 v1, 2, v112
	v_lshl_add_u64 v[2:3], v[2:3], 0, v[136:137]
	v_readlane_b32 s13, v255, 40
	v_sub_u32_e32 v0, v0, v1
	v_mov_b32_e32 v43, 0
	v_mul_u32_u24_e32 v35, 0xa0, v111
	v_and_b32_e32 v41, -16, v115
	v_lshl_add_u64 v[36:37], s[12:13], 0, v[2:3]
	v_subrev_u32_e32 v42, s6, v0
	v_mov_b32_e32 v40, 0xf149f2ca
	v_mov_b32_e32 v0, 0
	v_mov_b32_e32 v1, v43
	v_mov_b32_e32 v2, v43
	v_mov_b32_e32 v3, v43
	v_mov_b32_e32 v4, 0
	v_mov_b32_e32 v5, v43
	v_mov_b32_e32 v6, v43
	v_mov_b32_e32 v7, v43
	v_mov_b32_e32 v12, 0
	v_mov_b32_e32 v13, v43
	v_mov_b32_e32 v14, v43
	v_mov_b32_e32 v15, v43
	v_mov_b32_e32 v8, 0
	v_mov_b32_e32 v9, v43
	v_mov_b32_e32 v10, v43
	v_mov_b32_e32 v11, v43
.LBB0_406:
	s_cmp_lt_i32 s92, s84
	s_cselect_b64 s[56:57], -1, 0
	s_cmp_ge_i32 s92, s84
	s_cselect_b64 s[54:55], -1, 0
	s_and_b64 vcc, exec, s[54:55]
	s_cbranch_vccnz .LBB0_408
	s_waitcnt vmcnt(0)
	global_load_dwordx4 v[28:31], v[36:37], off
	global_load_dwordx4 v[24:27], v[38:39], off

.LBB0_414:
	v_bfe_u32 v218, v115, 2, 2
	s_lshl_b32 s57, s69, 5
	v_and_b32_e32 v203, 3, v115
	v_or_b32_e32 v202, s68, v218
	s_sub_i32 s58, 0xfe0, s57
	v_readlane_b32 s6, v255, 24
	v_add_u32_e32 v126, s58, v202
	v_ashrrev_i32_e32 v127, 31, v126
	v_or_b32_e32 v117, s6, v203
	v_readlane_b32 s6, v255, 25
	v_readlane_b32 s7, v255, 26
	s_movk_i32 s8, 0x60
	v_mul_u32_u24_e32 v2, 3, v117
	v_lshl_add_u64 v[118:119], v[126:127], 0, s[6:7]
	v_readlane_b32 s6, v255, 27
	v_readlane_b32 s7, v255, 28
	v_lshlrev_b32_e32 v136, 2, v2
	v_ashrrev_i32_e32 v125, 4, v115
	v_mov_b64_e32 v[0:1], s[6:7]
	v_mad_u64_u32 v[0:1], s[6:7], v118, s8, v[0:1]
	v_mad_i32_i24 v1, v119, s8, v1
	v_readlane_b32 s6, v255, 50
	v_lshl_add_u64 v[6:7], v[0:1], 0, v[136:137]
	v_add_u32_e32 v10, s63, v115
	v_lshl_or_b32 v136, v117, 19, s6
	v_readlane_b32 s6, v255, 29
	v_readlane_b32 s7, v255, 30
	v_lshlrev_b64 v[2:3], 7, v[126:127]
	v_lshlrev_b32_e32 v4, 3, v125
	v_lshl_add_u64 v[0:1], s[6:7], 0, v[136:137]
	v_readlane_b32 s6, v255, 22
	v_lshl_add_u64 v[0:1], v[0:1], 0, v[2:3]
	v_ashrrev_i32_e32 v5, 31, v4
	v_lshlrev_b64 v[8:9], 6, v[118:119]
	v_readlane_b32 s7, v255, 23
	v_ashrrev_i32_e32 v120, 3, v10
	v_lshl_add_u64 v[0:1], v[4:5], 1, v[0:1]
	v_lshl_add_u64 v[8:9], s[6:7], 0, v[8:9]
	v_ashrrev_i32_e32 v121, 31, v120
	v_lshlrev_b32_e32 v10, 3, v115
	global_load_dwordx4 v[36:39], v[0:1], off
	s_nop 0
	global_load_dwordx4 v[0:3], v[0:1], off offset:64
	s_waitcnt vmcnt(0)
	global_load_dwordx4 v[44:47], v[8:9], off
	global_load_dwordx4 v[32:35], v[8:9], off offset:16
	global_load_dwordx4 v[40:43], v[8:9], off offset:32
	global_load_dwordx4 v[28:31], v[8:9], off offset:48
	v_lshlrev_b64 v[8:9], 7, v[120:121]
	v_and_b32_e32 v124, 56, v10
	v_lshl_add_u64 v[8:9], s[64:65], 0, v[8:9]
	v_lshlrev_b32_e32 v136, 1, v124
	v_readlane_b32 s6, v255, 31
	v_lshl_add_u64 v[8:9], v[8:9], 0, v[136:137]
	v_lshlrev_b64 v[122:123], 13, v[120:121]
	v_readlane_b32 s7, v255, 32
	global_load_dwordx4 v[20:23], v[8:9], off
	s_add_i32 s56, s58, s68
	v_lshl_add_u64 v[8:9], s[6:7], 0, v[122:123]
	v_lshl_add_u64 v[128:129], v[8:9], 0, v[136:137]
	global_load_dwordx3 v[112:114], v[6:7], off
	global_load_dwordx4 v[24:27], v[128:129], off
	s_sub_i32 s7, s56, 28
	s_ashr_i32 s7, s7, 8
	s_or_b32 s6, s56, 3
	s_add_i32 s7, s7, 1
	s_cmp_gt_i32 s6, 30
	v_and_b32_e32 v121, 15, v115
	s_cselect_b32 s40, s7, 0
	v_lshlrev_b32_e32 v6, 6, v121
	s_cmp_gt_i32 s40, 0
	s_cselect_b64 s[38:39], -1, 0
	s_cmp_lt_i32 s40, 1
	v_lshlrev_b32_e32 v6, 1, v6
	s_cmp_gt_i32 s40, 1
	s_cselect_b64 s[20:21], -1, 0
	s_cmp_gt_i32 s40, 2
	s_cselect_b64 s[36:37], -1, 0
	s_cmp_gt_i32 s40, 3
	s_cselect_b64 s[18:19], -1, 0
	s_cmp_gt_i32 s40, 4
	s_cselect_b64 s[34:35], -1, 0
	s_cmp_gt_i32 s40, 5
	s_cselect_b64 s[16:17], -1, 0
	s_cmp_gt_i32 s40, 6
	s_cselect_b64 s[30:31], -1, 0
	s_cmp_gt_i32 s40, 7
	s_cselect_b64 s[14:15], -1, 0
	s_cmp_gt_i32 s40, 8
	s_cselect_b64 s[28:29], -1, 0
	s_cmp_gt_i32 s40, 9
	s_cselect_b64 s[12:13], -1, 0
	s_cmp_gt_i32 s40, 10
	s_cselect_b64 s[26:27], -1, 0
	s_cmp_gt_i32 s40, 11
	s_cselect_b64 s[10:11], -1, 0
	s_cmp_gt_i32 s40, 12
	s_cselect_b64 s[24:25], -1, 0
	s_cmp_gt_i32 s40, 13
	s_cselect_b64 s[8:9], -1, 0
	s_cmp_gt_i32 s40, 14
	s_cselect_b64 s[22:23], -1, 0
	s_cmp_gt_i32 s40, 15
	s_cselect_b64 s[6:7], -1, 0
	v_mov_b32_e32 v7, v137
	v_lshl_add_u64 v[138:139], s[42:43], 0, v[6:7]
	v_lshl_add_u64 v[138:139], v[4:5], 1, v[138:139]
	v_add_co_u32_e32 v138, vcc, 0x1000, v138
	s_nop 1
	v_addc_co_u32_e32 v139, vcc, 0, v139, vcc
	s_cmp_lt_i32 s40, 1
	s_cbranch_scc1 .Lcq_issued
	global_load_dwordx4 v[48:51], v[138:139], off offset:-4096
	global_load_dwordx4 v[140:143], v[138:139], off offset:-4032
	s_cmp_lt_i32 s40, 2
	s_cbranch_scc1 .Lcq_issued
	global_load_dwordx4 v[52:55], v[138:139], off offset:-2048
	global_load_dwordx4 v[144:147], v[138:139], off offset:-1984
	s_cmp_lt_i32 s40, 3
	s_cbranch_scc1 .Lcq_issued
	global_load_dwordx4 v[56:59], v[138:139], off offset:0
	global_load_dwordx4 v[148:151], v[138:139], off offset:64
	s_cmp_lt_i32 s40, 4
	s_cbranch_scc1 .Lcq_issued
	global_load_dwordx4 v[60:63], v[138:139], off offset:2048
	global_load_dwordx4 v[152:155], v[138:139], off offset:2112
	v_add_co_u32_e32 v138, vcc, 0x2000, v138
	s_nop 1
	v_addc_co_u32_e32 v139, vcc, 0, v139, vcc
	s_cmp_lt_i32 s40, 5
	s_cbranch_scc1 .Lcq_issued
	global_load_dwordx4 v[64:67], v[138:139], off offset:-4096
	global_load_dwordx4 v[156:159], v[138:139], off offset:-4032
	s_cmp_lt_i32 s40, 6
	s_cbranch_scc1 .Lcq_issued
	global_load_dwordx4 v[68:71], v[138:139], off offset:-2048
	global_load_dwordx4 v[160:163], v[138:139], off offset:-1984
	s_cmp_lt_i32 s40, 7
	s_cbranch_scc1 .Lcq_issued
	global_load_dwordx4 v[72:75], v[138:139], off offset:0
	global_load_dwordx4 v[164:167], v[138:139], off offset:64
	s_cmp_lt_i32 s40, 8
	s_cbranch_scc1 .Lcq_issued
	global_load_dwordx4 v[76:79], v[138:139], off offset:2048
	global_load_dwordx4 v[168:171], v[138:139], off offset:2112
	v_add_co_u32_e32 v138, vcc, 0x2000, v138
	s_nop 1
	v_addc_co_u32_e32 v139, vcc, 0, v139, vcc
	s_cmp_lt_i32 s40, 9
	s_cbranch_scc1 .Lcq_issued
	global_load_dwordx4 v[80:83], v[138:139], off offset:-4096
	global_load_dwordx4 v[172:175], v[138:139], off offset:-4032
	s_cmp_lt_i32 s40, 10
	s_cbranch_scc1 .Lcq_issued
	global_load_dwordx4 v[84:87], v[138:139], off offset:-2048
	global_load_dwordx4 v[176:179], v[138:139], off offset:-1984
	s_cmp_lt_i32 s40, 11
	s_cbranch_scc1 .Lcq_issued
	global_load_dwordx4 v[88:91], v[138:139], off offset:0
	global_load_dwordx4 v[180:183], v[138:139], off offset:64
	s_cmp_lt_i32 s40, 12
	s_cbranch_scc1 .Lcq_issued
	global_load_dwordx4 v[92:95], v[138:139], off offset:2048
	global_load_dwordx4 v[184:187], v[138:139], off offset:2112
	v_add_co_u32_e32 v138, vcc, 0x2000, v138
	s_nop 1
	v_addc_co_u32_e32 v139, vcc, 0, v139, vcc
	s_cmp_lt_i32 s40, 13
	s_cbranch_scc1 .Lcq_issued
	global_load_dwordx4 v[96:99], v[138:139], off offset:-4096
	global_load_dwordx4 v[188:191], v[138:139], off offset:-4032
	s_cmp_lt_i32 s40, 14
	s_cbranch_scc1 .Lcq_issued
	global_load_dwordx4 v[100:103], v[138:139], off offset:-2048
	global_load_dwordx4 v[192:195], v[138:139], off offset:-1984
	s_cmp_lt_i32 s40, 15
	s_cbranch_scc1 .Lcq_issued
	global_load_dwordx4 v[104:107], v[138:139], off offset:0
	global_load_dwordx4 v[196:199], v[138:139], off offset:64
	s_cmp_lt_i32 s40, 16
	s_cbranch_scc1 .Lcq_issued
	global_load_dwordx4 v[108:111], v[138:139], off offset:2048
	global_load_dwordx4 v[204:207], v[138:139], off offset:2112

.Lcq_done:
.LBB0_447:
	s_nop 6
	v_subrev_u32_e32 v6, 31, v126
	v_lshrrev_b32_e32 v6, 4, v6
	v_cmp_lt_i32_e32 vcc, 30, v126
	v_lshlrev_b32_e32 v116, 2, v125
	v_mul_f32_e32 v7, 0x3e38aa3b, v48
	v_cndmask_b32_e32 v6, -1, v6, vcc
	v_cmp_le_i32_e32 vcc, v116, v6
	v_mul_f32_e32 v9, 0x3e38aa3b, v49
	v_mul_f32_e32 v10, 0x3e38aa3b, v50
	v_cndmask_b32_e32 v7, v241, v7, vcc
	v_max_f32_e32 v8, 0xf149f2ca, v7
	v_cmp_lt_i32_e32 vcc, v116, v6
	v_cndmask_b32_e64 v8, v241, v8, s[38:39]
	v_mul_f32_e32 v11, 0x3e38aa3b, v53
	v_cndmask_b32_e32 v16, v241, v9, vcc
	v_or_b32_e32 v9, 2, v116
	v_max_f32_e32 v8, v8, v16
	v_cmp_le_i32_e32 vcc, v9, v6
	v_cndmask_b32_e64 v8, v241, v8, s[38:39]
	v_or_b32_e32 v9, 3, v116
	v_cndmask_b32_e32 v18, v241, v10, vcc
	v_max_f32_e32 v8, v8, v18
	v_mul_f32_e32 v10, 0x3e38aa3b, v51
	v_cmp_le_i32_e32 vcc, v9, v6
	v_cndmask_b32_e64 v8, v241, v8, s[38:39]
	v_add_u32_e32 v9, 16, v116
	v_cndmask_b32_e32 v131, v241, v10, vcc
	v_max_f32_e32 v8, v8, v131
	v_mul_f32_e32 v10, 0x3e38aa3b, v52
	v_cmp_le_i32_e32 vcc, v9, v6
	v_cndmask_b32_e64 v8, v241, v8, s[38:39]
	v_mul_f32_e32 v133, 0x3e38aa3b, v110
	v_cndmask_b32_e32 v140, v241, v10, vcc
	v_add_u32_e32 v10, 17, v116
	v_max_f32_e32 v9, v8, v140
	v_cmp_le_i32_e32 vcc, v10, v6
	v_cndmask_b32_e64 v9, v8, v9, s[20:21]
	v_add_u32_e32 v10, 18, v116
	v_cndmask_b32_e32 v141, v241, v11, vcc
	v_max_f32_e32 v9, v9, v141
	v_mul_f32_e32 v11, 0x3e38aa3b, v54
	v_cmp_le_i32_e32 vcc, v10, v6
	v_cndmask_b32_e64 v9, v8, v9, s[20:21]
	v_add_u32_e32 v10, 19, v116
	v_cndmask_b32_e32 v142, v241, v11, vcc
	v_max_f32_e32 v9, v9, v142
	v_mul_f32_e32 v11, 0x3e38aa3b, v55
	v_cmp_le_i32_e32 vcc, v10, v6
	v_cndmask_b32_e64 v9, v8, v9, s[20:21]
	v_mul_f32_e32 v10, 0x3e38aa3b, v56
	v_cndmask_b32_e32 v143, v241, v11, vcc
	v_max_f32_e32 v9, v9, v143
	v_cndmask_b32_e64 v8, v8, v9, s[20:21]
	v_add_u32_e32 v9, 32, v116
	v_cmp_le_i32_e32 vcc, v9, v6
	v_mul_f32_e32 v11, 0x3e38aa3b, v57
	v_mul_f32_e32 v134, 0x3e38aa3b, v111
	v_cndmask_b32_e32 v144, v241, v10, vcc
	v_add_u32_e32 v10, 33, v116
	v_max_f32_e32 v9, v8, v144
	v_cmp_le_i32_e32 vcc, v10, v6
	v_cndmask_b32_e64 v9, v8, v9, s[36:37]
	v_add_u32_e32 v10, 34, v116
	v_cndmask_b32_e32 v145, v241, v11, vcc
	v_max_f32_e32 v9, v9, v145
	v_mul_f32_e32 v11, 0x3e38aa3b, v58
	v_cmp_le_i32_e32 vcc, v10, v6
	v_cndmask_b32_e64 v9, v8, v9, s[36:37]
	v_add_u32_e32 v10, 35, v116
	v_cndmask_b32_e32 v146, v241, v11, vcc
	v_max_f32_e32 v9, v9, v146
	v_mul_f32_e32 v11, 0x3e38aa3b, v59
	v_cmp_le_i32_e32 vcc, v10, v6
	v_cndmask_b32_e64 v9, v8, v9, s[36:37]
	v_mul_f32_e32 v10, 0x3e38aa3b, v60
	v_cndmask_b32_e32 v152, v241, v11, vcc
	v_max_f32_e32 v9, v9, v152
	v_cndmask_b32_e64 v8, v8, v9, s[36:37]
	v_add_u32_e32 v9, 48, v116
	v_cmp_le_i32_e32 vcc, v9, v6
	v_mul_f32_e32 v11, 0x3e38aa3b, v61
	v_cndmask_b32_e64 v16, v49, v16, s[38:39]
	v_cndmask_b32_e32 v153, v241, v10, vcc
	v_add_u32_e32 v10, 49, v116
	v_max_f32_e32 v9, v8, v153
	v_cmp_le_i32_e32 vcc, v10, v6
	v_cndmask_b32_e64 v9, v8, v9, s[18:19]
	v_add_u32_e32 v10, 50, v116
	v_cndmask_b32_e32 v154, v241, v11, vcc
	v_max_f32_e32 v9, v9, v154
	v_mul_f32_e32 v11, 0x3e38aa3b, v62
	v_cmp_le_i32_e32 vcc, v10, v6
	v_cndmask_b32_e64 v9, v8, v9, s[18:19]
	v_add_u32_e32 v10, 51, v116
	v_cndmask_b32_e32 v155, v241, v11, vcc
	v_max_f32_e32 v9, v9, v155
	v_mul_f32_e32 v11, 0x3e38aa3b, v63
	v_cmp_le_i32_e32 vcc, v10, v6
	v_cndmask_b32_e64 v9, v8, v9, s[18:19]
	v_mul_f32_e32 v10, 0x3e38aa3b, v64
	v_cndmask_b32_e32 v156, v241, v11, vcc
	v_max_f32_e32 v9, v9, v156
	v_cndmask_b32_e64 v8, v8, v9, s[18:19]
	v_add_u32_e32 v9, 64, v116
	v_cmp_le_i32_e32 vcc, v9, v6
	v_mul_f32_e32 v11, 0x3e38aa3b, v65
	v_cndmask_b32_e64 v18, v50, v18, s[38:39]
	v_cndmask_b32_e32 v157, v241, v10, vcc
	v_max_f32_e32 v9, v8, v157
	v_add_u32_e32 v10, 0x41, v116
	v_cndmask_b32_e64 v9, v8, v9, s[34:35]
	v_cmp_le_i32_e32 vcc, v10, v6
	v_max_f32_e32 v9, v9, v9
	v_add_u32_e32 v10, 0x42, v116
	v_cndmask_b32_e32 v158, v241, v11, vcc
	v_max_f32_e32 v9, v9, v158
	v_cndmask_b32_e64 v9, v8, v9, s[34:35]
	v_mul_f32_e32 v11, 0x3e38aa3b, v66
	v_cmp_le_i32_e32 vcc, v10, v6
	v_max_f32_e32 v9, v9, v9
	v_add_u32_e32 v10, 0x43, v116
	v_cndmask_b32_e32 v159, v241, v11, vcc
	v_max_f32_e32 v9, v9, v159
	v_cndmask_b32_e64 v9, v8, v9, s[34:35]
	v_mul_f32_e32 v11, 0x3e38aa3b, v67
	v_cmp_le_i32_e32 vcc, v10, v6
	v_max_f32_e32 v9, v9, v9
	v_mul_f32_e32 v10, 0x3e38aa3b, v68
	v_cndmask_b32_e32 v160, v241, v11, vcc
	v_max_f32_e32 v9, v9, v160
	v_cndmask_b32_e64 v8, v8, v9, s[34:35]
	v_add_u32_e32 v9, 0x50, v116
	v_cmp_le_i32_e32 vcc, v9, v6
	v_max_f32_e32 v9, v8, v8
	v_mul_f32_e32 v11, 0x3e38aa3b, v69
	v_cndmask_b32_e32 v161, v241, v10, vcc
	v_max_f32_e32 v9, v9, v161
	v_add_u32_e32 v10, 0x51, v116
	v_cndmask_b32_e64 v9, v8, v9, s[16:17]
	v_cmp_le_i32_e32 vcc, v10, v6
	v_max_f32_e32 v9, v9, v9
	v_add_u32_e32 v10, 0x52, v116
	v_cndmask_b32_e32 v162, v241, v11, vcc
	v_max_f32_e32 v9, v9, v162
	v_cndmask_b32_e64 v9, v8, v9, s[16:17]
	v_mul_f32_e32 v11, 0x3e38aa3b, v70
	v_cmp_le_i32_e32 vcc, v10, v6
	v_max_f32_e32 v9, v9, v9
	v_add_u32_e32 v10, 0x53, v116
	v_cndmask_b32_e32 v163, v241, v11, vcc
	v_max_f32_e32 v9, v9, v163
	v_cndmask_b32_e64 v9, v8, v9, s[16:17]
	v_mul_f32_e32 v11, 0x3e38aa3b, v71
	v_cmp_le_i32_e32 vcc, v10, v6
	v_max_f32_e32 v9, v9, v9
	v_mul_f32_e32 v10, 0x3e38aa3b, v72
	v_cndmask_b32_e32 v164, v241, v11, vcc
	v_max_f32_e32 v9, v9, v164
	v_cndmask_b32_e64 v8, v8, v9, s[16:17]
	v_add_u32_e32 v9, 0x60, v116
	v_cmp_le_i32_e32 vcc, v9, v6
	v_max_f32_e32 v9, v8, v8
	v_mul_f32_e32 v11, 0x3e38aa3b, v73
	v_cndmask_b32_e32 v165, v241, v10, vcc
	v_max_f32_e32 v9, v9, v165
	v_add_u32_e32 v10, 0x61, v116
	v_cndmask_b32_e64 v9, v8, v9, s[30:31]
	v_cmp_le_i32_e32 vcc, v10, v6
	v_max_f32_e32 v9, v9, v9
	v_add_u32_e32 v10, 0x62, v116
	v_cndmask_b32_e32 v166, v241, v11, vcc
	v_max_f32_e32 v9, v9, v166
	v_cndmask_b32_e64 v9, v8, v9, s[30:31]
	v_mul_f32_e32 v11, 0x3e38aa3b, v74
	v_cmp_le_i32_e32 vcc, v10, v6
	v_max_f32_e32 v9, v9, v9
	v_add_u32_e32 v10, 0x63, v116
	v_cndmask_b32_e32 v167, v241, v11, vcc
	v_max_f32_e32 v9, v9, v167
	v_cndmask_b32_e64 v9, v8, v9, s[30:31]
	v_mul_f32_e32 v11, 0x3e38aa3b, v75
	v_cmp_le_i32_e32 vcc, v10, v6
	v_max_f32_e32 v9, v9, v9
	v_mul_f32_e32 v10, 0x3e38aa3b, v76
	v_cndmask_b32_e32 v168, v241, v11, vcc
	v_max_f32_e32 v9, v9, v168
	v_cndmask_b32_e64 v8, v8, v9, s[30:31]
	v_add_u32_e32 v9, 0x70, v116
	v_cmp_le_i32_e32 vcc, v9, v6
	v_max_f32_e32 v9, v8, v8
	v_mul_f32_e32 v11, 0x3e38aa3b, v77
	v_cndmask_b32_e32 v172, v241, v10, vcc
	v_max_f32_e32 v9, v9, v172
	v_add_u32_e32 v10, 0x71, v116
	v_cndmask_b32_e64 v9, v8, v9, s[14:15]
	v_cmp_le_i32_e32 vcc, v10, v6
	v_max_f32_e32 v9, v9, v9
	v_add_u32_e32 v10, 0x72, v116
	v_cndmask_b32_e32 v173, v241, v11, vcc
	v_max_f32_e32 v9, v9, v173
	v_cndmask_b32_e64 v9, v8, v9, s[14:15]
	v_mul_f32_e32 v11, 0x3e38aa3b, v78
	v_cmp_le_i32_e32 vcc, v10, v6
	v_max_f32_e32 v9, v9, v9
	v_add_u32_e32 v10, 0x73, v116
	v_cndmask_b32_e32 v174, v241, v11, vcc
	v_max_f32_e32 v9, v9, v174
	v_cndmask_b32_e64 v9, v8, v9, s[14:15]
	v_mul_f32_e32 v11, 0x3e38aa3b, v79
	v_cmp_le_i32_e32 vcc, v10, v6
	v_max_f32_e32 v9, v9, v9
	v_mul_f32_e32 v10, 0x3e38aa3b, v80
	v_cndmask_b32_e32 v175, v241, v11, vcc
	v_max_f32_e32 v9, v9, v175
	v_cndmask_b32_e64 v8, v8, v9, s[14:15]
	v_add_u32_e32 v9, 0x80, v116
	v_cmp_le_i32_e32 vcc, v9, v6
	v_max_f32_e32 v9, v8, v8
	v_mul_f32_e32 v11, 0x3e38aa3b, v81
	v_cndmask_b32_e32 v176, v241, v10, vcc
	v_max_f32_e32 v9, v9, v176
	v_add_u32_e32 v10, 0x81, v116
	v_cndmask_b32_e64 v9, v8, v9, s[28:29]
	v_cmp_le_i32_e32 vcc, v10, v6
	v_max_f32_e32 v9, v9, v9
	v_add_u32_e32 v10, 0x82, v116
	v_cndmask_b32_e32 v177, v241, v11, vcc
	v_max_f32_e32 v9, v9, v177
	v_cndmask_b32_e64 v9, v8, v9, s[28:29]
	v_mul_f32_e32 v11, 0x3e38aa3b, v82
	v_cmp_le_i32_e32 vcc, v10, v6
	v_max_f32_e32 v9, v9, v9
	v_add_u32_e32 v10, 0x83, v116
	v_cndmask_b32_e32 v178, v241, v11, vcc
	v_max_f32_e32 v9, v9, v178
	v_cndmask_b32_e64 v9, v8, v9, s[28:29]
	v_mul_f32_e32 v11, 0x3e38aa3b, v83
	v_cmp_le_i32_e32 vcc, v10, v6
	v_max_f32_e32 v9, v9, v9
	v_mul_f32_e32 v10, 0x3e38aa3b, v84
	v_cndmask_b32_e32 v179, v241, v11, vcc
	v_max_f32_e32 v9, v9, v179
	v_cndmask_b32_e64 v8, v8, v9, s[28:29]
	v_add_u32_e32 v9, 0x90, v116
	v_cmp_le_i32_e32 vcc, v9, v6
	v_max_f32_e32 v9, v8, v8
	v_mul_f32_e32 v11, 0x3e38aa3b, v85
	v_cndmask_b32_e32 v180, v241, v10, vcc
	v_max_f32_e32 v9, v9, v180
	v_add_u32_e32 v10, 0x91, v116
	v_cndmask_b32_e64 v9, v8, v9, s[12:13]
	v_cmp_le_i32_e32 vcc, v10, v6
	v_max_f32_e32 v9, v9, v9
	v_add_u32_e32 v10, 0x92, v116
	v_cndmask_b32_e32 v181, v241, v11, vcc
	v_max_f32_e32 v9, v9, v181
	v_cndmask_b32_e64 v9, v8, v9, s[12:13]
	v_mul_f32_e32 v11, 0x3e38aa3b, v86
	v_cmp_le_i32_e32 vcc, v10, v6
	v_max_f32_e32 v9, v9, v9
	v_add_u32_e32 v10, 0x93, v116
	v_cndmask_b32_e32 v182, v241, v11, vcc
	v_max_f32_e32 v9, v9, v182
	v_cndmask_b32_e64 v9, v8, v9, s[12:13]
	v_mul_f32_e32 v11, 0x3e38aa3b, v87
	v_cmp_le_i32_e32 vcc, v10, v6
	v_max_f32_e32 v9, v9, v9
	v_mul_f32_e32 v10, 0x3e38aa3b, v88
	v_cndmask_b32_e32 v183, v241, v11, vcc
	v_max_f32_e32 v9, v9, v183
	v_cndmask_b32_e64 v8, v8, v9, s[12:13]
	v_add_u32_e32 v9, 0xa0, v116
	v_cmp_le_i32_e32 vcc, v9, v6
	v_max_f32_e32 v9, v8, v8
	v_mul_f32_e32 v11, 0x3e38aa3b, v89
	v_cndmask_b32_e32 v184, v241, v10, vcc
	v_max_f32_e32 v9, v9, v184
	v_add_u32_e32 v10, 0xa1, v116
	v_cndmask_b32_e64 v9, v8, v9, s[26:27]
	v_cmp_le_i32_e32 vcc, v10, v6
	v_max_f32_e32 v9, v9, v9
	v_add_u32_e32 v10, 0xa2, v116
	v_cndmask_b32_e32 v188, v241, v11, vcc
	v_max_f32_e32 v9, v9, v188
	v_cndmask_b32_e64 v9, v8, v9, s[26:27]
	v_mul_f32_e32 v11, 0x3e38aa3b, v90
	v_cmp_le_i32_e32 vcc, v10, v6
	v_max_f32_e32 v9, v9, v9
	v_add_u32_e32 v10, 0xa3, v116
	v_cndmask_b32_e32 v189, v241, v11, vcc
	v_max_f32_e32 v9, v9, v189
	v_cndmask_b32_e64 v9, v8, v9, s[26:27]
	v_mul_f32_e32 v11, 0x3e38aa3b, v91
	v_cmp_le_i32_e32 vcc, v10, v6
	v_max_f32_e32 v9, v9, v9
	v_mul_f32_e32 v10, 0x3e38aa3b, v92
	v_cndmask_b32_e32 v190, v241, v11, vcc
	v_max_f32_e32 v9, v9, v190
	v_cndmask_b32_e64 v8, v8, v9, s[26:27]
	v_add_u32_e32 v9, 0xb0, v116
	v_cmp_le_i32_e32 vcc, v9, v6
	v_max_f32_e32 v9, v8, v8
	v_mul_f32_e32 v11, 0x3e38aa3b, v93
	v_cndmask_b32_e32 v150, v241, v10, vcc
	v_max_f32_e32 v9, v9, v150
	v_add_u32_e32 v10, 0xb1, v116
	v_cndmask_b32_e64 v9, v8, v9, s[10:11]
	v_cmp_le_i32_e32 vcc, v10, v6
	v_max_f32_e32 v9, v9, v9
	v_add_u32_e32 v10, 0xb2, v116
	v_cndmask_b32_e32 v151, v241, v11, vcc
	v_max_f32_e32 v9, v9, v151
	v_cndmask_b32_e64 v9, v8, v9, s[10:11]
	v_mul_f32_e32 v11, 0x3e38aa3b, v94
	v_cmp_le_i32_e32 vcc, v10, v6
	v_max_f32_e32 v9, v9, v9
	v_add_u32_e32 v10, 0xb3, v116
	v_cndmask_b32_e32 v148, v241, v11, vcc
	v_max_f32_e32 v9, v9, v148
	v_cndmask_b32_e64 v9, v8, v9, s[10:11]
	v_mul_f32_e32 v11, 0x3e38aa3b, v95
	v_cmp_le_i32_e32 vcc, v10, v6
	v_max_f32_e32 v9, v9, v9
	v_mul_f32_e32 v10, 0x3e38aa3b, v96
	v_cndmask_b32_e32 v149, v241, v11, vcc
	v_max_f32_e32 v9, v9, v149
	v_cndmask_b32_e64 v8, v8, v9, s[10:11]
	v_add_u32_e32 v9, 0xc0, v116
	v_cmp_le_i32_e32 vcc, v9, v6
	v_max_f32_e32 v9, v8, v8
	v_mul_f32_e32 v11, 0x3e38aa3b, v97
	v_cndmask_b32_e32 v139, v241, v10, vcc
	v_max_f32_e32 v9, v9, v139
	v_add_u32_e32 v10, 0xc1, v116
	v_cndmask_b32_e64 v9, v8, v9, s[24:25]
	v_cmp_le_i32_e32 vcc, v10, v6
	v_max_f32_e32 v9, v9, v9
	v_add_u32_e32 v10, 0xc2, v116
	v_cndmask_b32_e32 v147, v241, v11, vcc
	v_max_f32_e32 v9, v9, v147
	v_cndmask_b32_e64 v9, v8, v9, s[24:25]
	v_mul_f32_e32 v11, 0x3e38aa3b, v98
	v_cmp_le_i32_e32 vcc, v10, v6
	v_max_f32_e32 v9, v9, v9
	v_add_u32_e32 v10, 0xc3, v116
	v_cndmask_b32_e32 v135, v241, v11, vcc
	v_max_f32_e32 v9, v9, v135
	v_cndmask_b32_e64 v9, v8, v9, s[24:25]
	v_mul_f32_e32 v11, 0x3e38aa3b, v99
	v_cmp_le_i32_e32 vcc, v10, v6
	v_max_f32_e32 v9, v9, v9
	v_mul_f32_e32 v10, 0x3e38aa3b, v100
	v_cndmask_b32_e32 v138, v241, v11, vcc
	v_max_f32_e32 v9, v9, v138
	v_cndmask_b32_e64 v8, v8, v9, s[24:25]
	v_add_u32_e32 v9, 0xd0, v116
	v_cmp_le_i32_e32 vcc, v9, v6
	v_max_f32_e32 v9, v8, v8
	v_mul_f32_e32 v11, 0x3e38aa3b, v101
	v_cndmask_b32_e32 v130, v241, v10, vcc
	v_max_f32_e32 v9, v9, v130
	v_add_u32_e32 v10, 0xd1, v116
	v_cndmask_b32_e64 v9, v8, v9, s[8:9]
	v_cmp_le_i32_e32 vcc, v10, v6
	v_max_f32_e32 v9, v9, v9
	v_add_u32_e32 v10, 0xd2, v116
	v_cndmask_b32_e32 v132, v241, v11, vcc
	v_max_f32_e32 v9, v9, v132
	v_cndmask_b32_e64 v9, v8, v9, s[8:9]
	v_mul_f32_e32 v11, 0x3e38aa3b, v102
	v_cmp_le_i32_e32 vcc, v10, v6
	v_max_f32_e32 v9, v9, v9
	v_add_u32_e32 v10, 0xd3, v116
	v_cndmask_b32_e32 v17, v241, v11, vcc
	v_max_f32_e32 v9, v9, v17
	v_cndmask_b32_e64 v9, v8, v9, s[8:9]
	v_mul_f32_e32 v11, 0x3e38aa3b, v103
	v_cmp_le_i32_e32 vcc, v10, v6
	v_max_f32_e32 v9, v9, v9
	v_mul_f32_e32 v10, 0x3e38aa3b, v104
	v_cndmask_b32_e32 v19, v241, v11, vcc
	v_max_f32_e32 v9, v9, v19
	v_cndmask_b32_e64 v8, v8, v9, s[8:9]
	v_add_u32_e32 v9, 0xe0, v116
	v_cmp_le_i32_e32 vcc, v9, v6
	v_max_f32_e32 v9, v8, v8
	v_mul_f32_e32 v11, 0x3e38aa3b, v105
	v_cndmask_b32_e32 v14, v241, v10, vcc
	v_max_f32_e32 v9, v9, v14
	v_add_u32_e32 v10, 0xe1, v116
	v_cndmask_b32_e64 v9, v8, v9, s[22:23]
	v_cmp_le_i32_e32 vcc, v10, v6
	v_max_f32_e32 v9, v9, v9
	v_add_u32_e32 v10, 0xe2, v116
	v_cndmask_b32_e32 v15, v241, v11, vcc
	v_max_f32_e32 v9, v9, v15
	v_cndmask_b32_e64 v9, v8, v9, s[22:23]
	v_mul_f32_e32 v11, 0x3e38aa3b, v106
	v_cmp_le_i32_e32 vcc, v10, v6
	v_max_f32_e32 v9, v9, v9
	v_add_u32_e32 v10, 0xe3, v116
	v_cndmask_b32_e32 v12, v241, v11, vcc
	v_max_f32_e32 v9, v9, v12
	v_cndmask_b32_e64 v9, v8, v9, s[22:23]
	v_mul_f32_e32 v11, 0x3e38aa3b, v107
	v_cmp_le_i32_e32 vcc, v10, v6
	v_max_f32_e32 v9, v9, v9
	v_cndmask_b32_e64 v131, v51, v131, s[38:39]
	v_cndmask_b32_e32 v13, v241, v11, vcc
	v_max_f32_e32 v9, v9, v13
	v_cndmask_b32_e64 v127, v8, v9, s[22:23]
	v_add_u32_e32 v8, 0xf0, v116
	v_mul_f32_e32 v9, 0x3e38aa3b, v108
	v_cmp_le_i32_e32 vcc, v8, v6
	v_max_f32_e32 v8, v127, v127
	v_mul_f32_e32 v11, 0x3e38aa3b, v109
	v_cndmask_b32_e32 v10, v241, v9, vcc
	v_max_f32_e32 v8, v8, v10
	v_add_u32_e32 v9, 0xf1, v116
	v_cndmask_b32_e64 v8, v127, v8, s[6:7]
	v_cmp_le_i32_e32 vcc, v9, v6
	v_max_f32_e32 v8, v8, v8
	v_cndmask_b32_e64 v143, v55, v143, s[20:21]
	v_cndmask_b32_e32 v11, v241, v11, vcc
	v_max_f32_e32 v8, v8, v11
	v_cndmask_b32_e64 v9, v127, v8, s[6:7]
	v_add_u32_e32 v8, 0xf2, v116
	v_cmp_le_i32_e32 vcc, v8, v6
	v_max_f32_e32 v9, v9, v9
	v_cndmask_b32_e64 v150, v92, v150, s[10:11]
	v_cndmask_b32_e32 v8, v241, v133, vcc
	v_max_f32_e32 v9, v9, v8
	v_cndmask_b32_e64 v133, v127, v9, s[6:7]
	v_add_u32_e32 v9, 0xf3, v116
	v_cmp_le_i32_e32 vcc, v9, v6
	v_max_f32_e32 v6, v133, v133
	v_cndmask_b32_e64 v151, v93, v151, s[10:11]
	v_cndmask_b32_e32 v9, v241, v134, vcc
	v_max_f32_e32 v6, v6, v9
	v_cndmask_b32_e64 v6, v127, v6, s[6:7]
	v_lshlrev_b32_e32 v127, 2, v115
	v_xor_b32_e32 v216, 64, v127
	ds_bpermute_b32 v133, v216, v6
	v_max_f32_e32 v6, v6, v6
	v_xor_b32_e32 v217, 0x80, v127
	v_cndmask_b32_e64 v148, v94, v148, s[10:11]
	v_cndmask_b32_e64 v149, v95, v149, s[10:11]
	s_waitcnt lgkmcnt(0)
	v_max_f32_e32 v133, v133, v133
	v_max_f32_e32 v6, v6, v133
	ds_bpermute_b32 v133, v217, v6
	v_cndmask_b32_e64 v139, v96, v139, s[24:25]
	v_cndmask_b32_e64 v147, v97, v147, s[24:25]
	v_cndmask_b32_e64 v135, v98, v135, s[24:25]
	v_cndmask_b32_e64 v138, v99, v138, s[24:25]
	s_waitcnt lgkmcnt(0)
	v_max_f32_e32 v133, v133, v133
	v_max_f32_e32 v133, v6, v133
	v_cndmask_b32_e64 v6, v48, v7, s[38:39]
	v_sub_f32_e32 v7, v6, v133
	v_exp_f32_e32 v7, v7
	v_sub_f32_e32 v134, v16, v133
	v_exp_f32_e32 v134, v134
	v_cmp_lt_f32_e32 vcc, s89, v6
	v_cndmask_b32_e64 v130, v100, v130, s[8:9]
	v_cndmask_b32_e64 v132, v101, v132, s[8:9]
	v_cndmask_b32_e32 v6, 0, v7, vcc
	v_cmp_lt_f32_e32 vcc, s89, v16
	v_add_f32_e32 v169, 0, v6
	v_cndmask_b32_e64 v17, v102, v17, s[8:9]
	v_cndmask_b32_e32 v7, 0, v134, vcc
	v_sub_f32_e32 v134, v18, v133
	v_add_f32_e32 v16, v169, v7
	v_exp_f32_e32 v134, v134
	v_sub_f32_e32 v169, v131, v133
	v_exp_f32_e32 v169, v169
	v_cmp_lt_f32_e32 vcc, s89, v18
	v_cndmask_b32_e64 v19, v103, v19, s[8:9]
	v_cndmask_b32_e64 v14, v104, v14, s[22:23]
	v_cndmask_b32_e32 v18, 0, v134, vcc
	v_cmp_lt_f32_e32 vcc, s89, v131
	v_add_f32_e32 v16, v16, v18
	v_cndmask_b32_e64 v15, v105, v15, s[22:23]
	v_cndmask_b32_e32 v134, 0, v169, vcc
	v_add_f32_e32 v16, v16, v134
	v_cndmask_b32_e64 v169, 0, v16, s[38:39]
	v_cndmask_b32_e64 v16, v52, v140, s[20:21]
	v_sub_f32_e32 v131, v16, v133
	v_cndmask_b32_e64 v140, v53, v141, s[20:21]
	v_exp_f32_e32 v131, v131
	v_sub_f32_e32 v141, v140, v133
	v_exp_f32_e32 v141, v141
	v_cmp_lt_f32_e32 vcc, s89, v16
	v_cndmask_b32_e64 v12, v106, v12, s[22:23]
	v_cndmask_b32_e64 v13, v107, v13, s[22:23]
	v_cndmask_b32_e32 v16, 0, v131, vcc
	v_cmp_lt_f32_e32 vcc, s89, v140
	v_add_f32_e32 v170, v16, v169
	v_cndmask_b32_e64 v10, v108, v10, s[6:7]
	v_cndmask_b32_e32 v131, 0, v141, vcc
	v_cndmask_b32_e64 v141, v54, v142, s[20:21]
	v_sub_f32_e32 v142, v141, v133
	v_add_f32_e32 v140, v131, v170
	v_exp_f32_e32 v142, v142
	v_sub_f32_e32 v170, v143, v133
	v_exp_f32_e32 v170, v170
	v_cmp_lt_f32_e32 vcc, s89, v141
	v_cndmask_b32_e64 v11, v109, v11, s[6:7]
	v_cndmask_b32_e64 v8, v110, v8, s[6:7]
	v_cndmask_b32_e32 v204, 0, v142, vcc
	v_cmp_lt_f32_e32 vcc, s89, v143
	v_add_f32_e32 v140, v204, v140
	v_cndmask_b32_e64 v142, v57, v145, s[36:37]
	v_cndmask_b32_e32 v205, 0, v170, vcc
	v_add_f32_e32 v140, v205, v140
	v_cndmask_b32_e64 v169, v169, v140, s[20:21]
	v_cndmask_b32_e64 v140, v56, v144, s[36:37]
	v_sub_f32_e32 v141, v140, v133
	v_exp_f32_e32 v141, v141
	v_sub_f32_e32 v143, v142, v133
	v_exp_f32_e32 v143, v143
	v_cmp_lt_f32_e32 vcc, s89, v140
	v_cndmask_b32_e64 v145, v59, v152, s[36:37]
	v_cndmask_b32_e64 v9, v111, v9, s[6:7]
	v_cndmask_b32_e32 v140, 0, v141, vcc
	v_cmp_lt_f32_e32 vcc, s89, v142
	v_add_f32_e32 v144, v140, v169
	v_cndmask_b32_e64 v7, v49, v7, s[38:39]
	v_cndmask_b32_e32 v141, 0, v143, vcc
	v_cndmask_b32_e64 v143, v58, v146, s[36:37]
	v_add_f32_e32 v142, v141, v144
	v_sub_f32_e32 v144, v143, v133
	v_exp_f32_e32 v144, v144
	v_sub_f32_e32 v146, v145, v133
	v_exp_f32_e32 v146, v146
	v_cmp_lt_f32_e32 vcc, s89, v143
	v_cndmask_b32_e64 v6, v48, v6, s[38:39]
	s_nop 0
	v_cndmask_b32_e32 v143, 0, v144, vcc
	v_cmp_lt_f32_e32 vcc, s89, v145
	v_add_f32_e32 v144, v143, v142
	s_nop 0
	v_cndmask_b32_e32 v142, 0, v146, vcc
	v_add_f32_e32 v144, v142, v144
	v_cndmask_b32_e64 v152, v169, v144, s[36:37]
	v_cndmask_b32_e64 v144, v60, v153, s[18:19]
	v_sub_f32_e32 v145, v144, v133
	v_cndmask_b32_e64 v146, v61, v154, s[18:19]
	v_exp_f32_e32 v145, v145
	v_sub_f32_e32 v153, v146, v133
	v_exp_f32_e32 v153, v153
	v_cmp_lt_f32_e32 vcc, s89, v144
	s_nop 1
	v_cndmask_b32_e32 v144, 0, v145, vcc
	v_cmp_lt_f32_e32 vcc, s89, v146
	v_add_f32_e32 v154, v144, v152
	v_cndmask_b32_e64 v146, v62, v155, s[18:19]
	v_cndmask_b32_e32 v145, 0, v153, vcc
	v_add_f32_e32 v153, v145, v154
	v_sub_f32_e32 v154, v146, v133
	v_cndmask_b32_e64 v155, v63, v156, s[18:19]
	v_exp_f32_e32 v154, v154
	v_sub_f32_e32 v156, v155, v133
	v_exp_f32_e32 v156, v156
	v_cmp_lt_f32_e32 vcc, s89, v146
	s_nop 1
	v_cndmask_b32_e32 v146, 0, v154, vcc
	v_cmp_lt_f32_e32 vcc, s89, v155
	v_add_f32_e32 v153, v146, v153
	v_cndmask_b32_e64 v155, v65, v158, s[34:35]
	v_cndmask_b32_e32 v171, 0, v156, vcc
	v_add_f32_e32 v153, v171, v153
	v_cndmask_b32_e64 v152, v152, v153, s[18:19]
	v_cndmask_b32_e64 v153, v64, v157, s[34:35]
	v_sub_f32_e32 v154, v153, v133
	v_exp_f32_e32 v154, v154
	v_sub_f32_e32 v156, v155, v133
	v_cmp_lt_f32_e32 vcc, s89, v153
	v_exp_f32_e32 v157, v156
	v_cndmask_b32_e64 v158, v67, v160, s[34:35]
	v_cndmask_b32_e32 v156, 0, v154, vcc
	v_cndmask_b32_e64 v154, v66, v159, s[34:35]
	v_cmp_lt_f32_e32 vcc, s89, v155
	v_sub_f32_e32 v155, v154, v133
	v_exp_f32_e32 v155, v155
	v_sub_f32_e32 v159, v158, v133
	v_exp_f32_e32 v160, v159
	v_add_f32_e32 v153, v156, v152
	v_cndmask_b32_e32 v157, 0, v157, vcc
	v_cmp_lt_f32_e32 vcc, s89, v154
	v_add_f32_e32 v153, v157, v153
	s_nop 0
	v_cndmask_b32_e32 v159, 0, v155, vcc
	v_cmp_lt_f32_e32 vcc, s89, v158
	v_add_f32_e32 v153, v159, v153
	v_cndmask_b32_e64 v155, v69, v162, s[16:17]
	v_cndmask_b32_e32 v158, 0, v160, vcc
	v_add_f32_e32 v153, v158, v153
	v_cndmask_b32_e64 v152, v152, v153, s[34:35]
	v_cndmask_b32_e64 v153, v68, v161, s[16:17]
	v_sub_f32_e32 v154, v153, v133
	v_exp_f32_e32 v154, v154
	v_sub_f32_e32 v160, v155, v133
	v_cmp_lt_f32_e32 vcc, s89, v153
	v_exp_f32_e32 v161, v160
	v_cndmask_b32_e64 v162, v71, v164, s[16:17]
	v_cndmask_b32_e32 v160, 0, v154, vcc
	v_cndmask_b32_e64 v154, v70, v163, s[16:17]
	v_cmp_lt_f32_e32 vcc, s89, v155
	v_sub_f32_e32 v155, v154, v133
	v_exp_f32_e32 v155, v155
	v_sub_f32_e32 v163, v162, v133
	v_exp_f32_e32 v163, v163
	v_add_f32_e32 v153, v160, v152
	v_cndmask_b32_e32 v161, 0, v161, vcc
	v_cmp_lt_f32_e32 vcc, s89, v154
	v_add_f32_e32 v153, v161, v153
	v_cndmask_b32_e64 v164, v75, v168, s[30:31]
	v_cndmask_b32_e32 v170, 0, v155, vcc
	v_cmp_lt_f32_e32 vcc, s89, v162
	v_add_f32_e32 v153, v170, v153
	v_cndmask_b32_e64 v155, v73, v166, s[30:31]
	v_cndmask_b32_e32 v169, 0, v163, vcc
	v_add_f32_e32 v153, v169, v153
	v_cndmask_b32_e64 v152, v152, v153, s[16:17]
	v_cndmask_b32_e64 v153, v72, v165, s[30:31]
	v_sub_f32_e32 v154, v153, v133
	v_exp_f32_e32 v154, v154
	v_sub_f32_e32 v162, v155, v133
	v_cmp_lt_f32_e32 vcc, s89, v153
	v_exp_f32_e32 v163, v162
	v_sub_f32_e32 v165, v164, v133
	v_cndmask_b32_e32 v162, 0, v154, vcc
	v_cndmask_b32_e64 v154, v74, v167, s[30:31]
	v_cmp_lt_f32_e32 vcc, s89, v155
	v_sub_f32_e32 v155, v154, v133
	v_exp_f32_e32 v155, v155
	v_exp_f32_e32 v166, v165
	v_add_f32_e32 v153, v162, v152
	v_cndmask_b32_e32 v163, 0, v163, vcc
	v_cmp_lt_f32_e32 vcc, s89, v154
	v_add_f32_e32 v153, v163, v153
	s_nop 0
	v_cndmask_b32_e32 v165, 0, v155, vcc
	v_cmp_lt_f32_e32 vcc, s89, v164
	v_add_f32_e32 v153, v165, v153
	v_cndmask_b32_e64 v155, v77, v173, s[14:15]
	v_cndmask_b32_e32 v164, 0, v166, vcc
	v_add_f32_e32 v153, v164, v153
	v_cndmask_b32_e64 v152, v152, v153, s[30:31]
	v_cndmask_b32_e64 v153, v76, v172, s[14:15]
	v_sub_f32_e32 v154, v153, v133
	v_exp_f32_e32 v154, v154
	v_sub_f32_e32 v166, v155, v133
	v_cmp_lt_f32_e32 vcc, s89, v153
	v_exp_f32_e32 v167, v166
	v_cndmask_b32_e64 v172, v79, v175, s[14:15]
	v_cndmask_b32_e32 v166, 0, v154, vcc
	v_cndmask_b32_e64 v154, v78, v174, s[14:15]
	v_cmp_lt_f32_e32 vcc, s89, v155
	v_sub_f32_e32 v155, v154, v133
	v_exp_f32_e32 v155, v155
	v_sub_f32_e32 v168, v172, v133
	v_exp_f32_e32 v173, v168
	v_add_f32_e32 v153, v166, v152
	v_cndmask_b32_e32 v167, 0, v167, vcc
	v_cmp_lt_f32_e32 vcc, s89, v154
	v_add_f32_e32 v153, v167, v153
	v_cndmask_b32_e64 v174, v83, v179, s[28:29]
	v_cndmask_b32_e32 v168, 0, v155, vcc
	v_cmp_lt_f32_e32 vcc, s89, v172
	v_add_f32_e32 v153, v168, v153
	v_cndmask_b32_e64 v155, v81, v177, s[28:29]
	v_cndmask_b32_e32 v187, 0, v173, vcc
	v_add_f32_e32 v153, v187, v153
	v_cndmask_b32_e64 v152, v152, v153, s[14:15]
	v_cndmask_b32_e64 v153, v80, v176, s[28:29]
	v_sub_f32_e32 v154, v153, v133
	v_exp_f32_e32 v154, v154
	v_sub_f32_e32 v172, v155, v133
	v_cmp_lt_f32_e32 vcc, s89, v153
	v_exp_f32_e32 v173, v172
	v_sub_f32_e32 v175, v174, v133
	v_cndmask_b32_e32 v172, 0, v154, vcc
	v_cndmask_b32_e64 v154, v82, v178, s[28:29]
	v_cmp_lt_f32_e32 vcc, s89, v155
	v_sub_f32_e32 v155, v154, v133
	v_exp_f32_e32 v155, v155
	v_exp_f32_e32 v176, v175
	v_add_f32_e32 v153, v172, v152
	v_cndmask_b32_e32 v173, 0, v173, vcc
	v_cmp_lt_f32_e32 vcc, s89, v154
	v_add_f32_e32 v153, v173, v153
	v_cndmask_b32_e64 v178, v87, v183, s[12:13]
	v_cndmask_b32_e32 v175, 0, v155, vcc
	v_cmp_lt_f32_e32 vcc, s89, v174
	v_add_f32_e32 v153, v175, v153
	v_cndmask_b32_e64 v155, v85, v181, s[12:13]
	v_cndmask_b32_e32 v174, 0, v176, vcc
	v_add_f32_e32 v153, v174, v153
	v_cndmask_b32_e64 v152, v152, v153, s[28:29]
	v_cndmask_b32_e64 v153, v84, v180, s[12:13]
	v_sub_f32_e32 v154, v153, v133
	v_exp_f32_e32 v154, v154
	v_sub_f32_e32 v176, v155, v133
	v_cmp_lt_f32_e32 vcc, s89, v153
	v_exp_f32_e32 v177, v176
	v_sub_f32_e32 v179, v178, v133
	v_cndmask_b32_e32 v176, 0, v154, vcc
	v_cndmask_b32_e64 v154, v86, v182, s[12:13]
	v_cmp_lt_f32_e32 vcc, s89, v155
	v_sub_f32_e32 v155, v154, v133
	v_exp_f32_e32 v155, v155
	v_exp_f32_e32 v179, v179
	v_add_f32_e32 v153, v176, v152
	v_cndmask_b32_e32 v177, 0, v177, vcc
	v_cmp_lt_f32_e32 vcc, s89, v154
	v_add_f32_e32 v153, v177, v153
	v_cndmask_b32_e64 v180, v91, v190, s[26:27]
	v_cndmask_b32_e32 v186, 0, v155, vcc
	v_cmp_lt_f32_e32 vcc, s89, v178
	v_add_f32_e32 v153, v186, v153
	v_cndmask_b32_e64 v155, v89, v188, s[26:27]
	v_cndmask_b32_e32 v185, 0, v179, vcc
	v_add_f32_e32 v153, v185, v153
	v_cndmask_b32_e64 v152, v152, v153, s[12:13]
	v_cndmask_b32_e64 v153, v88, v184, s[26:27]
	v_sub_f32_e32 v154, v153, v133
	v_exp_f32_e32 v154, v154
	v_sub_f32_e32 v178, v155, v133
	v_cmp_lt_f32_e32 vcc, s89, v153
	v_exp_f32_e32 v179, v178
	v_sub_f32_e32 v181, v180, v133
	v_cndmask_b32_e32 v178, 0, v154, vcc
	v_cndmask_b32_e64 v154, v90, v189, s[26:27]
	v_cmp_lt_f32_e32 vcc, s89, v155
	v_sub_f32_e32 v155, v154, v133
	v_exp_f32_e32 v155, v155
	v_exp_f32_e32 v182, v181
	v_add_f32_e32 v153, v178, v152
	v_cndmask_b32_e32 v179, 0, v179, vcc
	v_cmp_lt_f32_e32 vcc, s89, v154
	v_add_f32_e32 v153, v179, v153
	v_sub_f32_e32 v154, v151, v133
	v_cndmask_b32_e32 v181, 0, v155, vcc
	v_cmp_lt_f32_e32 vcc, s89, v180
	v_add_f32_e32 v153, v181, v153
	v_exp_f32_e32 v154, v154
	v_cndmask_b32_e32 v180, 0, v182, vcc
	v_add_f32_e32 v153, v180, v153
	v_cndmask_b32_e64 v152, v152, v153, s[26:27]
	v_sub_f32_e32 v153, v150, v133
	v_exp_f32_e32 v153, v153
	v_cmp_lt_f32_e32 vcc, s89, v150
	s_nop 1
	v_cndmask_b32_e32 v182, 0, v153, vcc
	v_cmp_lt_f32_e32 vcc, s89, v151
	v_sub_f32_e32 v151, v148, v133
	v_exp_f32_e32 v151, v151
	v_cndmask_b32_e32 v183, 0, v154, vcc
	v_sub_f32_e32 v153, v149, v133
	v_cmp_lt_f32_e32 vcc, s89, v148
	v_exp_f32_e32 v153, v153
	v_add_f32_e32 v150, v182, v152
	v_cndmask_b32_e32 v184, 0, v151, vcc
	v_cmp_lt_f32_e32 vcc, s89, v149
	v_sub_f32_e32 v149, v139, v133
	v_exp_f32_e32 v149, v149
	v_add_f32_e32 v150, v183, v150
	v_add_f32_e32 v148, v184, v150
	v_cndmask_b32_e32 v223, 0, v153, vcc
	v_sub_f32_e32 v150, v147, v133
	v_cmp_lt_f32_e32 vcc, s89, v139
	v_exp_f32_e32 v150, v150
	v_add_f32_e32 v148, v223, v148
	v_cndmask_b32_e32 v188, 0, v149, vcc
	v_cmp_lt_f32_e32 vcc, s89, v147
	v_sub_f32_e32 v147, v135, v133
	v_exp_f32_e32 v147, v147
	v_cndmask_b32_e32 v189, 0, v150, vcc
	v_sub_f32_e32 v149, v138, v133
	v_cmp_lt_f32_e32 vcc, s89, v135
	v_exp_f32_e32 v149, v149
	v_cndmask_b32_e64 v148, v152, v148, s[10:11]
	v_cndmask_b32_e32 v191, 0, v147, vcc
	v_cmp_lt_f32_e32 vcc, s89, v138
	v_sub_f32_e32 v138, v130, v133
	v_exp_f32_e32 v138, v138
	v_add_f32_e32 v139, v188, v148
	v_add_f32_e32 v139, v189, v139
	v_add_f32_e32 v135, v191, v139
	v_cndmask_b32_e32 v190, 0, v149, vcc
	v_sub_f32_e32 v139, v132, v133
	v_cmp_lt_f32_e32 vcc, s89, v130
	v_exp_f32_e32 v139, v139
	v_add_f32_e32 v135, v190, v135
	v_cndmask_b32_e32 v192, 0, v138, vcc
	v_cmp_lt_f32_e32 vcc, s89, v132
	v_sub_f32_e32 v132, v17, v133
	v_exp_f32_e32 v132, v132
	v_cndmask_b32_e32 v193, 0, v139, vcc
	v_sub_f32_e32 v138, v19, v133
	v_cmp_lt_f32_e32 vcc, s89, v17
	v_exp_f32_e32 v138, v138
	v_cndmask_b32_e64 v135, v148, v135, s[24:25]
	v_cndmask_b32_e32 v222, 0, v132, vcc
	v_cmp_lt_f32_e32 vcc, s89, v19
	v_sub_f32_e32 v19, v14, v133
	v_exp_f32_e32 v19, v19
	v_add_f32_e32 v130, v192, v135
	v_add_f32_e32 v130, v193, v130
	v_add_f32_e32 v17, v222, v130
	v_cndmask_b32_e32 v221, 0, v138, vcc
	v_sub_f32_e32 v130, v15, v133
	v_cmp_lt_f32_e32 vcc, s89, v14
	v_exp_f32_e32 v130, v130
	v_add_f32_e32 v17, v221, v17
	v_cndmask_b32_e32 v194, 0, v19, vcc
	v_cmp_lt_f32_e32 vcc, s89, v15
	v_sub_f32_e32 v15, v12, v133
	v_exp_f32_e32 v15, v15
	v_cndmask_b32_e32 v195, 0, v130, vcc
	v_sub_f32_e32 v19, v13, v133
	v_cmp_lt_f32_e32 vcc, s89, v12
	v_exp_f32_e32 v19, v19
	v_cndmask_b32_e64 v17, v135, v17, s[8:9]
	v_cndmask_b32_e32 v197, 0, v15, vcc
	v_cmp_lt_f32_e32 vcc, s89, v13
	v_sub_f32_e32 v13, v10, v133
	v_exp_f32_e32 v13, v13
	v_add_f32_e32 v14, v194, v17
	v_add_f32_e32 v14, v195, v14
	v_add_f32_e32 v12, v197, v14
	v_cndmask_b32_e32 v196, 0, v19, vcc
	v_sub_f32_e32 v14, v11, v133
	v_cmp_lt_f32_e32 vcc, s89, v10
	v_exp_f32_e32 v14, v14
	v_add_f32_e32 v12, v196, v12
	v_cndmask_b32_e32 v198, 0, v13, vcc
	v_cmp_lt_f32_e32 vcc, s89, v11
	v_sub_f32_e32 v11, v8, v133
	v_exp_f32_e32 v11, v11
	v_sub_f32_e32 v13, v9, v133
	v_exp_f32_e32 v13, v13
	v_cndmask_b32_e64 v12, v17, v12, s[22:23]
	v_add_f32_e32 v10, v198, v12
	v_cndmask_b32_e32 v199, 0, v14, vcc
	v_cmp_lt_f32_e32 vcc, s89, v8
	v_add_f32_e32 v10, v199, v10
	s_nop 0
	v_cndmask_b32_e32 v220, 0, v11, vcc
	v_cmp_lt_f32_e32 vcc, s89, v9
	v_add_f32_e32 v8, v220, v10
	s_nop 0
	v_cndmask_b32_e32 v219, 0, v13, vcc
	v_add_f32_e32 v8, v219, v8
	v_cndmask_b32_e64 v8, v12, v8, s[6:7]
	ds_bpermute_b32 v9, v216, v8
	s_waitcnt lgkmcnt(0)
	v_add_f32_e32 v8, v8, v9
	ds_bpermute_b32 v9, v217, v8
	s_waitcnt lgkmcnt(0)
	v_add_f32_e32 v8, v8, v9
	v_div_scale_f32 v9, s[40:41], v8, v8, 1.0
	v_rcp_f32_e32 v10, v9
	v_readlane_b32 s40, v255, 33
	v_readlane_b32 s41, v255, 34
	v_fma_f32 v11, -v9, v10, 1.0
	v_fmac_f32_e32 v10, v11, v10
	v_div_scale_f32 v11, vcc, 1.0, v8, 1.0
	v_mul_f32_e32 v12, v11, v10
	v_fma_f32 v13, -v9, v12, v11
	v_fmac_f32_e32 v12, v13, v10
	v_fma_f32 v9, -v9, v12, v11
	v_div_fmas_f32 v9, v9, v10, v12
	v_div_fixup_f32 v9, v9, v8, 1.0
	v_cmp_lt_f32_e32 vcc, 0, v8
	v_cndmask_b32_e64 v8, v50, v18, s[38:39]
	v_lshl_add_u64 v[148:149], v[4:5], 1, s[40:41]
	v_cndmask_b32_e32 v152, 0, v9, vcc
	v_cndmask_b32_e64 v9, v51, v134, s[38:39]
	v_pk_mul_f32 v[6:7], v[152:153], v[6:7] op_sel_hi:[0,1]
	v_pk_mul_f32 v[8:9], v[152:153], v[8:9] op_sel_hi:[0,1]
	v_cndmask_b32_e64 v135, v51, v9, s[38:39]
	v_cndmask_b32_e64 v134, v50, v8, s[38:39]
	v_cndmask_b32_e64 v139, v49, v7, s[38:39]
	v_cndmask_b32_e64 v138, v48, v6, s[38:39]
	v_cndmask_b32_e64 v7, v55, v205, s[20:21]
	v_cndmask_b32_e64 v6, v54, v204, s[20:21]
	v_cndmask_b32_e64 v9, v53, v131, s[20:21]
	v_cndmask_b32_e64 v8, v52, v16, s[20:21]
	v_pk_mul_f32 v[8:9], v[152:153], v[8:9] op_sel_hi:[0,1]
	v_pk_mul_f32 v[6:7], v[152:153], v[6:7] op_sel_hi:[0,1]
	v_lshlrev_b32_e32 v4, 8, v121
	v_cndmask_b32_e64 v5, 0, 1, s[38:39]
	v_cndmask_b32_e64 v131, v55, v7, s[20:21]
	v_cndmask_b32_e64 v130, v54, v6, s[20:21]
	v_cndmask_b32_e64 v133, v53, v9, s[20:21]
	v_cndmask_b32_e64 v132, v52, v8, s[20:21]
	v_cmp_ne_u32_e64 s[40:41], 1, v5
	s_andn2_b64 vcc, exec, s[38:39]
	v_lshlrev_b32_e32 v150, 1, v4
	s_cbranch_vccnz .LBB0_449
	v_mov_b32_e32 v151, v137
	v_lshl_add_u64 v[154:155], v[148:149], 0, v[150:151]
	v_add_co_u32_e32 v8, vcc, s83, v154
	global_load_dwordx4 v[4:7], v[154:155], off
	s_nop 0
	v_addc_co_u32_e32 v9, vcc, 0, v155, vcc
	v_add_co_u32_e32 v12, vcc, 0x4000, v154
	global_load_dwordx4 v[8:11], v[8:9], off
	s_nop 0
	v_addc_co_u32_e32 v13, vcc, 0, v155, vcc
	v_add_co_u32_e32 v154, vcc, 0x6000, v154
	global_load_dwordx4 v[12:15], v[12:13], off
	s_nop 0
	v_addc_co_u32_e32 v155, vcc, 0, v155, vcc
	global_load_dwordx4 v[224:227], v[154:155], off
	v_cvt_pk_bf16_f32 v16, v138, v139
	v_cvt_pk_bf16_f32 v17, v134, v135
	v_cvt_pk_bf16_f32 v18, v132, v133
	v_cvt_pk_bf16_f32 v19, v130, v131
	s_waitcnt vmcnt(0) lgkmcnt(0)
	s_nop 0
	v_mfma_f32_16x16x32_bf16 v[4:7], v[4:7], v[16:19], 0
	v_mfma_f32_16x16x32_bf16 v[8:11], v[8:11], v[16:19], 0
	v_mfma_f32_16x16x32_bf16 v[12:15], v[12:15], v[16:19], 0
	v_mfma_f32_16x16x32_bf16 v[16:19], v[224:227], v[16:19], 0
	s_branch .LBB0_450

.LBB0_585:
	s_cmp_eq_u64 s[14:15], 0
	s_cselect_b64 s[40:41], -1, 0
	s_cmp_lg_u64 s[14:15], 0
	s_mov_b64 s[52:53], 0
	s_cselect_b64 s[54:55], -1, 0
	s_and_b64 vcc, exec, s[40:41]
	s_mov_b32 s59, 0
	s_cbranch_vccnz .LBB0_587
	s_ff1_i32_b64 s59, s[14:15]
	s_waitcnt vmcnt(0)
	v_lshl_add_u32 v40, s59, 6, v120
	s_add_u32 s6, s14, -1
	v_ashrrev_i32_e32 v41, 31, v40
	s_addc_u32 s7, s15, -1
	v_lshlrev_b64 v[40:41], 7, v[40:41]
	s_lshl_b32 s92, s59, 7
	v_lshl_add_u64 v[40:41], v[132:133], 0, v[40:41]
	v_lshl_add_u64 v[42:43], v[128:129], 0, s[92:93]
	global_load_dwordx4 v[44:47], v[40:41], off
	s_nop 0
	global_load_dwordx4 v[40:43], v[42:43], off
	s_and_b64 s[52:53], s[6:7], s[14:15]

.LBB0_603:
	s_waitcnt vmcnt(0)
	ds_bpermute_b32 v40, v216, v121
	s_sub_i32 s6, 0xde0, s57
	s_lshr_b32 s6, s6, 6
	s_cmpk_gt_u32 s58, 0x1ff
	s_cselect_b32 s45, s6, 0
	s_lshl_b32 s92, s45, 6
	s_waitcnt lgkmcnt(0)
	v_add_f32_e32 v121, v121, v40
	v_add_u32_e32 v40, s92, v120
	v_ashrrev_i32_e32 v41, 31, v40
	v_lshlrev_b64 v[40:41], 7, v[40:41]
	v_lshl_add_u64 v[40:41], s[66:67], 0, v[40:41]
	v_readlane_b32 s6, v255, 37
	v_lshl_add_u64 v[40:41], v[40:41], 0, v[136:137]
	v_readlane_b32 s7, v255, 38
	global_load_dwordx4 v[42:45], v[40:41], off
	ds_bpermute_b32 v125, v217, v121
	v_lshl_add_u64 v[40:41], s[6:7], 0, v[122:123]
	v_lshl_add_u64 v[46:47], s[92:93], 1, v[40:41]
	v_lshl_add_u64 v[46:47], v[46:47], 0, v[136:137]
	global_load_dwordx4 v[46:49], v[46:47], off
	v_mov_b32_e32 v83, 0
	v_lshl_add_u32 v50, v130, 1, 0
	s_cmp_gt_u32 s45, s44
	v_mov_b32_e32 v82, v83
	v_mov_b32_e32 v81, v83
	v_mov_b32_e32 v80, v83
	v_mov_b32_e32 v95, v83
	v_mov_b32_e32 v94, v83
	v_mov_b32_e32 v93, v83
	v_mov_b32_e32 v92, v83
	v_mov_b32_e32 v107, v83
	v_mov_b32_e32 v106, v83
	v_mov_b32_e32 v105, v83
	v_mov_b32_e32 v104, v83
	v_mov_b32_e32 v111, v83
	v_mov_b32_e32 v110, v83
	v_mov_b32_e32 v109, v83
	v_mov_b32_e32 v108, v83
	v_mov_b32_e32 v151, v83
	s_waitcnt vmcnt(0) lgkmcnt(0)
	ds_write_b128 v50, v[42:45] offset:16384
	ds_write_b128 v50, v[46:49] offset:26624
	s_waitcnt lgkmcnt(0)
	s_barrier
	s_cbranch_scc1 .LBB0_385
	v_readlane_b32 s6, v255, 46
	v_lshl_add_u64 v[126:127], v[40:41], 0, v[136:137]
	v_mov_b32_e32 v124, 0
	v_add_u32_e32 v40, s6, v218
	v_sub_u32_e32 v40, v40, v135
	v_subrev_u32_e32 v40, s57, v40
	v_lshl_add_u64 v[122:123], s[66:67], 0, v[136:137]
	s_add_i32 s54, s56, 0xfffffe04
	v_add_u32_e32 v115, 64, v120
	v_subrev_u32_e32 v120, s92, v40
	v_mov_b32_e32 v136, 0xf149f2ca
	s_mov_b32 s55, 0
	v_mov_b32_e32 v144, 0
	v_mov_b32_e32 v145, v124
	v_mov_b32_e32 v146, 0
	v_mov_b32_e32 v147, v124
	v_mov_b32_e32 v140, 0
	v_mov_b32_e32 v141, v124
	v_mov_b32_e32 v142, 0
	v_mov_b32_e32 v143, v124
	v_mov_b32_e32 v134, 0
	v_mov_b32_e32 v135, v124
	v_mov_b32_e32 v138, 0
	v_mov_b32_e32 v139, v124
	v_mov_b32_e32 v128, 0
	v_mov_b32_e32 v129, v124
	v_mov_b32_e32 v132, 0
	v_mov_b32_e32 v133, v124
.LBB0_605:
	s_cmp_lt_u32 s45, s44
	s_cselect_b64 s[40:41], -1, 0
	s_cmp_ge_u32 s45, s44
	s_cselect_b64 s[38:39], -1, 0
	s_and_b64 vcc, exec, s[38:39]
	s_cbranch_vccnz .LBB0_607
	s_waitcnt vmcnt(0)
	v_add_u32_e32 v42, s92, v115
	v_ashrrev_i32_e32 v43, 31, v42
	v_lshlrev_b64 v[42:43], 7, v[42:43]
	v_lshl_add_u64 v[40:41], s[92:93], 1, v[126:127]
	v_lshl_add_u64 v[42:43], v[122:123], 0, v[42:43]
	global_load_dwordx4 v[44:47], v[42:43], off
	s_nop 0
	global_load_dwordx4 v[40:43], v[40:41], off offset:128

.LBB0_617:
	s_ashr_i32 s6, s45, 2
	s_max_i32 s6, s6, 0x80
	s_add_i32 s56, s45, 0xf0
	s_addk_i32 s6, 0xff80
	v_lshlrev_b32_e32 v16, 12, v111
	s_ashr_i32 s57, s56, 8
	s_lshr_b32 s58, s6, 6
	v_lshlrev_b64 v[92:93], 1, v[90:91]
	s_mov_b64 s[78:79], 0x40000
	s_movk_i32 s84, 0x121
	s_cmp_gt_i32 s58, s57
	v_lshl_add_u64 v[98:99], v[32:33], 0, v[92:93]
	v_lshlrev_b32_e32 v96, 1, v16
	v_lshlrev_b32_e32 v94, 13, v111
	s_cbranch_scc1 .LBB0_622
	v_add_co_u32_e32 v20, vcc, 0xc00000, v98
	v_readlane_b32 s7, v255, 47
	s_nop 0
	v_addc_co_u32_e32 v21, vcc, 0, v99, vcc
	global_load_dwordx4 v[16:19], v[20:21], off
	s_nop 0
	global_load_dwordx4 v[20:23], v[20:21], off offset:64
	v_lshl_or_b32 v136, v111, 9, s7
	v_readlane_b32 s10, v255, 48
	s_waitcnt vmcnt(0)
	v_lshl_add_u64 v[24:25], s[38:39], 0, v[136:137]
	s_mov_b64 s[8:9], 0xc00000
	v_mov_b32_e32 v97, v137
	v_readlane_b32 s11, v255, 49
	v_lshl_add_u64 v[100:101], v[24:25], 0, s[8:9]
	v_lshl_add_u64 v[24:25], s[52:53], 0, v[96:97]
	s_mov_b32 s11, s93
	s_mov_b32 s12, s10
	v_writelane_b32 v255, s12, 48
	v_lshl_add_u64 v[24:25], v[24:25], 0, s[10:11]
	v_lshl_add_u64 v[24:25], v[24:25], 0, v[92:93]
	v_writelane_b32 v255, s13, 49
	s_mov_b32 s41, s93
	s_lshr_b32 s92, s6, 6
	v_lshl_add_u64 v[102:103], v[24:25], 0, s[8:9]
	s_and_b32 s54, s6, 0xffffffc0
	s_lshl_b64 s[8:9], s[40:41], 19
	s_lshl_b64 s[6:7], s[92:93], 7
	v_readlane_b32 s10, v255, 44
	s_add_u32 s6, s10, s6
	v_readlane_b32 s10, v255, 45
	s_addc_u32 s7, s10, s7
	s_add_u32 s6, s6, s8
	v_mov_b32_e32 v95, v137
	s_addc_u32 s7, s7, s9
	v_lshl_add_u64 v[104:105], s[6:7], 0, v[94:95]
	s_lshl_b64 s[6:7], s[92:93], 15
	s_add_u32 s6, s8, s6
	v_ashrrev_i32_e32 v26, 2, v88
	v_lshlrev_b32_e32 v24, 2, v112
	s_addc_u32 s7, s9, s7
	v_add_u32_e32 v25, s54, v24
	v_sub_u32_e32 v24, v26, v24
	s_add_u32 s6, s74, s6
	v_subrev_u32_e32 v24, s54, v24
	s_addc_u32 s7, s75, s7
	v_sub_u32_e32 v97, v25, v26
	v_add_u32_e32 v116, 0xffffff9d, v24
	v_lshl_add_u64 v[106:107], s[6:7], 0, v[136:137]
	s_mov_b32 s92, s58
	s_branch .LBB0_620
.LBB0_619:
	v_lshl_add_u64 v[48:49], v[104:105], 0, v[92:93]
	v_add_co_u32_e32 v28, vcc, 0xc460000, v48
	v_lshl_add_u64 v[80:81], v[106:107], 0, v[92:93]
	s_nop 0
	v_addc_co_u32_e32 v29, vcc, 0, v49, vcc
	v_add_co_u32_e32 v36, vcc, 0xc440000, v48
	global_load_dwordx4 v[24:27], v[28:29], off offset:192
	s_nop 0
	global_load_dwordx4 v[28:31], v[28:29], off offset:128
	v_addc_co_u32_e32 v37, vcc, 0, v49, vcc
	v_add_co_u32_e32 v44, vcc, 0xc420000, v48
	global_load_dwordx4 v[32:35], v[36:37], off offset:192
	s_nop 0
	global_load_dwordx4 v[36:39], v[36:37], off offset:128
	v_addc_co_u32_e32 v45, vcc, 0, v49, vcc
	v_add_co_u32_e32 v52, vcc, 0xc400000, v48
	global_load_dwordx4 v[40:43], v[44:45], off offset:192
	s_nop 0
	global_load_dwordx4 v[44:47], v[44:45], off offset:128
	v_addc_co_u32_e32 v53, vcc, 0, v49, vcc
	v_add_co_u32_e32 v60, vcc, 0xa00e000, v80
	global_load_dwordx4 v[48:51], v[52:53], off offset:192
	s_nop 0
	global_load_dwordx4 v[52:55], v[52:53], off offset:128
	v_addc_co_u32_e32 v61, vcc, 0, v81, vcc
	v_add_co_u32_e32 v64, vcc, 0xa00c000, v80
	global_load_dwordx4 v[56:59], v[60:61], off offset:64
	global_load_dwordx4 v[68:71], v[60:61], off
	v_addc_co_u32_e32 v65, vcc, 0, v81, vcc
	v_add_co_u32_e32 v76, vcc, 0xa00a000, v80
	global_load_dwordx4 v[60:63], v[64:65], off offset:64
	global_load_dwordx4 v[72:75], v[64:65], off
	v_addc_co_u32_e32 v77, vcc, 0, v81, vcc
	v_add_co_u32_e32 v84, vcc, 0xa008000, v80
	global_load_dwordx4 v[64:67], v[76:77], off offset:64
	s_nop 0
	global_load_dwordx4 v[76:79], v[76:77], off
	v_addc_co_u32_e32 v85, vcc, 0, v81, vcc
	global_load_dwordx4 v[80:83], v[84:85], off offset:64
	s_nop 0
	global_load_dwordx4 v[84:87], v[84:85], off
	v_add_u32_e32 v95, 35, v116
	v_cmp_gt_u32_e64 s[22:23], s47, v95
	v_add_u32_e32 v95, 64, v97
	v_add_u32_e32 v122, 0xffffff90, v116
	v_add_u32_e32 v123, 0xffffff8f, v116
	v_cmp_gt_u32_e64 s[20:21], s88, v95
	v_add_u32_e32 v118, 0xffffffa0, v116
	v_add_u32_e32 v119, 0xffffff9f, v116
	v_cmp_gt_u32_e64 s[8:9], s88, v122
	v_cmp_gt_u32_e32 vcc, s88, v123
	v_cndmask_b32_e64 v95, 2, 0, s[20:21]
	v_cmp_gt_u32_e64 s[16:17], s88, v118
	v_cmp_gt_u32_e64 s[18:19], s88, v119
	v_cndmask_b32_e64 v122, 64, 0, s[8:9]
	v_cndmask_b32_e64 v123, v244, 0, vcc
	v_cndmask_b32_e64 v118, 4, 0, s[16:17]
	v_cndmask_b32_e64 v119, 8, 0, s[18:19]
	v_add_u32_e32 v120, 0xffffff92, v116
	v_add_u32_e32 v121, 0xffffff91, v116
	v_or3_b32 v95, v122, v123, v95
	v_cmp_gt_u32_e64 s[6:7], s88, v120
	v_cmp_gt_u32_e64 s[10:11], s88, v121
	v_or3_b32 v95, v118, v119, v95
	v_add_u32_e32 v118, 3, v116
	v_add_u32_e32 v119, 2, v116
	v_cndmask_b32_e64 v120, 16, 0, s[6:7]
	v_cndmask_b32_e64 v121, 32, 0, s[10:11]
	v_cmp_gt_u32_e64 s[14:15], s47, v118
	v_cmp_gt_u32_e64 s[12:13], s47, v119
	v_or3_b32 v95, v120, v121, v95
	v_cndmask_b32_e64 v118, 0, v245, s[14:15]
	v_cndmask_b32_e64 v119, 0, v240, s[12:13]
	v_or3_b32 v95, v118, v95, v119
	v_add_u32_e32 v118, 1, v116
	v_cmp_gt_u32_e64 s[24:25], s47, v118
	v_add_u32_e32 v120, -13, v116
	v_add_u32_e32 v121, -14, v116
	v_cndmask_b32_e64 v118, 0, v246, s[24:25]
	v_cmp_gt_u32_e64 s[24:25], s47, v116
	v_add_u32_e32 v122, -15, v116
	v_add_u32_e32 v123, -16, v116
	v_cndmask_b32_e64 v119, 0, v247, s[24:25]
	v_cmp_gt_u32_e64 s[24:25], s47, v120
	v_or_b32_e32 v118, v118, v119
	v_or_b32_e32 v119, v118, v95
	v_cndmask_b32_e64 v120, 0, v248, s[24:25]
	v_cmp_gt_u32_e64 s[24:25], s47, v121
	s_add_i32 s58, s58, 2
	s_min_i32 s92, s58, s57
	s_waitcnt vmcnt(0) lgkmcnt(0)
	v_mfma_f32_16x16x32_bf16 v[68:71], v[68:71], v[16:19], 0
	v_cndmask_b32_e64 v121, 0, v249, s[24:25]
	v_cmp_gt_u32_e64 s[24:25], s47, v122
	v_or_b32_e32 v120, v120, v121
	v_mfma_f32_16x16x32_bf16 v[84:87], v[84:87], v[16:19], 0
	v_cndmask_b32_e64 v122, 0, v250, s[24:25]
	v_cmp_gt_u32_e64 s[24:25], s47, v123
	v_or_b32_e32 v121, v120, v119
	v_mfma_f32_16x16x32_bf16 v[76:79], v[76:79], v[16:19], 0
	v_cndmask_b32_e64 v123, 0, v251, s[24:25]
	v_or_b32_e32 v122, v122, v123
	s_lshl_b32 s54, s92, 6
	v_mfma_f32_16x16x32_bf16 v[72:75], v[72:75], v[16:19], 0
	s_cmp_gt_i32 s58, s57
	v_add_u32_e32 v97, 0x80, v97
	v_add_u32_e32 v116, 0xffffff80, v116
	v_mfma_f32_16x16x32_bf16 v[80:83], v[80:83], v[20:23], v[84:87]
	v_mfma_f32_16x16x32_bf16 v[64:67], v[64:67], v[20:23], v[76:79]
	v_mfma_f32_16x16x32_bf16 v[60:63], v[60:63], v[20:23], v[72:75]
	v_mfma_f32_16x16x32_bf16 v[56:59], v[56:59], v[20:23], v[68:71]
	s_nop 4
	v_mul_f32_e32 v72, 0x3e38aa3b, v83
	v_bitop3_b32 v73, v118, s95, v95 bitop3:0xc8
	v_cndmask_b32_e64 v72, v72, v241, s[18:19]
	v_mul_f32_e32 v68, 0x3e38aa3b, v80
	v_mul_f32_e32 v69, 0x3e38aa3b, v81
	v_cndmask_b32_e64 v68, v241, v68, s[22:23]
	v_cndmask_b32_e64 v69, v69, v241, s[20:21]
	v_mul_f32_e32 v71, 0x3e38aa3b, v82
	v_max3_f32 v70, v68, s71, v69
	v_cndmask_b32_e64 v71, v71, v241, s[16:17]
	v_mul_f32_e32 v64, 0x3e38aa3b, v64
	v_mul_f32_e32 v65, 0x3e38aa3b, v65
	v_cmp_eq_u32_e64 s[36:37], 0, v73
	v_bitop3_b32 v73, v118, s48, v95 bitop3:0xc8
	v_max3_f32 v70, v70, v71, v72
	v_cndmask_b32_e64 v64, v64, v241, s[6:7]
	v_cndmask_b32_e64 v65, v65, v241, s[10:11]
	v_mul_f32_e32 v66, 0x3e38aa3b, v66
	v_mul_f32_e32 v67, 0x3e38aa3b, v67
	v_cmp_eq_u32_e64 s[26:27], 0, v73
	v_bitop3_b32 v73, v120, s90, v119 bitop3:0xc8
	v_max3_f32 v70, v70, v64, v65
	v_cndmask_b32_e64 v66, v66, v241, s[8:9]
	v_cndmask_b32_e32 v67, v67, v241, vcc
	v_mul_f32_e32 v60, 0x3e38aa3b, v60
	v_mul_f32_e32 v61, 0x3e38aa3b, v61
	v_cmp_eq_u32_e64 s[34:35], 0, v73
	v_bitop3_b32 v73, v120, s83, v119 bitop3:0xc8
	v_max3_f32 v70, v70, v66, v67
	v_cndmask_b32_e64 v60, v241, v60, s[14:15]
	v_cndmask_b32_e64 v61, v241, v61, s[12:13]
	v_mul_f32_e32 v62, 0x3e38aa3b, v62
	v_mul_f32_e32 v63, 0x3e38aa3b, v63
	v_cmp_eq_u32_e64 s[30:31], 0, v73
	v_bitop3_b32 v73, v122, s50, v121 bitop3:0xc8
	v_max3_f32 v70, v70, v60, v61
	v_cndmask_b32_e64 v62, v62, v241, s[36:37]
	v_cndmask_b32_e64 v63, v63, v241, s[26:27]
	v_mul_f32_e32 v56, 0x3e38aa3b, v56
	v_mul_f32_e32 v57, 0x3e38aa3b, v57
	v_cmp_eq_u32_e64 s[28:29], 0, v73
	v_bitop3_b32 v73, v122, s82, v121 bitop3:0xc8
	v_max3_f32 v70, v70, v62, v63
	v_cndmask_b32_e64 v56, v56, v241, s[34:35]
	v_cndmask_b32_e64 v57, v57, v241, s[30:31]
	v_mul_f32_e32 v58, 0x3e38aa3b, v58
	v_cmp_eq_u32_e64 s[24:25], 0, v73
	v_mul_f32_e32 v59, 0x3e38aa3b, v59
	v_max3_f32 v70, v70, v56, v57
	v_cndmask_b32_e64 v58, v58, v241, s[28:29]
	v_cndmask_b32_e64 v59, v59, v241, s[24:25]
	v_max3_f32 v70, v70, v58, v59
	ds_bpermute_b32 v73, v109, v70
	s_waitcnt lgkmcnt(0)
	v_max_f32_e32 v73, v73, v73
	v_max_f32_e32 v70, v70, v73
	ds_bpermute_b32 v73, v108, v70
	s_waitcnt lgkmcnt(0)
	v_max3_f32 v118, v117, v70, v73
	v_sub_f32_e32 v68, v68, v118
	v_exp_f32_e32 v68, v68
	v_sub_f32_e32 v69, v69, v118
	v_exp_f32_e32 v69, v69
	v_sub_f32_e32 v71, v71, v118
	v_exp_f32_e32 v71, v71
	v_sub_f32_e32 v72, v72, v118
	v_exp_f32_e32 v72, v72
	v_sub_f32_e32 v64, v64, v118
	v_cndmask_b32_e64 v68, 0, v68, s[22:23]
	v_exp_f32_e32 v64, v64
	v_sub_f32_e32 v65, v65, v118
	v_add_f32_e32 v73, 0, v68
	v_cndmask_b32_e64 v69, v69, 0, s[20:21]
	v_exp_f32_e32 v65, v65
	v_sub_f32_e32 v66, v66, v118
	v_sub_f32_e32 v57, v57, v118
	v_add_f32_e32 v73, v69, v73
	v_cndmask_b32_e64 v71, v71, 0, s[16:17]
	v_exp_f32_e32 v66, v66
	v_sub_f32_e32 v67, v67, v118
	v_exp_f32_e32 v57, v57
	v_add_f32_e32 v73, v71, v73
	v_cndmask_b32_e64 v72, v72, 0, s[18:19]
	v_exp_f32_e32 v67, v67
	v_sub_f32_e32 v60, v60, v118
	v_add_f32_e32 v73, v72, v73
	v_cndmask_b32_e64 v74, v64, 0, s[6:7]
	v_exp_f32_e32 v60, v60
	v_sub_f32_e32 v61, v61, v118
	v_add_f32_e32 v64, v74, v73
	v_cndmask_b32_e64 v65, v65, 0, s[10:11]
	v_exp_f32_e32 v61, v61
	v_sub_f32_e32 v62, v62, v118
	v_add_f32_e32 v64, v65, v64
	v_cndmask_b32_e64 v66, v66, 0, s[8:9]
	v_exp_f32_e32 v62, v62
	v_sub_f32_e32 v63, v63, v118
	v_cndmask_b32_e64 v75, v57, 0, s[30:31]
	v_sub_f32_e32 v57, v58, v118
	v_add_f32_e32 v64, v66, v64
	v_cndmask_b32_e64 v67, v67, 0, vcc
	v_exp_f32_e32 v63, v63
	v_sub_f32_e32 v56, v56, v118
	v_exp_f32_e32 v57, v57
	v_add_f32_e32 v64, v67, v64
	v_cndmask_b32_e64 v60, 0, v60, s[14:15]
	v_exp_f32_e32 v56, v56
	v_add_f32_e32 v64, v60, v64
	v_cndmask_b32_e64 v61, 0, v61, s[12:13]
	v_add_f32_e32 v64, v61, v64
	v_cndmask_b32_e64 v62, v62, 0, s[36:37]
	v_add_f32_e32 v64, v62, v64
	v_cndmask_b32_e64 v63, v63, 0, s[26:27]
	v_cndmask_b32_e64 v76, v57, 0, s[28:29]
	v_sub_f32_e32 v57, v59, v118
	v_sub_f32_e32 v70, v117, v118
	v_add_f32_e32 v64, v63, v64
	v_cndmask_b32_e64 v73, v56, 0, s[34:35]
	v_exp_f32_e32 v57, v57
	v_add_f32_e32 v56, v73, v64
	v_exp_f32_e32 v64, v70
	v_add_f32_e32 v56, v75, v56
	v_add_f32_e32 v56, v76, v56
	v_cndmask_b32_e64 v77, v57, 0, s[24:25]
	v_add_f32_e32 v119, v77, v56
	v_cvt_pk_bf16_f32 v56, v68, v69
	v_cvt_pk_bf16_f32 v57, v71, v72
	v_cvt_pk_bf16_f32 v58, v74, v65
	v_cvt_pk_bf16_f32 v59, v66, v67
	v_pk_mul_f32 v[10:11], v[10:11], v[64:65] op_sel_hi:[1,0]
	v_pk_mul_f32 v[8:9], v[8:9], v[64:65] op_sel_hi:[1,0]
	v_pk_mul_f32 v[14:15], v[14:15], v[64:65] op_sel_hi:[1,0]
	v_pk_mul_f32 v[12:13], v[12:13], v[64:65] op_sel_hi:[1,0]
	v_pk_mul_f32 v[6:7], v[6:7], v[64:65] op_sel_hi:[1,0]
	v_pk_mul_f32 v[4:5], v[4:5], v[64:65] op_sel_hi:[1,0]
	v_pk_mul_f32 v[2:3], v[2:3], v[64:65] op_sel_hi:[1,0]
	v_pk_mul_f32 v[0:1], v[0:1], v[64:65] op_sel_hi:[1,0]
	v_mfma_f32_16x16x32_bf16 v[8:11], v[52:55], v[56:59], v[8:11]
	v_cvt_pk_bf16_f32 v60, v60, v61
	v_cvt_pk_bf16_f32 v61, v62, v63
	v_cvt_pk_bf16_f32 v62, v73, v75
	v_mfma_f32_16x16x32_bf16 v[12:15], v[44:47], v[56:59], v[12:15]
	v_cvt_pk_bf16_f32 v63, v76, v77
	s_mov_b64 s[6:7], 0x100
	v_fmac_f32_e32 v119, v114, v64
	v_mfma_f32_16x16x32_bf16 v[4:7], v[36:39], v[56:59], v[4:7]
	v_lshl_add_u64 v[104:105], v[104:105], 0, s[6:7]
	s_mov_b64 s[6:7], 0x10000
	v_lshl_add_u64 v[106:107], v[106:107], 0, s[6:7]
	v_mfma_f32_16x16x32_bf16 v[0:3], v[28:31], v[56:59], v[0:3]
	s_cselect_b64 s[6:7], -1, 0
	v_mov_b32_e32 v117, v118
	v_mov_b32_e32 v114, v119
	v_mfma_f32_16x16x32_bf16 v[8:11], v[48:51], v[60:63], v[8:11]
	v_mfma_f32_16x16x32_bf16 v[12:15], v[40:43], v[60:63], v[12:15]
	v_mfma_f32_16x16x32_bf16 v[4:7], v[32:35], v[60:63], v[4:7]
	v_mfma_f32_16x16x32_bf16 v[0:3], v[24:27], v[60:63], v[0:3]
	s_andn2_b64 vcc, exec, s[6:7]
	s_cbranch_vccz .LBB0_623
.LBB0_620:
	s_lshl_b64 s[6:7], s[92:93], 15
	v_lshl_add_u64 v[24:25], v[100:101], 0, s[6:7]
	v_lshl_add_u64 v[24:25], v[90:91], 1, v[24:25]
	v_add_co_u32_e32 v26, vcc, s50, v24
	s_movk_i32 s6, 0x6000
	s_nop 0
	v_addc_co_u32_e32 v27, vcc, 0, v25, vcc
	global_load_dwordx4 v[56:59], v[26:27], off offset:64
	global_load_dwordx4 v[72:75], v[26:27], off
	v_add_co_u32_e32 v26, vcc, s83, v24
	s_mov_b32 s55, s93
	s_nop 0
	v_addc_co_u32_e32 v27, vcc, 0, v25, vcc
	global_load_dwordx4 v[60:63], v[26:27], off offset:64
	global_load_dwordx4 v[76:79], v[26:27], off
	global_load_dwordx4 v[64:67], v[24:25], off offset:64
	global_load_dwordx4 v[80:83], v[24:25], off
	v_add_co_u32_e32 v24, vcc, s6, v24
	s_mov_b32 s6, 0x40000
	s_nop 0
	v_addc_co_u32_e32 v25, vcc, 0, v25, vcc
	global_load_dwordx4 v[120:123], v[24:25], off
	global_load_dwordx4 v[68:71], v[24:25], off offset:64
	v_lshl_add_u64 v[24:25], s[54:55], 1, v[102:103]
	v_add_co_u32_e32 v26, vcc, s0, v24
	global_load_dwordx4 v[52:55], v[24:25], off
	global_load_dwordx4 v[48:51], v[24:25], off offset:64
	v_addc_co_u32_e32 v27, vcc, 0, v25, vcc
	global_load_dwordx4 v[44:47], v[26:27], off
	global_load_dwordx4 v[40:43], v[26:27], off offset:64
	v_add_co_u32_e32 v26, vcc, s6, v24
	v_add_u32_e32 v95, 0x63, v116
	s_nop 0
	v_addc_co_u32_e32 v27, vcc, 0, v25, vcc
	v_add_co_u32_e32 v28, vcc, s76, v24
	global_load_dwordx4 v[36:39], v[26:27], off
	global_load_dwordx4 v[32:35], v[26:27], off offset:64
	v_addc_co_u32_e32 v29, vcc, 0, v25, vcc
	global_load_dwordx4 v[24:27], v[28:29], off
	s_nop 0
	global_load_dwordx4 v[28:31], v[28:29], off offset:64
	v_cmp_gt_u32_e64 s[20:21], s88, v97
	v_add_u32_e32 v114, 0x61, v116
	v_add_u32_e32 v117, 0x60, v116
	v_cmp_gt_u32_e64 s[22:23], s47, v95
	v_cndmask_b32_e64 v95, 2, 0, s[20:21]
	v_cmp_lt_u32_e64 s[12:13], s49, v114
	v_cmp_lt_u32_e64 s[18:19], s49, v117
	s_cmp_ge_i32 s58, s57
	v_cndmask_b32_e64 v114, 4, 0, s[12:13]
	v_cndmask_b32_e64 v117, 8, 0, s[18:19]
	s_waitcnt vmcnt(0) lgkmcnt(0)
	v_mfma_f32_16x16x32_bf16 v[84:87], v[80:83], v[16:19], 0
	v_mfma_f32_16x16x32_bf16 v[80:83], v[76:79], v[16:19], 0
	v_mfma_f32_16x16x32_bf16 v[76:79], v[72:75], v[16:19], 0
	v_mfma_f32_16x16x32_bf16 v[72:75], v[120:123], v[16:19], 0
	v_add_u32_e32 v122, 0x51, v116
	v_add_u32_e32 v123, 0x50, v116
	v_cmp_lt_u32_e64 s[8:9], s49, v122
	v_cmp_lt_u32_e32 vcc, s49, v123
	v_add_u32_e32 v120, 0x53, v116
	v_cndmask_b32_e64 v122, 64, 0, s[8:9]
	v_cndmask_b32_e64 v123, v244, 0, vcc
	v_add_u32_e32 v121, 0x52, v116
	v_or3_b32 v95, v95, v122, v123
	v_cmp_lt_u32_e64 s[6:7], s49, v120
	v_cmp_lt_u32_e64 s[10:11], s49, v121
	v_or3_b32 v95, v114, v117, v95
	v_add_u32_e32 v114, 0x43, v116
	v_add_u32_e32 v117, 0x42, v116
	v_cndmask_b32_e64 v120, 16, 0, s[6:7]
	v_cndmask_b32_e64 v121, 32, 0, s[10:11]
	v_cmp_gt_u32_e64 s[16:17], s47, v114
	v_cmp_gt_u32_e64 s[14:15], s47, v117
	v_or3_b32 v95, v120, v121, v95
	v_cndmask_b32_e64 v114, 0, v245, s[16:17]
	v_cndmask_b32_e64 v117, 0, v240, s[14:15]
	v_or3_b32 v95, v114, v95, v117
	v_add_u32_e32 v114, 0x41, v116
	v_mfma_f32_16x16x32_bf16 v[64:67], v[64:67], v[20:23], v[84:87]
	v_cmp_gt_u32_e64 s[24:25], s47, v114
	v_add_u32_e32 v117, 64, v116
	v_add_u32_e32 v120, 51, v116
	v_cndmask_b32_e64 v114, 0, v246, s[24:25]
	v_cmp_gt_u32_e64 s[24:25], s47, v117
	v_mfma_f32_16x16x32_bf16 v[60:63], v[60:63], v[20:23], v[80:83]
	v_add_u32_e32 v121, 50, v116
	v_cndmask_b32_e64 v117, 0, v247, s[24:25]
	v_cmp_gt_u32_e64 s[24:25], s47, v120
	v_or_b32_e32 v114, v114, v117
	v_add_u32_e32 v122, 49, v116
	v_cndmask_b32_e64 v120, 0, v248, s[24:25]
	v_cmp_gt_u32_e64 s[24:25], s47, v121
	v_mfma_f32_16x16x32_bf16 v[56:59], v[56:59], v[20:23], v[76:79]
	v_mul_f32_e32 v64, 0x3e38aa3b, v64
	v_mul_f32_e32 v65, 0x3e38aa3b, v65
	v_cndmask_b32_e64 v121, 0, v249, s[24:25]
	v_cmp_gt_u32_e64 s[24:25], s47, v122
	v_add_u32_e32 v123, 48, v116
	v_mfma_f32_16x16x32_bf16 v[68:71], v[68:71], v[20:23], v[72:75]
	v_cndmask_b32_e64 v64, v241, v64, s[22:23]
	v_cndmask_b32_e64 v65, v65, v241, s[20:21]
	v_mul_f32_e32 v66, 0x3e38aa3b, v66
	v_mul_f32_e32 v67, 0x3e38aa3b, v67
	v_bitop3_b32 v73, v114, s95, v95 bitop3:0xc8
	v_or_b32_e32 v117, v114, v95
	v_or_b32_e32 v120, v120, v121
	v_cndmask_b32_e64 v122, 0, v250, s[24:25]
	v_cmp_gt_u32_e64 s[24:25], s47, v123
	v_max3_f32 v72, v64, s71, v65
	v_cndmask_b32_e64 v66, v66, v241, s[12:13]
	v_cndmask_b32_e64 v67, v67, v241, s[18:19]
	v_mul_f32_e32 v60, 0x3e38aa3b, v60
	v_mul_f32_e32 v61, 0x3e38aa3b, v61
	v_cmp_eq_u32_e64 s[36:37], 0, v73
	v_bitop3_b32 v73, v114, s48, v95 bitop3:0xc8
	v_cndmask_b32_e64 v123, 0, v251, s[24:25]
	v_max3_f32 v72, v72, v66, v67
	v_cndmask_b32_e64 v60, v60, v241, s[6:7]
	v_cndmask_b32_e64 v61, v61, v241, s[10:11]
	v_mul_f32_e32 v62, 0x3e38aa3b, v62
	v_mul_f32_e32 v63, 0x3e38aa3b, v63
	v_cmp_eq_u32_e64 s[26:27], 0, v73
	v_bitop3_b32 v73, v120, s90, v117 bitop3:0xc8
	v_or_b32_e32 v121, v120, v117
	v_or_b32_e32 v122, v122, v123
	v_max3_f32 v72, v72, v60, v61
	v_cndmask_b32_e64 v62, v62, v241, s[8:9]
	v_cndmask_b32_e32 v63, v63, v241, vcc
	v_mul_f32_e32 v56, 0x3e38aa3b, v56
	v_mul_f32_e32 v57, 0x3e38aa3b, v57
	v_cmp_eq_u32_e64 s[34:35], 0, v73
	v_bitop3_b32 v73, v120, s83, v117 bitop3:0xc8
	v_max3_f32 v72, v72, v62, v63
	v_cndmask_b32_e64 v56, v241, v56, s[16:17]
	v_cndmask_b32_e64 v57, v241, v57, s[14:15]
	v_mul_f32_e32 v58, 0x3e38aa3b, v58
	v_mul_f32_e32 v59, 0x3e38aa3b, v59
	v_cmp_eq_u32_e64 s[30:31], 0, v73
	v_bitop3_b32 v73, v122, s50, v121 bitop3:0xc8
	v_max3_f32 v72, v72, v56, v57
	v_cndmask_b32_e64 v58, v58, v241, s[36:37]
	v_cndmask_b32_e64 v59, v59, v241, s[26:27]
	v_mul_f32_e32 v68, 0x3e38aa3b, v68
	v_mul_f32_e32 v69, 0x3e38aa3b, v69
	v_cmp_eq_u32_e64 s[28:29], 0, v73
	v_bitop3_b32 v73, v122, s82, v121 bitop3:0xc8
	v_max3_f32 v72, v72, v58, v59
	v_cndmask_b32_e64 v68, v68, v241, s[34:35]
	v_cndmask_b32_e64 v69, v69, v241, s[30:31]
	v_mul_f32_e32 v70, 0x3e38aa3b, v70
	v_cmp_eq_u32_e64 s[24:25], 0, v73
	v_mul_f32_e32 v71, 0x3e38aa3b, v71
	v_max3_f32 v72, v72, v68, v69
	v_cndmask_b32_e64 v70, v70, v241, s[28:29]
	v_cndmask_b32_e64 v71, v71, v241, s[24:25]
	v_max3_f32 v72, v72, v70, v71
	ds_bpermute_b32 v73, v109, v72
	s_waitcnt lgkmcnt(0)
	v_max_f32_e32 v73, v73, v73
	v_max_f32_e32 v72, v72, v73
	ds_bpermute_b32 v73, v108, v72
	s_waitcnt lgkmcnt(0)
	v_max3_f32 v117, v118, v72, v73
	v_sub_f32_e32 v57, v57, v117
	v_exp_f32_e32 v57, v57
	v_sub_f32_e32 v64, v64, v117
	v_exp_f32_e32 v64, v64
	v_sub_f32_e32 v65, v65, v117
	v_cndmask_b32_e64 v75, 0, v57, s[14:15]
	v_sub_f32_e32 v57, v58, v117
	v_exp_f32_e32 v57, v57
	v_exp_f32_e32 v65, v65
	v_sub_f32_e32 v66, v66, v117
	v_exp_f32_e32 v66, v66
	v_cndmask_b32_e64 v76, v57, 0, s[36:37]
	v_sub_f32_e32 v57, v59, v117
	v_exp_f32_e32 v57, v57
	v_sub_f32_e32 v67, v67, v117
	v_exp_f32_e32 v67, v67
	v_sub_f32_e32 v60, v60, v117
	v_cndmask_b32_e64 v77, v57, 0, s[26:27]
	v_sub_f32_e32 v57, v68, v117
	v_exp_f32_e32 v57, v57
	v_cndmask_b32_e64 v73, 0, v64, s[22:23]
	v_exp_f32_e32 v60, v60
	v_sub_f32_e32 v61, v61, v117
	v_cndmask_b32_e64 v68, v57, 0, s[34:35]
	v_sub_f32_e32 v57, v69, v117
	v_add_f32_e32 v64, 0, v73
	v_cndmask_b32_e64 v65, v65, 0, s[20:21]
	v_exp_f32_e32 v61, v61
	v_sub_f32_e32 v62, v62, v117
	v_exp_f32_e32 v57, v57
	v_add_f32_e32 v64, v65, v64
	v_cndmask_b32_e64 v66, v66, 0, s[12:13]
	v_exp_f32_e32 v62, v62
	v_sub_f32_e32 v63, v63, v117
	v_add_f32_e32 v64, v66, v64
	v_cndmask_b32_e64 v67, v67, 0, s[18:19]
	v_exp_f32_e32 v63, v63
	v_sub_f32_e32 v56, v56, v117
	v_add_f32_e32 v64, v67, v64
	v_cndmask_b32_e64 v60, v60, 0, s[6:7]
	v_exp_f32_e32 v56, v56
	v_add_f32_e32 v64, v60, v64
	v_cndmask_b32_e64 v61, v61, 0, s[10:11]
	v_cndmask_b32_e64 v69, v57, 0, s[30:31]
	v_sub_f32_e32 v57, v70, v117
	v_add_f32_e32 v64, v61, v64
	v_cndmask_b32_e64 v62, v62, 0, s[8:9]
	v_exp_f32_e32 v57, v57
	v_add_f32_e32 v64, v62, v64
	v_cndmask_b32_e64 v63, v63, 0, vcc
	v_add_f32_e32 v64, v63, v64
	v_cndmask_b32_e64 v74, 0, v56, s[16:17]
	v_add_f32_e32 v56, v74, v64
	v_add_f32_e32 v56, v75, v56
	v_cndmask_b32_e64 v70, v57, 0, s[28:29]
	v_sub_f32_e32 v57, v71, v117
	v_sub_f32_e32 v72, v118, v117
	v_add_f32_e32 v56, v76, v56
	v_exp_f32_e32 v57, v57
	v_add_f32_e32 v56, v77, v56
	v_exp_f32_e32 v64, v72
	v_add_f32_e32 v56, v68, v56
	v_add_f32_e32 v56, v69, v56
	v_add_f32_e32 v56, v70, v56
	v_cndmask_b32_e64 v71, v57, 0, s[24:25]
	v_add_f32_e32 v114, v71, v56
	v_cvt_pk_bf16_f32 v56, v73, v65
	v_cvt_pk_bf16_f32 v57, v66, v67
	v_cvt_pk_bf16_f32 v58, v60, v61
	v_cvt_pk_bf16_f32 v59, v62, v63
	v_pk_mul_f32 v[10:11], v[10:11], v[64:65] op_sel_hi:[1,0]
	v_pk_mul_f32 v[8:9], v[8:9], v[64:65] op_sel_hi:[1,0]
	v_pk_mul_f32 v[14:15], v[14:15], v[64:65] op_sel_hi:[1,0]
	v_pk_mul_f32 v[12:13], v[12:13], v[64:65] op_sel_hi:[1,0]
	v_pk_mul_f32 v[6:7], v[6:7], v[64:65] op_sel_hi:[1,0]
	v_pk_mul_f32 v[4:5], v[4:5], v[64:65] op_sel_hi:[1,0]
	v_pk_mul_f32 v[2:3], v[2:3], v[64:65] op_sel_hi:[1,0]
	v_pk_mul_f32 v[0:1], v[0:1], v[64:65] op_sel_hi:[1,0]
	v_mfma_f32_16x16x32_bf16 v[8:11], v[52:55], v[56:59], v[8:11]
	v_cvt_pk_bf16_f32 v60, v74, v75
	v_cvt_pk_bf16_f32 v61, v76, v77
	v_cvt_pk_bf16_f32 v62, v68, v69
	v_mfma_f32_16x16x32_bf16 v[12:15], v[44:47], v[56:59], v[12:15]
	v_cvt_pk_bf16_f32 v63, v70, v71
	v_fmac_f32_e32 v114, v119, v64
	v_mfma_f32_16x16x32_bf16 v[4:7], v[36:39], v[56:59], v[4:7]
	v_mfma_f32_16x16x32_bf16 v[0:3], v[24:27], v[56:59], v[0:3]
	v_mfma_f32_16x16x32_bf16 v[8:11], v[48:51], v[60:63], v[8:11]
	v_mfma_f32_16x16x32_bf16 v[12:15], v[40:43], v[60:63], v[12:15]
	v_mfma_f32_16x16x32_bf16 v[4:7], v[32:35], v[60:63], v[4:7]
	v_mfma_f32_16x16x32_bf16 v[0:3], v[28:31], v[60:63], v[0:3]
	s_cbranch_scc0 .LBB0_619
	s_branch .LBB0_623

.LBB0_623:
	s_ashr_i32 s6, s45, 4
	s_max_i32 s8, s6, 0x80
	s_addk_i32 s8, 0xff80
	s_ashr_i32 s54, s56, 10
	s_lshr_b32 s45, s8, 6
	s_cmp_le_i32 s45, s54
	s_mov_b64 s[6:7], -1
	s_cbranch_scc0 .LBB0_629
	v_add_co_u32_e32 v16, vcc, 0x1800000, v98
	s_and_b32 s7, s44, 15
	s_nop 0
	v_addc_co_u32_e32 v17, vcc, 0, v99, vcc
	global_load_dwordx4 v[32:35], v[16:17], off
	global_load_dwordx4 v[36:39], v[16:17], off offset:64
	v_or_b32_e32 v16, s7, v113
	v_lshlrev_b32_e32 v136, 7, v16
	v_lshl_add_u64 v[16:17], s[38:39], 0, v[136:137]
	s_mov_b64 s[10:11], 0x1800000
	v_mov_b32_e32 v97, v137
	v_lshl_add_u64 v[48:49], v[16:17], 0, s[10:11]
	v_lshl_add_u64 v[16:17], s[52:53], 0, v[96:97]
	s_lshl_b32 s92, s7, 9
	v_lshl_add_u64 v[16:17], v[16:17], 0, s[92:93]
	s_add_i32 s72, s72, s73
	v_lshl_add_u64 v[16:17], v[16:17], 0, v[92:93]
	s_mov_b32 s41, s93
	s_and_b32 s9, s72, 15
	s_lshr_b32 s92, s8, 6
	v_lshl_add_u64 v[50:51], v[16:17], 0, s[10:11]
	s_and_b32 s6, s8, 0xffffffc0
	s_lshl_b64 s[10:11], s[40:41], 19
	s_lshl_b32 s12, s9, 9
	s_lshl_b64 s[8:9], s[92:93], 7
	s_add_u32 s8, s74, s8
	s_addc_u32 s9, s75, s9
	s_add_u32 s8, s8, s12
	s_addc_u32 s9, s9, 0
	s_add_u32 s8, s8, s10
	v_mov_b32_e32 v95, v137
	s_addc_u32 s9, s9, s11
	v_lshlrev_b32_e32 v116, 2, v112
	v_lshl_add_u64 v[52:53], s[8:9], 0, v[94:95]
	s_lshl_b64 s[8:9], s[92:93], 17
	v_ashrrev_i32_e32 v18, 4, v88
	v_add_u32_e32 v16, s6, v116
	s_add_u32 s8, s10, s8
	v_sub_u32_e32 v64, v16, v18
	v_sub_u32_e32 v16, v18, v116
	s_addc_u32 s9, s11, s9
	s_lshl_b32 s7, s7, 7
	v_subrev_u32_e32 v16, s6, v16
	s_add_u32 s8, s74, s8
	v_add_u32_e32 v65, 0xffffff9d, v16
	v_lshl_or_b32 v136, v111, 11, s7
	s_addc_u32 s9, s75, s9
	s_waitcnt vmcnt(0)
	v_mov_b64_e32 v[30:31], v[10:11]
	v_mov_b64_e32 v[26:27], v[14:15]
	v_mov_b64_e32 v[22:23], v[6:7]
	v_mov_b64_e32 v[18:19], v[2:3]
	v_lshl_add_u64 v[54:55], s[8:9], 0, v[136:137]
	s_mov_b32 s92, s45
	v_mov_b32_e32 v40, v114
	v_mov_b64_e32 v[28:29], v[8:9]
	v_mov_b64_e32 v[24:25], v[12:13]
	v_mov_b64_e32 v[20:21], v[4:5]
	v_mov_b64_e32 v[16:17], v[0:1]
	s_branch .LBB0_626
.LBB0_625:
	v_lshl_add_u64 v[58:59], v[52:53], 0, v[92:93]
	v_add_co_u32_e32 v56, vcc, 0xd060000, v58
	s_mov_b64 s[24:25], vcc
	v_add_co_u32_e32 v60, vcc, 0xd040000, v58
	s_mov_b64 s[6:7], vcc
	v_add_co_u32_e32 v62, vcc, 0xd020000, v58
	s_mov_b64 s[26:27], vcc
	v_add_co_u32_e32 v106, vcc, 0xd000000, v58
	v_lshl_add_u64 v[72:73], v[54:55], 0, v[92:93]
	s_mov_b64 s[28:29], vcc
	v_add_co_u32_e32 v94, vcc, 0xac38000, v72
	v_add_u32_e32 v57, 64, v64
	s_nop 0
	v_addc_co_u32_e32 v95, vcc, 0, v73, vcc
	v_add_co_u32_e32 v84, vcc, 0xac30000, v72
	global_load_dwordx4 v[40:43], v[94:95], off
	s_nop 0
	v_addc_co_u32_e32 v85, vcc, 0, v73, vcc
	v_add_co_u32_e32 v80, vcc, 0xac28000, v72
	global_load_dwordx4 v[44:47], v[84:85], off
	s_nop 0
	v_addc_co_u32_e32 v81, vcc, 0, v73, vcc
	global_load_dwordx4 v[68:71], v[80:81], off
	v_add_co_u32_e32 v76, vcc, 0xac20000, v72
	v_add_u32_e32 v100, 0xffffff90, v65
	s_nop 0
	v_addc_co_u32_e32 v77, vcc, 0, v73, vcc
	global_load_dwordx4 v[72:75], v[76:77], off
	s_nop 0
	global_load_dwordx4 v[76:79], v[76:77], off offset:64
	s_nop 0
	global_load_dwordx4 v[80:83], v[80:81], off offset:64
	s_nop 0
	global_load_dwordx4 v[84:87], v[84:85], off offset:64
	s_nop 0
	global_load_dwordx4 v[94:97], v[94:95], off offset:64
	v_add_u32_e32 v101, 0xffffff8f, v65
	v_add_u32_e32 v61, 0xffffffa0, v65
	v_add_u32_e32 v63, 0xffffff9f, v65
	v_add_u32_e32 v98, 0xffffff92, v65
	v_add_u32_e32 v99, 0xffffff91, v65
	v_cmp_gt_u32_e64 s[20:21], s88, v57
	v_cmp_gt_u32_e64 s[12:13], s88, v100
	v_cmp_gt_u32_e64 s[14:15], s88, v101
	v_add_u32_e32 v104, 1, v65
	v_cndmask_b32_e64 v107, 2, 0, s[20:21]
	v_cmp_gt_u32_e64 s[22:23], s88, v61
	v_cmp_gt_u32_e64 s[16:17], s88, v63
	v_cmp_gt_u32_e64 s[18:19], s88, v98
	v_cmp_gt_u32_e64 s[10:11], s88, v99
	v_cndmask_b32_e64 v98, 64, 0, s[12:13]
	v_cndmask_b32_e64 v99, v244, 0, s[14:15]
	v_add_u32_e32 v102, 3, v65
	v_add_u32_e32 v103, 2, v65
	v_cmp_gt_u32_e32 vcc, s47, v65
	v_cndmask_b32_e64 v61, 4, 0, s[22:23]
	v_cndmask_b32_e64 v63, 8, 0, s[16:17]
	v_cmp_gt_u32_e64 s[30:31], s47, v104
	v_or3_b32 v98, v98, v99, v107
	v_cndmask_b32_e32 v105, 0, v247, vcc
	v_add_u32_e32 v111, -13, v65
	v_cndmask_b32_e64 v112, 16, 0, s[18:19]
	v_cndmask_b32_e64 v113, 32, 0, s[10:11]
	v_cmp_gt_u32_e32 vcc, s47, v102
	v_cmp_gt_u32_e64 s[8:9], s47, v103
	v_cndmask_b32_e64 v100, 0, v246, s[30:31]
	v_addc_co_u32_e64 v57, s[24:25], 0, v59, s[24:25]
	v_or3_b32 v61, v61, v63, v98
	v_addc_co_u32_e64 v63, s[24:25], 0, v59, s[26:27]
	v_addc_co_u32_e64 v107, s[24:25], 0, v59, s[28:29]
	v_cndmask_b32_e32 v117, 0, v245, vcc
	v_cndmask_b32_e64 v118, 0, v240, s[8:9]
	v_or_b32_e32 v119, v100, v105
	v_cmp_gt_u32_e64 s[24:25], s47, v111
	v_add_u32_e32 v111, -14, v65
	v_add_u32_e32 v58, 35, v65
	v_cmp_gt_u32_e64 s[36:37], s47, v58
	s_add_i32 s45, s45, 2
	s_min_i32 s92, s45, s54
	v_add_u32_e32 v64, 0x80, v64
	v_lshl_add_u64 v[54:55], v[54:55], 0, s[78:79]
	s_waitcnt vmcnt(0) lgkmcnt(0)
	v_mfma_f32_16x16x32_bf16 v[72:75], v[72:75], v[32:35], 0
	v_mfma_f32_16x16x32_bf16 v[68:71], v[68:71], v[32:35], 0
	v_mfma_f32_16x16x32_bf16 v[98:101], v[40:43], v[32:35], 0
	v_or3_b32 v40, v112, v113, v61
	v_or3_b32 v61, v117, v40, v118
	v_mfma_f32_16x16x32_bf16 v[102:105], v[44:47], v[32:35], 0
	global_load_dwordx4 v[40:43], v[106:107], off offset:192
	global_load_dwordx4 v[44:47], v[106:107], off offset:128
	v_cndmask_b32_e64 v107, 0, v248, s[24:25]
	v_cmp_gt_u32_e64 s[24:25], s47, v111
	v_mfma_f32_16x16x32_bf16 v[68:71], v[80:83], v[36:39], v[68:71]
	v_add_u32_e32 v81, -16, v65
	v_cndmask_b32_e64 v111, 0, v249, s[24:25]
	v_or_b32_e32 v106, v119, v61
	v_mfma_f32_16x16x32_bf16 v[72:75], v[76:79], v[36:39], v[72:75]
	v_add_u32_e32 v76, -15, v65
	v_cmp_gt_u32_e64 s[24:25], s47, v76
	s_nop 1
	v_mul_f32_e32 v68, 0x3e38aa3b, v68
	v_mfma_f32_16x16x32_bf16 v[76:79], v[84:87], v[36:39], v[102:105]
	v_cndmask_b32_e64 v80, 0, v250, s[24:25]
	v_cmp_gt_u32_e64 s[24:25], s47, v81
	v_mul_f32_e32 v72, 0x3e38aa3b, v72
	v_mul_f32_e32 v58, 0x3e38aa3b, v73
	v_cndmask_b32_e64 v81, 0, v251, s[24:25]
	v_or_b32_e32 v84, v80, v81
	v_mfma_f32_16x16x32_bf16 v[80:83], v[94:97], v[36:39], v[98:101]
	v_cndmask_b32_e64 v94, v241, v72, s[36:37]
	v_mul_f32_e32 v72, 0x3e38aa3b, v74
	v_cndmask_b32_e64 v95, v58, v241, s[20:21]
	v_cndmask_b32_e64 v98, v68, v241, s[18:19]
	v_mul_f32_e32 v68, 0x3e38aa3b, v69
	v_cndmask_b32_e64 v99, v68, v241, s[10:11]
	v_mul_f32_e32 v68, 0x3e38aa3b, v70
	v_cndmask_b32_e64 v100, v68, v241, s[12:13]
	v_mul_f32_e32 v68, 0x3e38aa3b, v71
	v_cndmask_b32_e64 v101, v68, v241, s[14:15]
	v_mul_f32_e32 v68, 0x3e38aa3b, v76
	v_cndmask_b32_e64 v96, v72, v241, s[22:23]
	v_mul_f32_e32 v72, 0x3e38aa3b, v75
	v_cndmask_b32_e32 v102, v241, v68, vcc
	v_mul_f32_e32 v68, 0x3e38aa3b, v77
	v_or_b32_e32 v107, v107, v111
	v_max3_f32 v58, v94, s71, v95
	v_cndmask_b32_e64 v97, v72, v241, s[16:17]
	v_cndmask_b32_e64 v103, v241, v68, s[8:9]
	v_bitop3_b32 v68, v119, s95, v61 bitop3:0xc8
	v_bitop3_b32 v61, v119, s48, v61 bitop3:0xc8
	v_max3_f32 v58, v58, v96, v97
	v_cmp_eq_u32_e64 s[28:29], 0, v68
	v_mul_f32_e32 v68, 0x3e38aa3b, v79
	v_cmp_eq_u32_e64 s[34:35], 0, v61
	v_bitop3_b32 v61, v107, s90, v106 bitop3:0xc8
	v_or_b32_e32 v111, v107, v106
	v_max3_f32 v58, v58, v98, v99
	v_cndmask_b32_e64 v105, v68, v241, s[34:35]
	v_mul_f32_e32 v68, 0x3e38aa3b, v80
	v_cmp_eq_u32_e64 s[24:25], 0, v61
	v_bitop3_b32 v61, v107, s83, v106 bitop3:0xc8
	v_max3_f32 v58, v58, v100, v101
	v_mul_f32_e32 v69, 0x3e38aa3b, v78
	v_cndmask_b32_e64 v112, v68, v241, s[24:25]
	v_mul_f32_e32 v68, 0x3e38aa3b, v81
	v_cmp_eq_u32_e64 s[26:27], 0, v61
	v_bitop3_b32 v61, v84, s50, v111 bitop3:0xc8
	v_max3_f32 v58, v58, v102, v103
	v_cndmask_b32_e64 v104, v69, v241, s[28:29]
	v_cndmask_b32_e64 v106, v68, v241, s[26:27]
	v_mul_f32_e32 v68, 0x3e38aa3b, v82
	v_cmp_eq_u32_e64 s[30:31], 0, v61
	v_bitop3_b32 v61, v84, s82, v111 bitop3:0xc8
	v_max3_f32 v58, v58, v104, v105
	v_cndmask_b32_e64 v107, v68, v241, s[30:31]
	v_mul_f32_e32 v68, 0x3e38aa3b, v83
	v_cmp_eq_u32_e64 s[38:39], 0, v61
	v_max3_f32 v58, v58, v112, v106
	v_addc_co_u32_e64 v61, s[6:7], 0, v59, s[6:7]
	v_cndmask_b32_e64 v111, v68, v241, s[38:39]
	v_max3_f32 v58, v58, v107, v111
	ds_bpermute_b32 v76, v109, v58
	global_load_dwordx4 v[68:71], v[62:63], off offset:192
	global_load_dwordx4 v[72:75], v[62:63], off offset:128
	s_lshl_b32 s6, s92, 6
	s_cmp_gt_i32 s45, s54
	v_add_u32_e32 v65, 0xffffff80, v65
	s_waitcnt lgkmcnt(0)
	v_max_f32_e32 v59, v76, v76
	v_max_f32_e32 v62, v58, v59
	global_load_dwordx4 v[76:79], v[60:61], off offset:192
	s_nop 0
	global_load_dwordx4 v[58:61], v[60:61], off offset:128
	s_nop 0
	global_load_dwordx4 v[80:83], v[56:57], off offset:192
	global_load_dwordx4 v[84:87], v[56:57], off offset:128
	ds_bpermute_b32 v63, v108, v62
	s_waitcnt lgkmcnt(0)
	v_max3_f32 v117, v67, v62, v63
	v_sub_f32_e32 v56, v94, v117
	v_exp_f32_e32 v56, v56
	v_sub_f32_e32 v57, v67, v117
	v_sub_f32_e32 v63, v96, v117
	v_exp_f32_e32 v63, v63
	v_cndmask_b32_e64 v62, 0, v56, s[36:37]
	v_sub_f32_e32 v56, v95, v117
	v_exp_f32_e32 v56, v56
	v_add_f32_e32 v67, 0, v62
	v_sub_f32_e32 v95, v98, v117
	v_exp_f32_e32 v95, v95
	v_cndmask_b32_e64 v94, v56, 0, s[20:21]
	v_add_f32_e32 v56, v94, v67
	v_sub_f32_e32 v67, v97, v117
	v_exp_f32_e32 v67, v67
	v_cndmask_b32_e64 v63, v63, 0, s[22:23]
	v_add_f32_e32 v56, v63, v56
	v_cndmask_b32_e64 v96, v95, 0, s[18:19]
	v_cndmask_b32_e64 v67, v67, 0, s[16:17]
	v_add_f32_e32 v56, v67, v56
	v_sub_f32_e32 v95, v99, v117
	v_sub_f32_e32 v97, v100, v117
	v_exp_f32_e32 v95, v95
	v_exp_f32_e32 v97, v97
	v_add_f32_e32 v113, v96, v56
	v_sub_f32_e32 v56, v102, v117
	v_exp_f32_e32 v56, v56
	v_sub_f32_e32 v98, v101, v117
	v_exp_f32_e32 v98, v98
	v_cndmask_b32_e64 v118, v95, 0, s[10:11]
	v_cndmask_b32_e64 v119, v97, 0, s[12:13]
	v_sub_f32_e32 v95, v103, v117
	v_sub_f32_e32 v97, v104, v117
	v_exp_f32_e32 v95, v95
	v_exp_f32_e32 v97, v97
	v_cndmask_b32_e32 v102, 0, v56, vcc
	v_sub_f32_e32 v56, v112, v117
	v_exp_f32_e32 v56, v56
	v_cndmask_b32_e64 v120, v98, 0, s[14:15]
	v_sub_f32_e32 v98, v105, v117
	v_exp_f32_e32 v98, v98
	v_cndmask_b32_e64 v103, 0, v95, s[8:9]
	v_cndmask_b32_e64 v104, v97, 0, s[28:29]
	v_sub_f32_e32 v95, v106, v117
	v_sub_f32_e32 v97, v107, v117
	v_exp_f32_e32 v95, v95
	v_exp_f32_e32 v97, v97
	v_cndmask_b32_e64 v106, v56, 0, s[24:25]
	v_exp_f32_e32 v56, v57
	v_cndmask_b32_e64 v105, v98, 0, s[34:35]
	v_sub_f32_e32 v98, v111, v117
	v_exp_f32_e32 v98, v98
	v_cndmask_b32_e64 v107, v95, 0, s[26:27]
	v_cndmask_b32_e64 v111, v97, 0, s[30:31]
	v_cvt_pk_bf16_f32 v94, v62, v94
	v_cvt_pk_bf16_f32 v95, v63, v67
	v_cvt_pk_bf16_f32 v96, v96, v118
	v_cvt_pk_bf16_f32 v97, v119, v120
	v_pk_mul_f32 v[30:31], v[30:31], v[56:57] op_sel_hi:[1,0]
	v_pk_mul_f32 v[28:29], v[28:29], v[56:57] op_sel_hi:[1,0]
	v_cndmask_b32_e64 v112, v98, 0, s[38:39]
	v_cvt_pk_bf16_f32 v98, v102, v103
	s_waitcnt vmcnt(0)
	v_mfma_f32_16x16x32_bf16 v[28:31], v[44:47], v[94:97], v[28:31]
	v_cvt_pk_bf16_f32 v99, v104, v105
	v_cvt_pk_bf16_f32 v100, v106, v107
	v_cvt_pk_bf16_f32 v101, v111, v112
	v_pk_mul_f32 v[26:27], v[26:27], v[56:57] op_sel_hi:[1,0]
	v_pk_mul_f32 v[24:25], v[24:25], v[56:57] op_sel_hi:[1,0]
	v_mfma_f32_16x16x32_bf16 v[28:31], v[40:43], v[98:101], v[28:31]
	v_add_f32_e32 v40, v118, v113
	v_add_f32_e32 v40, v119, v40
	v_add_f32_e32 v40, v120, v40
	v_add_f32_e32 v40, v102, v40
	v_add_f32_e32 v40, v103, v40
	v_pk_mul_f32 v[22:23], v[22:23], v[56:57] op_sel_hi:[1,0]
	v_pk_mul_f32 v[20:21], v[20:21], v[56:57] op_sel_hi:[1,0]
	v_pk_mul_f32 v[18:19], v[18:19], v[56:57] op_sel_hi:[1,0]
	v_pk_mul_f32 v[16:17], v[16:17], v[56:57] op_sel_hi:[1,0]
	v_mfma_f32_16x16x32_bf16 v[24:27], v[72:75], v[94:97], v[24:27]
	v_add_f32_e32 v40, v104, v40
	v_add_f32_e32 v40, v105, v40
	v_add_f32_e32 v40, v106, v40
	v_mfma_f32_16x16x32_bf16 v[20:23], v[58:61], v[94:97], v[20:23]
	v_add_f32_e32 v40, v107, v40
	v_add_f32_e32 v40, v111, v40
	v_add_f32_e32 v40, v112, v40
	v_mfma_f32_16x16x32_bf16 v[16:19], v[84:87], v[94:97], v[16:19]
	v_fmac_f32_e32 v40, v66, v56
	s_mov_b64 s[8:9], 0x100
	v_lshl_add_u64 v[52:53], v[52:53], 0, s[8:9]
	v_mfma_f32_16x16x32_bf16 v[24:27], v[68:71], v[98:101], v[24:27]
	s_cselect_b64 s[8:9], -1, 0
	v_mov_b32_e32 v66, v40
	v_mfma_f32_16x16x32_bf16 v[20:23], v[76:79], v[98:101], v[20:23]
	v_mfma_f32_16x16x32_bf16 v[16:19], v[80:83], v[98:101], v[16:19]
	s_andn2_b64 vcc, exec, s[8:9]
	s_cbranch_vccz .LBB0_628
.LBB0_626:
	s_lshl_b64 s[8:9], s[92:93], 17
	v_lshl_add_u64 v[42:43], v[48:49], 0, s[8:9]
	v_lshl_add_u64 v[46:47], v[90:91], 1, v[42:43]
	global_load_dwordx4 v[42:45], v[46:47], off
	v_add_co_u32_e32 v74, vcc, s82, v46
	v_add_u32_e32 v100, 0x41, v65
	s_nop 0
	v_addc_co_u32_e32 v75, vcc, 0, v47, vcc
	global_load_dwordx4 v[56:59], v[74:75], off
	v_add_co_u32_e32 v78, vcc, s94, v46
	v_add_u32_e32 v101, 64, v65
	s_nop 0
	v_addc_co_u32_e32 v79, vcc, 0, v47, vcc
	global_load_dwordx4 v[60:63], v[78:79], off
	v_add_co_u32_e32 v82, vcc, s51, v46
	v_cmp_gt_u32_e64 s[22:23], s47, v100
	s_nop 0
	v_addc_co_u32_e32 v83, vcc, 0, v47, vcc
	global_load_dwordx4 v[66:69], v[82:83], off
	global_load_dwordx4 v[70:73], v[46:47], off offset:64
	s_nop 0
	global_load_dwordx4 v[74:77], v[74:75], off offset:64
	s_nop 0
	global_load_dwordx4 v[78:81], v[78:79], off offset:64
	s_nop 0
	global_load_dwordx4 v[82:85], v[82:83], off offset:64
	v_add_u32_e32 v103, 51, v65
	v_cndmask_b32_e64 v122, 0, v246, s[22:23]
	v_cmp_gt_u32_e64 s[22:23], s47, v101
	v_add_u32_e32 v104, 50, v65
	v_add_u32_e32 v105, 49, v65
	v_cndmask_b32_e64 v123, 0, v247, s[22:23]
	v_cmp_gt_u32_e64 s[22:23], s47, v103
	s_mov_b32 s7, s93
	v_add_u32_e32 v41, 0x63, v65
	v_cndmask_b32_e64 v103, 0, v248, s[22:23]
	v_cmp_gt_u32_e64 s[22:23], s47, v104
	v_add_u32_e32 v96, 0x51, v65
	v_add_u32_e32 v97, 0x50, v65
	v_add_u32_e32 v106, 48, v65
	v_cndmask_b32_e64 v104, 0, v249, s[22:23]
	v_cmp_gt_u32_e64 s[22:23], s47, v105
	v_cmp_gt_u32_e32 vcc, s88, v64
	v_add_u32_e32 v86, 0x61, v65
	v_add_u32_e32 v87, 0x60, v65
	v_lshl_add_u64 v[46:47], s[6:7], 1, v[50:51]
	v_cmp_lt_u32_e64 s[12:13], s49, v96
	v_cmp_lt_u32_e64 s[14:15], s49, v97
	v_cndmask_b32_e64 v105, 0, v250, s[22:23]
	v_cmp_gt_u32_e64 s[22:23], s47, v106
	v_cmp_gt_u32_e64 s[30:31], s47, v41
	v_cndmask_b32_e64 v102, 2, 0, vcc
	v_add_u32_e32 v94, 0x53, v65
	v_add_u32_e32 v95, 0x52, v65
	v_cmp_lt_u32_e64 s[20:21], s49, v86
	v_cmp_lt_u32_e64 s[16:17], s49, v87
	v_cndmask_b32_e64 v118, 64, 0, s[12:13]
	v_cndmask_b32_e64 v119, v244, 0, s[14:15]
	v_cndmask_b32_e64 v106, 0, v251, s[22:23]
	v_add_co_u32_e64 v86, s[22:23], s0, v46
	v_add_u32_e32 v98, 0x43, v65
	v_add_u32_e32 v99, 0x42, v65
	v_cndmask_b32_e64 v107, 4, 0, s[20:21]
	v_cndmask_b32_e64 v111, 8, 0, s[16:17]
	v_cmp_lt_u32_e64 s[18:19], s49, v94
	v_cmp_lt_u32_e64 s[10:11], s49, v95
	v_addc_co_u32_e64 v87, s[22:23], 0, v47, s[22:23]
	v_or3_b32 v102, v102, v118, v119
	v_cndmask_b32_e64 v112, 16, 0, s[18:19]
	v_cndmask_b32_e64 v113, 32, 0, s[10:11]
	v_cmp_gt_u32_e64 s[6:7], s47, v98
	v_cmp_gt_u32_e64 s[8:9], s47, v99
	global_load_dwordx4 v[94:97], v[46:47], off
	global_load_dwordx4 v[98:101], v[46:47], off offset:64
	v_cndmask_b32_e64 v120, 0, v245, s[6:7]
	v_cndmask_b32_e64 v121, 0, v240, s[8:9]
	v_or_b32_e32 v118, v122, v123
	v_or_b32_e32 v103, v103, v104
	v_or_b32_e32 v104, v105, v106
	s_mov_b32 s38, 0x40000
	s_cmp_ge_i32 s45, s54
	s_waitcnt vmcnt(0) lgkmcnt(0)
	v_mfma_f32_16x16x32_bf16 v[66:69], v[66:69], v[32:35], 0
	v_mfma_f32_16x16x32_bf16 v[42:45], v[42:45], v[32:35], 0
	v_mfma_f32_16x16x32_bf16 v[56:59], v[56:59], v[32:35], 0
	v_mfma_f32_16x16x32_bf16 v[42:45], v[70:73], v[36:39], v[42:45]
	v_mfma_f32_16x16x32_bf16 v[60:63], v[60:63], v[32:35], 0
	v_mfma_f32_16x16x32_bf16 v[56:59], v[74:77], v[36:39], v[56:59]
	s_nop 5
	v_mul_f32_e32 v42, 0x3e38aa3b, v42
	v_cndmask_b32_e64 v41, v241, v42, s[30:31]
	v_mul_f32_e32 v42, 0x3e38aa3b, v43
	v_mul_f32_e32 v43, 0x3e38aa3b, v44
	v_mfma_f32_16x16x32_bf16 v[66:69], v[82:85], v[36:39], v[66:69]
	v_cndmask_b32_e64 v83, v43, v241, s[20:21]
	v_mul_f32_e32 v43, 0x3e38aa3b, v45
	global_load_dwordx4 v[70:73], v[86:87], off
	global_load_dwordx4 v[74:77], v[86:87], off offset:64
	v_or3_b32 v86, v107, v111, v102
	v_mfma_f32_16x16x32_bf16 v[60:63], v[78:81], v[36:39], v[60:63]
	v_cndmask_b32_e64 v84, v43, v241, s[16:17]
	v_mul_f32_e32 v43, 0x3e38aa3b, v56
	v_or3_b32 v86, v112, v113, v86
	v_cndmask_b32_e64 v85, v43, v241, s[18:19]
	v_mul_f32_e32 v43, 0x3e38aa3b, v57
	v_or3_b32 v78, v120, v86, v121
	v_cndmask_b32_e64 v86, v43, v241, s[10:11]
	v_mul_f32_e32 v43, 0x3e38aa3b, v58
	v_cndmask_b32_e64 v87, v43, v241, s[12:13]
	v_mul_f32_e32 v43, 0x3e38aa3b, v59
	v_cndmask_b32_e64 v102, v43, v241, s[14:15]
	v_mul_f32_e32 v43, 0x3e38aa3b, v60
	v_cndmask_b32_e64 v105, v241, v43, s[6:7]
	v_mul_f32_e32 v43, 0x3e38aa3b, v61
	v_cndmask_b32_e32 v82, v42, v241, vcc
	v_cndmask_b32_e64 v106, v241, v43, s[8:9]
	v_bitop3_b32 v43, v118, s95, v78 bitop3:0xc8
	v_or_b32_e32 v79, v118, v78
	v_max3_f32 v42, v41, s71, v82
	v_mul_f32_e32 v44, 0x3e38aa3b, v62
	v_cmp_eq_u32_e64 s[26:27], 0, v43
	v_bitop3_b32 v43, v118, s48, v78 bitop3:0xc8
	v_max3_f32 v42, v42, v83, v84
	v_cndmask_b32_e64 v107, v44, v241, s[26:27]
	v_mul_f32_e32 v44, 0x3e38aa3b, v63
	v_cmp_eq_u32_e64 s[34:35], 0, v43
	v_bitop3_b32 v43, v103, s90, v79 bitop3:0xc8
	v_or_b32_e32 v80, v103, v79
	v_max3_f32 v42, v42, v85, v86
	v_cndmask_b32_e64 v111, v44, v241, s[34:35]
	v_mul_f32_e32 v44, 0x3e38aa3b, v66
	v_cmp_eq_u32_e64 s[22:23], 0, v43
	v_bitop3_b32 v43, v103, s83, v79 bitop3:0xc8
	v_max3_f32 v42, v42, v87, v102
	v_cndmask_b32_e64 v66, v44, v241, s[22:23]
	v_mul_f32_e32 v44, 0x3e38aa3b, v67
	v_cmp_eq_u32_e64 s[24:25], 0, v43
	v_bitop3_b32 v43, v104, s50, v80 bitop3:0xc8
	v_max3_f32 v42, v42, v105, v106
	v_cndmask_b32_e64 v103, v44, v241, s[24:25]
	v_mul_f32_e32 v44, 0x3e38aa3b, v68
	v_cmp_eq_u32_e64 s[28:29], 0, v43
	v_bitop3_b32 v43, v104, s82, v80 bitop3:0xc8
	v_max3_f32 v42, v42, v107, v111
	v_cndmask_b32_e64 v68, v44, v241, s[28:29]
	v_mul_f32_e32 v44, 0x3e38aa3b, v69
	v_cmp_eq_u32_e64 s[36:37], 0, v43
	v_max3_f32 v42, v42, v66, v103
	v_add_co_u32_e64 v56, s[38:39], s38, v46
	v_cndmask_b32_e64 v69, v44, v241, s[36:37]
	v_max3_f32 v60, v42, v68, v69
	ds_bpermute_b32 v61, v109, v60
	v_addc_co_u32_e64 v57, s[38:39], 0, v47, s[38:39]
	v_add_co_u32_e64 v46, s[38:39], s76, v46
	s_waitcnt lgkmcnt(0)
	v_max_f32_e32 v61, v61, v61
	v_max_f32_e32 v60, v60, v61
	ds_bpermute_b32 v61, v108, v60
	v_addc_co_u32_e64 v47, s[38:39], 0, v47, s[38:39]
	global_load_dwordx4 v[42:45], v[56:57], off
	s_nop 0
	global_load_dwordx4 v[56:59], v[56:57], off offset:64
	s_waitcnt lgkmcnt(0)
	v_max3_f32 v67, v117, v60, v61
	global_load_dwordx4 v[60:63], v[46:47], off
	global_load_dwordx4 v[78:81], v[46:47], off offset:64
	v_sub_f32_e32 v47, v82, v67
	v_sub_f32_e32 v82, v83, v67
	v_exp_f32_e32 v82, v82
	v_sub_f32_e32 v41, v41, v67
	v_exp_f32_e32 v41, v41
	v_exp_f32_e32 v47, v47
	v_cndmask_b32_e64 v104, v82, 0, s[20:21]
	v_sub_f32_e32 v82, v84, v67
	v_exp_f32_e32 v82, v82
	v_cndmask_b32_e64 v41, 0, v41, s[30:31]
	v_add_f32_e32 v83, 0, v41
	v_cndmask_b32_e64 v47, v47, 0, vcc
	v_add_f32_e32 v83, v47, v83
	v_sub_f32_e32 v84, v85, v67
	v_add_f32_e32 v83, v104, v83
	v_cndmask_b32_e64 v85, v82, 0, s[16:17]
	v_exp_f32_e32 v84, v84
	v_add_f32_e32 v82, v85, v83
	v_sub_f32_e32 v83, v86, v67
	v_exp_f32_e32 v83, v83
	v_cndmask_b32_e64 v84, v84, 0, s[18:19]
	v_add_f32_e32 v82, v84, v82
	v_sub_f32_e32 v86, v87, v67
	v_sub_f32_e32 v87, v102, v67
	v_cndmask_b32_e64 v102, v83, 0, s[10:11]
	v_add_f32_e32 v112, v102, v82
	v_sub_f32_e32 v82, v105, v67
	v_exp_f32_e32 v82, v82
	v_exp_f32_e32 v86, v86
	v_sub_f32_e32 v105, v107, v67
	v_exp_f32_e32 v87, v87
	v_cndmask_b32_e64 v107, 0, v82, s[6:7]
	v_sub_f32_e32 v82, v103, v67
	v_exp_f32_e32 v82, v82
	v_sub_f32_e32 v46, v117, v67
	v_sub_f32_e32 v83, v106, v67
	v_exp_f32_e32 v83, v83
	v_exp_f32_e32 v46, v46
	v_cndmask_b32_e64 v86, v86, 0, s[12:13]
	v_exp_f32_e32 v105, v105
	v_sub_f32_e32 v106, v111, v67
	v_cndmask_b32_e64 v87, v87, 0, s[14:15]
	v_exp_f32_e32 v106, v106
	v_sub_f32_e32 v66, v66, v67
	v_sub_f32_e32 v68, v68, v67
	v_sub_f32_e32 v69, v69, v67
	v_cndmask_b32_e64 v117, v82, 0, s[24:25]
	v_cvt_pk_bf16_f32 v82, v41, v47
	v_add_f32_e32 v41, v86, v112
	v_exp_f32_e32 v66, v66
	v_exp_f32_e32 v68, v68
	v_exp_f32_e32 v69, v69
	v_add_f32_e32 v41, v87, v41
	v_cndmask_b32_e64 v111, 0, v83, s[8:9]
	v_cvt_pk_bf16_f32 v83, v104, v85
	v_cvt_pk_bf16_f32 v84, v84, v102
	v_cvt_pk_bf16_f32 v85, v86, v87
	v_pk_mul_f32 v[30:31], v[30:31], v[46:47] op_sel_hi:[1,0]
	v_pk_mul_f32 v[28:29], v[28:29], v[46:47] op_sel_hi:[1,0]
	v_pk_mul_f32 v[26:27], v[26:27], v[46:47] op_sel_hi:[1,0]
	v_pk_mul_f32 v[24:25], v[24:25], v[46:47] op_sel_hi:[1,0]
	v_add_f32_e32 v41, v107, v41
	v_pk_mul_f32 v[22:23], v[22:23], v[46:47] op_sel_hi:[1,0]
	v_pk_mul_f32 v[20:21], v[20:21], v[46:47] op_sel_hi:[1,0]
	v_pk_mul_f32 v[18:19], v[18:19], v[46:47] op_sel_hi:[1,0]
	v_pk_mul_f32 v[16:17], v[16:17], v[46:47] op_sel_hi:[1,0]
	v_cndmask_b32_e64 v113, v105, 0, s[26:27]
	v_mfma_f32_16x16x32_bf16 v[28:31], v[94:97], v[82:85], v[28:31]
	v_add_f32_e32 v41, v111, v41
	v_cndmask_b32_e64 v106, v106, 0, s[34:35]
	v_add_f32_e32 v41, v113, v41
	s_waitcnt vmcnt(0)
	v_mfma_f32_16x16x32_bf16 v[24:27], v[70:73], v[82:85], v[24:27]
	v_cndmask_b32_e64 v66, v66, 0, s[22:23]
	v_cndmask_b32_e64 v68, v68, 0, s[28:29]
	v_cndmask_b32_e64 v69, v69, 0, s[36:37]
	v_mfma_f32_16x16x32_bf16 v[20:23], v[42:45], v[82:85], v[20:23]
	v_add_f32_e32 v41, v106, v41
	v_cvt_pk_bf16_f32 v102, v107, v111
	v_cvt_pk_bf16_f32 v103, v113, v106
	s_waitcnt lgkmcnt(0)
	v_mfma_f32_16x16x32_bf16 v[16:19], v[60:63], v[82:85], v[16:19]
	v_cvt_pk_bf16_f32 v104, v66, v117
	v_cvt_pk_bf16_f32 v105, v68, v69
	v_add_f32_e32 v41, v66, v41
	v_add_f32_e32 v41, v117, v41
	v_mfma_f32_16x16x32_bf16 v[28:31], v[98:101], v[102:105], v[28:31]
	v_add_f32_e32 v41, v68, v41
	v_add_f32_e32 v66, v69, v41
	v_fmac_f32_e32 v66, v40, v46
	v_mfma_f32_16x16x32_bf16 v[24:27], v[74:77], v[102:105], v[24:27]
	v_mfma_f32_16x16x32_bf16 v[20:23], v[56:59], v[102:105], v[20:23]
	v_mfma_f32_16x16x32_bf16 v[16:19], v[78:81], v[102:105], v[16:19]
	s_cbranch_scc0 .LBB0_625

.LBB0_632:
	v_readlane_b32 s4, v254, 26
	v_readlane_b32 s5, v254, 27
	v_readlane_b32 s18, v254, 40
	v_readlane_b32 s19, v254, 41
	s_mov_b64 s[4:5], s[18:19]
	v_mbcnt_lo_u32_b32 v0, -1, 0
	v_mbcnt_hi_u32_b32 v0, -1, v0
	v_readlane_b32 s2, v254, 4
	s_waitcnt vmcnt(0) lgkmcnt(0)
	v_readlane_b32 s6, v254, 28
	v_readlane_b32 s7, v254, 29
	v_cmp_eq_u32_e32 vcc, 0, v0
	v_readlane_b32 s3, v254, 5
	s_and_b64 s[6:7], s[2:3], vcc
	v_readlane_b32 s8, v254, 30
	v_readlane_b32 s9, v254, 31
	v_readlane_b32 s10, v254, 32
	v_readlane_b32 s11, v254, 33
	v_readlane_b32 s12, v254, 34
	v_readlane_b32 s13, v254, 35
	v_readlane_b32 s14, v254, 36
	v_readlane_b32 s15, v254, 37
	v_readlane_b32 s16, v254, 38
	v_readlane_b32 s17, v254, 39
	s_waitcnt lgkmcnt(0)
	s_barrier
	s_and_saveexec_b64 s[2:3], s[6:7]
	v_readlane_b32 s63, v255, 21
	s_cbranch_execz .LBB0_648
	v_readlane_b32 s6, v255, 1
	s_add_i32 s16, s6, 3
	s_getreg_b32 s6, hwreg(HW_REG_XCC_ID, 0, 4)
	s_lshl_b32 s6, s6, 8
	s_and_b32 s6, s6, 0x700
	s_add_u32 s15, s4, s6
	s_addc_u32 s14, s5, 0
	v_mov_b32_e32 v0, s15
	v_add_co_u32_e32 v8, vcc, 0x2000, v0
	v_mov_b32_e32 v0, s14
	s_nop 0
	v_addc_co_u32_e32 v9, vcc, 0, v0, vcc
	v_mov_b32_e32 v0, s4
	v_add_co_u32_e32 v10, vcc, 0x2000, v0
	v_mov_b32_e32 v0, s5
	s_nop 0
	v_addc_co_u32_e32 v11, vcc, 0, v0, vcc
	global_load_dword v12, v[8:9], off sc1
	global_load_dword v0, v[10:11], off sc1
	global_load_dword v1, v[10:11], off offset:256 sc1
	global_load_dword v2, v[10:11], off offset:512 sc1
	global_load_dword v3, v[10:11], off offset:768 sc1
	global_load_dword v4, v[10:11], off offset:1024 sc1
	global_load_dword v5, v[10:11], off offset:1280 sc1
	global_load_dword v6, v[10:11], off offset:1536 sc1
	global_load_dword v7, v[10:11], off offset:1792 sc1
	v_mov_b32_e32 v10, 1
	global_atomic_add v8, v[8:9], v10, off offset:2048 sc0
	s_waitcnt vmcnt(0) lgkmcnt(0)
	v_mul_lo_u32 v9, v12, s16
	v_add_u32_e32 v8, 1, v8
	v_cmp_ne_u32_e32 vcc, v8, v9
	s_and_saveexec_b64 s[6:7], vcc
	s_xor_b64 s[6:7], exec, s[6:7]
	s_cbranch_execz .LBB0_638
	v_mov_b32_e32 v0, s15
	v_add_co_u32_e32 v0, vcc, 0x3000, v0
	v_mov_b32_e32 v1, s14
	s_nop 0
	v_addc_co_u32_e32 v1, vcc, 0, v1, vcc
	global_load_dword v0, v[0:1], off sc1
	s_add_u32 s8, s15, 0x3000
	s_addc_u32 s9, s14, 0
	s_waitcnt vmcnt(0) lgkmcnt(0)
	v_cmp_gt_u32_e32 vcc, s16, v0
	s_and_saveexec_b64 s[10:11], vcc
	s_cbranch_execz .LBB0_637
	s_mov_b64 s[12:13], 0

.LBB0_670:
	s_lshl_b32 s22, s39, 8
	v_mbcnt_lo_u32_b32 v105, -1, 0
	v_mbcnt_hi_u32_b32 v105, -1, v105
	s_add_i32 s22, s22, s31
	v_and_or_b32 v104, v105, 15, s22
	s_lshl_b32 s22, s40, 8
	v_ashrrev_i32_e32 v105, 1, v105
	s_or_b32 s22, s22, s34
	v_and_b32_e32 v105, -8, v105
	v_add_u32_e32 v106, s22, v105
	v_mov_b64_e32 v[108:109], s[14:15]
	v_ashrrev_i32_e32 v107, 31, v106
	v_mad_i64_i32 v[108:109], s[22:23], v104, s72, v[108:109]
	v_lshlrev_b64 v[106:107], 1, v[106:107]
	v_lshl_add_u64 v[156:157], v[108:109], 0, v[106:107]
	global_load_dwordx4 v[162:165], v[156:157], off
	global_load_dwordx4 v[166:169], v[156:157], off offset:256
	v_ashrrev_i32_e32 v105, 31, v104
	v_lshlrev_b64 v[104:105], 11, v[104:105]
	v_lshl_add_u64 v[104:105], s[12:13], 0, v[104:105]
	v_lshl_add_u64 v[158:159], v[104:105], 0, v[106:107]
	v_add_co_u32_e32 v104, vcc, s51, v156
	s_mov_b32 s22, 0x48000
	s_nop 0
	v_addc_co_u32_e32 v105, vcc, 0, v157, vcc
	global_load_dwordx4 v[170:173], v[104:105], off
	global_load_dwordx4 v[120:123], v[104:105], off offset:256
	v_add_co_u32_e32 v104, vcc, s1, v156
	s_mov_b64 s[24:25], 0xc0000
	s_nop 0
	v_addc_co_u32_e32 v105, vcc, 0, v157, vcc
	global_load_dwordx4 v[116:119], v[104:105], off
	global_load_dwordx4 v[112:115], v[104:105], off offset:256
	v_add_co_u32_e32 v104, vcc, s22, v156
	v_mov_b64_e32 v[238:239], v[242:243]
	s_nop 0
	v_addc_co_u32_e32 v105, vcc, 0, v157, vcc
	global_load_dwordx4 v[108:111], v[104:105], off
	s_nop 0
	global_load_dwordx4 v[104:107], v[104:105], off offset:256
	v_mov_b64_e32 v[242:243], v[244:245]
	v_mov_b32_e32 v244, v251
	v_mov_b32_e32 v245, v240
	v_mov_b32_e32 v240, v246
	v_mov_b32_e32 v246, v247
	v_mov_b32_e32 v247, v248
	v_mov_b32_e32 v248, v249
	v_mov_b32_e32 v249, v250
	v_mov_b32_e32 v250, 0x4000
	v_mov_b32_e32 v251, 0x8000
	s_waitcnt vmcnt(0) lgkmcnt(0)
	v_lshlrev_b32_e32 v174, 16, v162
	v_and_b32_e32 v175, 0xffff0000, v162
	v_lshlrev_b32_e32 v162, 16, v163
	v_and_b32_e32 v163, 0xffff0000, v163
	v_pk_fma_f32 v[148:149], v[148:149], v[162:163], 0 op_sel_hi:[1,1,0]
	v_lshlrev_b32_e32 v162, 16, v164
	v_and_b32_e32 v163, 0xffff0000, v164
	v_lshlrev_b32_e32 v164, 16, v165
	v_and_b32_e32 v165, 0xffff0000, v165
	v_pk_fma_f32 v[146:147], v[146:147], v[174:175], 0 op_sel_hi:[1,1,0]
	v_pk_fma_f32 v[164:165], v[144:145], v[164:165], 0 op_sel_hi:[1,1,0]
	v_pk_fma_f32 v[144:145], v[142:143], v[162:163], 0 op_sel_hi:[1,1,0]
	v_cvt_pk_bf16_f32 v142, v146, v147
	v_cvt_pk_bf16_f32 v143, v148, v149
	v_cvt_pk_bf16_f32 v144, v144, v145
	v_cvt_pk_bf16_f32 v145, v164, v165
	global_store_dwordx4 v[158:159], v[142:145], off
	s_nop 1
	v_lshlrev_b32_e32 v142, 16, v166
	v_and_b32_e32 v143, 0xffff0000, v166
	v_lshlrev_b32_e32 v144, 16, v167
	v_and_b32_e32 v145, 0xffff0000, v167
	v_pk_fma_f32 v[140:141], v[140:141], v[144:145], 0 op_sel_hi:[1,1,0]
	v_pk_fma_f32 v[138:139], v[138:139], v[142:143], 0 op_sel_hi:[1,1,0]
	v_lshlrev_b32_e32 v142, 16, v168
	v_and_b32_e32 v143, 0xffff0000, v168
	v_lshlrev_b32_e32 v144, 16, v169
	v_and_b32_e32 v145, 0xffff0000, v169
	v_pk_fma_f32 v[144:145], v[134:135], v[144:145], 0 op_sel_hi:[1,1,0]
	v_pk_fma_f32 v[134:135], v[132:133], v[142:143], 0 op_sel_hi:[1,1,0]
	v_cvt_pk_bf16_f32 v132, v138, v139
	v_cvt_pk_bf16_f32 v133, v140, v141
	v_cvt_pk_bf16_f32 v134, v134, v135
	v_cvt_pk_bf16_f32 v135, v144, v145
	global_store_dwordx4 v[158:159], v[132:135], off offset:256
	s_nop 1
	v_lshlrev_b32_e32 v132, 16, v170
	v_and_b32_e32 v133, 0xffff0000, v170
	v_lshlrev_b32_e32 v134, 16, v171
	v_and_b32_e32 v135, 0xffff0000, v171
	v_pk_fma_f32 v[130:131], v[130:131], v[134:135], 0 op_sel_hi:[1,1,0]
	v_pk_fma_f32 v[128:129], v[128:129], v[132:133], 0 op_sel_hi:[1,1,0]
	v_lshlrev_b32_e32 v132, 16, v172
	v_and_b32_e32 v133, 0xffff0000, v172
	v_lshlrev_b32_e32 v134, 16, v173
	v_and_b32_e32 v135, 0xffff0000, v173
	v_pk_fma_f32 v[134:135], v[126:127], v[134:135], 0 op_sel_hi:[1,1,0]
	v_pk_fma_f32 v[126:127], v[124:125], v[132:133], 0 op_sel_hi:[1,1,0]
	v_cvt_pk_bf16_f32 v124, v128, v129
	v_add_co_u32_e32 v128, vcc, s82, v158
	v_cvt_pk_bf16_f32 v125, v130, v131
	v_cvt_pk_bf16_f32 v126, v126, v127
	v_cvt_pk_bf16_f32 v127, v134, v135
	v_addc_co_u32_e32 v129, vcc, 0, v159, vcc
	global_store_dwordx4 v[128:129], v[124:127], off
	s_nop 1
	v_lshlrev_b32_e32 v124, 16, v120
	v_and_b32_e32 v125, 0xffff0000, v120
	v_lshlrev_b32_e32 v120, 16, v121
	v_and_b32_e32 v121, 0xffff0000, v121
	v_pk_fma_f32 v[102:103], v[102:103], v[120:121], 0 op_sel_hi:[1,1,0]
	v_lshlrev_b32_e32 v120, 16, v122
	v_and_b32_e32 v121, 0xffff0000, v122
	v_lshlrev_b32_e32 v122, 16, v123
	v_and_b32_e32 v123, 0xffff0000, v123
	v_pk_fma_f32 v[100:101], v[100:101], v[124:125], 0 op_sel_hi:[1,1,0]
	v_pk_fma_f32 v[122:123], v[98:99], v[122:123], 0 op_sel_hi:[1,1,0]
	v_pk_fma_f32 v[98:99], v[96:97], v[120:121], 0 op_sel_hi:[1,1,0]
	v_cvt_pk_bf16_f32 v96, v100, v101
	v_cvt_pk_bf16_f32 v97, v102, v103
	v_cvt_pk_bf16_f32 v98, v98, v99
	v_cvt_pk_bf16_f32 v99, v122, v123
	global_store_dwordx4 v[128:129], v[96:99], off offset:256
	s_nop 1
	v_lshlrev_b32_e32 v96, 16, v116
	v_and_b32_e32 v97, 0xffff0000, v116
	v_lshlrev_b32_e32 v98, 16, v117
	v_and_b32_e32 v99, 0xffff0000, v117
	v_pk_fma_f32 v[94:95], v[94:95], v[98:99], 0 op_sel_hi:[1,1,0]
	v_pk_fma_f32 v[92:93], v[92:93], v[96:97], 0 op_sel_hi:[1,1,0]
	v_lshlrev_b32_e32 v96, 16, v118
	v_and_b32_e32 v97, 0xffff0000, v118
	v_lshlrev_b32_e32 v98, 16, v119
	v_and_b32_e32 v99, 0xffff0000, v119
	v_pk_fma_f32 v[98:99], v[90:91], v[98:99], 0 op_sel_hi:[1,1,0]
	v_pk_fma_f32 v[90:91], v[88:89], v[96:97], 0 op_sel_hi:[1,1,0]
	v_cvt_pk_bf16_f32 v88, v92, v93
	v_add_co_u32_e32 v92, vcc, s94, v158
	v_cvt_pk_bf16_f32 v89, v94, v95
	v_cvt_pk_bf16_f32 v90, v90, v91
	v_cvt_pk_bf16_f32 v91, v98, v99
	v_addc_co_u32_e32 v93, vcc, 0, v159, vcc
	global_store_dwordx4 v[92:93], v[88:91], off
	s_nop 1
	v_lshlrev_b32_e32 v88, 16, v112
	v_and_b32_e32 v89, 0xffff0000, v112
	v_lshlrev_b32_e32 v90, 16, v113
	v_and_b32_e32 v91, 0xffff0000, v113
	v_pk_fma_f32 v[86:87], v[86:87], v[90:91], 0 op_sel_hi:[1,1,0]
	v_pk_fma_f32 v[84:85], v[84:85], v[88:89], 0 op_sel_hi:[1,1,0]
	v_lshlrev_b32_e32 v88, 16, v114
	v_and_b32_e32 v89, 0xffff0000, v114
	v_lshlrev_b32_e32 v90, 16, v115
	v_and_b32_e32 v91, 0xffff0000, v115
	v_pk_fma_f32 v[90:91], v[82:83], v[90:91], 0 op_sel_hi:[1,1,0]
	v_pk_fma_f32 v[82:83], v[80:81], v[88:89], 0 op_sel_hi:[1,1,0]
	v_cvt_pk_bf16_f32 v80, v84, v85
	v_cvt_pk_bf16_f32 v81, v86, v87
	v_cvt_pk_bf16_f32 v82, v82, v83
	v_cvt_pk_bf16_f32 v83, v90, v91
	global_store_dwordx4 v[92:93], v[80:83], off offset:256
	s_nop 1
	v_lshlrev_b32_e32 v80, 16, v108
	v_and_b32_e32 v81, 0xffff0000, v108
	v_lshlrev_b32_e32 v82, 16, v109
	v_and_b32_e32 v83, 0xffff0000, v109
	v_pk_fma_f32 v[78:79], v[78:79], v[82:83], 0 op_sel_hi:[1,1,0]
	v_pk_fma_f32 v[76:77], v[76:77], v[80:81], 0 op_sel_hi:[1,1,0]
	v_lshlrev_b32_e32 v80, 16, v110
	v_and_b32_e32 v81, 0xffff0000, v110
	v_lshlrev_b32_e32 v82, 16, v111
	v_and_b32_e32 v83, 0xffff0000, v111
	v_pk_fma_f32 v[82:83], v[74:75], v[82:83], 0 op_sel_hi:[1,1,0]
	v_pk_fma_f32 v[74:75], v[72:73], v[80:81], 0 op_sel_hi:[1,1,0]
	v_cvt_pk_bf16_f32 v72, v76, v77
	v_add_co_u32_e32 v76, vcc, s51, v158
	v_cvt_pk_bf16_f32 v73, v78, v79
	v_cvt_pk_bf16_f32 v74, v74, v75
	v_cvt_pk_bf16_f32 v75, v82, v83
	v_addc_co_u32_e32 v77, vcc, 0, v159, vcc
	global_store_dwordx4 v[76:77], v[72:75], off
	s_nop 1
	v_lshlrev_b32_e32 v72, 16, v104
	v_and_b32_e32 v73, 0xffff0000, v104
	v_lshlrev_b32_e32 v74, 16, v105
	v_and_b32_e32 v75, 0xffff0000, v105
	v_pk_fma_f32 v[70:71], v[70:71], v[74:75], 0 op_sel_hi:[1,1,0]
	v_pk_fma_f32 v[68:69], v[68:69], v[72:73], 0 op_sel_hi:[1,1,0]
	v_lshlrev_b32_e32 v72, 16, v106
	v_and_b32_e32 v73, 0xffff0000, v106
	v_lshlrev_b32_e32 v74, 16, v107
	v_and_b32_e32 v75, 0xffff0000, v107
	v_pk_fma_f32 v[74:75], v[66:67], v[74:75], 0 op_sel_hi:[1,1,0]
	v_pk_fma_f32 v[66:67], v[64:65], v[72:73], 0 op_sel_hi:[1,1,0]
	v_cvt_pk_bf16_f32 v64, v68, v69
	v_cvt_pk_bf16_f32 v65, v70, v71
	v_cvt_pk_bf16_f32 v66, v66, v67
	v_cvt_pk_bf16_f32 v67, v74, v75
	v_lshl_add_u64 v[68:69], v[156:157], 0, s[24:25]
	v_lshl_add_u64 v[70:71], v[158:159], 0, s[78:79]
	global_store_dwordx4 v[76:77], v[64:67], off offset:256
	global_load_dwordx4 v[72:75], v[68:69], off
	global_load_dwordx4 v[76:79], v[68:69], off offset:256
	v_add_co_u32_e32 v64, vcc, s51, v68
	s_waitcnt vmcnt(0) lgkmcnt(0)
	v_lshlrev_b32_e32 v100, 16, v72
	v_addc_co_u32_e32 v65, vcc, 0, v69, vcc
	global_load_dwordx4 v[80:83], v[64:65], off
	global_load_dwordx4 v[84:87], v[64:65], off offset:256
	v_add_co_u32_e32 v64, vcc, s1, v68
	v_and_b32_e32 v101, 0xffff0000, v72
	s_nop 0
	v_addc_co_u32_e32 v65, vcc, 0, v69, vcc
	global_load_dwordx4 v[88:91], v[64:65], off
	global_load_dwordx4 v[92:95], v[64:65], off offset:256
	v_add_co_u32_e32 v64, vcc, s22, v68
	v_lshlrev_b32_e32 v72, 16, v73
	s_nop 0
	v_addc_co_u32_e32 v65, vcc, 0, v69, vcc
	global_load_dwordx4 v[96:99], v[64:65], off
	s_nop 0
	global_load_dwordx4 v[64:67], v[64:65], off offset:256
	v_and_b32_e32 v73, 0xffff0000, v73
	v_pk_fma_f32 v[62:63], v[62:63], v[72:73], 0 op_sel_hi:[1,1,0]
	v_lshlrev_b32_e32 v72, 16, v74
	v_and_b32_e32 v73, 0xffff0000, v74
	v_lshlrev_b32_e32 v74, 16, v75
	v_and_b32_e32 v75, 0xffff0000, v75
	v_pk_fma_f32 v[60:61], v[60:61], v[100:101], 0 op_sel_hi:[1,1,0]
	v_pk_fma_f32 v[74:75], v[58:59], v[74:75], 0 op_sel_hi:[1,1,0]
	v_pk_fma_f32 v[58:59], v[56:57], v[72:73], 0 op_sel_hi:[1,1,0]
	v_cvt_pk_bf16_f32 v56, v60, v61
	v_cvt_pk_bf16_f32 v57, v62, v63
	v_cvt_pk_bf16_f32 v58, v58, v59
	v_cvt_pk_bf16_f32 v59, v74, v75
	global_store_dwordx4 v[70:71], v[56:59], off
	s_mov_b64 s[22:23], -1
	s_nop 0
	v_lshlrev_b32_e32 v56, 16, v76
	v_and_b32_e32 v57, 0xffff0000, v76
	v_lshlrev_b32_e32 v58, 16, v77
	v_and_b32_e32 v59, 0xffff0000, v77
	v_pk_fma_f32 v[54:55], v[54:55], v[58:59], 0 op_sel_hi:[1,1,0]
	v_pk_fma_f32 v[52:53], v[52:53], v[56:57], 0 op_sel_hi:[1,1,0]
	v_lshlrev_b32_e32 v56, 16, v78
	v_and_b32_e32 v57, 0xffff0000, v78
	v_lshlrev_b32_e32 v58, 16, v79
	v_and_b32_e32 v59, 0xffff0000, v79
	v_pk_fma_f32 v[58:59], v[50:51], v[58:59], 0 op_sel_hi:[1,1,0]
	v_pk_fma_f32 v[50:51], v[48:49], v[56:57], 0 op_sel_hi:[1,1,0]
	v_cvt_pk_bf16_f32 v48, v52, v53
	v_cvt_pk_bf16_f32 v49, v54, v55
	v_cvt_pk_bf16_f32 v50, v50, v51
	v_cvt_pk_bf16_f32 v51, v58, v59
	global_store_dwordx4 v[70:71], v[48:51], off offset:256
	s_waitcnt vmcnt(0) lgkmcnt(0)
	s_nop 0
	v_lshlrev_b32_e32 v48, 16, v80
	v_and_b32_e32 v49, 0xffff0000, v80
	v_lshlrev_b32_e32 v50, 16, v81
	v_and_b32_e32 v51, 0xffff0000, v81
	v_pk_fma_f32 v[46:47], v[46:47], v[50:51], 0 op_sel_hi:[1,1,0]
	v_pk_fma_f32 v[44:45], v[44:45], v[48:49], 0 op_sel_hi:[1,1,0]
	v_lshlrev_b32_e32 v48, 16, v82
	v_and_b32_e32 v49, 0xffff0000, v82
	v_lshlrev_b32_e32 v50, 16, v83
	v_and_b32_e32 v51, 0xffff0000, v83
	v_pk_fma_f32 v[50:51], v[42:43], v[50:51], 0 op_sel_hi:[1,1,0]
	v_pk_fma_f32 v[42:43], v[40:41], v[48:49], 0 op_sel_hi:[1,1,0]
	v_cvt_pk_bf16_f32 v40, v44, v45
	v_add_co_u32_e32 v44, vcc, s82, v70
	v_cvt_pk_bf16_f32 v41, v46, v47
	v_cvt_pk_bf16_f32 v42, v42, v43
	v_cvt_pk_bf16_f32 v43, v50, v51
	v_addc_co_u32_e32 v45, vcc, 0, v71, vcc
	global_store_dwordx4 v[44:45], v[40:43], off
	s_nop 1
	v_lshlrev_b32_e32 v40, 16, v84
	v_and_b32_e32 v41, 0xffff0000, v84
	v_lshlrev_b32_e32 v42, 16, v85
	v_and_b32_e32 v43, 0xffff0000, v85
	v_pk_fma_f32 v[38:39], v[38:39], v[42:43], 0 op_sel_hi:[1,1,0]
	v_pk_fma_f32 v[36:37], v[36:37], v[40:41], 0 op_sel_hi:[1,1,0]
	v_lshlrev_b32_e32 v40, 16, v86
	v_and_b32_e32 v41, 0xffff0000, v86
	v_lshlrev_b32_e32 v42, 16, v87
	v_and_b32_e32 v43, 0xffff0000, v87
	v_pk_fma_f32 v[42:43], v[34:35], v[42:43], 0 op_sel_hi:[1,1,0]
	v_pk_fma_f32 v[34:35], v[32:33], v[40:41], 0 op_sel_hi:[1,1,0]
	v_cvt_pk_bf16_f32 v32, v36, v37
	v_cvt_pk_bf16_f32 v33, v38, v39
	v_cvt_pk_bf16_f32 v34, v34, v35
	v_cvt_pk_bf16_f32 v35, v42, v43
	global_store_dwordx4 v[44:45], v[32:35], off offset:256
	s_nop 1
	v_lshlrev_b32_e32 v32, 16, v88
	v_and_b32_e32 v33, 0xffff0000, v88
	v_lshlrev_b32_e32 v34, 16, v89
	v_and_b32_e32 v35, 0xffff0000, v89
	v_pk_fma_f32 v[30:31], v[30:31], v[34:35], 0 op_sel_hi:[1,1,0]
	v_pk_fma_f32 v[28:29], v[28:29], v[32:33], 0 op_sel_hi:[1,1,0]
	v_lshlrev_b32_e32 v32, 16, v90
	v_and_b32_e32 v33, 0xffff0000, v90
	v_lshlrev_b32_e32 v34, 16, v91
	v_and_b32_e32 v35, 0xffff0000, v91
	v_pk_fma_f32 v[34:35], v[26:27], v[34:35], 0 op_sel_hi:[1,1,0]
	v_pk_fma_f32 v[26:27], v[24:25], v[32:33], 0 op_sel_hi:[1,1,0]
	v_cvt_pk_bf16_f32 v24, v28, v29
	v_add_co_u32_e32 v28, vcc, s94, v70
	v_cvt_pk_bf16_f32 v25, v30, v31
	v_cvt_pk_bf16_f32 v26, v26, v27
	v_cvt_pk_bf16_f32 v27, v34, v35
	v_addc_co_u32_e32 v29, vcc, 0, v71, vcc
	global_store_dwordx4 v[28:29], v[24:27], off
	s_nop 1
	v_lshlrev_b32_e32 v24, 16, v92
	v_and_b32_e32 v25, 0xffff0000, v92
	v_lshlrev_b32_e32 v26, 16, v93
	v_and_b32_e32 v27, 0xffff0000, v93
	v_pk_fma_f32 v[22:23], v[22:23], v[26:27], 0 op_sel_hi:[1,1,0]
	v_pk_fma_f32 v[20:21], v[20:21], v[24:25], 0 op_sel_hi:[1,1,0]
	v_lshlrev_b32_e32 v24, 16, v94
	v_and_b32_e32 v25, 0xffff0000, v94
	v_lshlrev_b32_e32 v26, 16, v95
	v_and_b32_e32 v27, 0xffff0000, v95
	v_pk_fma_f32 v[26:27], v[18:19], v[26:27], 0 op_sel_hi:[1,1,0]
	v_pk_fma_f32 v[18:19], v[16:17], v[24:25], 0 op_sel_hi:[1,1,0]
	v_cvt_pk_bf16_f32 v16, v20, v21
	v_cvt_pk_bf16_f32 v17, v22, v23
	v_cvt_pk_bf16_f32 v18, v18, v19
	v_cvt_pk_bf16_f32 v19, v26, v27
	global_store_dwordx4 v[28:29], v[16:19], off offset:256
	s_nop 1
	v_lshlrev_b32_e32 v16, 16, v96
	v_and_b32_e32 v17, 0xffff0000, v96
	v_lshlrev_b32_e32 v18, 16, v97
	v_and_b32_e32 v19, 0xffff0000, v97
	v_pk_fma_f32 v[14:15], v[14:15], v[18:19], 0 op_sel_hi:[1,1,0]
	v_pk_fma_f32 v[12:13], v[12:13], v[16:17], 0 op_sel_hi:[1,1,0]
	v_lshlrev_b32_e32 v16, 16, v98
	v_and_b32_e32 v17, 0xffff0000, v98
	v_lshlrev_b32_e32 v18, 16, v99
	v_and_b32_e32 v19, 0xffff0000, v99
	v_pk_fma_f32 v[18:19], v[10:11], v[18:19], 0 op_sel_hi:[1,1,0]
	v_pk_fma_f32 v[10:11], v[8:9], v[16:17], 0 op_sel_hi:[1,1,0]
	v_cvt_pk_bf16_f32 v8, v12, v13
	v_add_co_u32_e32 v12, vcc, s51, v70
	v_cvt_pk_bf16_f32 v9, v14, v15
	v_cvt_pk_bf16_f32 v10, v10, v11
	v_cvt_pk_bf16_f32 v11, v18, v19
	v_addc_co_u32_e32 v13, vcc, 0, v71, vcc
	global_store_dwordx4 v[12:13], v[8:11], off
	s_and_b64 vcc, exec, s[2:3]
	s_nop 0
	v_lshlrev_b32_e32 v8, 16, v64
	v_and_b32_e32 v9, 0xffff0000, v64
	v_lshlrev_b32_e32 v10, 16, v65
	v_and_b32_e32 v11, 0xffff0000, v65
	v_pk_fma_f32 v[6:7], v[6:7], v[10:11], 0 op_sel_hi:[1,1,0]
	v_pk_fma_f32 v[4:5], v[4:5], v[8:9], 0 op_sel_hi:[1,1,0]
	v_lshlrev_b32_e32 v8, 16, v66
	v_and_b32_e32 v9, 0xffff0000, v66
	v_lshlrev_b32_e32 v10, 16, v67
	v_and_b32_e32 v11, 0xffff0000, v67
	v_pk_fma_f32 v[10:11], v[2:3], v[10:11], 0 op_sel_hi:[1,1,0]
	v_pk_fma_f32 v[2:3], v[0:1], v[8:9], 0 op_sel_hi:[1,1,0]
	v_cvt_pk_bf16_f32 v0, v4, v5
	v_cvt_pk_bf16_f32 v1, v6, v7
	v_cvt_pk_bf16_f32 v2, v2, v3
	v_cvt_pk_bf16_f32 v3, v10, v11
	global_store_dwordx4 v[12:13], v[0:3], off offset:256
	s_nop 1
	v_lshl_add_u64 v[0:1], v[68:69], 0, s[24:25]
	v_lshl_add_u64 v[2:3], v[70:71], 0, s[78:79]
	s_cbranch_vccnz .LBB0_657
	s_andn2_b64 vcc, exec, s[10:11]
	s_cbranch_vccnz .LBB0_656
	s_barrier
	s_branch .LBB0_656

.LBB0_696:
	s_lshl_b32 s4, s45, 8
	v_mbcnt_lo_u32_b32 v129, -1, 0
	v_mbcnt_hi_u32_b32 v129, -1, v129
	s_add_i32 s4, s4, s39
	v_and_or_b32 v128, v129, 15, s4
	s_lshl_b32 s4, s52, 8
	v_ashrrev_i32_e32 v129, 1, v129
	s_or_b32 s4, s4, s40
	v_and_b32_e32 v129, -8, v129
	v_add_u32_e32 v130, s4, v129
	v_ashrrev_i32_e32 v129, 31, v128
	v_mov_b64_e32 v[132:133], s[14:15]
	v_ashrrev_i32_e32 v131, 31, v130
	v_mad_i64_i32 v[132:133], s[4:5], v128, s72, v[132:133]
	v_lshlrev_b64 v[130:131], 1, v[130:131]
	v_lshlrev_b64 v[128:129], 11, v[128:129]
	v_lshl_add_u64 v[196:197], v[132:133], 0, v[130:131]
	v_lshl_add_u64 v[128:129], s[12:13], 0, v[128:129]
	v_lshl_add_u64 v[198:199], v[128:129], 0, v[130:131]
	global_load_dwordx4 v[204:207], v[196:197], off
	global_load_dwordx4 v[220:223], v[198:199], off
	global_load_dwordx4 v[174:177], v[196:197], off offset:256
	global_load_dwordx4 v[182:185], v[198:199], off offset:256
	v_add_co_u32_e32 v128, vcc, s51, v196
	s_mov_b32 s4, 0x48000
	s_nop 0
	v_addc_co_u32_e32 v129, vcc, 0, v197, vcc
	global_load_dwordx4 v[170:173], v[128:129], off
	v_add_co_u32_e32 v218, vcc, s82, v198
	s_mov_b64 s[24:25], 0xc0000
	s_nop 0
	v_addc_co_u32_e32 v219, vcc, 0, v199, vcc
	global_load_dwordx4 v[178:181], v[218:219], off
	global_load_dwordx4 v[158:161], v[128:129], off offset:256
	global_load_dwordx4 v[166:169], v[218:219], off offset:256
	v_add_co_u32_e32 v128, vcc, s1, v196
	s_waitcnt vmcnt(0) lgkmcnt(0)
	v_lshlrev_b32_e32 v208, 16, v220
	v_addc_co_u32_e32 v129, vcc, 0, v197, vcc
	global_load_dwordx4 v[154:157], v[128:129], off
	v_add_co_u32_e32 v216, vcc, s94, v198
	v_and_b32_e32 v209, 0xffff0000, v220
	s_nop 0
	v_addc_co_u32_e32 v217, vcc, 0, v199, vcc
	global_load_dwordx4 v[162:165], v[216:217], off
	global_load_dwordx4 v[142:145], v[128:129], off offset:256
	global_load_dwordx4 v[150:153], v[216:217], off offset:256
	v_add_co_u32_e32 v128, vcc, s4, v196
	v_lshlrev_b32_e32 v210, 16, v221
	s_nop 0
	v_addc_co_u32_e32 v129, vcc, 0, v197, vcc
	global_load_dwordx4 v[132:135], v[128:129], off
	v_add_co_u32_e32 v200, vcc, s51, v198
	v_and_b32_e32 v211, 0xffff0000, v221
	s_nop 0
	v_addc_co_u32_e32 v201, vcc, 0, v199, vcc
	global_load_dwordx4 v[146:149], v[200:201], off
	s_nop 0
	global_load_dwordx4 v[128:131], v[128:129], off offset:256
	s_nop 0
	global_load_dwordx4 v[138:141], v[200:201], off offset:256
	v_lshlrev_b32_e32 v220, 16, v204
	v_and_b32_e32 v221, 0xffff0000, v204
	v_lshlrev_b32_e32 v204, 16, v205
	v_and_b32_e32 v205, 0xffff0000, v205
	v_lshlrev_b32_e32 v212, 16, v222
	v_and_b32_e32 v213, 0xffff0000, v222
	v_lshlrev_b32_e32 v214, 16, v223
	v_and_b32_e32 v215, 0xffff0000, v223
	v_pk_fma_f32 v[126:127], v[126:127], v[204:205], v[210:211]
	v_lshlrev_b32_e32 v204, 16, v206
	v_and_b32_e32 v205, 0xffff0000, v206
	v_lshlrev_b32_e32 v206, 16, v207
	v_and_b32_e32 v207, 0xffff0000, v207
	v_pk_fma_f32 v[124:125], v[124:125], v[220:221], v[208:209]
	v_pk_fma_f32 v[206:207], v[122:123], v[206:207], v[214:215]
	v_pk_fma_f32 v[122:123], v[120:121], v[204:205], v[212:213]
	v_cvt_pk_bf16_f32 v120, v124, v125
	v_cvt_pk_bf16_f32 v121, v126, v127
	v_cvt_pk_bf16_f32 v122, v122, v123
	v_cvt_pk_bf16_f32 v123, v206, v207
	global_store_dwordx4 v[198:199], v[120:123], off
	v_lshlrev_b32_e32 v124, 16, v184
	v_and_b32_e32 v125, 0xffff0000, v184
	v_lshlrev_b32_e32 v120, 16, v182
	v_and_b32_e32 v121, 0xffff0000, v182
	v_lshlrev_b32_e32 v122, 16, v183
	v_and_b32_e32 v123, 0xffff0000, v183
	v_lshlrev_b32_e32 v182, 16, v174
	v_and_b32_e32 v183, 0xffff0000, v174
	v_lshlrev_b32_e32 v174, 16, v175
	v_and_b32_e32 v175, 0xffff0000, v175
	v_lshlrev_b32_e32 v126, 16, v185
	v_and_b32_e32 v127, 0xffff0000, v185
	v_pk_fma_f32 v[118:119], v[118:119], v[174:175], v[122:123]
	v_pk_fma_f32 v[116:117], v[116:117], v[182:183], v[120:121]
	v_lshlrev_b32_e32 v120, 16, v176
	v_and_b32_e32 v121, 0xffff0000, v176
	v_lshlrev_b32_e32 v122, 16, v177
	v_and_b32_e32 v123, 0xffff0000, v177
	v_pk_fma_f32 v[122:123], v[114:115], v[122:123], v[126:127]
	v_pk_fma_f32 v[114:115], v[112:113], v[120:121], v[124:125]
	v_cvt_pk_bf16_f32 v112, v116, v117
	v_cvt_pk_bf16_f32 v113, v118, v119
	v_cvt_pk_bf16_f32 v114, v114, v115
	v_cvt_pk_bf16_f32 v115, v122, v123
	global_store_dwordx4 v[198:199], v[112:115], off offset:256
	v_lshlrev_b32_e32 v120, 16, v170
	v_and_b32_e32 v121, 0xffff0000, v170
	v_lshlrev_b32_e32 v112, 16, v178
	v_and_b32_e32 v113, 0xffff0000, v178
	v_lshlrev_b32_e32 v114, 16, v179
	v_and_b32_e32 v115, 0xffff0000, v179
	v_lshlrev_b32_e32 v122, 16, v171
	v_and_b32_e32 v123, 0xffff0000, v171
	v_lshlrev_b32_e32 v116, 16, v180
	v_and_b32_e32 v117, 0xffff0000, v180
	v_lshlrev_b32_e32 v118, 16, v181
	v_and_b32_e32 v119, 0xffff0000, v181
	v_pk_fma_f32 v[110:111], v[110:111], v[122:123], v[114:115]
	v_pk_fma_f32 v[108:109], v[108:109], v[120:121], v[112:113]
	v_lshlrev_b32_e32 v112, 16, v172
	v_and_b32_e32 v113, 0xffff0000, v172
	v_lshlrev_b32_e32 v114, 16, v173
	v_and_b32_e32 v115, 0xffff0000, v173
	v_pk_fma_f32 v[114:115], v[106:107], v[114:115], v[118:119]
	v_pk_fma_f32 v[106:107], v[104:105], v[112:113], v[116:117]
	v_cvt_pk_bf16_f32 v104, v108, v109
	v_cvt_pk_bf16_f32 v105, v110, v111
	v_cvt_pk_bf16_f32 v106, v106, v107
	v_cvt_pk_bf16_f32 v107, v114, v115
	global_store_dwordx4 v[218:219], v[104:107], off
	v_lshlrev_b32_e32 v112, 16, v158
	v_and_b32_e32 v113, 0xffff0000, v158
	v_lshlrev_b32_e32 v104, 16, v166
	v_and_b32_e32 v105, 0xffff0000, v166
	v_lshlrev_b32_e32 v106, 16, v167
	v_and_b32_e32 v107, 0xffff0000, v167
	v_lshlrev_b32_e32 v114, 16, v159
	v_and_b32_e32 v115, 0xffff0000, v159
	v_lshlrev_b32_e32 v108, 16, v168
	v_and_b32_e32 v109, 0xffff0000, v168
	v_lshlrev_b32_e32 v110, 16, v169
	v_and_b32_e32 v111, 0xffff0000, v169
	v_pk_fma_f32 v[102:103], v[102:103], v[114:115], v[106:107]
	v_pk_fma_f32 v[100:101], v[100:101], v[112:113], v[104:105]
	v_lshlrev_b32_e32 v104, 16, v160
	v_and_b32_e32 v105, 0xffff0000, v160
	v_lshlrev_b32_e32 v106, 16, v161
	v_and_b32_e32 v107, 0xffff0000, v161
	v_pk_fma_f32 v[106:107], v[98:99], v[106:107], v[110:111]
	v_pk_fma_f32 v[98:99], v[96:97], v[104:105], v[108:109]
	v_cvt_pk_bf16_f32 v96, v100, v101
	v_cvt_pk_bf16_f32 v97, v102, v103
	v_cvt_pk_bf16_f32 v98, v98, v99
	v_cvt_pk_bf16_f32 v99, v106, v107
	global_store_dwordx4 v[218:219], v[96:99], off offset:256
	s_waitcnt vmcnt(0) lgkmcnt(0)
	v_lshlrev_b32_e32 v104, 16, v154
	v_and_b32_e32 v105, 0xffff0000, v154
	v_lshlrev_b32_e32 v96, 16, v162
	v_and_b32_e32 v97, 0xffff0000, v162
	v_lshlrev_b32_e32 v98, 16, v163
	v_and_b32_e32 v99, 0xffff0000, v163
	v_lshlrev_b32_e32 v106, 16, v155
	v_and_b32_e32 v107, 0xffff0000, v155
	v_lshlrev_b32_e32 v100, 16, v164
	v_and_b32_e32 v101, 0xffff0000, v164
	v_lshlrev_b32_e32 v102, 16, v165
	v_and_b32_e32 v103, 0xffff0000, v165
	v_pk_fma_f32 v[94:95], v[94:95], v[106:107], v[98:99]
	v_pk_fma_f32 v[92:93], v[92:93], v[104:105], v[96:97]
	v_lshlrev_b32_e32 v96, 16, v156
	v_and_b32_e32 v97, 0xffff0000, v156
	v_lshlrev_b32_e32 v98, 16, v157
	v_and_b32_e32 v99, 0xffff0000, v157
	v_pk_fma_f32 v[98:99], v[90:91], v[98:99], v[102:103]
	v_pk_fma_f32 v[90:91], v[88:89], v[96:97], v[100:101]
	v_cvt_pk_bf16_f32 v88, v92, v93
	v_cvt_pk_bf16_f32 v89, v94, v95
	v_cvt_pk_bf16_f32 v90, v90, v91
	v_cvt_pk_bf16_f32 v91, v98, v99
	global_store_dwordx4 v[216:217], v[88:91], off
	v_lshlrev_b32_e32 v96, 16, v142
	v_and_b32_e32 v97, 0xffff0000, v142
	v_lshlrev_b32_e32 v88, 16, v150
	v_and_b32_e32 v89, 0xffff0000, v150
	v_lshlrev_b32_e32 v90, 16, v151
	v_and_b32_e32 v91, 0xffff0000, v151
	v_lshlrev_b32_e32 v98, 16, v143
	v_and_b32_e32 v99, 0xffff0000, v143
	v_lshlrev_b32_e32 v92, 16, v152
	v_and_b32_e32 v93, 0xffff0000, v152
	v_lshlrev_b32_e32 v94, 16, v153
	v_and_b32_e32 v95, 0xffff0000, v153
	v_pk_fma_f32 v[86:87], v[86:87], v[98:99], v[90:91]
	v_pk_fma_f32 v[84:85], v[84:85], v[96:97], v[88:89]
	v_lshlrev_b32_e32 v88, 16, v144
	v_and_b32_e32 v89, 0xffff0000, v144
	v_lshlrev_b32_e32 v90, 16, v145
	v_and_b32_e32 v91, 0xffff0000, v145
	v_pk_fma_f32 v[90:91], v[82:83], v[90:91], v[94:95]
	v_pk_fma_f32 v[82:83], v[80:81], v[88:89], v[92:93]
	v_cvt_pk_bf16_f32 v80, v84, v85
	v_cvt_pk_bf16_f32 v81, v86, v87
	v_cvt_pk_bf16_f32 v82, v82, v83
	v_cvt_pk_bf16_f32 v83, v90, v91
	global_store_dwordx4 v[216:217], v[80:83], off offset:256
	v_lshlrev_b32_e32 v88, 16, v132
	v_and_b32_e32 v89, 0xffff0000, v132
	v_lshlrev_b32_e32 v80, 16, v146
	v_and_b32_e32 v81, 0xffff0000, v146
	v_lshlrev_b32_e32 v82, 16, v147
	v_and_b32_e32 v83, 0xffff0000, v147
	v_lshlrev_b32_e32 v90, 16, v133
	v_and_b32_e32 v91, 0xffff0000, v133
	v_lshlrev_b32_e32 v84, 16, v148
	v_and_b32_e32 v85, 0xffff0000, v148
	v_lshlrev_b32_e32 v86, 16, v149
	v_and_b32_e32 v87, 0xffff0000, v149
	v_pk_fma_f32 v[78:79], v[78:79], v[90:91], v[82:83]
	v_pk_fma_f32 v[76:77], v[76:77], v[88:89], v[80:81]
	v_lshlrev_b32_e32 v80, 16, v134
	v_and_b32_e32 v81, 0xffff0000, v134
	v_lshlrev_b32_e32 v82, 16, v135
	v_and_b32_e32 v83, 0xffff0000, v135
	v_pk_fma_f32 v[82:83], v[74:75], v[82:83], v[86:87]
	v_pk_fma_f32 v[74:75], v[72:73], v[80:81], v[84:85]
	v_cvt_pk_bf16_f32 v72, v76, v77
	v_cvt_pk_bf16_f32 v73, v78, v79
	v_cvt_pk_bf16_f32 v74, v74, v75
	v_cvt_pk_bf16_f32 v75, v82, v83
	global_store_dwordx4 v[200:201], v[72:75], off
	v_lshlrev_b32_e32 v80, 16, v128
	v_and_b32_e32 v81, 0xffff0000, v128
	v_lshlrev_b32_e32 v72, 16, v138
	v_and_b32_e32 v73, 0xffff0000, v138
	v_lshlrev_b32_e32 v74, 16, v139
	v_and_b32_e32 v75, 0xffff0000, v139
	v_lshlrev_b32_e32 v82, 16, v129
	v_and_b32_e32 v83, 0xffff0000, v129
	v_lshlrev_b32_e32 v76, 16, v140
	v_and_b32_e32 v77, 0xffff0000, v140
	v_lshlrev_b32_e32 v78, 16, v141
	v_and_b32_e32 v79, 0xffff0000, v141
	v_pk_fma_f32 v[70:71], v[70:71], v[82:83], v[74:75]
	v_pk_fma_f32 v[68:69], v[68:69], v[80:81], v[72:73]
	v_lshlrev_b32_e32 v72, 16, v130
	v_and_b32_e32 v73, 0xffff0000, v130
	v_lshlrev_b32_e32 v74, 16, v131
	v_and_b32_e32 v75, 0xffff0000, v131
	v_pk_fma_f32 v[74:75], v[66:67], v[74:75], v[78:79]
	v_pk_fma_f32 v[66:67], v[64:65], v[72:73], v[76:77]
	v_cvt_pk_bf16_f32 v64, v68, v69
	v_cvt_pk_bf16_f32 v65, v70, v71
	v_cvt_pk_bf16_f32 v66, v66, v67
	v_cvt_pk_bf16_f32 v67, v74, v75
	v_lshl_add_u64 v[92:93], v[196:197], 0, s[24:25]
	v_lshl_add_u64 v[94:95], v[198:199], 0, s[78:79]
	global_store_dwordx4 v[200:201], v[64:67], off offset:256
	global_load_dwordx4 v[102:105], v[92:93], off
	global_load_dwordx4 v[106:109], v[94:95], off
	global_load_dwordx4 v[110:113], v[92:93], off offset:256
	global_load_dwordx4 v[114:117], v[94:95], off offset:256
	v_add_co_u32_e32 v64, vcc, s51, v92
	s_waitcnt vmcnt(0) lgkmcnt(0)
	v_lshlrev_b32_e32 v144, 16, v102
	v_addc_co_u32_e32 v65, vcc, 0, v93, vcc
	global_load_dwordx4 v[118:121], v[64:65], off
	v_add_co_u32_e32 v100, vcc, s82, v94
	v_lshlrev_b32_e32 v134, 16, v106
	s_nop 0
	v_addc_co_u32_e32 v101, vcc, 0, v95, vcc
	global_load_dwordx4 v[122:125], v[100:101], off
	global_load_dwordx4 v[126:129], v[64:65], off offset:256
	global_load_dwordx4 v[130:133], v[100:101], off offset:256
	v_add_co_u32_e32 v64, vcc, s1, v92
	v_and_b32_e32 v135, 0xffff0000, v106
	s_nop 0
	v_addc_co_u32_e32 v65, vcc, 0, v93, vcc
	global_load_dwordx4 v[88:91], v[64:65], off
	v_add_co_u32_e32 v98, vcc, s94, v94
	v_lshlrev_b32_e32 v106, 16, v107
	s_nop 0
	v_addc_co_u32_e32 v99, vcc, 0, v95, vcc
	global_load_dwordx4 v[138:141], v[98:99], off
	global_load_dwordx4 v[80:83], v[64:65], off offset:256
	global_load_dwordx4 v[84:87], v[98:99], off offset:256
	v_add_co_u32_e32 v64, vcc, s4, v92
	v_and_b32_e32 v107, 0xffff0000, v107
	s_nop 0
	v_addc_co_u32_e32 v65, vcc, 0, v93, vcc
	global_load_dwordx4 v[72:75], v[64:65], off
	v_add_co_u32_e32 v96, vcc, s51, v94
	v_and_b32_e32 v145, 0xffff0000, v102
	s_nop 0
	v_addc_co_u32_e32 v97, vcc, 0, v95, vcc
	global_load_dwordx4 v[76:79], v[96:97], off
	s_nop 0
	global_load_dwordx4 v[64:67], v[64:65], off offset:256
	s_nop 0
	global_load_dwordx4 v[68:71], v[96:97], off offset:256
	v_lshlrev_b32_e32 v102, 16, v103
	v_and_b32_e32 v103, 0xffff0000, v103
	v_lshlrev_b32_e32 v142, 16, v108
	v_and_b32_e32 v143, 0xffff0000, v108
	v_lshlrev_b32_e32 v108, 16, v109
	v_and_b32_e32 v109, 0xffff0000, v109
	v_pk_fma_f32 v[62:63], v[62:63], v[102:103], v[106:107]
	v_lshlrev_b32_e32 v102, 16, v104
	v_and_b32_e32 v103, 0xffff0000, v104
	v_lshlrev_b32_e32 v104, 16, v105
	v_and_b32_e32 v105, 0xffff0000, v105
	v_pk_fma_f32 v[60:61], v[60:61], v[144:145], v[134:135]
	v_pk_fma_f32 v[104:105], v[58:59], v[104:105], v[108:109]
	v_pk_fma_f32 v[58:59], v[56:57], v[102:103], v[142:143]
	v_cvt_pk_bf16_f32 v56, v60, v61
	v_cvt_pk_bf16_f32 v57, v62, v63
	v_cvt_pk_bf16_f32 v58, v58, v59
	v_cvt_pk_bf16_f32 v59, v104, v105
	global_store_dwordx4 v[94:95], v[56:59], off
	v_lshlrev_b32_e32 v102, 16, v110
	v_and_b32_e32 v103, 0xffff0000, v110
	v_lshlrev_b32_e32 v56, 16, v114
	v_and_b32_e32 v57, 0xffff0000, v114
	v_lshlrev_b32_e32 v58, 16, v115
	v_and_b32_e32 v59, 0xffff0000, v115
	v_lshlrev_b32_e32 v104, 16, v111
	v_and_b32_e32 v105, 0xffff0000, v111
	v_lshlrev_b32_e32 v60, 16, v116
	v_and_b32_e32 v61, 0xffff0000, v116
	v_lshlrev_b32_e32 v62, 16, v117
	v_and_b32_e32 v63, 0xffff0000, v117
	v_pk_fma_f32 v[54:55], v[54:55], v[104:105], v[58:59]
	v_pk_fma_f32 v[52:53], v[52:53], v[102:103], v[56:57]
	v_lshlrev_b32_e32 v56, 16, v112
	v_and_b32_e32 v57, 0xffff0000, v112
	v_lshlrev_b32_e32 v58, 16, v113
	v_and_b32_e32 v59, 0xffff0000, v113
	v_pk_fma_f32 v[58:59], v[50:51], v[58:59], v[62:63]
	v_pk_fma_f32 v[50:51], v[48:49], v[56:57], v[60:61]
	v_cvt_pk_bf16_f32 v48, v52, v53
	v_cvt_pk_bf16_f32 v49, v54, v55
	v_cvt_pk_bf16_f32 v50, v50, v51
	v_cvt_pk_bf16_f32 v51, v58, v59
	global_store_dwordx4 v[94:95], v[48:51], off offset:256
	s_mov_b64 s[4:5], -1
	s_and_b64 vcc, exec, s[2:3]
	s_waitcnt vmcnt(0) lgkmcnt(0)
	v_lshlrev_b32_e32 v56, 16, v118
	v_and_b32_e32 v57, 0xffff0000, v118
	v_lshlrev_b32_e32 v58, 16, v119
	v_and_b32_e32 v59, 0xffff0000, v119
	v_lshlrev_b32_e32 v48, 16, v122
	v_and_b32_e32 v49, 0xffff0000, v122
	v_lshlrev_b32_e32 v50, 16, v123
	v_and_b32_e32 v51, 0xffff0000, v123
	v_lshlrev_b32_e32 v52, 16, v124
	v_and_b32_e32 v53, 0xffff0000, v124
	v_lshlrev_b32_e32 v54, 16, v125
	v_and_b32_e32 v55, 0xffff0000, v125
	v_pk_fma_f32 v[46:47], v[46:47], v[58:59], v[50:51]
	v_pk_fma_f32 v[44:45], v[44:45], v[56:57], v[48:49]
	v_lshlrev_b32_e32 v48, 16, v120
	v_and_b32_e32 v49, 0xffff0000, v120
	v_lshlrev_b32_e32 v50, 16, v121
	v_and_b32_e32 v51, 0xffff0000, v121
	v_pk_fma_f32 v[50:51], v[42:43], v[50:51], v[54:55]
	v_pk_fma_f32 v[42:43], v[40:41], v[48:49], v[52:53]
	v_cvt_pk_bf16_f32 v40, v44, v45
	v_cvt_pk_bf16_f32 v41, v46, v47
	v_cvt_pk_bf16_f32 v42, v42, v43
	v_cvt_pk_bf16_f32 v43, v50, v51
	global_store_dwordx4 v[100:101], v[40:43], off
	v_lshlrev_b32_e32 v48, 16, v126
	v_and_b32_e32 v49, 0xffff0000, v126
	v_lshlrev_b32_e32 v40, 16, v130
	v_and_b32_e32 v41, 0xffff0000, v130
	v_lshlrev_b32_e32 v42, 16, v131
	v_and_b32_e32 v43, 0xffff0000, v131
	v_lshlrev_b32_e32 v50, 16, v127
	v_and_b32_e32 v51, 0xffff0000, v127
	v_lshlrev_b32_e32 v44, 16, v132
	v_and_b32_e32 v45, 0xffff0000, v132
	v_lshlrev_b32_e32 v46, 16, v133
	v_and_b32_e32 v47, 0xffff0000, v133
	v_pk_fma_f32 v[38:39], v[38:39], v[50:51], v[42:43]
	v_pk_fma_f32 v[36:37], v[36:37], v[48:49], v[40:41]
	v_lshlrev_b32_e32 v40, 16, v128
	v_and_b32_e32 v41, 0xffff0000, v128
	v_lshlrev_b32_e32 v42, 16, v129
	v_and_b32_e32 v43, 0xffff0000, v129
	v_pk_fma_f32 v[42:43], v[34:35], v[42:43], v[46:47]
	v_pk_fma_f32 v[34:35], v[32:33], v[40:41], v[44:45]
	v_cvt_pk_bf16_f32 v32, v36, v37
	v_cvt_pk_bf16_f32 v33, v38, v39
	v_cvt_pk_bf16_f32 v34, v34, v35
	v_cvt_pk_bf16_f32 v35, v42, v43
	global_store_dwordx4 v[100:101], v[32:35], off offset:256
	v_lshlrev_b32_e32 v40, 16, v88
	v_and_b32_e32 v41, 0xffff0000, v88
	v_lshlrev_b32_e32 v32, 16, v138
	v_and_b32_e32 v33, 0xffff0000, v138
	v_lshlrev_b32_e32 v34, 16, v139
	v_and_b32_e32 v35, 0xffff0000, v139
	v_lshlrev_b32_e32 v42, 16, v89
	v_and_b32_e32 v43, 0xffff0000, v89
	v_lshlrev_b32_e32 v36, 16, v140
	v_and_b32_e32 v37, 0xffff0000, v140
	v_lshlrev_b32_e32 v38, 16, v141
	v_and_b32_e32 v39, 0xffff0000, v141
	v_pk_fma_f32 v[30:31], v[30:31], v[42:43], v[34:35]
	v_pk_fma_f32 v[28:29], v[28:29], v[40:41], v[32:33]
	v_lshlrev_b32_e32 v32, 16, v90
	v_and_b32_e32 v33, 0xffff0000, v90
	v_lshlrev_b32_e32 v34, 16, v91
	v_and_b32_e32 v35, 0xffff0000, v91
	v_pk_fma_f32 v[34:35], v[26:27], v[34:35], v[38:39]
	v_pk_fma_f32 v[26:27], v[24:25], v[32:33], v[36:37]
	v_cvt_pk_bf16_f32 v24, v28, v29
	v_cvt_pk_bf16_f32 v25, v30, v31
	v_cvt_pk_bf16_f32 v26, v26, v27
	v_cvt_pk_bf16_f32 v27, v34, v35
	global_store_dwordx4 v[98:99], v[24:27], off
	v_lshlrev_b32_e32 v32, 16, v80
	v_and_b32_e32 v33, 0xffff0000, v80
	v_lshlrev_b32_e32 v24, 16, v84
	v_and_b32_e32 v25, 0xffff0000, v84
	v_lshlrev_b32_e32 v26, 16, v85
	v_and_b32_e32 v27, 0xffff0000, v85
	v_lshlrev_b32_e32 v34, 16, v81
	v_and_b32_e32 v35, 0xffff0000, v81
	v_lshlrev_b32_e32 v28, 16, v86
	v_and_b32_e32 v29, 0xffff0000, v86
	v_lshlrev_b32_e32 v30, 16, v87
	v_and_b32_e32 v31, 0xffff0000, v87
	v_pk_fma_f32 v[22:23], v[22:23], v[34:35], v[26:27]
	v_pk_fma_f32 v[20:21], v[20:21], v[32:33], v[24:25]
	v_lshlrev_b32_e32 v24, 16, v82
	v_and_b32_e32 v25, 0xffff0000, v82
	v_lshlrev_b32_e32 v26, 16, v83
	v_and_b32_e32 v27, 0xffff0000, v83
	v_pk_fma_f32 v[26:27], v[18:19], v[26:27], v[30:31]
	v_pk_fma_f32 v[18:19], v[16:17], v[24:25], v[28:29]
	v_cvt_pk_bf16_f32 v16, v20, v21
	v_cvt_pk_bf16_f32 v17, v22, v23
	v_cvt_pk_bf16_f32 v18, v18, v19
	v_cvt_pk_bf16_f32 v19, v26, v27
	global_store_dwordx4 v[98:99], v[16:19], off offset:256
	v_lshlrev_b32_e32 v24, 16, v72
	v_and_b32_e32 v25, 0xffff0000, v72
	v_lshlrev_b32_e32 v16, 16, v76
	v_and_b32_e32 v17, 0xffff0000, v76
	v_lshlrev_b32_e32 v18, 16, v77
	v_and_b32_e32 v19, 0xffff0000, v77
	v_lshlrev_b32_e32 v26, 16, v73
	v_and_b32_e32 v27, 0xffff0000, v73
	v_lshlrev_b32_e32 v20, 16, v78
	v_and_b32_e32 v21, 0xffff0000, v78
	v_lshlrev_b32_e32 v22, 16, v79
	v_and_b32_e32 v23, 0xffff0000, v79
	v_pk_fma_f32 v[14:15], v[14:15], v[26:27], v[18:19]
	v_pk_fma_f32 v[12:13], v[12:13], v[24:25], v[16:17]
	v_lshlrev_b32_e32 v16, 16, v74
	v_and_b32_e32 v17, 0xffff0000, v74
	v_lshlrev_b32_e32 v18, 16, v75
	v_and_b32_e32 v19, 0xffff0000, v75
	v_pk_fma_f32 v[18:19], v[10:11], v[18:19], v[22:23]
	v_pk_fma_f32 v[10:11], v[8:9], v[16:17], v[20:21]
	v_cvt_pk_bf16_f32 v8, v12, v13
	v_cvt_pk_bf16_f32 v9, v14, v15
	v_cvt_pk_bf16_f32 v10, v10, v11
	v_cvt_pk_bf16_f32 v11, v18, v19
	global_store_dwordx4 v[96:97], v[8:11], off
	v_lshlrev_b32_e32 v16, 16, v64
	v_and_b32_e32 v17, 0xffff0000, v64
	v_lshlrev_b32_e32 v8, 16, v68
	v_and_b32_e32 v9, 0xffff0000, v68
	v_lshlrev_b32_e32 v10, 16, v69
	v_and_b32_e32 v11, 0xffff0000, v69
	v_lshlrev_b32_e32 v18, 16, v65
	v_and_b32_e32 v19, 0xffff0000, v65
	v_lshlrev_b32_e32 v12, 16, v70
	v_and_b32_e32 v13, 0xffff0000, v70
	v_lshlrev_b32_e32 v14, 16, v71
	v_and_b32_e32 v15, 0xffff0000, v71
	v_pk_fma_f32 v[6:7], v[6:7], v[18:19], v[10:11]
	v_pk_fma_f32 v[4:5], v[4:5], v[16:17], v[8:9]
	v_lshlrev_b32_e32 v8, 16, v66
	v_and_b32_e32 v9, 0xffff0000, v66
	v_lshlrev_b32_e32 v10, 16, v67
	v_and_b32_e32 v11, 0xffff0000, v67
	v_pk_fma_f32 v[10:11], v[2:3], v[10:11], v[14:15]
	v_pk_fma_f32 v[2:3], v[0:1], v[8:9], v[12:13]
	v_cvt_pk_bf16_f32 v0, v4, v5
	v_cvt_pk_bf16_f32 v1, v6, v7
	v_cvt_pk_bf16_f32 v2, v2, v3
	v_cvt_pk_bf16_f32 v3, v10, v11
	global_store_dwordx4 v[96:97], v[0:3], off offset:256
	s_nop 1
	v_lshl_add_u64 v[0:1], v[92:93], 0, s[24:25]
	v_lshl_add_u64 v[2:3], v[94:95], 0, s[78:79]
	s_cbranch_vccnz .LBB0_683
	s_andn2_b64 vcc, exec, s[10:11]
	s_cbranch_vccnz .LBB0_682
	s_barrier
	s_branch .LBB0_682

.LBB0_724:
	s_lshl_b32 s20, s44, 8
	v_mbcnt_lo_u32_b32 v129, -1, 0
	v_mbcnt_hi_u32_b32 v129, -1, v129
	s_add_i32 s20, s20, s37
	v_and_or_b32 v128, v129, 15, s20
	s_lshl_b32 s20, s45, 8
	v_ashrrev_i32_e32 v129, 1, v129
	s_or_b32 s20, s20, s38
	v_and_b32_e32 v129, -8, v129
	v_add_u32_e32 v130, s20, v129
	v_ashrrev_i32_e32 v129, 31, v128
	v_mov_b64_e32 v[132:133], s[14:15]
	v_ashrrev_i32_e32 v131, 31, v130
	v_mad_i64_i32 v[132:133], s[20:21], v128, s72, v[132:133]
	v_lshlrev_b64 v[130:131], 1, v[130:131]
	v_lshlrev_b64 v[128:129], 11, v[128:129]
	v_lshl_add_u64 v[196:197], v[132:133], 0, v[130:131]
	v_lshl_add_u64 v[128:129], s[12:13], 0, v[128:129]
	v_lshl_add_u64 v[198:199], v[128:129], 0, v[130:131]
	global_load_dwordx4 v[204:207], v[196:197], off
	global_load_dwordx4 v[220:223], v[198:199], off
	global_load_dwordx4 v[174:177], v[196:197], off offset:256
	global_load_dwordx4 v[182:185], v[198:199], off offset:256
	v_add_co_u32_e32 v128, vcc, s51, v196
	s_mov_b32 s20, 0x48000
	s_nop 0
	v_addc_co_u32_e32 v129, vcc, 0, v197, vcc
	global_load_dwordx4 v[170:173], v[128:129], off
	v_add_co_u32_e32 v218, vcc, s82, v198
	s_mov_b64 s[22:23], 0xc0000
	s_nop 0
	v_addc_co_u32_e32 v219, vcc, 0, v199, vcc
	global_load_dwordx4 v[178:181], v[218:219], off
	global_load_dwordx4 v[158:161], v[128:129], off offset:256
	global_load_dwordx4 v[166:169], v[218:219], off offset:256
	v_add_co_u32_e32 v128, vcc, s1, v196
	s_waitcnt vmcnt(0) lgkmcnt(0)
	v_lshlrev_b32_e32 v208, 16, v220
	v_addc_co_u32_e32 v129, vcc, 0, v197, vcc
	global_load_dwordx4 v[154:157], v[128:129], off
	v_add_co_u32_e32 v216, vcc, s94, v198
	v_and_b32_e32 v209, 0xffff0000, v220
	s_nop 0
	v_addc_co_u32_e32 v217, vcc, 0, v199, vcc
	global_load_dwordx4 v[162:165], v[216:217], off
	global_load_dwordx4 v[142:145], v[128:129], off offset:256
	global_load_dwordx4 v[150:153], v[216:217], off offset:256
	v_add_co_u32_e32 v128, vcc, s20, v196
	v_lshlrev_b32_e32 v210, 16, v221
	s_nop 0
	v_addc_co_u32_e32 v129, vcc, 0, v197, vcc
	global_load_dwordx4 v[132:135], v[128:129], off
	v_add_co_u32_e32 v200, vcc, s51, v198
	v_and_b32_e32 v211, 0xffff0000, v221
	s_nop 0
	v_addc_co_u32_e32 v201, vcc, 0, v199, vcc
	global_load_dwordx4 v[146:149], v[200:201], off
	s_nop 0
	global_load_dwordx4 v[128:131], v[128:129], off offset:256
	s_nop 0
	global_load_dwordx4 v[138:141], v[200:201], off offset:256
	v_lshlrev_b32_e32 v220, 16, v204
	v_and_b32_e32 v221, 0xffff0000, v204
	v_lshlrev_b32_e32 v204, 16, v205
	v_and_b32_e32 v205, 0xffff0000, v205
	v_lshlrev_b32_e32 v212, 16, v222
	v_and_b32_e32 v213, 0xffff0000, v222
	v_lshlrev_b32_e32 v214, 16, v223
	v_and_b32_e32 v215, 0xffff0000, v223
	v_pk_fma_f32 v[126:127], v[126:127], v[204:205], v[210:211]
	v_lshlrev_b32_e32 v204, 16, v206
	v_and_b32_e32 v205, 0xffff0000, v206
	v_lshlrev_b32_e32 v206, 16, v207
	v_and_b32_e32 v207, 0xffff0000, v207
	v_pk_fma_f32 v[124:125], v[124:125], v[220:221], v[208:209]
	v_pk_fma_f32 v[206:207], v[122:123], v[206:207], v[214:215]
	v_pk_fma_f32 v[122:123], v[120:121], v[204:205], v[212:213]
	v_cvt_pk_bf16_f32 v120, v124, v125
	v_cvt_pk_bf16_f32 v121, v126, v127
	v_cvt_pk_bf16_f32 v122, v122, v123
	v_cvt_pk_bf16_f32 v123, v206, v207
	global_store_dwordx4 v[198:199], v[120:123], off
	v_lshlrev_b32_e32 v124, 16, v184
	v_and_b32_e32 v125, 0xffff0000, v184
	v_lshlrev_b32_e32 v120, 16, v182
	v_and_b32_e32 v121, 0xffff0000, v182
	v_lshlrev_b32_e32 v122, 16, v183
	v_and_b32_e32 v123, 0xffff0000, v183
	v_lshlrev_b32_e32 v182, 16, v174
	v_and_b32_e32 v183, 0xffff0000, v174
	v_lshlrev_b32_e32 v174, 16, v175
	v_and_b32_e32 v175, 0xffff0000, v175
	v_lshlrev_b32_e32 v126, 16, v185
	v_and_b32_e32 v127, 0xffff0000, v185
	v_pk_fma_f32 v[118:119], v[118:119], v[174:175], v[122:123]
	v_pk_fma_f32 v[116:117], v[116:117], v[182:183], v[120:121]
	v_lshlrev_b32_e32 v120, 16, v176
	v_and_b32_e32 v121, 0xffff0000, v176
	v_lshlrev_b32_e32 v122, 16, v177
	v_and_b32_e32 v123, 0xffff0000, v177
	v_pk_fma_f32 v[122:123], v[114:115], v[122:123], v[126:127]
	v_pk_fma_f32 v[114:115], v[112:113], v[120:121], v[124:125]
	v_cvt_pk_bf16_f32 v112, v116, v117
	v_cvt_pk_bf16_f32 v113, v118, v119
	v_cvt_pk_bf16_f32 v114, v114, v115
	v_cvt_pk_bf16_f32 v115, v122, v123
	global_store_dwordx4 v[198:199], v[112:115], off offset:256
	v_lshlrev_b32_e32 v120, 16, v170
	v_and_b32_e32 v121, 0xffff0000, v170
	v_lshlrev_b32_e32 v112, 16, v178
	v_and_b32_e32 v113, 0xffff0000, v178
	v_lshlrev_b32_e32 v114, 16, v179
	v_and_b32_e32 v115, 0xffff0000, v179
	v_lshlrev_b32_e32 v122, 16, v171
	v_and_b32_e32 v123, 0xffff0000, v171
	v_lshlrev_b32_e32 v116, 16, v180
	v_and_b32_e32 v117, 0xffff0000, v180
	v_lshlrev_b32_e32 v118, 16, v181
	v_and_b32_e32 v119, 0xffff0000, v181
	v_pk_fma_f32 v[110:111], v[110:111], v[122:123], v[114:115]
	v_pk_fma_f32 v[108:109], v[108:109], v[120:121], v[112:113]
	v_lshlrev_b32_e32 v112, 16, v172
	v_and_b32_e32 v113, 0xffff0000, v172
	v_lshlrev_b32_e32 v114, 16, v173
	v_and_b32_e32 v115, 0xffff0000, v173
	v_pk_fma_f32 v[114:115], v[106:107], v[114:115], v[118:119]
	v_pk_fma_f32 v[106:107], v[104:105], v[112:113], v[116:117]
	v_cvt_pk_bf16_f32 v104, v108, v109
	v_cvt_pk_bf16_f32 v105, v110, v111
	v_cvt_pk_bf16_f32 v106, v106, v107
	v_cvt_pk_bf16_f32 v107, v114, v115
	global_store_dwordx4 v[218:219], v[104:107], off
	v_lshlrev_b32_e32 v112, 16, v158
	v_and_b32_e32 v113, 0xffff0000, v158
	v_lshlrev_b32_e32 v104, 16, v166
	v_and_b32_e32 v105, 0xffff0000, v166
	v_lshlrev_b32_e32 v106, 16, v167
	v_and_b32_e32 v107, 0xffff0000, v167
	v_lshlrev_b32_e32 v114, 16, v159
	v_and_b32_e32 v115, 0xffff0000, v159
	v_lshlrev_b32_e32 v108, 16, v168
	v_and_b32_e32 v109, 0xffff0000, v168
	v_lshlrev_b32_e32 v110, 16, v169
	v_and_b32_e32 v111, 0xffff0000, v169
	v_pk_fma_f32 v[102:103], v[102:103], v[114:115], v[106:107]
	v_pk_fma_f32 v[100:101], v[100:101], v[112:113], v[104:105]
	v_lshlrev_b32_e32 v104, 16, v160
	v_and_b32_e32 v105, 0xffff0000, v160
	v_lshlrev_b32_e32 v106, 16, v161
	v_and_b32_e32 v107, 0xffff0000, v161
	v_pk_fma_f32 v[106:107], v[98:99], v[106:107], v[110:111]
	v_pk_fma_f32 v[98:99], v[96:97], v[104:105], v[108:109]
	v_cvt_pk_bf16_f32 v96, v100, v101
	v_cvt_pk_bf16_f32 v97, v102, v103
	v_cvt_pk_bf16_f32 v98, v98, v99
	v_cvt_pk_bf16_f32 v99, v106, v107
	global_store_dwordx4 v[218:219], v[96:99], off offset:256
	s_waitcnt vmcnt(0) lgkmcnt(0)
	v_lshlrev_b32_e32 v104, 16, v154
	v_and_b32_e32 v105, 0xffff0000, v154
	v_lshlrev_b32_e32 v96, 16, v162
	v_and_b32_e32 v97, 0xffff0000, v162
	v_lshlrev_b32_e32 v98, 16, v163
	v_and_b32_e32 v99, 0xffff0000, v163
	v_lshlrev_b32_e32 v106, 16, v155
	v_and_b32_e32 v107, 0xffff0000, v155
	v_lshlrev_b32_e32 v100, 16, v164
	v_and_b32_e32 v101, 0xffff0000, v164
	v_lshlrev_b32_e32 v102, 16, v165
	v_and_b32_e32 v103, 0xffff0000, v165
	v_pk_fma_f32 v[94:95], v[94:95], v[106:107], v[98:99]
	v_pk_fma_f32 v[92:93], v[92:93], v[104:105], v[96:97]
	v_lshlrev_b32_e32 v96, 16, v156
	v_and_b32_e32 v97, 0xffff0000, v156
	v_lshlrev_b32_e32 v98, 16, v157
	v_and_b32_e32 v99, 0xffff0000, v157
	v_pk_fma_f32 v[98:99], v[90:91], v[98:99], v[102:103]
	v_pk_fma_f32 v[90:91], v[88:89], v[96:97], v[100:101]
	v_cvt_pk_bf16_f32 v88, v92, v93
	v_cvt_pk_bf16_f32 v89, v94, v95
	v_cvt_pk_bf16_f32 v90, v90, v91
	v_cvt_pk_bf16_f32 v91, v98, v99
	global_store_dwordx4 v[216:217], v[88:91], off
	v_lshlrev_b32_e32 v96, 16, v142
	v_and_b32_e32 v97, 0xffff0000, v142
	v_lshlrev_b32_e32 v88, 16, v150
	v_and_b32_e32 v89, 0xffff0000, v150
	v_lshlrev_b32_e32 v90, 16, v151
	v_and_b32_e32 v91, 0xffff0000, v151
	v_lshlrev_b32_e32 v98, 16, v143
	v_and_b32_e32 v99, 0xffff0000, v143
	v_lshlrev_b32_e32 v92, 16, v152
	v_and_b32_e32 v93, 0xffff0000, v152
	v_lshlrev_b32_e32 v94, 16, v153
	v_and_b32_e32 v95, 0xffff0000, v153
	v_pk_fma_f32 v[86:87], v[86:87], v[98:99], v[90:91]
	v_pk_fma_f32 v[84:85], v[84:85], v[96:97], v[88:89]
	v_lshlrev_b32_e32 v88, 16, v144
	v_and_b32_e32 v89, 0xffff0000, v144
	v_lshlrev_b32_e32 v90, 16, v145
	v_and_b32_e32 v91, 0xffff0000, v145
	v_pk_fma_f32 v[90:91], v[82:83], v[90:91], v[94:95]
	v_pk_fma_f32 v[82:83], v[80:81], v[88:89], v[92:93]
	v_cvt_pk_bf16_f32 v80, v84, v85
	v_cvt_pk_bf16_f32 v81, v86, v87
	v_cvt_pk_bf16_f32 v82, v82, v83
	v_cvt_pk_bf16_f32 v83, v90, v91
	global_store_dwordx4 v[216:217], v[80:83], off offset:256
	v_lshlrev_b32_e32 v88, 16, v132
	v_and_b32_e32 v89, 0xffff0000, v132
	v_lshlrev_b32_e32 v80, 16, v146
	v_and_b32_e32 v81, 0xffff0000, v146
	v_lshlrev_b32_e32 v82, 16, v147
	v_and_b32_e32 v83, 0xffff0000, v147
	v_lshlrev_b32_e32 v90, 16, v133
	v_and_b32_e32 v91, 0xffff0000, v133
	v_lshlrev_b32_e32 v84, 16, v148
	v_and_b32_e32 v85, 0xffff0000, v148
	v_lshlrev_b32_e32 v86, 16, v149
	v_and_b32_e32 v87, 0xffff0000, v149
	v_pk_fma_f32 v[78:79], v[78:79], v[90:91], v[82:83]
	v_pk_fma_f32 v[76:77], v[76:77], v[88:89], v[80:81]
	v_lshlrev_b32_e32 v80, 16, v134
	v_and_b32_e32 v81, 0xffff0000, v134
	v_lshlrev_b32_e32 v82, 16, v135
	v_and_b32_e32 v83, 0xffff0000, v135
	v_pk_fma_f32 v[82:83], v[74:75], v[82:83], v[86:87]
	v_pk_fma_f32 v[74:75], v[72:73], v[80:81], v[84:85]
	v_cvt_pk_bf16_f32 v72, v76, v77
	v_cvt_pk_bf16_f32 v73, v78, v79
	v_cvt_pk_bf16_f32 v74, v74, v75
	v_cvt_pk_bf16_f32 v75, v82, v83
	global_store_dwordx4 v[200:201], v[72:75], off
	v_lshlrev_b32_e32 v80, 16, v128
	v_and_b32_e32 v81, 0xffff0000, v128
	v_lshlrev_b32_e32 v72, 16, v138
	v_and_b32_e32 v73, 0xffff0000, v138
	v_lshlrev_b32_e32 v74, 16, v139
	v_and_b32_e32 v75, 0xffff0000, v139
	v_lshlrev_b32_e32 v82, 16, v129
	v_and_b32_e32 v83, 0xffff0000, v129
	v_lshlrev_b32_e32 v76, 16, v140
	v_and_b32_e32 v77, 0xffff0000, v140
	v_lshlrev_b32_e32 v78, 16, v141
	v_and_b32_e32 v79, 0xffff0000, v141
	v_pk_fma_f32 v[70:71], v[70:71], v[82:83], v[74:75]
	v_pk_fma_f32 v[68:69], v[68:69], v[80:81], v[72:73]
	v_lshlrev_b32_e32 v72, 16, v130
	v_and_b32_e32 v73, 0xffff0000, v130
	v_lshlrev_b32_e32 v74, 16, v131
	v_and_b32_e32 v75, 0xffff0000, v131
	v_pk_fma_f32 v[74:75], v[66:67], v[74:75], v[78:79]
	v_pk_fma_f32 v[66:67], v[64:65], v[72:73], v[76:77]
	v_cvt_pk_bf16_f32 v64, v68, v69
	v_cvt_pk_bf16_f32 v65, v70, v71
	v_cvt_pk_bf16_f32 v66, v66, v67
	v_cvt_pk_bf16_f32 v67, v74, v75
	v_lshl_add_u64 v[92:93], v[196:197], 0, s[22:23]
	v_lshl_add_u64 v[94:95], v[198:199], 0, s[78:79]
	global_store_dwordx4 v[200:201], v[64:67], off offset:256
	global_load_dwordx4 v[102:105], v[92:93], off
	global_load_dwordx4 v[106:109], v[94:95], off
	global_load_dwordx4 v[110:113], v[92:93], off offset:256
	global_load_dwordx4 v[114:117], v[94:95], off offset:256
	v_add_co_u32_e32 v64, vcc, s51, v92
	s_waitcnt vmcnt(0) lgkmcnt(0)
	v_lshlrev_b32_e32 v144, 16, v102
	v_addc_co_u32_e32 v65, vcc, 0, v93, vcc
	global_load_dwordx4 v[118:121], v[64:65], off
	v_add_co_u32_e32 v100, vcc, s82, v94
	v_lshlrev_b32_e32 v134, 16, v106
	s_nop 0
	v_addc_co_u32_e32 v101, vcc, 0, v95, vcc
	global_load_dwordx4 v[122:125], v[100:101], off
	global_load_dwordx4 v[126:129], v[64:65], off offset:256
	global_load_dwordx4 v[130:133], v[100:101], off offset:256
	v_add_co_u32_e32 v64, vcc, s1, v92
	v_and_b32_e32 v135, 0xffff0000, v106
	s_nop 0
	v_addc_co_u32_e32 v65, vcc, 0, v93, vcc
	global_load_dwordx4 v[88:91], v[64:65], off
	v_add_co_u32_e32 v98, vcc, s94, v94
	v_lshlrev_b32_e32 v106, 16, v107
	s_nop 0
	v_addc_co_u32_e32 v99, vcc, 0, v95, vcc
	global_load_dwordx4 v[138:141], v[98:99], off
	global_load_dwordx4 v[80:83], v[64:65], off offset:256
	global_load_dwordx4 v[84:87], v[98:99], off offset:256
	v_add_co_u32_e32 v64, vcc, s20, v92
	v_and_b32_e32 v107, 0xffff0000, v107
	s_nop 0
	v_addc_co_u32_e32 v65, vcc, 0, v93, vcc
	global_load_dwordx4 v[72:75], v[64:65], off
	v_add_co_u32_e32 v96, vcc, s51, v94
	v_and_b32_e32 v145, 0xffff0000, v102
	s_nop 0
	v_addc_co_u32_e32 v97, vcc, 0, v95, vcc
	global_load_dwordx4 v[76:79], v[96:97], off
	s_nop 0
	global_load_dwordx4 v[64:67], v[64:65], off offset:256
	s_nop 0
	global_load_dwordx4 v[68:71], v[96:97], off offset:256
	v_lshlrev_b32_e32 v102, 16, v103
	v_and_b32_e32 v103, 0xffff0000, v103
	v_lshlrev_b32_e32 v142, 16, v108
	v_and_b32_e32 v143, 0xffff0000, v108
	v_lshlrev_b32_e32 v108, 16, v109
	v_and_b32_e32 v109, 0xffff0000, v109
	v_pk_fma_f32 v[62:63], v[62:63], v[102:103], v[106:107]
	v_lshlrev_b32_e32 v102, 16, v104
	v_and_b32_e32 v103, 0xffff0000, v104
	v_lshlrev_b32_e32 v104, 16, v105
	v_and_b32_e32 v105, 0xffff0000, v105
	v_pk_fma_f32 v[60:61], v[60:61], v[144:145], v[134:135]
	v_pk_fma_f32 v[104:105], v[58:59], v[104:105], v[108:109]
	v_pk_fma_f32 v[58:59], v[56:57], v[102:103], v[142:143]
	v_cvt_pk_bf16_f32 v56, v60, v61
	v_cvt_pk_bf16_f32 v57, v62, v63
	v_cvt_pk_bf16_f32 v58, v58, v59
	v_cvt_pk_bf16_f32 v59, v104, v105
	global_store_dwordx4 v[94:95], v[56:59], off
	v_lshlrev_b32_e32 v102, 16, v110
	v_and_b32_e32 v103, 0xffff0000, v110
	v_lshlrev_b32_e32 v56, 16, v114
	v_and_b32_e32 v57, 0xffff0000, v114
	v_lshlrev_b32_e32 v58, 16, v115
	v_and_b32_e32 v59, 0xffff0000, v115
	v_lshlrev_b32_e32 v104, 16, v111
	v_and_b32_e32 v105, 0xffff0000, v111
	v_lshlrev_b32_e32 v60, 16, v116
	v_and_b32_e32 v61, 0xffff0000, v116
	v_lshlrev_b32_e32 v62, 16, v117
	v_and_b32_e32 v63, 0xffff0000, v117
	v_pk_fma_f32 v[54:55], v[54:55], v[104:105], v[58:59]
	v_pk_fma_f32 v[52:53], v[52:53], v[102:103], v[56:57]
	v_lshlrev_b32_e32 v56, 16, v112
	v_and_b32_e32 v57, 0xffff0000, v112
	v_lshlrev_b32_e32 v58, 16, v113
	v_and_b32_e32 v59, 0xffff0000, v113
	v_pk_fma_f32 v[58:59], v[50:51], v[58:59], v[62:63]
	v_pk_fma_f32 v[50:51], v[48:49], v[56:57], v[60:61]
	v_cvt_pk_bf16_f32 v48, v52, v53
	v_cvt_pk_bf16_f32 v49, v54, v55
	v_cvt_pk_bf16_f32 v50, v50, v51
	v_cvt_pk_bf16_f32 v51, v58, v59
	global_store_dwordx4 v[94:95], v[48:51], off offset:256
	s_mov_b64 s[20:21], -1
	s_and_b64 vcc, exec, s[2:3]
	s_waitcnt vmcnt(0) lgkmcnt(0)
	v_lshlrev_b32_e32 v56, 16, v118
	v_and_b32_e32 v57, 0xffff0000, v118
	v_lshlrev_b32_e32 v58, 16, v119
	v_and_b32_e32 v59, 0xffff0000, v119
	v_lshlrev_b32_e32 v48, 16, v122
	v_and_b32_e32 v49, 0xffff0000, v122
	v_lshlrev_b32_e32 v50, 16, v123
	v_and_b32_e32 v51, 0xffff0000, v123
	v_lshlrev_b32_e32 v52, 16, v124
	v_and_b32_e32 v53, 0xffff0000, v124
	v_lshlrev_b32_e32 v54, 16, v125
	v_and_b32_e32 v55, 0xffff0000, v125
	v_pk_fma_f32 v[46:47], v[46:47], v[58:59], v[50:51]
	v_pk_fma_f32 v[44:45], v[44:45], v[56:57], v[48:49]
	v_lshlrev_b32_e32 v48, 16, v120
	v_and_b32_e32 v49, 0xffff0000, v120
	v_lshlrev_b32_e32 v50, 16, v121
	v_and_b32_e32 v51, 0xffff0000, v121
	v_pk_fma_f32 v[50:51], v[42:43], v[50:51], v[54:55]
	v_pk_fma_f32 v[42:43], v[40:41], v[48:49], v[52:53]
	v_cvt_pk_bf16_f32 v40, v44, v45
	v_cvt_pk_bf16_f32 v41, v46, v47
	v_cvt_pk_bf16_f32 v42, v42, v43
	v_cvt_pk_bf16_f32 v43, v50, v51
	global_store_dwordx4 v[100:101], v[40:43], off
	v_lshlrev_b32_e32 v48, 16, v126
	v_and_b32_e32 v49, 0xffff0000, v126
	v_lshlrev_b32_e32 v40, 16, v130
	v_and_b32_e32 v41, 0xffff0000, v130
	v_lshlrev_b32_e32 v42, 16, v131
	v_and_b32_e32 v43, 0xffff0000, v131
	v_lshlrev_b32_e32 v50, 16, v127
	v_and_b32_e32 v51, 0xffff0000, v127
	v_lshlrev_b32_e32 v44, 16, v132
	v_and_b32_e32 v45, 0xffff0000, v132
	v_lshlrev_b32_e32 v46, 16, v133
	v_and_b32_e32 v47, 0xffff0000, v133
	v_pk_fma_f32 v[38:39], v[38:39], v[50:51], v[42:43]
	v_pk_fma_f32 v[36:37], v[36:37], v[48:49], v[40:41]
	v_lshlrev_b32_e32 v40, 16, v128
	v_and_b32_e32 v41, 0xffff0000, v128
	v_lshlrev_b32_e32 v42, 16, v129
	v_and_b32_e32 v43, 0xffff0000, v129
	v_pk_fma_f32 v[42:43], v[34:35], v[42:43], v[46:47]
	v_pk_fma_f32 v[34:35], v[32:33], v[40:41], v[44:45]
	v_cvt_pk_bf16_f32 v32, v36, v37
	v_cvt_pk_bf16_f32 v33, v38, v39
	v_cvt_pk_bf16_f32 v34, v34, v35
	v_cvt_pk_bf16_f32 v35, v42, v43
	global_store_dwordx4 v[100:101], v[32:35], off offset:256
	v_lshlrev_b32_e32 v40, 16, v88
	v_and_b32_e32 v41, 0xffff0000, v88
	v_lshlrev_b32_e32 v32, 16, v138
	v_and_b32_e32 v33, 0xffff0000, v138
	v_lshlrev_b32_e32 v34, 16, v139
	v_and_b32_e32 v35, 0xffff0000, v139
	v_lshlrev_b32_e32 v42, 16, v89
	v_and_b32_e32 v43, 0xffff0000, v89
	v_lshlrev_b32_e32 v36, 16, v140
	v_and_b32_e32 v37, 0xffff0000, v140
	v_lshlrev_b32_e32 v38, 16, v141
	v_and_b32_e32 v39, 0xffff0000, v141
	v_pk_fma_f32 v[30:31], v[30:31], v[42:43], v[34:35]
	v_pk_fma_f32 v[28:29], v[28:29], v[40:41], v[32:33]
	v_lshlrev_b32_e32 v32, 16, v90
	v_and_b32_e32 v33, 0xffff0000, v90
	v_lshlrev_b32_e32 v34, 16, v91
	v_and_b32_e32 v35, 0xffff0000, v91
	v_pk_fma_f32 v[34:35], v[26:27], v[34:35], v[38:39]
	v_pk_fma_f32 v[26:27], v[24:25], v[32:33], v[36:37]
	v_cvt_pk_bf16_f32 v24, v28, v29
	v_cvt_pk_bf16_f32 v25, v30, v31
	v_cvt_pk_bf16_f32 v26, v26, v27
	v_cvt_pk_bf16_f32 v27, v34, v35
	global_store_dwordx4 v[98:99], v[24:27], off
	v_lshlrev_b32_e32 v32, 16, v80
	v_and_b32_e32 v33, 0xffff0000, v80
	v_lshlrev_b32_e32 v24, 16, v84
	v_and_b32_e32 v25, 0xffff0000, v84
	v_lshlrev_b32_e32 v26, 16, v85
	v_and_b32_e32 v27, 0xffff0000, v85
	v_lshlrev_b32_e32 v34, 16, v81
	v_and_b32_e32 v35, 0xffff0000, v81
	v_lshlrev_b32_e32 v28, 16, v86
	v_and_b32_e32 v29, 0xffff0000, v86
	v_lshlrev_b32_e32 v30, 16, v87
	v_and_b32_e32 v31, 0xffff0000, v87
	v_pk_fma_f32 v[22:23], v[22:23], v[34:35], v[26:27]
	v_pk_fma_f32 v[20:21], v[20:21], v[32:33], v[24:25]
	v_lshlrev_b32_e32 v24, 16, v82
	v_and_b32_e32 v25, 0xffff0000, v82
	v_lshlrev_b32_e32 v26, 16, v83
	v_and_b32_e32 v27, 0xffff0000, v83
	v_pk_fma_f32 v[26:27], v[18:19], v[26:27], v[30:31]
	v_pk_fma_f32 v[18:19], v[16:17], v[24:25], v[28:29]
	v_cvt_pk_bf16_f32 v16, v20, v21
	v_cvt_pk_bf16_f32 v17, v22, v23
	v_cvt_pk_bf16_f32 v18, v18, v19
	v_cvt_pk_bf16_f32 v19, v26, v27
	global_store_dwordx4 v[98:99], v[16:19], off offset:256
	v_lshlrev_b32_e32 v24, 16, v72
	v_and_b32_e32 v25, 0xffff0000, v72
	v_lshlrev_b32_e32 v16, 16, v76
	v_and_b32_e32 v17, 0xffff0000, v76
	v_lshlrev_b32_e32 v18, 16, v77
	v_and_b32_e32 v19, 0xffff0000, v77
	v_lshlrev_b32_e32 v26, 16, v73
	v_and_b32_e32 v27, 0xffff0000, v73
	v_lshlrev_b32_e32 v20, 16, v78
	v_and_b32_e32 v21, 0xffff0000, v78
	v_lshlrev_b32_e32 v22, 16, v79
	v_and_b32_e32 v23, 0xffff0000, v79
	v_pk_fma_f32 v[14:15], v[14:15], v[26:27], v[18:19]
	v_pk_fma_f32 v[12:13], v[12:13], v[24:25], v[16:17]
	v_lshlrev_b32_e32 v16, 16, v74
	v_and_b32_e32 v17, 0xffff0000, v74
	v_lshlrev_b32_e32 v18, 16, v75
	v_and_b32_e32 v19, 0xffff0000, v75
	v_pk_fma_f32 v[18:19], v[10:11], v[18:19], v[22:23]
	v_pk_fma_f32 v[10:11], v[8:9], v[16:17], v[20:21]
	v_cvt_pk_bf16_f32 v8, v12, v13
	v_cvt_pk_bf16_f32 v9, v14, v15
	v_cvt_pk_bf16_f32 v10, v10, v11
	v_cvt_pk_bf16_f32 v11, v18, v19
	global_store_dwordx4 v[96:97], v[8:11], off
	v_lshlrev_b32_e32 v16, 16, v64
	v_and_b32_e32 v17, 0xffff0000, v64
	v_lshlrev_b32_e32 v8, 16, v68
	v_and_b32_e32 v9, 0xffff0000, v68
	v_lshlrev_b32_e32 v10, 16, v69
	v_and_b32_e32 v11, 0xffff0000, v69
	v_lshlrev_b32_e32 v18, 16, v65
	v_and_b32_e32 v19, 0xffff0000, v65
	v_lshlrev_b32_e32 v12, 16, v70
	v_and_b32_e32 v13, 0xffff0000, v70
	v_lshlrev_b32_e32 v14, 16, v71
	v_and_b32_e32 v15, 0xffff0000, v71
	v_pk_fma_f32 v[6:7], v[6:7], v[18:19], v[10:11]
	v_pk_fma_f32 v[4:5], v[4:5], v[16:17], v[8:9]
	v_lshlrev_b32_e32 v8, 16, v66
	v_and_b32_e32 v9, 0xffff0000, v66
	v_lshlrev_b32_e32 v10, 16, v67
	v_and_b32_e32 v11, 0xffff0000, v67
	v_pk_fma_f32 v[10:11], v[2:3], v[10:11], v[14:15]
	v_pk_fma_f32 v[2:3], v[0:1], v[8:9], v[12:13]
	v_cvt_pk_bf16_f32 v0, v4, v5
	v_cvt_pk_bf16_f32 v1, v6, v7
	v_cvt_pk_bf16_f32 v2, v2, v3
	v_cvt_pk_bf16_f32 v3, v10, v11
	global_store_dwordx4 v[96:97], v[0:3], off offset:256
	s_nop 1
	v_lshl_add_u64 v[0:1], v[92:93], 0, s[22:23]
	v_lshl_add_u64 v[2:3], v[94:95], 0, s[78:79]
	s_cbranch_vccnz .LBB0_709
	s_andn2_b64 vcc, exec, s[10:11]
	s_cbranch_vccnz .LBB0_708
	s_barrier
	s_branch .LBB0_708

.LBB0_728:
	v_readlane_b32 s4, v254, 26
	v_readlane_b32 s5, v254, 27
	v_readlane_b32 s18, v254, 40
	v_readlane_b32 s19, v254, 41
	s_mov_b64 s[4:5], s[18:19]
	v_mbcnt_lo_u32_b32 v0, -1, 0
	v_mbcnt_hi_u32_b32 v0, -1, v0
	v_readlane_b32 s2, v254, 4
	s_waitcnt vmcnt(0) lgkmcnt(0)
	v_readlane_b32 s6, v254, 28
	v_readlane_b32 s7, v254, 29
	v_cmp_eq_u32_e32 vcc, 0, v0
	v_readlane_b32 s3, v254, 5
	s_and_b64 s[6:7], s[2:3], vcc
	v_readlane_b32 s8, v254, 30
	v_readlane_b32 s9, v254, 31
	v_readlane_b32 s10, v254, 32
	v_readlane_b32 s11, v254, 33
	v_readlane_b32 s12, v254, 34
	v_readlane_b32 s13, v254, 35
	v_readlane_b32 s14, v254, 36
	v_readlane_b32 s15, v254, 37
	v_readlane_b32 s16, v254, 38
	v_readlane_b32 s17, v254, 39
	s_waitcnt lgkmcnt(0)
	s_barrier
	s_and_saveexec_b64 s[2:3], s[6:7]
	s_cbranch_execz .LBB0_744
	v_readlane_b32 s6, v255, 1
	s_add_i32 s16, s6, 4
	s_getreg_b32 s6, hwreg(HW_REG_XCC_ID, 0, 4)
	s_lshl_b32 s6, s6, 8
	s_and_b32 s6, s6, 0x700
	s_add_u32 s15, s4, s6
	s_addc_u32 s14, s5, 0
	v_mov_b32_e32 v0, s15
	v_add_co_u32_e32 v8, vcc, 0x2000, v0
	v_mov_b32_e32 v0, s14
	s_nop 0
	v_addc_co_u32_e32 v9, vcc, 0, v0, vcc
	v_mov_b32_e32 v0, s4
	v_add_co_u32_e32 v10, vcc, 0x2000, v0
	v_mov_b32_e32 v0, s5
	s_nop 0
	v_addc_co_u32_e32 v11, vcc, 0, v0, vcc
	global_load_dword v12, v[8:9], off sc1
	global_load_dword v0, v[10:11], off sc1
	global_load_dword v1, v[10:11], off offset:256 sc1
	global_load_dword v2, v[10:11], off offset:512 sc1
	global_load_dword v3, v[10:11], off offset:768 sc1
	global_load_dword v4, v[10:11], off offset:1024 sc1
	global_load_dword v5, v[10:11], off offset:1280 sc1
	global_load_dword v6, v[10:11], off offset:1536 sc1
	global_load_dword v7, v[10:11], off offset:1792 sc1
	v_mov_b32_e32 v10, 1
	global_atomic_add v8, v[8:9], v10, off offset:2048 sc0
	s_waitcnt vmcnt(0) lgkmcnt(0)
	v_mul_lo_u32 v9, v12, s16
	v_add_u32_e32 v8, 1, v8
	v_cmp_ne_u32_e32 vcc, v8, v9
	s_and_saveexec_b64 s[6:7], vcc
	s_xor_b64 s[6:7], exec, s[6:7]
	s_cbranch_execz .LBB0_734
	v_mov_b32_e32 v0, s15
	v_add_co_u32_e32 v0, vcc, 0x3000, v0
	v_mov_b32_e32 v1, s14
	s_nop 0
	v_addc_co_u32_e32 v1, vcc, 0, v1, vcc
	global_load_dword v0, v[0:1], off sc1
	s_add_u32 s8, s15, 0x3000
	s_addc_u32 s9, s14, 0
	s_waitcnt vmcnt(0) lgkmcnt(0)
	v_cmp_gt_u32_e32 vcc, s16, v0
	s_and_saveexec_b64 s[10:11], vcc
	s_cbranch_execz .LBB0_733
	s_mov_b64 s[12:13], 0

.LBB0_764:
	s_lshl_b32 s15, s22, 8
	v_mbcnt_lo_u32_b32 v141, -1, 0
	v_mbcnt_hi_u32_b32 v141, -1, v141
	s_add_i32 s15, s15, s38
	v_and_or_b32 v140, v141, 15, s15
	s_lshl_b32 s15, s43, 8
	v_ashrrev_i32_e32 v141, 1, v141
	v_and_b32_e32 v141, -8, v141
	s_or_b32 s15, s15, s39
	v_add_u32_e32 v144, s15, v141
	v_ashrrev_i32_e32 v141, 31, v140
	v_lshlrev_b64 v[140:141], 12, v[140:141]
	v_lshl_add_u64 v[140:141], s[10:11], 0, v[140:141]
	v_ashrrev_i32_e32 v145, 31, v144
	v_lshl_add_u64 v[140:141], v[144:145], 2, v[140:141]
	v_add_co_u32_e32 v208, vcc, s94, v140
	global_load_dwordx4 v[144:147], v[140:141], off
	global_load_dwordx4 v[148:151], v[140:141], off offset:16
	global_load_dwordx4 v[152:155], v[140:141], off offset:512
	global_load_dwordx4 v[156:159], v[140:141], off offset:528
	v_addc_co_u32_e32 v209, vcc, 0, v141, vcc
	v_add_co_u32_e32 v210, vcc, s0, v140
	global_load_dwordx4 v[160:163], v[208:209], off
	global_load_dwordx4 v[164:167], v[208:209], off offset:16
	global_load_dwordx4 v[168:171], v[208:209], off offset:512
	global_load_dwordx4 v[172:175], v[208:209], off offset:528
	v_addc_co_u32_e32 v211, vcc, 0, v141, vcc
	v_add_co_u32_e32 v212, vcc, s1, v140
	global_load_dwordx4 v[176:179], v[210:211], off
	global_load_dwordx4 v[180:183], v[210:211], off offset:16
	global_load_dwordx4 v[184:187], v[210:211], off offset:512
	global_load_dwordx4 v[188:191], v[210:211], off offset:528
	v_addc_co_u32_e32 v213, vcc, 0, v141, vcc
	global_load_dwordx4 v[192:195], v[212:213], off
	global_load_dwordx4 v[196:199], v[212:213], off offset:16
	global_load_dwordx4 v[200:203], v[212:213], off offset:512
	global_load_dwordx4 v[204:207], v[212:213], off offset:528
	s_mov_b64 s[24:25], 0x80000
	s_waitcnt vmcnt(0) lgkmcnt(0)
	v_pk_add_f32 v[126:127], v[126:127], v[146:147]
	v_pk_add_f32 v[124:125], v[124:125], v[144:145]
	v_pk_add_f32 v[122:123], v[122:123], v[150:151]
	v_pk_add_f32 v[98:99], v[98:99], v[158:159]
	v_pk_add_f32 v[96:97], v[96:97], v[156:157]
	v_pk_add_f32 v[120:121], v[120:121], v[148:149]
	v_pk_add_f32 v[106:107], v[106:107], v[154:155]
	v_pk_add_f32 v[104:105], v[104:105], v[152:153]
	global_store_dwordx4 v[140:141], v[124:127], off
	global_store_dwordx4 v[140:141], v[120:123], off offset:16
	global_store_dwordx4 v[140:141], v[104:107], off offset:512
	global_store_dwordx4 v[140:141], v[96:99], off offset:528
	v_pk_add_f32 v[90:91], v[90:91], v[170:171]
	v_pk_add_f32 v[106:107], v[114:115], v[166:167]
	v_pk_add_f32 v[98:99], v[118:119], v[162:163]
	v_pk_add_f32 v[96:97], v[116:117], v[160:161]
	v_pk_add_f32 v[104:105], v[112:113], v[164:165]
	v_pk_add_f32 v[88:89], v[88:89], v[168:169]
	v_pk_add_f32 v[82:83], v[82:83], v[174:175]
	v_pk_add_f32 v[64:65], v[64:65], v[204:205]
	v_pk_add_f32 v[80:81], v[80:81], v[172:173]
	v_pk_add_f32 v[110:111], v[110:111], v[178:179]
	v_pk_add_f32 v[108:109], v[108:109], v[176:177]
	v_pk_add_f32 v[102:103], v[102:103], v[182:183]
	v_pk_add_f32 v[100:101], v[100:101], v[180:181]
	v_pk_add_f32 v[78:79], v[78:79], v[186:187]
	v_pk_add_f32 v[76:77], v[76:77], v[184:185]
	v_pk_add_f32 v[74:75], v[74:75], v[190:191]
	v_pk_add_f32 v[72:73], v[72:73], v[188:189]
	v_pk_add_f32 v[94:95], v[94:95], v[194:195]
	v_pk_add_f32 v[92:93], v[92:93], v[192:193]
	v_pk_add_f32 v[86:87], v[86:87], v[198:199]
	v_pk_add_f32 v[84:85], v[84:85], v[196:197]
	v_pk_add_f32 v[70:71], v[70:71], v[202:203]
	v_pk_add_f32 v[68:69], v[68:69], v[200:201]
	v_pk_add_f32 v[66:67], v[66:67], v[206:207]
	global_store_dwordx4 v[208:209], v[96:99], off
	global_store_dwordx4 v[208:209], v[104:107], off offset:16
	global_store_dwordx4 v[208:209], v[88:91], off offset:512
	global_store_dwordx4 v[208:209], v[80:83], off offset:528
	global_store_dwordx4 v[210:211], v[108:111], off
	global_store_dwordx4 v[210:211], v[100:103], off offset:16
	global_store_dwordx4 v[210:211], v[76:79], off offset:512
	global_store_dwordx4 v[210:211], v[72:75], off offset:528
	global_store_dwordx4 v[212:213], v[92:95], off
	global_store_dwordx4 v[212:213], v[84:87], off offset:16
	global_store_dwordx4 v[212:213], v[68:71], off offset:512
	global_store_dwordx4 v[212:213], v[64:67], off offset:528
	s_nop 1
	v_lshl_add_u64 v[64:65], v[140:141], 0, s[24:25]
	v_mov_b64_e32 v[66:67], v[64:65]
	global_load_dwordx4 v[68:71], v[64:65], off
	global_load_dwordx4 v[72:75], v[64:65], off offset:16
	global_load_dwordx4 v[76:79], v[64:65], off offset:512
	global_load_dwordx4 v[80:83], v[64:65], off offset:528
	v_add_co_u32_e32 v96, vcc, s94, v64
	s_waitcnt vmcnt(0) lgkmcnt(0)
	v_pk_add_f32 v[62:63], v[62:63], v[70:71]
	v_addc_co_u32_e32 v97, vcc, 0, v65, vcc
	v_add_co_u32_e32 v112, vcc, s0, v64
	global_load_dwordx4 v[84:87], v[96:97], off
	global_load_dwordx4 v[88:91], v[96:97], off offset:16
	global_load_dwordx4 v[92:95], v[96:97], off offset:512
	s_nop 0
	global_load_dwordx4 v[96:99], v[96:97], off offset:528
	v_addc_co_u32_e32 v113, vcc, 0, v65, vcc
	v_add_co_u32_e32 v140, vcc, s1, v64
	global_load_dwordx4 v[100:103], v[112:113], off
	global_load_dwordx4 v[104:107], v[112:113], off offset:16
	global_load_dwordx4 v[108:111], v[112:113], off offset:512
	s_nop 0
	global_load_dwordx4 v[112:115], v[112:113], off offset:528
	v_addc_co_u32_e32 v141, vcc, 0, v65, vcc
	global_load_dwordx4 v[116:119], v[140:141], off
	global_load_dwordx4 v[120:123], v[140:141], off offset:16
	global_load_dwordx4 v[124:127], v[140:141], off offset:512
	global_load_dwordx4 v[144:147], v[140:141], off offset:528
	v_add_co_u32_e32 v140, vcc, s94, v66
	v_pk_add_f32 v[60:61], v[60:61], v[68:69]
	s_nop 0
	v_addc_co_u32_e32 v141, vcc, 0, v67, vcc
	v_add_co_u32_e32 v148, vcc, s0, v66
	v_pk_add_f32 v[34:35], v[34:35], v[82:83]
	s_nop 0
	v_addc_co_u32_e32 v149, vcc, 0, v67, vcc
	v_add_co_u32_e32 v150, vcc, s1, v66
	v_pk_add_f32 v[32:33], v[32:33], v[80:81]
	s_nop 0
	v_addc_co_u32_e32 v151, vcc, 0, v67, vcc
	v_pk_add_f32 v[58:59], v[58:59], v[74:75]
	v_pk_add_f32 v[56:57], v[56:57], v[72:73]
	v_pk_add_f32 v[42:43], v[42:43], v[78:79]
	v_pk_add_f32 v[40:41], v[40:41], v[76:77]
	global_store_dwordx4 v[66:67], v[60:63], off
	global_store_dwordx4 v[66:67], v[56:59], off offset:16
	global_store_dwordx4 v[66:67], v[40:43], off offset:512
	global_store_dwordx4 v[66:67], v[32:35], off offset:528
	s_andn2_b64 vcc, exec, s[2:3]
	s_mov_b64 s[2:3], -1
	s_waitcnt vmcnt(0) lgkmcnt(0)
	v_pk_add_f32 v[34:35], v[54:55], v[86:87]
	v_pk_add_f32 v[32:33], v[52:53], v[84:85]
	v_pk_add_f32 v[42:43], v[50:51], v[90:91]
	v_pk_add_f32 v[40:41], v[48:49], v[88:89]
	v_pk_add_f32 v[26:27], v[26:27], v[94:95]
	v_pk_add_f32 v[24:25], v[24:25], v[92:93]
	v_pk_add_f32 v[22:23], v[22:23], v[98:99]
	v_pk_add_f32 v[20:21], v[20:21], v[96:97]
	v_pk_add_f32 v[46:47], v[46:47], v[102:103]
	v_pk_add_f32 v[44:45], v[44:45], v[100:101]
	v_pk_add_f32 v[38:39], v[38:39], v[106:107]
	v_pk_add_f32 v[2:3], v[2:3], v[146:147]
	v_pk_add_f32 v[0:1], v[0:1], v[144:145]
	v_pk_add_f32 v[36:37], v[36:37], v[104:105]
	v_pk_add_f32 v[18:19], v[18:19], v[110:111]
	v_pk_add_f32 v[16:17], v[16:17], v[108:109]
	v_pk_add_f32 v[14:15], v[14:15], v[114:115]
	v_pk_add_f32 v[12:13], v[12:13], v[112:113]
	v_pk_add_f32 v[30:31], v[30:31], v[118:119]
	v_pk_add_f32 v[28:29], v[28:29], v[116:117]
	v_pk_add_f32 v[10:11], v[10:11], v[122:123]
	global_store_dwordx4 v[140:141], v[32:35], off
	global_store_dwordx4 v[140:141], v[40:43], off offset:16
	global_store_dwordx4 v[140:141], v[24:27], off offset:512
	global_store_dwordx4 v[140:141], v[20:23], off offset:528
	global_store_dwordx4 v[148:149], v[44:47], off
	global_store_dwordx4 v[148:149], v[36:39], off offset:16
	global_store_dwordx4 v[148:149], v[16:19], off offset:512
	global_store_dwordx4 v[148:149], v[12:15], off offset:528
	global_store_dwordx4 v[150:151], v[28:31], off
	v_pk_add_f32 v[8:9], v[8:9], v[120:121]
	v_pk_add_f32 v[6:7], v[6:7], v[126:127]
	v_pk_add_f32 v[4:5], v[4:5], v[124:125]
	global_store_dwordx4 v[150:151], v[0:3], off offset:528
	global_store_dwordx4 v[150:151], v[8:11], off offset:16
	global_store_dwordx4 v[150:151], v[4:7], off offset:512
	v_lshl_add_u64 v[0:1], v[64:65], 0, s[24:25]
	v_lshl_add_u64 v[2:3], v[66:67], 0, s[24:25]
	s_cbranch_vccnz .LBB0_753
	s_andn2_b64 vcc, exec, s[8:9]
	s_cbranch_vccnz .LBB0_752
	s_barrier
	s_branch .LBB0_752

.LBB0_768:
	v_readlane_b32 s4, v254, 26
	v_readlane_b32 s2, v255, 1
	v_readlane_b32 s5, v254, 27
	v_readlane_b32 s18, v254, 40
	v_readlane_b32 s19, v254, 41
	s_add_i32 s2, s2, 5
	s_mov_b64 s[4:5], s[18:19]
	v_writelane_b32 v255, s2, 1
	v_mbcnt_lo_u32_b32 v0, -1, 0
	v_mbcnt_hi_u32_b32 v0, -1, v0
	v_readlane_b32 s2, v254, 4
	s_waitcnt vmcnt(0) lgkmcnt(0)
	v_readlane_b32 s6, v254, 28
	v_readlane_b32 s7, v254, 29
	v_cmp_eq_u32_e32 vcc, 0, v0
	v_readlane_b32 s3, v254, 5
	s_and_b64 s[6:7], s[2:3], vcc
	v_readlane_b32 s8, v254, 30
	v_readlane_b32 s9, v254, 31
	v_readlane_b32 s10, v254, 32
	v_readlane_b32 s11, v254, 33
	v_readlane_b32 s12, v254, 34
	v_readlane_b32 s13, v254, 35
	v_readlane_b32 s14, v254, 36
	v_readlane_b32 s15, v254, 37
	v_readlane_b32 s16, v254, 38
	v_readlane_b32 s17, v254, 39
	s_waitcnt lgkmcnt(0)
	s_barrier
	s_and_saveexec_b64 s[2:3], s[6:7]
	s_cbranch_execz .LBB0_226
	s_getreg_b32 s6, hwreg(HW_REG_XCC_ID, 0, 4)
	s_lshl_b32 s6, s6, 8
	s_and_b32 s6, s6, 0x700
	s_add_u32 s15, s4, s6
	s_addc_u32 s14, s5, 0
	v_mov_b32_e32 v0, s15
	v_add_co_u32_e32 v8, vcc, 0x2000, v0
	v_mov_b32_e32 v0, s14
	s_nop 0
	v_addc_co_u32_e32 v9, vcc, 0, v0, vcc
	v_mov_b32_e32 v0, s4
	v_add_co_u32_e32 v10, vcc, 0x2000, v0
	v_mov_b32_e32 v0, s5
	s_nop 0
	v_addc_co_u32_e32 v11, vcc, 0, v0, vcc
	global_load_dword v12, v[8:9], off sc1
	global_load_dword v0, v[10:11], off sc1
	global_load_dword v1, v[10:11], off offset:256 sc1
	global_load_dword v2, v[10:11], off offset:512 sc1
	global_load_dword v3, v[10:11], off offset:768 sc1
	global_load_dword v4, v[10:11], off offset:1024 sc1
	global_load_dword v5, v[10:11], off offset:1280 sc1
	global_load_dword v6, v[10:11], off offset:1536 sc1
	global_load_dword v7, v[10:11], off offset:1792 sc1
	v_mov_b32_e32 v10, 1
	global_atomic_add v8, v[8:9], v10, off offset:2048 sc0
	v_readlane_b32 s18, v255, 1
	s_waitcnt vmcnt(0) lgkmcnt(0)
	v_add_u32_e32 v8, 1, v8
	v_mul_lo_u32 v9, v12, s18
	v_cmp_ne_u32_e32 vcc, v8, v9
	s_and_saveexec_b64 s[6:7], vcc
	s_xor_b64 s[6:7], exec, s[6:7]
	s_cbranch_execz .LBB0_774
	v_mov_b32_e32 v0, s15
	v_add_co_u32_e32 v0, vcc, 0x3000, v0
	v_mov_b32_e32 v1, s14
	s_nop 0
	v_addc_co_u32_e32 v1, vcc, 0, v1, vcc
	global_load_dword v0, v[0:1], off sc1
	s_add_u32 s8, s15, 0x3000
	s_addc_u32 s9, s14, 0
	s_waitcnt vmcnt(0) lgkmcnt(0)
	v_cmp_gt_u32_e32 vcc, s18, v0
	s_and_saveexec_b64 s[10:11], vcc
	s_cbranch_execz .LBB0_773
	s_mov_b64 s[12:13], 0
.LBB0_772:
	v_mov_b64_e32 v[0:1], s[8:9]
	s_sleep 2
	global_load_dword v0, v[0:1], off sc1
	s_waitcnt vmcnt(0) lgkmcnt(0)
	v_readfirstlane_b32 s16, v0
	s_cmp_ge_u32 s16, s18
	s_cselect_b64 s[16:17], -1, 0
	s_and_b64 s[16:17], exec, s[16:17]
	s_or_b64 s[12:13], s[16:17], s[12:13]
	s_andn2_b64 exec, exec, s[12:13]
	s_cbranch_execnz .LBB0_772

.LBB0_774:
	s_andn2_saveexec_b64 s[6:7], s[6:7]
	s_cbranch_execz .LBB0_225
	v_cmp_ne_u32_e32 vcc, 0, v0
	s_movk_i32 s8, 0x3000
	buffer_wbl2 sc1
	v_cndmask_b32_e64 v0, 0, 1, vcc
	v_cmp_ne_u32_e32 vcc, 0, v1
	s_waitcnt vmcnt(0)
	s_nop 1
	v_addc_co_u32_e32 v0, vcc, 0, v0, vcc
	v_cmp_ne_u32_e32 vcc, 0, v2
	s_nop 1
	v_cndmask_b32_e64 v1, 0, 1, vcc
	v_cmp_ne_u32_e32 vcc, 0, v3
	v_mov_b32_e32 v3, 1
	s_nop 0
	v_addc_co_u32_e32 v0, vcc, v0, v1, vcc
	v_cmp_ne_u32_e32 vcc, 0, v4
	s_nop 1
	v_cndmask_b32_e64 v1, 0, 1, vcc
	v_cmp_ne_u32_e32 vcc, 0, v5
	s_nop 1
	v_addc_co_u32_e32 v0, vcc, v0, v1, vcc
	v_cmp_ne_u32_e32 vcc, 0, v6
	s_nop 1
	v_cndmask_b32_e64 v1, 0, 1, vcc
	v_cmp_ne_u32_e32 vcc, 0, v7
	s_nop 1
	v_addc_co_u32_e32 v2, vcc, v0, v1, vcc
	v_mov_b32_e32 v0, s4
	v_add_co_u32_e32 v0, vcc, s8, v0
	v_mov_b32_e32 v1, s5
	s_nop 0
	v_addc_co_u32_e32 v1, vcc, 0, v1, vcc
	global_atomic_add v0, v[0:1], v3, off offset:2048 sc0
	v_mul_lo_u32 v1, v2, s18
	s_add_u32 s4, s4, 0x3900
	s_addc_u32 s5, s5, 0
	s_waitcnt vmcnt(0) lgkmcnt(0)
	v_add_u32_e32 v0, 1, v0
	v_cmp_ne_u32_e32 vcc, v0, v1
	s_and_saveexec_b64 s[8:9], vcc
	s_xor_b64 s[8:9], exec, s[8:9]
	s_cbranch_execz .LBB0_780
	v_mov_b64_e32 v[0:1], s[4:5]
	global_load_dword v0, v[0:1], off sc1
	s_waitcnt vmcnt(0) lgkmcnt(0)
	v_cmp_gt_u32_e32 vcc, s18, v0
	s_and_saveexec_b64 s[10:11], vcc
	s_cbranch_execz .LBB0_779
	s_mov_b64 s[12:13], 0
.LBB0_778:
	v_mov_b64_e32 v[0:1], s[4:5]
	s_sleep 2
	global_load_dword v0, v[0:1], off sc1
	s_waitcnt vmcnt(0) lgkmcnt(0)
	v_readfirstlane_b32 s16, v0
	s_cmp_ge_u32 s16, s18
	s_cselect_b64 s[16:17], -1, 0
	s_and_b64 s[16:17], exec, s[16:17]
	s_or_b64 s[12:13], s[16:17], s[12:13]
	s_andn2_b64 exec, exec, s[12:13]
	s_cbranch_execnz .LBB0_778

.LBB0_780:
	s_andn2_saveexec_b64 s[8:9], s[8:9]
	s_cbranch_execz .LBB0_224
	v_mov_b64_e32 v[0:1], s[4:5]
	v_mov_b32_e32 v2, 1
	global_atomic_add v[0:1], v2, off
	s_branch .LBB0_224

.LBB0_785:
	s_mov_b64 s[10:11], -1
	s_cmpk_gt_i32 s19, 0xaff
	v_add_u32_e32 v31, 0x420, v24
	v_add_u32_e32 v32, 0x428, v24
	v_add_u32_e32 v29, 0x840, v24
	v_add_u32_e32 v30, 0x848, v24
	v_add_u32_e32 v27, 0xc60, v24
	v_add_u32_e32 v28, 0xc68, v24
	v_add_u32_e32 v25, 0x1080, v24
	v_add_u32_e32 v26, 0x1088, v24
	v_add_u32_e32 v12, 0x14a0, v24
	v_add_u32_e32 v13, 0x14a8, v24
	v_add_u32_e32 v10, 0x18c0, v24
	v_add_u32_e32 v11, 0x18c8, v24
	v_add_u32_e32 v2, 0x1ce0, v24
	v_add_u32_e32 v3, 0x1ce8, v24
	s_cbranch_scc0 .LBB0_787
	s_and_b32 s10, s17, 0x7fffffc0
	s_addk_i32 s10, 0xea00
	s_and_b32 s20, s12, 0x3e0
	v_add_u32_e32 v34, s10, v15
	s_lshl_b32 s92, s20, 2
	v_ashrrev_i32_e32 v35, 31, v34
	v_lshl_add_u64 v[0:1], v[4:5], 0, s[92:93]
	v_lshlrev_b64 v[34:35], 12, v[34:35]
	v_lshl_add_u64 v[34:35], v[0:1], 0, v[34:35]
	global_load_dwordx4 v[34:37], v[34:35], off
	s_mov_b32 s11, s93
	s_waitcnt vmcnt(0)
	ds_write2_b32 v24, v34, v35 offset1:1
	ds_write2_b32 v24, v36, v37 offset0:2 offset1:3
	v_add_u32_e32 v34, s10, v16
	v_ashrrev_i32_e32 v35, 31, v34
	v_lshlrev_b64 v[34:35], 12, v[34:35]
	v_lshl_add_u64 v[34:35], v[0:1], 0, v[34:35]
	global_load_dwordx4 v[34:37], v[34:35], off
	s_waitcnt vmcnt(0)
	ds_write2_b32 v31, v34, v35 offset1:1
	ds_write2_b32 v32, v36, v37 offset1:1
	v_add_u32_e32 v34, s10, v17
	v_ashrrev_i32_e32 v35, 31, v34
	v_lshlrev_b64 v[34:35], 12, v[34:35]
	v_lshl_add_u64 v[34:35], v[0:1], 0, v[34:35]
	global_load_dwordx4 v[34:37], v[34:35], off
	s_waitcnt vmcnt(0)
	ds_write2_b32 v29, v34, v35 offset1:1
	ds_write2_b32 v30, v36, v37 offset1:1
	v_add_u32_e32 v34, s10, v18
	v_ashrrev_i32_e32 v35, 31, v34
	v_lshlrev_b64 v[34:35], 12, v[34:35]
	v_lshl_add_u64 v[34:35], v[0:1], 0, v[34:35]
	global_load_dwordx4 v[34:37], v[34:35], off
	s_waitcnt vmcnt(0)
	ds_write2_b32 v27, v34, v35 offset1:1
	ds_write2_b32 v28, v36, v37 offset1:1
	v_add_u32_e32 v34, s10, v19
	v_ashrrev_i32_e32 v35, 31, v34
	v_lshlrev_b64 v[34:35], 12, v[34:35]
	v_lshl_add_u64 v[34:35], v[0:1], 0, v[34:35]
	global_load_dwordx4 v[34:37], v[34:35], off
	s_waitcnt vmcnt(0)
	ds_write2_b32 v25, v34, v35 offset1:1
	ds_write2_b32 v26, v36, v37 offset1:1
	v_add_u32_e32 v34, s10, v20
	v_ashrrev_i32_e32 v35, 31, v34
	v_lshlrev_b64 v[34:35], 12, v[34:35]
	v_lshl_add_u64 v[34:35], v[0:1], 0, v[34:35]
	global_load_dwordx4 v[34:37], v[34:35], off
	s_waitcnt vmcnt(0)
	ds_write2_b32 v12, v34, v35 offset1:1
	ds_write2_b32 v13, v36, v37 offset1:1
	v_add_u32_e32 v34, s10, v21
	v_ashrrev_i32_e32 v35, 31, v34
	v_lshlrev_b64 v[34:35], 12, v[34:35]
	v_lshl_add_u64 v[34:35], v[0:1], 0, v[34:35]
	global_load_dwordx4 v[34:37], v[34:35], off
	s_waitcnt vmcnt(0)
	ds_write2_b32 v10, v34, v35 offset1:1
	ds_write2_b32 v11, v36, v37 offset1:1
	v_add_u32_e32 v34, s10, v22
	v_ashrrev_i32_e32 v35, 31, v34
	v_lshlrev_b64 v[34:35], 12, v[34:35]
	v_lshl_add_u64 v[0:1], v[0:1], 0, v[34:35]
	global_load_dwordx4 v[34:37], v[0:1], off
	v_lshl_add_u64 v[0:1], s[10:11], 1, v[6:7]
	s_waitcnt vmcnt(0)
	ds_write2_b32 v2, v34, v35 offset1:1
	ds_write2_b32 v3, v36, v37 offset1:1
	s_waitcnt lgkmcnt(0)
	ds_read_b32 v33, v23
	ds_read_b32 v34, v23 offset:132
	s_waitcnt lgkmcnt(0)
	v_cvt_pk_bf16_f32 v34, v33, v34
	ds_read_b32 v33, v23 offset:264
	ds_read_b32 v35, v23 offset:396
	s_waitcnt lgkmcnt(0)
	v_cvt_pk_bf16_f32 v35, v33, v35
	ds_read_b32 v33, v23 offset:528
	ds_read_b32 v36, v23 offset:660
	s_waitcnt lgkmcnt(0)
	v_cvt_pk_bf16_f32 v36, v33, v36
	ds_read_b32 v33, v23 offset:792
	ds_read_b32 v37, v23 offset:924
	s_waitcnt lgkmcnt(0)
	v_cvt_pk_bf16_f32 v37, v33, v37
	v_add_u32_e32 v33, s20, v15
	v_mad_i64_i32 v[38:39], s[10:11], v33, s63, v[0:1]
	global_store_dwordx4 v[38:39], v[34:37], off
	ds_read_b32 v33, v23 offset:32
	ds_read_b32 v34, v23 offset:164
	s_waitcnt lgkmcnt(0)
	v_cvt_pk_bf16_f32 v34, v33, v34
	ds_read_b32 v33, v23 offset:296
	ds_read_b32 v35, v23 offset:428
	s_waitcnt lgkmcnt(0)
	v_cvt_pk_bf16_f32 v35, v33, v35
	ds_read_b32 v33, v23 offset:560
	ds_read_b32 v36, v23 offset:692
	s_waitcnt lgkmcnt(0)
	v_cvt_pk_bf16_f32 v36, v33, v36
	ds_read_b32 v33, v23 offset:824
	ds_read_b32 v37, v23 offset:956
	s_waitcnt lgkmcnt(0)
	v_cvt_pk_bf16_f32 v37, v33, v37
	v_add_u32_e32 v33, s20, v16
	v_mad_i64_i32 v[38:39], s[10:11], v33, s63, v[0:1]
	global_store_dwordx4 v[38:39], v[34:37], off
	ds_read_b32 v33, v23 offset:64
	ds_read_b32 v34, v23 offset:196
	s_waitcnt lgkmcnt(0)
	v_cvt_pk_bf16_f32 v34, v33, v34
	ds_read_b32 v33, v23 offset:328
	ds_read_b32 v35, v23 offset:460
	s_waitcnt lgkmcnt(0)
	v_cvt_pk_bf16_f32 v35, v33, v35
	ds_read_b32 v33, v23 offset:592
	ds_read_b32 v36, v23 offset:724
	s_waitcnt lgkmcnt(0)
	v_cvt_pk_bf16_f32 v36, v33, v36
	ds_read_b32 v33, v23 offset:856
	ds_read_b32 v37, v23 offset:988
	s_waitcnt lgkmcnt(0)
	v_cvt_pk_bf16_f32 v37, v33, v37
	v_add_u32_e32 v33, s20, v17
	v_mad_i64_i32 v[38:39], s[10:11], v33, s63, v[0:1]
	global_store_dwordx4 v[38:39], v[34:37], off
	ds_read_b32 v33, v23 offset:96
	ds_read_b32 v34, v23 offset:228
	s_waitcnt lgkmcnt(0)
	v_cvt_pk_bf16_f32 v34, v33, v34
	ds_read_b32 v33, v23 offset:360
	ds_read_b32 v35, v23 offset:492
	s_waitcnt lgkmcnt(0)
	v_cvt_pk_bf16_f32 v35, v33, v35
	ds_read_b32 v33, v23 offset:624
	ds_read_b32 v36, v23 offset:756
	s_waitcnt lgkmcnt(0)
	v_cvt_pk_bf16_f32 v36, v33, v36
	ds_read_b32 v33, v23 offset:888
	ds_read_b32 v37, v23 offset:1020
	s_waitcnt lgkmcnt(0)
	v_cvt_pk_bf16_f32 v37, v33, v37
	v_add_u32_e32 v33, s20, v18
	v_mad_i64_i32 v[0:1], s[10:11], v33, s63, v[0:1]
	global_store_dwordx4 v[0:1], v[34:37], off
	s_waitcnt lgkmcnt(0)
	s_mov_b64 s[10:11], 0
.LBB0_787:
	s_andn2_b64 vcc, exec, s[10:11]
	s_cbranch_vccnz .LBB0_784
	s_mul_hi_i32 s10, s19, 0x2e8ba2e9
	s_lshr_b32 s11, s10, 31
	s_ashr_i32 s10, s10, 5
	s_add_i32 s21, s10, s11
	s_mul_i32 s10, s21, 0xffffea00
	s_add_i32 s20, s12, s10
	s_mul_i32 s10, s21, 0xfffff500
	s_add_i32 s10, s14, s10
	s_and_b32 s10, s10, 0xffffff80
	s_and_b32 s11, s20, 0x60
	s_or_b32 s10, s10, s11
	v_readlane_b32 s52, v254, 26
	s_bitcmp0_b32 s19, 2
	v_readlane_b32 s56, v254, 30
	v_readlane_b32 s58, v254, 32
	v_readlane_b32 s57, v254, 31
	v_readlane_b32 s59, v254, 33
	s_cselect_b32 s22, s56, s58
	s_cselect_b32 s11, s57, s59
	s_add_u32 s22, s22, s8
	s_addc_u32 s23, s11, s9
	s_ashr_i32 s11, s10, 31
	s_lshl_b64 s[10:11], s[10:11], 2
	s_add_u32 s22, s22, s10
	s_addc_u32 s23, s23, s11
	s_lshl_b32 s10, s21, 6
	v_lshl_add_u64 v[0:1], s[22:23], 0, v[136:137]
	v_add_u32_e32 v33, s10, v15
	s_movk_i32 s11, 0x2c00
	v_mad_i64_i32 v[34:35], s[22:23], v33, s11, v[0:1]
	global_load_dwordx4 v[34:37], v[34:35], off
	v_add_u32_e32 v33, s10, v16
	v_readlane_b32 s62, v254, 36
	v_readlane_b32 s63, v254, 37
	s_movk_i32 s63, 0x1600
	v_readlane_b32 s62, v254, 9
	v_readlane_b32 s53, v254, 27
	v_readlane_b32 s54, v254, 28
	v_readlane_b32 s55, v254, 29
	v_readlane_b32 s60, v254, 34
	v_readlane_b32 s61, v254, 35
	v_readlane_b32 s64, v254, 38
	v_readlane_b32 s65, v254, 39
	v_readlane_b32 s66, v254, 40
	v_readlane_b32 s67, v254, 41
	s_waitcnt vmcnt(0)
	ds_write2_b32 v24, v34, v35 offset1:1
	ds_write2_b32 v24, v36, v37 offset0:2 offset1:3
	v_mad_i64_i32 v[34:35], s[22:23], v33, s11, v[0:1]
	global_load_dwordx4 v[34:37], v[34:35], off
	s_waitcnt vmcnt(0)
	ds_write2_b32 v31, v34, v35 offset1:1
	ds_write2_b32 v32, v36, v37 offset1:1
	v_add_u32_e32 v31, s10, v17
	v_mad_i64_i32 v[32:33], s[22:23], v31, s11, v[0:1]
	global_load_dwordx4 v[32:35], v[32:33], off
	s_waitcnt vmcnt(0)
	ds_write2_b32 v29, v32, v33 offset1:1
	ds_write2_b32 v30, v34, v35 offset1:1
	v_add_u32_e32 v29, s10, v18
	v_mad_i64_i32 v[30:31], s[22:23], v29, s11, v[0:1]
	global_load_dwordx4 v[30:33], v[30:31], off
	s_waitcnt vmcnt(0)
	ds_write2_b32 v27, v30, v31 offset1:1
	ds_write2_b32 v28, v32, v33 offset1:1
	v_add_u32_e32 v27, s10, v19
	v_mad_i64_i32 v[28:29], s[22:23], v27, s11, v[0:1]
	global_load_dwordx4 v[28:31], v[28:29], off
	s_waitcnt vmcnt(0)
	ds_write2_b32 v25, v28, v29 offset1:1
	ds_write2_b32 v26, v30, v31 offset1:1
	v_add_u32_e32 v25, s10, v20
	v_mad_i64_i32 v[26:27], s[22:23], v25, s11, v[0:1]
	global_load_dwordx4 v[26:29], v[26:27], off
	s_waitcnt vmcnt(0)
	ds_write2_b32 v12, v26, v27 offset1:1
	ds_write2_b32 v13, v28, v29 offset1:1
	v_add_u32_e32 v12, s10, v21
	v_mad_i64_i32 v[12:13], s[22:23], v12, s11, v[0:1]
	global_load_dwordx4 v[26:29], v[12:13], off
	s_waitcnt vmcnt(0)
	ds_write2_b32 v10, v26, v27 offset1:1
	ds_write2_b32 v11, v28, v29 offset1:1
	v_add_u32_e32 v10, s10, v22
	v_mad_i64_i32 v[0:1], s[22:23], v10, s11, v[0:1]
	global_load_dwordx4 v[10:13], v[0:1], off
	s_ashr_i32 s11, s10, 31
	s_waitcnt vmcnt(0)
	ds_write2_b32 v2, v10, v11 offset1:1
	ds_write2_b32 v3, v12, v13 offset1:1
	s_waitcnt lgkmcnt(0)
	ds_read_b32 v0, v23
	ds_read_b32 v1, v23 offset:132
	v_lshl_add_u64 v[10:11], s[10:11], 1, v[8:9]
	s_waitcnt lgkmcnt(0)
	v_cvt_pk_bf16_f32 v0, v0, v1
	ds_read_b32 v1, v23 offset:264
	ds_read_b32 v2, v23 offset:396
	s_waitcnt lgkmcnt(0)
	v_cvt_pk_bf16_f32 v1, v1, v2
	ds_read_b32 v2, v23 offset:528
	ds_read_b32 v3, v23 offset:660
	s_waitcnt lgkmcnt(0)
	v_cvt_pk_bf16_f32 v2, v2, v3
	ds_read_b32 v3, v23 offset:792
	ds_read_b32 v12, v23 offset:924
	s_waitcnt lgkmcnt(0)
	v_cvt_pk_bf16_f32 v3, v3, v12
	v_add_u32_e32 v12, s20, v15
	v_ashrrev_i32_e32 v13, 31, v12
	v_lshlrev_b64 v[26:27], 11, v[12:13]
	v_lshl_add_u64 v[26:27], v[10:11], 0, v[26:27]
	global_store_dwordx4 v[26:27], v[0:3], off
	ds_read_b32 v0, v23 offset:32
	ds_read_b32 v1, v23 offset:164
	v_add_u32_e32 v26, 8, v12
	v_ashrrev_i32_e32 v27, 31, v26
	v_lshlrev_b64 v[26:27], 11, v[26:27]
	v_lshl_add_u64 v[26:27], v[10:11], 0, v[26:27]
	s_waitcnt lgkmcnt(0)
	v_cvt_pk_bf16_f32 v0, v0, v1
	ds_read_b32 v1, v23 offset:296
	ds_read_b32 v2, v23 offset:428
	s_waitcnt lgkmcnt(0)
	v_cvt_pk_bf16_f32 v1, v1, v2
	ds_read_b32 v2, v23 offset:560
	ds_read_b32 v3, v23 offset:692
	s_waitcnt lgkmcnt(0)
	v_cvt_pk_bf16_f32 v2, v2, v3
	ds_read_b32 v3, v23 offset:824
	ds_read_b32 v13, v23 offset:956
	s_waitcnt lgkmcnt(0)
	v_cvt_pk_bf16_f32 v3, v3, v13
	global_store_dwordx4 v[26:27], v[0:3], off
	ds_read_b32 v0, v23 offset:64
	ds_read_b32 v1, v23 offset:196
	v_add_u32_e32 v26, 16, v12
	v_ashrrev_i32_e32 v27, 31, v26
	v_lshlrev_b64 v[26:27], 11, v[26:27]
	v_lshl_add_u64 v[26:27], v[10:11], 0, v[26:27]
	s_waitcnt lgkmcnt(0)
	v_cvt_pk_bf16_f32 v0, v0, v1
	ds_read_b32 v1, v23 offset:328
	ds_read_b32 v2, v23 offset:460
	v_add_u32_e32 v12, 24, v12
	s_waitcnt lgkmcnt(0)
	v_cvt_pk_bf16_f32 v1, v1, v2
	ds_read_b32 v2, v23 offset:592
	ds_read_b32 v3, v23 offset:724
	s_waitcnt lgkmcnt(0)
	v_cvt_pk_bf16_f32 v2, v2, v3
	ds_read_b32 v3, v23 offset:856
	ds_read_b32 v13, v23 offset:988
	s_waitcnt lgkmcnt(0)
	v_cvt_pk_bf16_f32 v3, v3, v13
	global_store_dwordx4 v[26:27], v[0:3], off
	ds_read_b32 v0, v23 offset:96
	ds_read_b32 v1, v23 offset:228
	s_waitcnt lgkmcnt(0)
	v_cvt_pk_bf16_f32 v0, v0, v1
	ds_read_b32 v1, v23 offset:360
	ds_read_b32 v2, v23 offset:492
	s_waitcnt lgkmcnt(0)
	v_cvt_pk_bf16_f32 v1, v1, v2
	ds_read_b32 v2, v23 offset:624
	ds_read_b32 v3, v23 offset:756
	s_waitcnt lgkmcnt(0)
	v_cvt_pk_bf16_f32 v2, v2, v3
	ds_read_b32 v3, v23 offset:888
	ds_read_b32 v13, v23 offset:1020
	s_waitcnt lgkmcnt(0)
	v_cvt_pk_bf16_f32 v3, v3, v13
	v_ashrrev_i32_e32 v13, 31, v12
	v_lshlrev_b64 v[12:13], 11, v[12:13]
	v_lshl_add_u64 v[10:11], v[10:11], 0, v[12:13]
	global_store_dwordx4 v[10:11], v[0:3], off
	s_waitcnt lgkmcnt(0)
	s_branch .LBB0_784

.LBB0_792:
	s_ashr_i32 s3, s2, 31
	s_lshl_b64 s[4:5], s[2:3], 12
	v_lshl_add_u64 v[16:17], v[80:81], 0, s[4:5]
	s_add_i32 s4, s2, s28
	s_cmp_lt_i32 s4, 0x8000
	global_load_dwordx4 v[72:75], v[16:17], off
	global_load_dwordx4 v[68:71], v[16:17], off offset:1024
	global_load_dwordx4 v[64:67], v[16:17], off offset:3072
	global_load_dwordx4 v[76:79], v[16:17], off offset:2048
	s_cselect_b32 s6, s4, s2
	s_ashr_i32 s7, s6, 31
	s_lshl_b64 s[6:7], s[6:7], 12
	s_add_i32 s10, s17, s2
	s_cmp_lt_i32 s10, 0x8000
	v_lshl_add_u64 v[16:17], v[80:81], 0, s[6:7]
	s_cselect_b64 s[12:13], -1, 0
	global_load_dwordx4 v[60:63], v[16:17], off
	global_load_dwordx4 v[56:59], v[16:17], off offset:1024
	global_load_dwordx4 v[52:55], v[16:17], off offset:2048
	global_load_dwordx4 v[48:51], v[16:17], off offset:3072
	s_and_b64 s[6:7], s[12:13], exec
	s_cselect_b32 s6, s10, s2
	s_ashr_i32 s7, s6, 31
	s_lshl_b64 s[6:7], s[6:7], 12
	v_lshl_add_u64 v[16:17], v[80:81], 0, s[6:7]
	s_waitcnt vmcnt(0)
	global_load_dwordx4 v[44:47], v[16:17], off
	global_load_dwordx4 v[40:43], v[16:17], off offset:1024
	global_load_dwordx4 v[36:39], v[16:17], off offset:2048
	s_add_i32 s6, s18, s2
	s_cmp_lt_i32 s6, 0x8000
	s_cselect_b64 s[8:9], -1, 0
	s_and_b64 s[14:15], s[8:9], exec
	s_cselect_b32 s14, s6, s2
	global_load_dwordx4 v[32:35], v[16:17], off offset:3072
	s_ashr_i32 s15, s14, 31
	s_lshl_b64 s[14:15], s[14:15], 12
	v_lshl_add_u64 v[16:17], v[80:81], 0, s[14:15]
	global_load_dwordx4 v[28:31], v[16:17], off
	global_load_dwordx4 v[24:27], v[16:17], off offset:1024
	global_load_dwordx4 v[20:23], v[16:17], off offset:2048
	s_nop 0
	global_load_dwordx4 v[16:19], v[16:17], off offset:3072
	s_lshl_b64 s[14:15], s[2:3], 11
	s_cmpk_gt_i32 s4, 0x7fff
	s_waitcnt lgkmcnt(0)
	v_pk_mul_f32 v[90:91], v[74:75], v[74:75]
	v_pk_mul_f32 v[92:93], v[72:73], v[72:73]
	v_pk_mul_f32 v[94:95], v[70:71], v[70:71]
	v_pk_mul_f32 v[96:97], v[68:69], v[68:69]
	v_mul_f32_e32 v101, v64, v64
	v_mul_f32_e32 v98, v77, v77
	v_mul_f32_e32 v100, v79, v79
	v_pk_mov_b32 v[102:103], v[92:93], v[90:91] op_sel:[1,0]
	v_mov_b32_e32 v93, v91
	v_pk_mov_b32 v[90:91], v[96:97], v[94:95] op_sel:[1,0]
	v_mov_b32_e32 v97, v95
	v_mul_f32_e32 v105, v66, v66
	v_mul_f32_e32 v106, v67, v67
	v_pk_fma_f32 v[94:95], v[76:77], v[76:77], v[98:99] op_sel_hi:[1,1,0]
	v_pk_fma_f32 v[98:99], v[78:79], v[78:79], v[100:101] op_sel_hi:[1,1,0]
	v_pk_add_f32 v[92:93], v[102:103], v[92:93]
	v_pk_add_f32 v[90:91], v[90:91], v[96:97]
	v_mul_f32_e32 v104, v65, v65
	v_mov_b32_e32 v95, v105
	v_mov_b32_e32 v99, v106
	v_pk_add_f32 v[92:93], v[92:93], v[92:93] op_sel:[0,1] op_sel_hi:[1,0]
	v_pk_add_f32 v[90:91], v[90:91], v[90:91] op_sel:[0,1] op_sel_hi:[1,0]
	v_pk_add_f32 v[94:95], v[94:95], v[98:99]
	v_mov_b32_e32 v93, v101
	v_mov_b32_e32 v91, v104
	v_mul_f32_e32 v96, v61, v61
	v_mul_f32_e32 v97, v63, v63
	v_mul_f32_e32 v98, v57, v57
	v_mul_f32_e32 v99, v59, v59
	v_mul_f32_e32 v100, v53, v53
	v_mul_f32_e32 v101, v55, v55
	v_pk_add_f32 v[90:91], v[92:93], v[90:91]
	v_fmac_f32_e32 v96, v60, v60
	v_fmac_f32_e32 v97, v62, v62
	v_fmac_f32_e32 v98, v56, v56
	v_fmac_f32_e32 v99, v58, v58
	v_mul_f32_e32 v102, v49, v49
	v_mul_f32_e32 v103, v51, v51
	v_fmac_f32_e32 v100, v52, v52
	v_fmac_f32_e32 v101, v54, v54
	v_pk_add_f32 v[90:91], v[90:91], v[94:95]
	v_add_f32_e32 v92, v96, v97
	v_add_f32_e32 v93, v98, v99
	v_fmac_f32_e32 v102, v48, v48
	v_fmac_f32_e32 v103, v50, v50
	v_add_f32_e32 v94, v100, v101
	v_add_f32_e32 v90, v90, v91
	v_add_f32_e32 v91, v92, v93
	v_add_f32_e32 v91, v91, v94
	v_add_f32_e32 v92, v102, v103
	v_add_f32_e32 v91, v91, v92
	s_waitcnt vmcnt(0)
	v_mul_f32_e32 v92, v45, v45
	v_mul_f32_e32 v93, v47, v47
	v_fmac_f32_e32 v92, v44, v44
	v_fmac_f32_e32 v93, v46, v46
	v_add_f32_e32 v92, v92, v93
	v_mul_f32_e32 v93, v41, v41
	v_mul_f32_e32 v94, v43, v43
	v_fmac_f32_e32 v93, v40, v40
	v_fmac_f32_e32 v94, v42, v42
	v_add_f32_e32 v93, v93, v94
	v_add_f32_e32 v92, v92, v93
	v_mul_f32_e32 v93, v37, v37
	v_mul_f32_e32 v94, v39, v39
	v_fmac_f32_e32 v93, v36, v36
	v_fmac_f32_e32 v94, v38, v38
	v_add_f32_e32 v93, v93, v94
	v_add_f32_e32 v92, v92, v93
	v_mul_f32_e32 v93, v33, v33
	v_mul_f32_e32 v94, v35, v35
	v_fmac_f32_e32 v93, v32, v32
	v_fmac_f32_e32 v94, v34, v34
	v_add_f32_e32 v93, v93, v94
	v_add_f32_e32 v92, v92, v93
	v_mul_f32_e32 v93, v29, v29
	v_mul_f32_e32 v94, v31, v31
	v_fmac_f32_e32 v93, v28, v28
	v_fmac_f32_e32 v94, v30, v30
	v_add_f32_e32 v93, v93, v94
	v_mul_f32_e32 v94, v25, v25
	v_mul_f32_e32 v95, v27, v27
	v_fmac_f32_e32 v94, v24, v24
	v_fmac_f32_e32 v95, v26, v26
	v_add_f32_e32 v94, v94, v95
	v_add_f32_e32 v93, v93, v94
	v_mul_f32_e32 v94, v21, v21
	v_mul_f32_e32 v95, v23, v23
	ds_bpermute_b32 v96, v84, v90
	v_fmac_f32_e32 v94, v20, v20
	v_fmac_f32_e32 v95, v22, v22
	v_add_f32_e32 v94, v94, v95
	v_add_f32_e32 v93, v93, v94
	v_mul_f32_e32 v94, v17, v17
	v_mul_f32_e32 v95, v19, v19
	v_fmac_f32_e32 v94, v16, v16
	v_fmac_f32_e32 v95, v18, v18
	v_add_f32_e32 v94, v94, v95
	s_waitcnt lgkmcnt(0)
	v_add_f32_e32 v90, v90, v96
	v_add_f32_e32 v93, v93, v94
	ds_bpermute_b32 v96, v85, v90
	ds_bpermute_b32 v97, v84, v91
	ds_bpermute_b32 v94, v84, v92
	ds_bpermute_b32 v95, v84, v93
	s_waitcnt lgkmcnt(3)
	v_add_f32_e32 v90, v90, v96
	s_waitcnt lgkmcnt(2)
	v_add_f32_e32 v91, v91, v97
	s_waitcnt lgkmcnt(1)
	v_add_f32_e32 v92, v92, v94
	s_waitcnt lgkmcnt(0)
	v_add_f32_e32 v93, v93, v95
	ds_bpermute_b32 v95, v86, v90
	ds_bpermute_b32 v97, v85, v91
	ds_bpermute_b32 v94, v85, v92
	s_waitcnt lgkmcnt(2)
	v_add_f32_e32 v90, v90, v95
	s_waitcnt lgkmcnt(1)
	v_add_f32_e32 v91, v91, v97
	s_waitcnt lgkmcnt(0)
	v_add_f32_e32 v92, v92, v94
	ds_bpermute_b32 v95, v87, v90
	ds_bpermute_b32 v96, v86, v91
	ds_bpermute_b32 v97, v86, v92
	ds_bpermute_b32 v94, v85, v93
	s_waitcnt lgkmcnt(3)
	v_add_f32_e32 v90, v90, v95
	s_waitcnt lgkmcnt(2)
	v_add_f32_e32 v91, v91, v96
	s_waitcnt lgkmcnt(1)
	v_add_f32_e32 v92, v92, v97
	ds_bpermute_b32 v97, v88, v90
	ds_bpermute_b32 v95, v87, v91
	s_waitcnt lgkmcnt(2)
	v_add_f32_e32 v93, v93, v94
	ds_bpermute_b32 v94, v86, v93
	ds_bpermute_b32 v96, v87, v92
	s_waitcnt lgkmcnt(3)
	v_add_f32_e32 v90, v90, v97
	s_waitcnt lgkmcnt(2)
	v_add_f32_e32 v91, v91, v95
	ds_bpermute_b32 v95, v89, v90
	s_waitcnt lgkmcnt(2)
	v_add_f32_e32 v93, v93, v94
	ds_bpermute_b32 v94, v87, v93
	s_waitcnt lgkmcnt(2)
	v_add_f32_e32 v92, v92, v96
	ds_bpermute_b32 v96, v88, v92
	s_waitcnt lgkmcnt(2)
	v_add_f32_e32 v90, v90, v95
	v_mov_b32_e32 v95, 0x358637bd
	v_fmamk_f32 v90, v90, 0x3a800000, v95
	v_mul_f32_e32 v95, 0x4f800000, v90
	v_cmp_gt_f32_e32 vcc, s16, v90
	s_waitcnt lgkmcnt(1)
	v_add_f32_e32 v93, v93, v94
	ds_bpermute_b32 v94, v88, v91
	v_cndmask_b32_e32 v95, v90, v95, vcc
	ds_bpermute_b32 v97, v88, v93
	v_sqrt_f32_e32 v98, v95
	s_waitcnt lgkmcnt(2)
	v_add_f32_e32 v92, v92, v96
	s_waitcnt lgkmcnt(1)
	v_add_f32_e32 v94, v91, v94
	v_add_u32_e32 v91, -1, v98
	s_waitcnt lgkmcnt(0)
	v_add_f32_e32 v90, v93, v97
	v_fma_f32 v93, -v91, v98, v95
	v_cmp_ge_f32_e64 s[2:3], 0, v93
	v_add_u32_e32 v93, 1, v98
	v_fma_f32 v96, -v93, v98, v95
	v_cndmask_b32_e64 v91, v98, v91, s[2:3]
	v_cmp_lt_f32_e64 s[2:3], 0, v96
	s_nop 1
	v_cndmask_b32_e64 v91, v91, v93, s[2:3]
	v_mul_f32_e32 v93, 0x37800000, v91
	v_cndmask_b32_e32 v91, v91, v93, vcc
	v_mov_b32_e32 v93, 0x260
	v_cmp_class_f32_e32 vcc, v95, v93
	ds_bpermute_b32 v93, v89, v92
	s_nop 0
	v_cndmask_b32_e32 v96, v91, v95, vcc
	v_div_scale_f32 v97, s[2:3], v96, v96, 1.0
	v_rcp_f32_e32 v98, v97
	ds_bpermute_b32 v95, v89, v94
	ds_bpermute_b32 v91, v89, v90
	v_fma_f32 v99, -v97, v98, 1.0
	v_fmac_f32_e32 v98, v99, v98
	v_div_scale_f32 v99, vcc, 1.0, v96, 1.0
	v_mul_f32_e32 v100, v99, v98
	v_fma_f32 v101, -v97, v100, v99
	v_fmac_f32_e32 v100, v101, v98
	v_fma_f32 v97, -v97, v100, v99
	v_div_fmas_f32 v97, v97, v98, v100
	v_div_fixup_f32 v96, v97, v96, 1.0
	v_pk_mul_f32 v[68:69], v[68:69], v[96:97] op_sel_hi:[1,0]
	v_pk_mul_f32 v[70:71], v[70:71], v[96:97] op_sel_hi:[1,0]
	v_pk_mul_f32 v[68:69], v[4:5], v[68:69]
	v_pk_mul_f32 v[70:71], v[6:7], v[70:71]
	v_lshl_add_u64 v[98:99], v[82:83], 0, s[14:15]
	v_cvt_pk_bf16_f32 v68, v68, v69
	v_cvt_pk_bf16_f32 v69, v70, v71
	v_pk_mul_f32 v[72:73], v[72:73], v[96:97] op_sel_hi:[1,0]
	v_pk_mul_f32 v[74:75], v[74:75], v[96:97] op_sel_hi:[1,0]
	global_store_dwordx2 v[98:99], v[68:69], off offset:512
	v_pk_mul_f32 v[68:69], v[76:77], v[96:97] op_sel_hi:[1,0]
	v_pk_mul_f32 v[70:71], v[78:79], v[96:97] op_sel_hi:[1,0]
	v_pk_mul_f32 v[64:65], v[64:65], v[96:97] op_sel_hi:[1,0]
	v_pk_mul_f32 v[66:67], v[66:67], v[96:97] op_sel_hi:[1,0]
	v_pk_mul_f32 v[74:75], v[2:3], v[74:75]
	v_pk_mul_f32 v[72:73], v[0:1], v[72:73]
	v_pk_mul_f32 v[70:71], v[10:11], v[70:71]
	v_pk_mul_f32 v[68:69], v[8:9], v[68:69]
	v_pk_mul_f32 v[66:67], v[14:15], v[66:67]
	v_pk_mul_f32 v[64:65], v[12:13], v[64:65]
	v_cvt_pk_bf16_f32 v72, v72, v73
	v_cvt_pk_bf16_f32 v73, v74, v75
	v_cvt_pk_bf16_f32 v68, v68, v69
	v_cvt_pk_bf16_f32 v69, v70, v71
	v_cvt_pk_bf16_f32 v64, v64, v65
	v_cvt_pk_bf16_f32 v65, v66, v67
	global_store_dwordx2 v[98:99], v[72:73], off
	global_store_dwordx2 v[98:99], v[68:69], off offset:1024
	global_store_dwordx2 v[98:99], v[64:65], off offset:1536
	s_cbranch_scc0 .LBB0_795
	s_andn2_b64 vcc, exec, s[12:13]
	s_cbranch_vccz .LBB0_796

.LBB0_795:
	s_waitcnt lgkmcnt(0)
	v_add_f32_e32 v64, v94, v95
	v_mov_b32_e32 v65, 0x358637bd
	v_fmamk_f32 v64, v64, 0x3a800000, v65
	v_mul_f32_e32 v65, 0x4f800000, v64
	v_cmp_gt_f32_e32 vcc, s16, v64
	s_ashr_i32 s5, s4, 31
	s_nop 0
	v_cndmask_b32_e32 v64, v64, v65, vcc
	v_sqrt_f32_e32 v65, v64
	s_nop 0
	v_add_u32_e32 v66, -1, v65
	v_fma_f32 v68, -v66, v65, v64
	v_add_u32_e32 v67, 1, v65
	v_cmp_ge_f32_e64 s[2:3], 0, v68
	s_nop 1
	v_cndmask_b32_e64 v66, v65, v66, s[2:3]
	v_fma_f32 v65, -v67, v65, v64
	v_cmp_lt_f32_e64 s[2:3], 0, v65
	s_nop 1
	v_cndmask_b32_e64 v65, v66, v67, s[2:3]
	v_mul_f32_e32 v66, 0x37800000, v65
	v_cndmask_b32_e32 v65, v65, v66, vcc
	v_mov_b32_e32 v66, 0x260
	v_cmp_class_f32_e32 vcc, v64, v66
	s_nop 1
	v_cndmask_b32_e32 v64, v65, v64, vcc
	v_div_scale_f32 v65, s[2:3], v64, v64, 1.0
	v_rcp_f32_e32 v66, v65
	s_lshl_b64 s[2:3], s[4:5], 11
	v_fma_f32 v67, -v65, v66, 1.0
	v_fmac_f32_e32 v66, v67, v66
	v_div_scale_f32 v67, vcc, 1.0, v64, 1.0
	v_mul_f32_e32 v68, v67, v66
	v_fma_f32 v69, -v65, v68, v67
	v_fmac_f32_e32 v68, v69, v66
	v_fma_f32 v65, -v65, v68, v67
	v_div_fmas_f32 v65, v65, v66, v68
	v_div_fixup_f32 v64, v65, v64, 1.0
	v_pk_mul_f32 v[60:61], v[60:61], v[64:65] op_sel_hi:[1,0]
	v_pk_mul_f32 v[62:63], v[62:63], v[64:65] op_sel_hi:[1,0]
	v_pk_mul_f32 v[56:57], v[56:57], v[64:65] op_sel_hi:[1,0]
	v_pk_mul_f32 v[58:59], v[58:59], v[64:65] op_sel_hi:[1,0]
	v_pk_mul_f32 v[52:53], v[52:53], v[64:65] op_sel_hi:[1,0]
	v_pk_mul_f32 v[54:55], v[54:55], v[64:65] op_sel_hi:[1,0]
	v_pk_mul_f32 v[48:49], v[48:49], v[64:65] op_sel_hi:[1,0]
	v_pk_mul_f32 v[50:51], v[50:51], v[64:65] op_sel_hi:[1,0]
	v_pk_mul_f32 v[62:63], v[2:3], v[62:63]
	v_pk_mul_f32 v[60:61], v[0:1], v[60:61]
	v_pk_mul_f32 v[58:59], v[6:7], v[58:59]
	v_pk_mul_f32 v[56:57], v[4:5], v[56:57]
	v_pk_mul_f32 v[54:55], v[10:11], v[54:55]
	v_pk_mul_f32 v[52:53], v[8:9], v[52:53]
	v_pk_mul_f32 v[50:51], v[14:15], v[50:51]
	v_pk_mul_f32 v[48:49], v[12:13], v[48:49]
	v_lshl_add_u64 v[66:67], v[82:83], 0, s[2:3]
	v_cvt_pk_bf16_f32 v60, v60, v61
	v_cvt_pk_bf16_f32 v61, v62, v63
	v_cvt_pk_bf16_f32 v56, v56, v57
	v_cvt_pk_bf16_f32 v57, v58, v59
	v_cvt_pk_bf16_f32 v52, v52, v53
	v_cvt_pk_bf16_f32 v53, v54, v55
	v_cvt_pk_bf16_f32 v48, v48, v49
	v_cvt_pk_bf16_f32 v49, v50, v51
	global_store_dwordx2 v[66:67], v[60:61], off
	global_store_dwordx2 v[66:67], v[56:57], off offset:512
	global_store_dwordx2 v[66:67], v[52:53], off offset:1024
	global_store_dwordx2 v[66:67], v[48:49], off offset:1536
	s_andn2_b64 vcc, exec, s[12:13]
	s_cbranch_vccnz .LBB0_794
.LBB0_796:
	s_waitcnt lgkmcnt(0)
	v_add_f32_e32 v48, v92, v93
	v_mov_b32_e32 v49, 0x358637bd
	v_fmamk_f32 v48, v48, 0x3a800000, v49
	v_mul_f32_e32 v49, 0x4f800000, v48
	v_cmp_gt_f32_e32 vcc, s16, v48
	s_ashr_i32 s11, s10, 31
	s_nop 0
	v_cndmask_b32_e32 v48, v48, v49, vcc
	v_sqrt_f32_e32 v49, v48
	s_nop 0
	v_add_u32_e32 v50, -1, v49
	v_fma_f32 v52, -v50, v49, v48
	v_add_u32_e32 v51, 1, v49
	v_cmp_ge_f32_e64 s[2:3], 0, v52
	s_nop 1
	v_cndmask_b32_e64 v50, v49, v50, s[2:3]
	v_fma_f32 v49, -v51, v49, v48
	v_cmp_lt_f32_e64 s[2:3], 0, v49
	s_nop 1
	v_cndmask_b32_e64 v49, v50, v51, s[2:3]
	v_mul_f32_e32 v50, 0x37800000, v49
	v_cndmask_b32_e32 v49, v49, v50, vcc
	v_mov_b32_e32 v50, 0x260
	v_cmp_class_f32_e32 vcc, v48, v50
	s_nop 1
	v_cndmask_b32_e32 v48, v49, v48, vcc
	v_div_scale_f32 v49, s[2:3], v48, v48, 1.0
	v_rcp_f32_e32 v50, v49
	s_lshl_b64 s[2:3], s[10:11], 11
	v_fma_f32 v51, -v49, v50, 1.0
	v_fmac_f32_e32 v50, v51, v50
	v_div_scale_f32 v51, vcc, 1.0, v48, 1.0
	v_mul_f32_e32 v52, v51, v50
	v_fma_f32 v53, -v49, v52, v51
	v_fmac_f32_e32 v52, v53, v50
	v_fma_f32 v49, -v49, v52, v51
	v_div_fmas_f32 v49, v49, v50, v52
	v_div_fixup_f32 v48, v49, v48, 1.0
	v_pk_mul_f32 v[44:45], v[44:45], v[48:49] op_sel_hi:[1,0]
	v_pk_mul_f32 v[46:47], v[46:47], v[48:49] op_sel_hi:[1,0]
	v_pk_mul_f32 v[40:41], v[40:41], v[48:49] op_sel_hi:[1,0]
	v_pk_mul_f32 v[42:43], v[42:43], v[48:49] op_sel_hi:[1,0]
	v_pk_mul_f32 v[36:37], v[36:37], v[48:49] op_sel_hi:[1,0]
	v_pk_mul_f32 v[38:39], v[38:39], v[48:49] op_sel_hi:[1,0]
	v_pk_mul_f32 v[32:33], v[32:33], v[48:49] op_sel_hi:[1,0]
	v_pk_mul_f32 v[34:35], v[34:35], v[48:49] op_sel_hi:[1,0]
	v_pk_mul_f32 v[46:47], v[2:3], v[46:47]
	v_pk_mul_f32 v[44:45], v[0:1], v[44:45]
	v_pk_mul_f32 v[42:43], v[6:7], v[42:43]
	v_pk_mul_f32 v[40:41], v[4:5], v[40:41]
	v_pk_mul_f32 v[38:39], v[10:11], v[38:39]
	v_pk_mul_f32 v[36:37], v[8:9], v[36:37]
	v_pk_mul_f32 v[34:35], v[14:15], v[34:35]
	v_pk_mul_f32 v[32:33], v[12:13], v[32:33]
	v_lshl_add_u64 v[50:51], v[82:83], 0, s[2:3]
	v_cvt_pk_bf16_f32 v44, v44, v45
	v_cvt_pk_bf16_f32 v45, v46, v47
	v_cvt_pk_bf16_f32 v40, v40, v41
	v_cvt_pk_bf16_f32 v41, v42, v43
	v_cvt_pk_bf16_f32 v36, v36, v37
	v_cvt_pk_bf16_f32 v37, v38, v39
	v_cvt_pk_bf16_f32 v32, v32, v33
	v_cvt_pk_bf16_f32 v33, v34, v35
	global_store_dwordx2 v[50:51], v[44:45], off
	global_store_dwordx2 v[50:51], v[40:41], off offset:512
	global_store_dwordx2 v[50:51], v[36:37], off offset:1024
	global_store_dwordx2 v[50:51], v[32:33], off offset:1536
	s_andn2_b64 vcc, exec, s[8:9]
	s_cbranch_vccnz .LBB0_791
.LBB0_797:
	s_waitcnt lgkmcnt(0)
	v_add_f32_e32 v32, v90, v91
	v_mov_b32_e32 v33, 0x358637bd
	v_fmamk_f32 v32, v32, 0x3a800000, v33
	v_mul_f32_e32 v33, 0x4f800000, v32
	v_cmp_gt_f32_e32 vcc, s16, v32
	s_ashr_i32 s7, s6, 31
	s_nop 0
	v_cndmask_b32_e32 v32, v32, v33, vcc
	v_sqrt_f32_e32 v33, v32
	s_nop 0
	v_add_u32_e32 v34, -1, v33
	v_fma_f32 v36, -v34, v33, v32
	v_add_u32_e32 v35, 1, v33
	v_cmp_ge_f32_e64 s[2:3], 0, v36
	s_nop 1
	v_cndmask_b32_e64 v34, v33, v34, s[2:3]
	v_fma_f32 v33, -v35, v33, v32
	v_cmp_lt_f32_e64 s[2:3], 0, v33
	s_nop 1
	v_cndmask_b32_e64 v33, v34, v35, s[2:3]
	v_mul_f32_e32 v34, 0x37800000, v33
	v_cndmask_b32_e32 v33, v33, v34, vcc
	v_mov_b32_e32 v34, 0x260
	v_cmp_class_f32_e32 vcc, v32, v34
	s_nop 1
	v_cndmask_b32_e32 v32, v33, v32, vcc
	v_div_scale_f32 v33, s[2:3], v32, v32, 1.0
	v_rcp_f32_e32 v34, v33
	s_lshl_b64 s[2:3], s[6:7], 11
	v_fma_f32 v35, -v33, v34, 1.0
	v_fmac_f32_e32 v34, v35, v34
	v_div_scale_f32 v35, vcc, 1.0, v32, 1.0
	v_mul_f32_e32 v36, v35, v34
	v_fma_f32 v37, -v33, v36, v35
	v_fmac_f32_e32 v36, v37, v34
	v_fma_f32 v33, -v33, v36, v35
	v_div_fmas_f32 v33, v33, v34, v36
	v_div_fixup_f32 v32, v33, v32, 1.0
	v_pk_mul_f32 v[28:29], v[28:29], v[32:33] op_sel_hi:[1,0]
	v_pk_mul_f32 v[30:31], v[30:31], v[32:33] op_sel_hi:[1,0]
	v_pk_mul_f32 v[24:25], v[24:25], v[32:33] op_sel_hi:[1,0]
	v_pk_mul_f32 v[26:27], v[26:27], v[32:33] op_sel_hi:[1,0]
	v_pk_mul_f32 v[20:21], v[20:21], v[32:33] op_sel_hi:[1,0]
	v_pk_mul_f32 v[22:23], v[22:23], v[32:33] op_sel_hi:[1,0]
	v_pk_mul_f32 v[16:17], v[16:17], v[32:33] op_sel_hi:[1,0]
	v_pk_mul_f32 v[18:19], v[18:19], v[32:33] op_sel_hi:[1,0]
	v_pk_mul_f32 v[30:31], v[2:3], v[30:31]
	v_pk_mul_f32 v[28:29], v[0:1], v[28:29]
	v_pk_mul_f32 v[26:27], v[6:7], v[26:27]
	v_pk_mul_f32 v[24:25], v[4:5], v[24:25]
	v_pk_mul_f32 v[22:23], v[10:11], v[22:23]
	v_pk_mul_f32 v[20:21], v[8:9], v[20:21]
	v_pk_mul_f32 v[18:19], v[14:15], v[18:19]
	v_pk_mul_f32 v[16:17], v[12:13], v[16:17]
	v_lshl_add_u64 v[34:35], v[82:83], 0, s[2:3]
	v_cvt_pk_bf16_f32 v28, v28, v29
	v_cvt_pk_bf16_f32 v29, v30, v31
	v_cvt_pk_bf16_f32 v24, v24, v25
	v_cvt_pk_bf16_f32 v25, v26, v27
	v_cvt_pk_bf16_f32 v20, v20, v21
	v_cvt_pk_bf16_f32 v21, v22, v23
	v_cvt_pk_bf16_f32 v16, v16, v17
	v_cvt_pk_bf16_f32 v17, v18, v19
	global_store_dwordx2 v[34:35], v[28:29], off
	global_store_dwordx2 v[34:35], v[24:25], off offset:512
	global_store_dwordx2 v[34:35], v[20:21], off offset:1024
	global_store_dwordx2 v[34:35], v[16:17], off offset:1536
	s_branch .LBB0_791
.LBB0_798:
	v_readlane_b32 s4, v254, 26
	v_readlane_b32 s5, v254, 27
	v_readlane_b32 s18, v254, 40
	v_readlane_b32 s19, v254, 41
	s_mov_b64 s[4:5], s[18:19]
	v_mbcnt_lo_u32_b32 v0, -1, 0
	v_mbcnt_hi_u32_b32 v0, -1, v0
	v_readlane_b32 s2, v254, 4
	s_waitcnt vmcnt(0) lgkmcnt(0)
	v_readlane_b32 s6, v254, 28
	v_readlane_b32 s7, v254, 29
	v_cmp_eq_u32_e32 vcc, 0, v0
	v_readlane_b32 s3, v254, 5
	s_and_b64 s[6:7], s[2:3], vcc
	v_readlane_b32 s8, v254, 30
	v_readlane_b32 s9, v254, 31
	v_readlane_b32 s10, v254, 32
	v_readlane_b32 s11, v254, 33
	v_readlane_b32 s12, v254, 34
	v_readlane_b32 s13, v254, 35
	v_readlane_b32 s14, v254, 36
	v_readlane_b32 s15, v254, 37
	v_readlane_b32 s16, v254, 38
	v_readlane_b32 s17, v254, 39
	s_waitcnt lgkmcnt(0)
	s_barrier
	s_and_saveexec_b64 s[2:3], s[6:7]
	s_cbranch_execz .LBB0_814
	v_readlane_b32 s6, v255, 0
	s_add_i32 s16, s6, 14
	s_getreg_b32 s6, hwreg(HW_REG_XCC_ID, 0, 4)
	s_lshl_b32 s6, s6, 8
	s_and_b32 s6, s6, 0x700
	s_add_u32 s15, s4, s6
	s_addc_u32 s14, s5, 0
	v_mov_b32_e32 v0, s15
	v_add_co_u32_e32 v8, vcc, 0x2000, v0
	v_mov_b32_e32 v0, s14
	s_nop 0
	v_addc_co_u32_e32 v9, vcc, 0, v0, vcc
	v_mov_b32_e32 v0, s4
	v_add_co_u32_e32 v10, vcc, 0x2000, v0
	v_mov_b32_e32 v0, s5
	s_nop 0
	v_addc_co_u32_e32 v11, vcc, 0, v0, vcc
	global_load_dword v12, v[8:9], off sc1
	global_load_dword v0, v[10:11], off sc1
	global_load_dword v1, v[10:11], off offset:256 sc1
	global_load_dword v2, v[10:11], off offset:512 sc1
	global_load_dword v3, v[10:11], off offset:768 sc1
	global_load_dword v4, v[10:11], off offset:1024 sc1
	global_load_dword v5, v[10:11], off offset:1280 sc1
	global_load_dword v6, v[10:11], off offset:1536 sc1
	global_load_dword v7, v[10:11], off offset:1792 sc1
	v_mov_b32_e32 v10, 1
	global_atomic_add v8, v[8:9], v10, off offset:2048 sc0
	s_waitcnt vmcnt(0) lgkmcnt(0)
	v_mul_lo_u32 v9, v12, s16
	v_add_u32_e32 v8, 1, v8
	v_cmp_ne_u32_e32 vcc, v8, v9
	s_and_saveexec_b64 s[6:7], vcc
	s_xor_b64 s[6:7], exec, s[6:7]
	s_cbranch_execz .LBB0_804
	v_mov_b32_e32 v0, s15
	v_add_co_u32_e32 v0, vcc, 0x3000, v0
	v_mov_b32_e32 v1, s14
	s_nop 0
	v_addc_co_u32_e32 v1, vcc, 0, v1, vcc
	global_load_dword v0, v[0:1], off sc1
	s_add_u32 s8, s15, 0x3000
	s_addc_u32 s9, s14, 0
	s_waitcnt vmcnt(0) lgkmcnt(0)
	v_cmp_gt_u32_e32 vcc, s16, v0
	s_and_saveexec_b64 s[10:11], vcc
	s_cbranch_execz .LBB0_803
	s_mov_b64 s[12:13], 0

.LBB0_826:
	s_lshl_b32 s15, s22, 8
	v_mbcnt_lo_u32_b32 v142, -1, 0
	v_mbcnt_hi_u32_b32 v142, -1, v142
	s_add_i32 s15, s15, s39
	v_and_or_b32 v143, v142, 15, s15
	s_lshl_b32 s15, s23, 7
	v_ashrrev_i32_e32 v142, 1, v142
	s_or_b32 s15, s15, s40
	v_and_b32_e32 v142, -8, v142
	v_add_u32_e32 v142, s15, v142
	v_mov_b64_e32 v[144:145], s[10:11]
	v_mad_i64_i32 v[144:145], s[22:23], v143, s63, v[144:145]
	v_ashrrev_i32_e32 v143, 31, v142
	v_lshl_add_u64 v[142:143], v[142:143], 1, v[144:145]
	v_mul_f32_e32 v144, 0xbfb8aa3b, v124
	v_mul_f32_e32 v145, 0xbfb8aa3b, v125
	v_exp_f32_e32 v144, v144
	v_exp_f32_e32 v145, v145
	s_mov_b64 s[22:23], 0x16000
	s_mov_b64 s[24:25], 0x58000
	v_add_f32_e32 v144, 1.0, v144
	v_add_f32_e32 v145, 1.0, v145
	v_rcp_f32_e32 v144, v144
	v_rcp_f32_e32 v145, v145
	s_andn2_b64 vcc, exec, s[2:3]
	v_pk_mul_f32 v[124:125], v[124:125], v[144:145]
	s_nop 0
	v_pk_mul_f32 v[120:121], v[124:125], v[120:121]
	v_mul_f32_e32 v124, 0xbfb8aa3b, v126
	v_mul_f32_e32 v125, 0xbfb8aa3b, v127
	v_exp_f32_e32 v124, v124
	v_exp_f32_e32 v125, v125
	v_add_f32_e32 v124, 1.0, v124
	v_add_f32_e32 v125, 1.0, v125
	v_rcp_f32_e32 v124, v124
	v_rcp_f32_e32 v125, v125
	s_nop 0
	v_pk_mul_f32 v[124:125], v[126:127], v[124:125]
	s_nop 0
	v_pk_mul_f32 v[122:123], v[124:125], v[122:123]
	v_mul_f32_e32 v124, 0xbfb8aa3b, v116
	v_mul_f32_e32 v125, 0xbfb8aa3b, v117
	v_exp_f32_e32 v124, v124
	v_exp_f32_e32 v125, v125
	v_add_f32_e32 v124, 1.0, v124
	v_add_f32_e32 v125, 1.0, v125
	v_rcp_f32_e32 v124, v124
	v_rcp_f32_e32 v125, v125
	s_nop 0
	v_pk_mul_f32 v[116:117], v[116:117], v[124:125]
	s_nop 0
	v_pk_mul_f32 v[116:117], v[116:117], v[112:113]
	v_mul_f32_e32 v112, 0xbfb8aa3b, v118
	v_mul_f32_e32 v113, 0xbfb8aa3b, v119
	v_exp_f32_e32 v112, v112
	v_exp_f32_e32 v113, v113
	v_add_f32_e32 v112, 1.0, v112
	v_add_f32_e32 v113, 1.0, v113
	v_rcp_f32_e32 v112, v112
	v_rcp_f32_e32 v113, v113
	s_nop 0
	v_pk_mul_f32 v[112:113], v[118:119], v[112:113]
	s_nop 0
	v_pk_mul_f32 v[118:119], v[112:113], v[114:115]
	v_cvt_pk_bf16_f32 v112, v120, v121
	v_cvt_pk_bf16_f32 v113, v122, v123
	v_cvt_pk_bf16_f32 v114, v116, v117
	v_cvt_pk_bf16_f32 v115, v118, v119
	global_store_dwordx4 v[142:143], v[112:115], off nt
	s_nop 1
	v_mul_f32_e32 v114, 0xbfb8aa3b, v108
	v_mul_f32_e32 v115, 0xbfb8aa3b, v109
	v_exp_f32_e32 v114, v114
	v_exp_f32_e32 v115, v115
	v_lshl_add_u64 v[112:113], v[142:143], 0, s[22:23]
	v_add_f32_e32 v114, 1.0, v114
	v_add_f32_e32 v115, 1.0, v115
	v_rcp_f32_e32 v114, v114
	v_rcp_f32_e32 v115, v115
	s_nop 0
	v_pk_mul_f32 v[108:109], v[108:109], v[114:115]
	s_nop 0
	v_pk_mul_f32 v[104:105], v[108:109], v[104:105]
	v_mul_f32_e32 v108, 0xbfb8aa3b, v110
	v_mul_f32_e32 v109, 0xbfb8aa3b, v111
	v_exp_f32_e32 v108, v108
	v_exp_f32_e32 v109, v109
	v_add_f32_e32 v108, 1.0, v108
	v_add_f32_e32 v109, 1.0, v109
	v_rcp_f32_e32 v108, v108
	v_rcp_f32_e32 v109, v109
	s_nop 0
	v_pk_mul_f32 v[108:109], v[110:111], v[108:109]
	s_nop 0
	v_pk_mul_f32 v[106:107], v[108:109], v[106:107]
	v_mul_f32_e32 v108, 0xbfb8aa3b, v100
	v_mul_f32_e32 v109, 0xbfb8aa3b, v101
	v_exp_f32_e32 v108, v108
	v_exp_f32_e32 v109, v109
	v_add_f32_e32 v108, 1.0, v108
	v_add_f32_e32 v109, 1.0, v109
	v_rcp_f32_e32 v108, v108
	v_rcp_f32_e32 v109, v109
	s_nop 0
	v_pk_mul_f32 v[100:101], v[100:101], v[108:109]
	s_nop 0
	v_pk_mul_f32 v[100:101], v[100:101], v[96:97]
	v_mul_f32_e32 v96, 0xbfb8aa3b, v102
	v_mul_f32_e32 v97, 0xbfb8aa3b, v103
	v_exp_f32_e32 v96, v96
	v_exp_f32_e32 v97, v97
	v_add_f32_e32 v96, 1.0, v96
	v_add_f32_e32 v97, 1.0, v97
	v_rcp_f32_e32 v96, v96
	v_rcp_f32_e32 v97, v97
	s_nop 0
	v_pk_mul_f32 v[96:97], v[102:103], v[96:97]
	s_nop 0
	v_pk_mul_f32 v[102:103], v[96:97], v[98:99]
	v_cvt_pk_bf16_f32 v96, v104, v105
	v_cvt_pk_bf16_f32 v97, v106, v107
	v_cvt_pk_bf16_f32 v98, v100, v101
	v_cvt_pk_bf16_f32 v99, v102, v103
	global_store_dwordx4 v[112:113], v[96:99], off nt
	s_nop 1
	v_mul_f32_e32 v98, 0xbfb8aa3b, v92
	v_mul_f32_e32 v99, 0xbfb8aa3b, v93
	v_exp_f32_e32 v98, v98
	v_exp_f32_e32 v99, v99
	v_lshl_add_u64 v[96:97], v[112:113], 0, s[22:23]
	v_add_f32_e32 v98, 1.0, v98
	v_add_f32_e32 v99, 1.0, v99
	v_rcp_f32_e32 v98, v98
	v_rcp_f32_e32 v99, v99
	s_nop 0
	v_pk_mul_f32 v[92:93], v[92:93], v[98:99]
	s_nop 0
	v_pk_mul_f32 v[88:89], v[92:93], v[88:89]
	v_mul_f32_e32 v92, 0xbfb8aa3b, v94
	v_mul_f32_e32 v93, 0xbfb8aa3b, v95
	v_exp_f32_e32 v92, v92
	v_exp_f32_e32 v93, v93
	v_add_f32_e32 v92, 1.0, v92
	v_add_f32_e32 v93, 1.0, v93
	v_rcp_f32_e32 v92, v92
	v_rcp_f32_e32 v93, v93
	s_nop 0
	v_pk_mul_f32 v[92:93], v[94:95], v[92:93]
	s_nop 0
	v_pk_mul_f32 v[90:91], v[92:93], v[90:91]
	v_mul_f32_e32 v92, 0xbfb8aa3b, v84
	v_mul_f32_e32 v93, 0xbfb8aa3b, v85
	v_exp_f32_e32 v92, v92
	v_exp_f32_e32 v93, v93
	v_add_f32_e32 v92, 1.0, v92
	v_add_f32_e32 v93, 1.0, v93
	v_rcp_f32_e32 v92, v92
	v_rcp_f32_e32 v93, v93
	s_nop 0
	v_pk_mul_f32 v[84:85], v[84:85], v[92:93]
	s_nop 0
	v_pk_mul_f32 v[84:85], v[84:85], v[80:81]
	v_mul_f32_e32 v80, 0xbfb8aa3b, v86
	v_mul_f32_e32 v81, 0xbfb8aa3b, v87
	v_exp_f32_e32 v80, v80
	v_exp_f32_e32 v81, v81
	v_add_f32_e32 v80, 1.0, v80
	v_add_f32_e32 v81, 1.0, v81
	v_rcp_f32_e32 v80, v80
	v_rcp_f32_e32 v81, v81
	s_nop 0
	v_pk_mul_f32 v[80:81], v[86:87], v[80:81]
	s_nop 0
	v_pk_mul_f32 v[86:87], v[80:81], v[82:83]
	v_cvt_pk_bf16_f32 v80, v88, v89
	v_cvt_pk_bf16_f32 v81, v90, v91
	v_cvt_pk_bf16_f32 v82, v84, v85
	v_cvt_pk_bf16_f32 v83, v86, v87
	global_store_dwordx4 v[96:97], v[80:83], off nt
	s_nop 1
	v_mul_f32_e32 v82, 0xbfb8aa3b, v76
	v_mul_f32_e32 v83, 0xbfb8aa3b, v77
	v_exp_f32_e32 v82, v82
	v_exp_f32_e32 v83, v83
	v_lshl_add_u64 v[80:81], v[96:97], 0, s[22:23]
	v_add_f32_e32 v82, 1.0, v82
	v_add_f32_e32 v83, 1.0, v83
	v_rcp_f32_e32 v82, v82
	v_rcp_f32_e32 v83, v83
	s_nop 0
	v_pk_mul_f32 v[76:77], v[76:77], v[82:83]
	s_nop 0
	v_pk_mul_f32 v[72:73], v[76:77], v[72:73]
	v_mul_f32_e32 v76, 0xbfb8aa3b, v78
	v_mul_f32_e32 v77, 0xbfb8aa3b, v79
	v_exp_f32_e32 v76, v76
	v_exp_f32_e32 v77, v77
	v_add_f32_e32 v76, 1.0, v76
	v_add_f32_e32 v77, 1.0, v77
	v_rcp_f32_e32 v76, v76
	v_rcp_f32_e32 v77, v77
	s_nop 0
	v_pk_mul_f32 v[76:77], v[78:79], v[76:77]
	s_nop 0
	v_pk_mul_f32 v[74:75], v[76:77], v[74:75]
	v_mul_f32_e32 v76, 0xbfb8aa3b, v68
	v_mul_f32_e32 v77, 0xbfb8aa3b, v69
	v_exp_f32_e32 v76, v76
	v_exp_f32_e32 v77, v77
	v_add_f32_e32 v76, 1.0, v76
	v_add_f32_e32 v77, 1.0, v77
	v_rcp_f32_e32 v76, v76
	v_rcp_f32_e32 v77, v77
	s_nop 0
	v_pk_mul_f32 v[68:69], v[68:69], v[76:77]
	s_nop 0
	v_pk_mul_f32 v[68:69], v[68:69], v[64:65]
	v_mul_f32_e32 v64, 0xbfb8aa3b, v70
	v_mul_f32_e32 v65, 0xbfb8aa3b, v71
	v_exp_f32_e32 v64, v64
	v_exp_f32_e32 v65, v65
	v_add_f32_e32 v64, 1.0, v64
	v_add_f32_e32 v65, 1.0, v65
	v_rcp_f32_e32 v64, v64
	v_rcp_f32_e32 v65, v65
	s_nop 0
	v_pk_mul_f32 v[64:65], v[70:71], v[64:65]
	s_nop 0
	v_pk_mul_f32 v[70:71], v[64:65], v[66:67]
	v_cvt_pk_bf16_f32 v64, v72, v73
	v_cvt_pk_bf16_f32 v65, v74, v75
	v_cvt_pk_bf16_f32 v66, v68, v69
	v_cvt_pk_bf16_f32 v67, v70, v71
	global_store_dwordx4 v[80:81], v[64:67], off nt
	s_nop 1
	v_mul_f32_e32 v66, 0xbfb8aa3b, v60
	v_mul_f32_e32 v67, 0xbfb8aa3b, v61
	v_exp_f32_e32 v66, v66
	v_exp_f32_e32 v67, v67
	v_lshl_add_u64 v[64:65], v[80:81], 0, s[22:23]
	v_add_f32_e32 v66, 1.0, v66
	v_add_f32_e32 v67, 1.0, v67
	v_rcp_f32_e32 v66, v66
	v_rcp_f32_e32 v67, v67
	v_lshl_add_u64 v[64:65], v[64:65], 0, s[24:25]
	v_pk_mul_f32 v[60:61], v[60:61], v[66:67]
	s_nop 0
	v_pk_mul_f32 v[56:57], v[60:61], v[56:57]
	v_mul_f32_e32 v60, 0xbfb8aa3b, v62
	v_mul_f32_e32 v61, 0xbfb8aa3b, v63
	v_exp_f32_e32 v60, v60
	v_exp_f32_e32 v61, v61
	v_add_f32_e32 v60, 1.0, v60
	v_add_f32_e32 v61, 1.0, v61
	v_rcp_f32_e32 v60, v60
	v_rcp_f32_e32 v61, v61
	s_nop 0
	v_pk_mul_f32 v[60:61], v[62:63], v[60:61]
	s_nop 0
	v_pk_mul_f32 v[58:59], v[60:61], v[58:59]
	v_mul_f32_e32 v60, 0xbfb8aa3b, v52
	v_mul_f32_e32 v61, 0xbfb8aa3b, v53
	v_exp_f32_e32 v60, v60
	v_exp_f32_e32 v61, v61
	v_add_f32_e32 v60, 1.0, v60
	v_add_f32_e32 v61, 1.0, v61
	v_rcp_f32_e32 v60, v60
	v_rcp_f32_e32 v61, v61
	s_nop 0
	v_pk_mul_f32 v[52:53], v[52:53], v[60:61]
	s_nop 0
	v_pk_mul_f32 v[52:53], v[52:53], v[48:49]
	v_mul_f32_e32 v48, 0xbfb8aa3b, v54
	v_mul_f32_e32 v49, 0xbfb8aa3b, v55
	v_exp_f32_e32 v48, v48
	v_exp_f32_e32 v49, v49
	v_add_f32_e32 v48, 1.0, v48
	v_add_f32_e32 v49, 1.0, v49
	v_rcp_f32_e32 v48, v48
	v_rcp_f32_e32 v49, v49
	s_nop 0
	v_pk_mul_f32 v[48:49], v[54:55], v[48:49]
	s_nop 0
	v_pk_mul_f32 v[54:55], v[48:49], v[50:51]
	v_cvt_pk_bf16_f32 v48, v56, v57
	v_cvt_pk_bf16_f32 v49, v58, v59
	v_cvt_pk_bf16_f32 v50, v52, v53
	v_cvt_pk_bf16_f32 v51, v54, v55
	global_store_dwordx4 v[64:65], v[48:51], off nt
	s_nop 1
	v_mul_f32_e32 v50, 0xbfb8aa3b, v44
	v_mul_f32_e32 v51, 0xbfb8aa3b, v45
	v_exp_f32_e32 v50, v50
	v_exp_f32_e32 v51, v51
	v_lshl_add_u64 v[48:49], v[64:65], 0, s[22:23]
	v_add_f32_e32 v50, 1.0, v50
	v_add_f32_e32 v51, 1.0, v51
	v_rcp_f32_e32 v50, v50
	v_rcp_f32_e32 v51, v51
	s_nop 0
	v_pk_mul_f32 v[44:45], v[44:45], v[50:51]
	s_nop 0
	v_pk_mul_f32 v[40:41], v[44:45], v[40:41]
	v_mul_f32_e32 v44, 0xbfb8aa3b, v46
	v_mul_f32_e32 v45, 0xbfb8aa3b, v47
	v_exp_f32_e32 v44, v44
	v_exp_f32_e32 v45, v45
	v_add_f32_e32 v44, 1.0, v44
	v_add_f32_e32 v45, 1.0, v45
	v_rcp_f32_e32 v44, v44
	v_rcp_f32_e32 v45, v45
	s_nop 0
	v_pk_mul_f32 v[44:45], v[46:47], v[44:45]
	s_nop 0
	v_pk_mul_f32 v[42:43], v[44:45], v[42:43]
	v_mul_f32_e32 v44, 0xbfb8aa3b, v36
	v_mul_f32_e32 v45, 0xbfb8aa3b, v37
	v_exp_f32_e32 v44, v44
	v_exp_f32_e32 v45, v45
	v_add_f32_e32 v44, 1.0, v44
	v_add_f32_e32 v45, 1.0, v45
	v_rcp_f32_e32 v44, v44
	v_rcp_f32_e32 v45, v45
	s_nop 0
	v_pk_mul_f32 v[36:37], v[36:37], v[44:45]
	s_nop 0
	v_pk_mul_f32 v[36:37], v[36:37], v[32:33]
	v_mul_f32_e32 v32, 0xbfb8aa3b, v38
	v_mul_f32_e32 v33, 0xbfb8aa3b, v39
	v_exp_f32_e32 v32, v32
	v_exp_f32_e32 v33, v33
	v_add_f32_e32 v32, 1.0, v32
	v_add_f32_e32 v33, 1.0, v33
	v_rcp_f32_e32 v32, v32
	v_rcp_f32_e32 v33, v33
	s_nop 0
	v_pk_mul_f32 v[32:33], v[38:39], v[32:33]
	s_nop 0
	v_pk_mul_f32 v[38:39], v[32:33], v[34:35]
	v_cvt_pk_bf16_f32 v32, v40, v41
	v_cvt_pk_bf16_f32 v33, v42, v43
	v_cvt_pk_bf16_f32 v34, v36, v37
	v_cvt_pk_bf16_f32 v35, v38, v39
	global_store_dwordx4 v[48:49], v[32:35], off nt
	s_nop 1
	v_mul_f32_e32 v34, 0xbfb8aa3b, v28
	v_mul_f32_e32 v35, 0xbfb8aa3b, v29
	v_exp_f32_e32 v34, v34
	v_exp_f32_e32 v35, v35
	v_lshl_add_u64 v[32:33], v[48:49], 0, s[22:23]
	v_add_f32_e32 v34, 1.0, v34
	v_add_f32_e32 v35, 1.0, v35
	v_rcp_f32_e32 v34, v34
	v_rcp_f32_e32 v35, v35
	s_nop 0
	v_pk_mul_f32 v[28:29], v[28:29], v[34:35]
	s_nop 0
	v_pk_mul_f32 v[24:25], v[28:29], v[24:25]
	v_mul_f32_e32 v28, 0xbfb8aa3b, v30
	v_mul_f32_e32 v29, 0xbfb8aa3b, v31
	v_exp_f32_e32 v28, v28
	v_exp_f32_e32 v29, v29
	v_add_f32_e32 v28, 1.0, v28
	v_add_f32_e32 v29, 1.0, v29
	v_rcp_f32_e32 v28, v28
	v_rcp_f32_e32 v29, v29
	s_nop 0
	v_pk_mul_f32 v[28:29], v[30:31], v[28:29]
	s_nop 0
	v_pk_mul_f32 v[26:27], v[28:29], v[26:27]
	v_mul_f32_e32 v28, 0xbfb8aa3b, v20
	v_mul_f32_e32 v29, 0xbfb8aa3b, v21
	v_exp_f32_e32 v28, v28
	v_exp_f32_e32 v29, v29
	v_add_f32_e32 v28, 1.0, v28
	v_add_f32_e32 v29, 1.0, v29
	v_rcp_f32_e32 v28, v28
	v_rcp_f32_e32 v29, v29
	s_nop 0
	v_pk_mul_f32 v[20:21], v[20:21], v[28:29]
	s_nop 0
	v_pk_mul_f32 v[20:21], v[20:21], v[16:17]
	v_mul_f32_e32 v16, 0xbfb8aa3b, v22
	v_mul_f32_e32 v17, 0xbfb8aa3b, v23
	v_exp_f32_e32 v16, v16
	v_exp_f32_e32 v17, v17
	v_add_f32_e32 v16, 1.0, v16
	v_add_f32_e32 v17, 1.0, v17
	v_rcp_f32_e32 v16, v16
	v_rcp_f32_e32 v17, v17
	s_nop 0
	v_pk_mul_f32 v[16:17], v[22:23], v[16:17]
	s_nop 0
	v_pk_mul_f32 v[22:23], v[16:17], v[18:19]
	v_cvt_pk_bf16_f32 v16, v24, v25
	v_cvt_pk_bf16_f32 v17, v26, v27
	v_cvt_pk_bf16_f32 v18, v20, v21
	v_cvt_pk_bf16_f32 v19, v22, v23
	global_store_dwordx4 v[32:33], v[16:19], off nt
	s_nop 1
	v_mul_f32_e32 v18, 0xbfb8aa3b, v12
	v_mul_f32_e32 v19, 0xbfb8aa3b, v13
	v_exp_f32_e32 v18, v18
	v_exp_f32_e32 v19, v19
	v_lshl_add_u64 v[16:17], v[32:33], 0, s[22:23]
	v_add_f32_e32 v18, 1.0, v18
	v_add_f32_e32 v19, 1.0, v19
	v_rcp_f32_e32 v18, v18
	v_rcp_f32_e32 v19, v19
	s_nop 0
	v_pk_mul_f32 v[12:13], v[12:13], v[18:19]
	s_nop 0
	v_pk_mul_f32 v[8:9], v[12:13], v[8:9]
	v_mul_f32_e32 v12, 0xbfb8aa3b, v14
	v_mul_f32_e32 v13, 0xbfb8aa3b, v15
	v_exp_f32_e32 v12, v12
	v_exp_f32_e32 v13, v13
	v_add_f32_e32 v12, 1.0, v12
	v_add_f32_e32 v13, 1.0, v13
	v_rcp_f32_e32 v12, v12
	v_rcp_f32_e32 v13, v13
	s_nop 0
	v_pk_mul_f32 v[12:13], v[14:15], v[12:13]
	s_nop 0
	v_pk_mul_f32 v[10:11], v[12:13], v[10:11]
	v_mul_f32_e32 v12, 0xbfb8aa3b, v4
	v_mul_f32_e32 v13, 0xbfb8aa3b, v5
	v_exp_f32_e32 v12, v12
	v_exp_f32_e32 v13, v13
	v_add_f32_e32 v12, 1.0, v12
	v_add_f32_e32 v13, 1.0, v13
	v_rcp_f32_e32 v12, v12
	v_rcp_f32_e32 v13, v13
	s_nop 0
	v_pk_mul_f32 v[4:5], v[4:5], v[12:13]
	s_nop 0
	v_pk_mul_f32 v[4:5], v[4:5], v[0:1]
	v_mul_f32_e32 v0, 0xbfb8aa3b, v6
	v_mul_f32_e32 v1, 0xbfb8aa3b, v7
	v_exp_f32_e32 v0, v0
	v_exp_f32_e32 v1, v1
	v_add_f32_e32 v0, 1.0, v0
	v_add_f32_e32 v1, 1.0, v1
	v_rcp_f32_e32 v0, v0
	v_rcp_f32_e32 v1, v1
	s_nop 0
	v_pk_mul_f32 v[0:1], v[6:7], v[0:1]
	s_nop 0
	v_pk_mul_f32 v[6:7], v[0:1], v[2:3]
	v_cvt_pk_bf16_f32 v0, v8, v9
	v_cvt_pk_bf16_f32 v1, v10, v11
	v_cvt_pk_bf16_f32 v2, v4, v5
	v_cvt_pk_bf16_f32 v3, v6, v7
	global_store_dwordx4 v[16:17], v[0:3], off nt
	s_nop 1
	v_lshl_add_u64 v[0:1], v[16:17], 0, s[22:23]
	s_mov_b64 s[22:23], -1
	v_lshl_add_u64 v[0:1], v[0:1], 0, s[24:25]
	s_cbranch_vccnz .LBB0_819
	s_andn2_b64 vcc, exec, s[8:9]
	s_cbranch_vccnz .LBB0_818
	s_barrier
	s_branch .LBB0_818

.LBB0_830:
	v_readlane_b32 s4, v254, 26
	v_readlane_b32 s5, v254, 27
	v_readlane_b32 s18, v254, 40
	v_readlane_b32 s19, v254, 41
	s_mov_b64 s[4:5], s[18:19]
	v_mbcnt_lo_u32_b32 v0, -1, 0
	v_mbcnt_hi_u32_b32 v0, -1, v0
	v_readlane_b32 s2, v254, 4
	s_waitcnt vmcnt(0) lgkmcnt(0)
	v_readlane_b32 s6, v254, 28
	v_readlane_b32 s7, v254, 29
	v_cmp_eq_u32_e32 vcc, 0, v0
	v_readlane_b32 s3, v254, 5
	s_and_b64 s[6:7], s[2:3], vcc
	v_readlane_b32 s8, v254, 30
	v_readlane_b32 s9, v254, 31
	v_readlane_b32 s10, v254, 32
	v_readlane_b32 s11, v254, 33
	v_readlane_b32 s12, v254, 34
	v_readlane_b32 s13, v254, 35
	v_readlane_b32 s14, v254, 36
	v_readlane_b32 s15, v254, 37
	v_readlane_b32 s16, v254, 38
	v_readlane_b32 s17, v254, 39
	s_waitcnt vmcnt(0) lgkmcnt(0)
	s_barrier
	s_and_saveexec_b64 s[2:3], s[6:7]
	s_cbranch_execz .LBB0_846
	v_readlane_b32 s6, v255, 0
	s_add_i32 s16, s6, 15
	s_getreg_b32 s6, hwreg(HW_REG_XCC_ID, 0, 4)
	s_lshl_b32 s6, s6, 8
	s_and_b32 s6, s6, 0x700
	s_add_u32 s15, s4, s6
	s_addc_u32 s14, s5, 0
	v_mov_b32_e32 v0, s15
	v_add_co_u32_e32 v8, vcc, 0x2000, v0
	v_mov_b32_e32 v0, s14
	s_nop 0
	v_addc_co_u32_e32 v9, vcc, 0, v0, vcc
	v_mov_b32_e32 v0, s4
	v_add_co_u32_e32 v10, vcc, 0x2000, v0
	v_mov_b32_e32 v0, s5
	s_nop 0
	v_addc_co_u32_e32 v11, vcc, 0, v0, vcc
	global_load_dword v12, v[8:9], off sc1
	global_load_dword v0, v[10:11], off sc1
	global_load_dword v1, v[10:11], off offset:256 sc1
	global_load_dword v2, v[10:11], off offset:512 sc1
	global_load_dword v3, v[10:11], off offset:768 sc1
	global_load_dword v4, v[10:11], off offset:1024 sc1
	global_load_dword v5, v[10:11], off offset:1280 sc1
	global_load_dword v6, v[10:11], off offset:1536 sc1
	global_load_dword v7, v[10:11], off offset:1792 sc1
	v_mov_b32_e32 v10, 1
	global_atomic_add v8, v[8:9], v10, off offset:2048 sc0
	s_waitcnt vmcnt(0) lgkmcnt(0)
	v_mul_lo_u32 v9, v12, s16
	v_add_u32_e32 v8, 1, v8
	v_cmp_ne_u32_e32 vcc, v8, v9
	s_and_saveexec_b64 s[6:7], vcc
	s_xor_b64 s[6:7], exec, s[6:7]
	s_cbranch_execz .LBB0_836
	v_mov_b32_e32 v0, s15
	v_add_co_u32_e32 v0, vcc, 0x3000, v0
	v_mov_b32_e32 v1, s14
	s_nop 0
	v_addc_co_u32_e32 v1, vcc, 0, v1, vcc
	global_load_dword v0, v[0:1], off sc1
	s_add_u32 s8, s15, 0x3000
	s_addc_u32 s9, s14, 0
	s_waitcnt vmcnt(0) lgkmcnt(0)
	v_cmp_gt_u32_e32 vcc, s16, v0
	s_and_saveexec_b64 s[10:11], vcc
	s_cbranch_execz .LBB0_835
	s_mov_b64 s[12:13], 0

.LBB0_870:
	s_lshl_b32 s18, s42, 8
	v_mbcnt_lo_u32_b32 v141, -1, 0
	v_mbcnt_hi_u32_b32 v141, -1, v141
	s_add_i32 s18, s18, s35
	v_and_or_b32 v140, v141, 15, s18
	s_lshl_b32 s18, s43, 8
	v_ashrrev_i32_e32 v141, 1, v141
	v_and_b32_e32 v141, -8, v141
	s_or_b32 s18, s18, s36
	v_add_u32_e32 v144, s18, v141
	v_ashrrev_i32_e32 v141, 31, v140
	v_lshlrev_b64 v[140:141], 12, v[140:141]
	v_lshl_add_u64 v[140:141], s[6:7], 0, v[140:141]
	v_ashrrev_i32_e32 v145, 31, v144
	v_lshl_add_u64 v[140:141], v[144:145], 2, v[140:141]
	v_add_co_u32_e32 v204, vcc, s94, v140
	global_load_dwordx4 v[144:147], v[140:141], off
	global_load_dwordx4 v[148:151], v[140:141], off offset:16
	global_load_dwordx4 v[152:155], v[140:141], off offset:512
	global_load_dwordx4 v[156:159], v[140:141], off offset:528
	v_addc_co_u32_e32 v205, vcc, 0, v141, vcc
	v_add_co_u32_e32 v206, vcc, s0, v140
	global_load_dwordx4 v[160:163], v[204:205], off
	global_load_dwordx4 v[164:167], v[204:205], off offset:16
	global_load_dwordx4 v[168:171], v[204:205], off offset:512
	global_load_dwordx4 v[172:175], v[204:205], off offset:528
	v_addc_co_u32_e32 v207, vcc, 0, v141, vcc
	v_add_co_u32_e32 v208, vcc, s1, v140
	global_load_dwordx4 v[176:179], v[206:207], off
	global_load_dwordx4 v[180:183], v[206:207], off offset:16
	global_load_dwordx4 v[184:187], v[206:207], off offset:512
	global_load_dwordx4 v[188:191], v[206:207], off offset:528
	v_addc_co_u32_e32 v209, vcc, 0, v141, vcc
	global_load_dwordx4 v[192:195], v[208:209], off
	global_load_dwordx4 v[196:199], v[208:209], off offset:16
	global_load_dwordx4 v[200:203], v[208:209], off offset:512
	global_load_dwordx4 v[216:219], v[208:209], off offset:528
	s_mov_b64 s[18:19], 0x80000
	s_waitcnt vmcnt(0) lgkmcnt(0)
	v_pk_fma_f32 v[126:127], v[126:127], 0.5, v[146:147] op_sel_hi:[1,0,1]
	v_pk_fma_f32 v[124:125], v[124:125], 0.5, v[144:145] op_sel_hi:[1,0,1]
	v_pk_fma_f32 v[122:123], v[122:123], 0.5, v[150:151] op_sel_hi:[1,0,1]
	v_pk_fma_f32 v[98:99], v[98:99], 0.5, v[158:159] op_sel_hi:[1,0,1]
	v_pk_fma_f32 v[96:97], v[96:97], 0.5, v[156:157] op_sel_hi:[1,0,1]
	v_pk_fma_f32 v[120:121], v[120:121], 0.5, v[148:149] op_sel_hi:[1,0,1]
	v_pk_fma_f32 v[106:107], v[106:107], 0.5, v[154:155] op_sel_hi:[1,0,1]
	v_pk_fma_f32 v[104:105], v[104:105], 0.5, v[152:153] op_sel_hi:[1,0,1]
	global_store_dwordx4 v[140:141], v[124:127], off
	global_store_dwordx4 v[140:141], v[120:123], off offset:16
	global_store_dwordx4 v[140:141], v[104:107], off offset:512
	global_store_dwordx4 v[140:141], v[96:99], off offset:528
	v_pk_fma_f32 v[90:91], v[90:91], 0.5, v[170:171] op_sel_hi:[1,0,1]
	v_pk_fma_f32 v[106:107], v[114:115], 0.5, v[166:167] op_sel_hi:[1,0,1]
	v_pk_fma_f32 v[98:99], v[118:119], 0.5, v[162:163] op_sel_hi:[1,0,1]
	v_pk_fma_f32 v[96:97], v[116:117], 0.5, v[160:161] op_sel_hi:[1,0,1]
	v_pk_fma_f32 v[104:105], v[112:113], 0.5, v[164:165] op_sel_hi:[1,0,1]
	v_pk_fma_f32 v[88:89], v[88:89], 0.5, v[168:169] op_sel_hi:[1,0,1]
	v_pk_fma_f32 v[82:83], v[82:83], 0.5, v[174:175] op_sel_hi:[1,0,1]
	v_pk_fma_f32 v[64:65], v[64:65], 0.5, v[216:217] op_sel_hi:[1,0,1]
	v_pk_fma_f32 v[80:81], v[80:81], 0.5, v[172:173] op_sel_hi:[1,0,1]
	v_pk_fma_f32 v[110:111], v[110:111], 0.5, v[178:179] op_sel_hi:[1,0,1]
	v_pk_fma_f32 v[108:109], v[108:109], 0.5, v[176:177] op_sel_hi:[1,0,1]
	v_pk_fma_f32 v[102:103], v[102:103], 0.5, v[182:183] op_sel_hi:[1,0,1]
	v_pk_fma_f32 v[100:101], v[100:101], 0.5, v[180:181] op_sel_hi:[1,0,1]
	v_pk_fma_f32 v[78:79], v[78:79], 0.5, v[186:187] op_sel_hi:[1,0,1]
	v_pk_fma_f32 v[76:77], v[76:77], 0.5, v[184:185] op_sel_hi:[1,0,1]
	v_pk_fma_f32 v[74:75], v[74:75], 0.5, v[190:191] op_sel_hi:[1,0,1]
	v_pk_fma_f32 v[72:73], v[72:73], 0.5, v[188:189] op_sel_hi:[1,0,1]
	v_pk_fma_f32 v[94:95], v[94:95], 0.5, v[194:195] op_sel_hi:[1,0,1]
	v_pk_fma_f32 v[92:93], v[92:93], 0.5, v[192:193] op_sel_hi:[1,0,1]
	v_pk_fma_f32 v[86:87], v[86:87], 0.5, v[198:199] op_sel_hi:[1,0,1]
	v_pk_fma_f32 v[84:85], v[84:85], 0.5, v[196:197] op_sel_hi:[1,0,1]
	v_pk_fma_f32 v[70:71], v[70:71], 0.5, v[202:203] op_sel_hi:[1,0,1]
	v_pk_fma_f32 v[68:69], v[68:69], 0.5, v[200:201] op_sel_hi:[1,0,1]
	v_pk_fma_f32 v[66:67], v[66:67], 0.5, v[218:219] op_sel_hi:[1,0,1]
	global_store_dwordx4 v[204:205], v[96:99], off
	global_store_dwordx4 v[204:205], v[104:107], off offset:16
	global_store_dwordx4 v[204:205], v[88:91], off offset:512
	global_store_dwordx4 v[204:205], v[80:83], off offset:528
	global_store_dwordx4 v[206:207], v[108:111], off
	global_store_dwordx4 v[206:207], v[100:103], off offset:16
	global_store_dwordx4 v[206:207], v[76:79], off offset:512
	global_store_dwordx4 v[206:207], v[72:75], off offset:528
	global_store_dwordx4 v[208:209], v[92:95], off
	global_store_dwordx4 v[208:209], v[84:87], off offset:16
	global_store_dwordx4 v[208:209], v[68:71], off offset:512
	global_store_dwordx4 v[208:209], v[64:67], off offset:528
	s_nop 1
	v_lshl_add_u64 v[64:65], v[140:141], 0, s[18:19]
	v_mov_b64_e32 v[66:67], v[64:65]
	global_load_dwordx4 v[68:71], v[66:67], off
	global_load_dwordx4 v[72:75], v[66:67], off offset:16
	global_load_dwordx4 v[76:79], v[66:67], off offset:512
	global_load_dwordx4 v[80:83], v[66:67], off offset:528
	v_add_co_u32_e32 v96, vcc, s94, v66
	s_waitcnt vmcnt(0) lgkmcnt(0)
	v_pk_fma_f32 v[62:63], v[62:63], 0.5, v[70:71] op_sel_hi:[1,0,1]
	v_addc_co_u32_e32 v97, vcc, 0, v67, vcc
	v_add_co_u32_e32 v112, vcc, s0, v66
	global_load_dwordx4 v[84:87], v[96:97], off
	global_load_dwordx4 v[88:91], v[96:97], off offset:16
	global_load_dwordx4 v[92:95], v[96:97], off offset:512
	s_nop 0
	global_load_dwordx4 v[96:99], v[96:97], off offset:528
	v_addc_co_u32_e32 v113, vcc, 0, v67, vcc
	v_add_co_u32_e32 v140, vcc, s1, v66
	global_load_dwordx4 v[100:103], v[112:113], off
	global_load_dwordx4 v[104:107], v[112:113], off offset:16
	global_load_dwordx4 v[108:111], v[112:113], off offset:512
	s_nop 0
	global_load_dwordx4 v[112:115], v[112:113], off offset:528
	v_addc_co_u32_e32 v141, vcc, 0, v67, vcc
	global_load_dwordx4 v[116:119], v[140:141], off
	global_load_dwordx4 v[120:123], v[140:141], off offset:16
	global_load_dwordx4 v[124:127], v[140:141], off offset:512
	global_load_dwordx4 v[144:147], v[140:141], off offset:528
	v_add_co_u32_e32 v140, vcc, s94, v64
	v_pk_fma_f32 v[60:61], v[60:61], 0.5, v[68:69] op_sel_hi:[1,0,1]
	s_nop 0
	v_addc_co_u32_e32 v141, vcc, 0, v65, vcc
	v_add_co_u32_e32 v148, vcc, s0, v64
	v_pk_fma_f32 v[34:35], v[34:35], 0.5, v[82:83] op_sel_hi:[1,0,1]
	s_nop 0
	v_addc_co_u32_e32 v149, vcc, 0, v65, vcc
	v_add_co_u32_e32 v150, vcc, s1, v64
	v_pk_fma_f32 v[32:33], v[32:33], 0.5, v[80:81] op_sel_hi:[1,0,1]
	s_nop 0
	v_addc_co_u32_e32 v151, vcc, 0, v65, vcc
	v_pk_fma_f32 v[58:59], v[58:59], 0.5, v[74:75] op_sel_hi:[1,0,1]
	v_pk_fma_f32 v[56:57], v[56:57], 0.5, v[72:73] op_sel_hi:[1,0,1]
	v_pk_fma_f32 v[42:43], v[42:43], 0.5, v[78:79] op_sel_hi:[1,0,1]
	v_pk_fma_f32 v[40:41], v[40:41], 0.5, v[76:77] op_sel_hi:[1,0,1]
	global_store_dwordx4 v[64:65], v[60:63], off
	global_store_dwordx4 v[64:65], v[56:59], off offset:16
	global_store_dwordx4 v[64:65], v[40:43], off offset:512
	global_store_dwordx4 v[64:65], v[32:35], off offset:528
	s_and_b64 vcc, exec, s[2:3]
	s_mov_b64 s[2:3], -1
	s_waitcnt vmcnt(0) lgkmcnt(0)
	v_pk_fma_f32 v[34:35], v[54:55], 0.5, v[86:87] op_sel_hi:[1,0,1]
	v_pk_fma_f32 v[32:33], v[52:53], 0.5, v[84:85] op_sel_hi:[1,0,1]
	v_pk_fma_f32 v[42:43], v[50:51], 0.5, v[90:91] op_sel_hi:[1,0,1]
	v_pk_fma_f32 v[40:41], v[48:49], 0.5, v[88:89] op_sel_hi:[1,0,1]
	v_pk_fma_f32 v[26:27], v[26:27], 0.5, v[94:95] op_sel_hi:[1,0,1]
	v_pk_fma_f32 v[24:25], v[24:25], 0.5, v[92:93] op_sel_hi:[1,0,1]
	v_pk_fma_f32 v[22:23], v[22:23], 0.5, v[98:99] op_sel_hi:[1,0,1]
	v_pk_fma_f32 v[20:21], v[20:21], 0.5, v[96:97] op_sel_hi:[1,0,1]
	v_pk_fma_f32 v[46:47], v[46:47], 0.5, v[102:103] op_sel_hi:[1,0,1]
	v_pk_fma_f32 v[44:45], v[44:45], 0.5, v[100:101] op_sel_hi:[1,0,1]
	v_pk_fma_f32 v[38:39], v[38:39], 0.5, v[106:107] op_sel_hi:[1,0,1]
	v_pk_fma_f32 v[2:3], v[2:3], 0.5, v[146:147] op_sel_hi:[1,0,1]
	v_pk_fma_f32 v[0:1], v[0:1], 0.5, v[144:145] op_sel_hi:[1,0,1]
	v_pk_fma_f32 v[36:37], v[36:37], 0.5, v[104:105] op_sel_hi:[1,0,1]
	v_pk_fma_f32 v[18:19], v[18:19], 0.5, v[110:111] op_sel_hi:[1,0,1]
	v_pk_fma_f32 v[16:17], v[16:17], 0.5, v[108:109] op_sel_hi:[1,0,1]
	v_pk_fma_f32 v[14:15], v[14:15], 0.5, v[114:115] op_sel_hi:[1,0,1]
	v_pk_fma_f32 v[12:13], v[12:13], 0.5, v[112:113] op_sel_hi:[1,0,1]
	v_pk_fma_f32 v[30:31], v[30:31], 0.5, v[118:119] op_sel_hi:[1,0,1]
	v_pk_fma_f32 v[28:29], v[28:29], 0.5, v[116:117] op_sel_hi:[1,0,1]
	v_pk_fma_f32 v[10:11], v[10:11], 0.5, v[122:123] op_sel_hi:[1,0,1]
	global_store_dwordx4 v[140:141], v[32:35], off
	global_store_dwordx4 v[140:141], v[40:43], off offset:16
	global_store_dwordx4 v[140:141], v[24:27], off offset:512
	global_store_dwordx4 v[140:141], v[20:23], off offset:528
	global_store_dwordx4 v[148:149], v[44:47], off
	global_store_dwordx4 v[148:149], v[36:39], off offset:16
	global_store_dwordx4 v[148:149], v[16:19], off offset:512
	global_store_dwordx4 v[148:149], v[12:15], off offset:528
	global_store_dwordx4 v[150:151], v[28:31], off
	v_pk_fma_f32 v[8:9], v[8:9], 0.5, v[120:121] op_sel_hi:[1,0,1]
	v_pk_fma_f32 v[6:7], v[6:7], 0.5, v[126:127] op_sel_hi:[1,0,1]
	v_pk_fma_f32 v[4:5], v[4:5], 0.5, v[124:125] op_sel_hi:[1,0,1]
	global_store_dwordx4 v[150:151], v[0:3], off offset:528
	global_store_dwordx4 v[150:151], v[8:11], off offset:16
	global_store_dwordx4 v[150:151], v[4:7], off offset:512
	v_lshl_add_u64 v[0:1], v[66:67], 0, s[18:19]
	v_lshl_add_u64 v[2:3], v[64:65], 0, s[18:19]
	s_cbranch_vccnz .LBB0_855
	s_andn2_b64 vcc, exec, s[12:13]
	s_cbranch_vccnz .LBB0_854
	s_barrier
	s_branch .LBB0_854

.LBB0_875:
	s_getreg_b32 s6, hwreg(HW_REG_XCC_ID, 0, 4)
	s_lshl_b32 s6, s6, 8
	s_and_b32 s6, s6, 0x700
	s_add_u32 s15, s4, s6
	s_addc_u32 s14, s5, 0
	v_mov_b32_e32 v0, s15
	v_add_co_u32_e32 v8, vcc, 0x2000, v0
	v_mov_b32_e32 v0, s14
	s_nop 0
	v_addc_co_u32_e32 v9, vcc, 0, v0, vcc
	v_mov_b32_e32 v0, s4
	v_add_co_u32_e32 v10, vcc, 0x2000, v0
	v_mov_b32_e32 v0, s5
	s_nop 0
	v_addc_co_u32_e32 v11, vcc, 0, v0, vcc
	global_load_dword v12, v[8:9], off sc1
	global_load_dword v0, v[10:11], off sc1
	global_load_dword v1, v[10:11], off offset:256 sc1
	global_load_dword v2, v[10:11], off offset:512 sc1
	global_load_dword v3, v[10:11], off offset:768 sc1
	global_load_dword v4, v[10:11], off offset:1024 sc1
	global_load_dword v5, v[10:11], off offset:1280 sc1
	global_load_dword v6, v[10:11], off offset:1536 sc1
	global_load_dword v7, v[10:11], off offset:1792 sc1
	v_mov_b32_e32 v10, 1
	global_atomic_add v8, v[8:9], v10, off offset:2048 sc0
	s_waitcnt vmcnt(0) lgkmcnt(0)
	v_mul_lo_u32 v9, v12, s34
	v_add_u32_e32 v8, 1, v8
	v_cmp_ne_u32_e32 vcc, v8, v9
	s_and_saveexec_b64 s[6:7], vcc
	s_xor_b64 s[6:7], exec, s[6:7]
	s_cbranch_execz .LBB0_880
	v_mov_b32_e32 v0, s15
	v_add_co_u32_e32 v0, vcc, 0x3000, v0
	v_mov_b32_e32 v1, s14
	s_nop 0
	v_addc_co_u32_e32 v1, vcc, 0, v1, vcc
	global_load_dword v0, v[0:1], off sc1
	s_add_u32 s8, s15, 0x3000
	s_addc_u32 s9, s14, 0
	s_waitcnt vmcnt(0) lgkmcnt(0)
	v_cmp_gt_u32_e32 vcc, s34, v0
	s_and_saveexec_b64 s[10:11], vcc
	s_cbranch_execz .LBB0_879
	s_mov_b64 s[12:13], 0
.LBB0_878:
	v_mov_b64_e32 v[0:1], s[8:9]
	s_sleep 2
	global_load_dword v0, v[0:1], off sc1
	s_waitcnt vmcnt(0) lgkmcnt(0)
	v_readfirstlane_b32 s16, v0
	s_cmp_ge_u32 s16, s34
	s_cselect_b64 s[16:17], -1, 0
	s_and_b64 s[16:17], exec, s[16:17]
	s_or_b64 s[12:13], s[16:17], s[12:13]
	s_andn2_b64 exec, exec, s[12:13]
	s_cbranch_execnz .LBB0_878

.LBB0_881:
	v_cmp_ne_u32_e32 vcc, 0, v0
	s_movk_i32 s8, 0x3000
	buffer_wbl2 sc1
	v_cndmask_b32_e64 v0, 0, 1, vcc
	v_cmp_ne_u32_e32 vcc, 0, v1
	s_waitcnt vmcnt(0)
	s_nop 1
	v_addc_co_u32_e32 v0, vcc, 0, v0, vcc
	v_cmp_ne_u32_e32 vcc, 0, v2
	s_nop 1
	v_cndmask_b32_e64 v1, 0, 1, vcc
	v_cmp_ne_u32_e32 vcc, 0, v3
	v_mov_b32_e32 v3, 1
	s_nop 0
	v_addc_co_u32_e32 v0, vcc, v0, v1, vcc
	v_cmp_ne_u32_e32 vcc, 0, v4
	s_nop 1
	v_cndmask_b32_e64 v1, 0, 1, vcc
	v_cmp_ne_u32_e32 vcc, 0, v5
	s_nop 1
	v_addc_co_u32_e32 v0, vcc, v0, v1, vcc
	v_cmp_ne_u32_e32 vcc, 0, v6
	s_nop 1
	v_cndmask_b32_e64 v1, 0, 1, vcc
	v_cmp_ne_u32_e32 vcc, 0, v7
	s_nop 1
	v_addc_co_u32_e32 v2, vcc, v0, v1, vcc
	v_mov_b32_e32 v0, s4
	v_add_co_u32_e32 v0, vcc, s8, v0
	v_mov_b32_e32 v1, s5
	s_nop 0
	v_addc_co_u32_e32 v1, vcc, 0, v1, vcc
	global_atomic_add v0, v[0:1], v3, off offset:2048 sc0
	v_mul_lo_u32 v1, v2, s34
	s_add_u32 s4, s4, 0x3900
	s_addc_u32 s5, s5, 0
	s_waitcnt vmcnt(0) lgkmcnt(0)
	v_add_u32_e32 v0, 1, v0
	v_cmp_ne_u32_e32 vcc, v0, v1
	s_and_saveexec_b64 s[8:9], vcc
	s_xor_b64 s[8:9], exec, s[8:9]
	s_cbranch_execz .LBB0_886
	v_mov_b64_e32 v[0:1], s[4:5]
	global_load_dword v0, v[0:1], off sc1
	s_waitcnt vmcnt(0) lgkmcnt(0)
	v_cmp_gt_u32_e32 vcc, s34, v0
	s_and_saveexec_b64 s[10:11], vcc
	s_cbranch_execz .LBB0_885
	s_mov_b64 s[12:13], 0
.LBB0_884:
	v_mov_b64_e32 v[0:1], s[4:5]
	s_sleep 2
	global_load_dword v0, v[0:1], off sc1
	s_waitcnt vmcnt(0) lgkmcnt(0)
	v_readfirstlane_b32 s16, v0
	s_cmp_ge_u32 s16, s34
	s_cselect_b64 s[16:17], -1, 0
	s_and_b64 s[16:17], exec, s[16:17]
	s_or_b64 s[12:13], s[16:17], s[12:13]
	s_andn2_b64 exec, exec, s[12:13]
	s_cbranch_execnz .LBB0_884

.LBB0_887:
	v_mov_b64_e32 v[0:1], s[4:5]
	v_mov_b32_e32 v2, 1
	global_atomic_add v[0:1], v2, off
	s_getpc_b64 s[98:99]

.LBB0_890:
	global_load_dwordx4 v[26:29], v[16:17], off
	global_load_dwordx4 v[30:33], v[16:17], off offset:1024
	global_load_dwordx4 v[34:37], v[16:17], off offset:3072
	global_load_dwordx4 v[38:41], v[16:17], off offset:2048
	s_add_i32 s2, s2, s4
	s_cmp_lt_i32 s2, 0x8000
	s_waitcnt vmcnt(0) lgkmcnt(0)
	v_pk_mul_f32 v[42:43], v[28:29], v[28:29]
	v_pk_mul_f32 v[44:45], v[26:27], v[26:27]
	v_pk_mul_f32 v[46:47], v[32:33], v[32:33]
	v_pk_mul_f32 v[48:49], v[30:31], v[30:31]
	v_pk_mov_b32 v[54:55], v[44:45], v[42:43] op_sel:[1,0]
	v_mov_b32_e32 v45, v43
	v_pk_mov_b32 v[42:43], v[48:49], v[46:47] op_sel:[1,0]
	v_mov_b32_e32 v49, v47
	v_mul_f32_e32 v53, v34, v34
	v_mul_f32_e32 v50, v39, v39
	v_mul_f32_e32 v52, v41, v41
	v_pk_add_f32 v[44:45], v[54:55], v[44:45]
	v_pk_add_f32 v[42:43], v[42:43], v[48:49]
	v_mul_f32_e32 v56, v35, v35
	v_mul_f32_e32 v57, v36, v36
	v_mul_f32_e32 v58, v37, v37
	v_pk_fma_f32 v[46:47], v[38:39], v[38:39], v[50:51] op_sel_hi:[1,1,0]
	v_pk_fma_f32 v[50:51], v[40:41], v[40:41], v[52:53] op_sel_hi:[1,1,0]
	v_pk_add_f32 v[44:45], v[44:45], v[44:45] op_sel:[0,1] op_sel_hi:[1,0]
	v_pk_add_f32 v[42:43], v[42:43], v[42:43] op_sel:[0,1] op_sel_hi:[1,0]
	v_mov_b32_e32 v47, v57
	v_mov_b32_e32 v51, v58
	v_mov_b32_e32 v45, v53
	v_mov_b32_e32 v43, v56
	v_pk_add_f32 v[46:47], v[46:47], v[50:51]
	v_pk_add_f32 v[42:43], v[44:45], v[42:43]
	s_nop 0
	v_pk_add_f32 v[42:43], v[42:43], v[46:47]
	s_nop 0
	v_add_f32_e32 v42, v42, v43
	ds_bpermute_b32 v43, v18, v42
	s_waitcnt lgkmcnt(0)
	v_add_f32_e32 v42, v42, v43
	ds_bpermute_b32 v43, v19, v42
	s_waitcnt lgkmcnt(0)
	v_add_f32_e32 v42, v42, v43
	ds_bpermute_b32 v43, v20, v42
	s_waitcnt lgkmcnt(0)
	v_add_f32_e32 v42, v42, v43
	ds_bpermute_b32 v43, v21, v42
	s_waitcnt lgkmcnt(0)
	v_add_f32_e32 v42, v42, v43
	ds_bpermute_b32 v43, v22, v42
	s_waitcnt lgkmcnt(0)
	v_add_f32_e32 v42, v42, v43
	ds_bpermute_b32 v43, v23, v42
	s_waitcnt lgkmcnt(0)
	v_add_f32_e32 v42, v42, v43
	v_fmamk_f32 v42, v42, 0x3a800000, v24
	v_mul_f32_e32 v43, 0x4f800000, v42
	v_cmp_gt_f32_e32 vcc, s3, v42
	s_nop 1
	v_cndmask_b32_e32 v42, v42, v43, vcc
	v_sqrt_f32_e32 v43, v42
	s_nop 0
	v_add_u32_e32 v44, -1, v43
	v_add_u32_e32 v45, 1, v43
	v_fma_f32 v46, -v44, v43, v42
	v_fma_f32 v47, -v45, v43, v42
	v_cmp_ge_f32_e64 s[0:1], 0, v46
	s_nop 1
	v_cndmask_b32_e64 v43, v43, v44, s[0:1]
	v_cmp_lt_f32_e64 s[0:1], 0, v47
	s_nop 1
	v_cndmask_b32_e64 v43, v43, v45, s[0:1]
	v_mul_f32_e32 v44, 0x37800000, v43
	v_cndmask_b32_e32 v43, v43, v44, vcc
	v_cmp_class_f32_e32 vcc, v42, v25
	s_nop 1
	v_cndmask_b32_e32 v42, v43, v42, vcc
	v_div_scale_f32 v43, s[0:1], v42, v42, 1.0
	v_rcp_f32_e32 v44, v43
	v_div_scale_f32 v45, vcc, 1.0, v42, 1.0
	v_fma_f32 v46, -v43, v44, 1.0
	v_fmac_f32_e32 v44, v46, v44
	v_mul_f32_e32 v46, v45, v44
	v_fma_f32 v47, -v43, v46, v45
	v_fmac_f32_e32 v46, v47, v44
	v_fma_f32 v43, -v43, v46, v45
	v_div_fmas_f32 v43, v43, v44, v46
	v_div_fixup_f32 v42, v43, v42, 1.0
	v_pk_mul_f32 v[26:27], v[26:27], v[42:43] op_sel_hi:[1,0]
	v_pk_mul_f32 v[28:29], v[28:29], v[42:43] op_sel_hi:[1,0]
	v_pk_mul_f32 v[30:31], v[30:31], v[42:43] op_sel_hi:[1,0]
	v_pk_mul_f32 v[32:33], v[32:33], v[42:43] op_sel_hi:[1,0]
	v_pk_mul_f32 v[38:39], v[38:39], v[42:43] op_sel_hi:[1,0]
	v_pk_mul_f32 v[40:41], v[40:41], v[42:43] op_sel_hi:[1,0]
	v_pk_mul_f32 v[44:45], v[34:35], v[42:43] op_sel_hi:[1,0]
	v_pk_mul_f32 v[42:43], v[36:37], v[42:43] op_sel_hi:[1,0]
	v_pk_mul_f32 v[28:29], v[2:3], v[28:29]
	v_pk_mul_f32 v[26:27], v[0:1], v[26:27]
	v_pk_mul_f32 v[32:33], v[6:7], v[32:33]
	v_pk_mul_f32 v[30:31], v[4:5], v[30:31]
	v_pk_mul_f32 v[36:37], v[10:11], v[40:41]
	v_pk_mul_f32 v[34:35], v[8:9], v[38:39]
	v_pk_mul_f32 v[40:41], v[14:15], v[42:43]
	v_pk_mul_f32 v[38:39], v[12:13], v[44:45]
	global_store_dwordx4 v[16:17], v[26:29], off
	global_store_dwordx4 v[16:17], v[30:33], off offset:1024
	global_store_dwordx4 v[16:17], v[34:37], off offset:2048
	global_store_dwordx4 v[16:17], v[38:41], off offset:3072
	v_lshl_add_u64 v[16:17], v[16:17], 0, s[6:7]
	s_cbranch_scc1 .LBB0_890
